# GEMM K-loops: removed the redundant s_setprio 0 / s_setprio 1 pair in the middle of each 32-MFMA section
# baseline (speedup 1.0000x reference)
; #define PG8_STAGE(bufoff, gbase, voff) do { _Pragma("unroll") for (int _i = 0; _i < 2; ++_i) \
;         __builtin_amdgcn_global_load_lds((const unsigned*)((const char*)(gbase) + (voff)[_i]), (PG8_LAS unsigned*)(lds + (bufoff) + ldsw + _i * 8192), 16, 0, 0); } while (0)
; #define PG8_LDA(dst, b, h) do { _Pragma("unroll") for (int m = 0; m < 4; ++m) _Pragma("unroll") for (int k = 0; k < 2; ++k) dst[m][k] = *(const PG8_LAS bf16x8*)(lds + PG8_SA(b, h) + aoff + m * 2048 + k * 1024); } while (0)
; #define PG8_LDB(dst, b, h) do { _Pragma("unroll") for (int n = 0; n < 2; ++n) _Pragma("unroll") for (int k = 0; k < 2; ++k) dst[n][k] = *(const PG8_LAS bf16x8*)(lds + PG8_SB(b, h) + boff + n * 2048 + k * 1024); } while (0)
; #define PG8_MMA(ai, bj, At, Bt) do { __builtin_amdgcn_s_setprio(1); _Pragma("unroll") for (int m = 0; m < 4; ++m) _Pragma("unroll") for (int n = 0; n < 2; ++n) _Pragma("unroll") for (int k = 0; k < 2; ++k) \
;         acc[ai][bj][m][n] = __builtin_amdgcn_mfma_f32_16x16x32_bf16(Bt[n][k], At[m][k], acc[ai][bj][m][n], 0, 0, 0); __builtin_amdgcn_s_setprio(0); } while (0)
; #define PG8_WAIT_V(n) asm volatile("s_waitcnt vmcnt(" #n ")" ::: "memory")
; #define PG8_BAR __builtin_amdgcn_s_barrier()
; template <class Epi, class Sched, bool ALIGN_EPI = false, bool SP2 = false>
; __device__ __forceinline__ void gemm_phase(PG8_LAS unsigned char* lds, const Gemm g, const Sched& S, const Epi& E) {
;     ...
;         for (int t = 0; t < nt; t += 2) {
;             const bool last = (t == nt - 2);
;             const char* a1 = cA + (size_t)(t + 1) * kstepA;
;             const char* a2 = last ? nA : cA + (size_t)(t + 2) * kstepA; const char* b2 = last ? nB : cB + (size_t)(t + 2) * kstep;
;             const char* a3 = a2 + kstepA; const char* b3 = b2 + kstep;
;             if (last && has_next) S.a_ready(nxt);
;             if constexpr (SP2) {
;             PG8_LDB(B0, 0, 0); PG8_LDB(B1, 0, 1); PG8_SCHED; PG8_LDA(At, 0, 0); PG8_STAGE(PG8_SA(1, 1), a1 + hstepA, voffA);
;             PG8_WAIT_V(8); PG8_WAIT_L(0); PG8_BAR; PG8_MMA(0, 0, At, B0); PG8_MMA(0, 1, At, B1); PG8_BAR; PG8_SCHED;
;             PG8_LDA(At, 0, 1); PG8_STAGE(PG8_SB(0, 0), b2, voffB); PG8_STAGE(PG8_SB(0, 1), b2 + hstep, voffB); PG8_STAGE(PG8_SA(0, 0), a2, voffA);
;             PG8_WAIT_V(8); PG8_WAIT_L(0); PG8_BAR; PG8_MMA(1, 0, At, B0); PG8_MMA(1, 1, At, B1); PG8_BAR; PG8_SCHED;
.LBB0_115:
	ds_read_b128 v[150:153], v158
	ds_read_b128 v[162:165], v158 offset:1024
	ds_read_b128 v[166:169], v158 offset:2048
	ds_read_b128 v[170:173], v158 offset:3072
	ds_read_b128 v[174:177], v159
	ds_read_b128 v[178:181], v159 offset:1024
	ds_read_b128 v[182:185], v159 offset:2048
	ds_read_b128 v[186:189], v159 offset:3072
	s_add_u32 s68, s34, 0xfff00080
	s_addc_u32 s69, s35, -1
	s_cmp_eq_u32 s67, 60
	s_cselect_b32 s87, s21, s69
	s_cselect_b32 s86, s27, s68
	s_cselect_b32 s85, s19, s66
	s_cselect_b32 s84, s31, s65
	v_lshl_add_u64 v[154:155], s[34:35], 0, v[140:141]
	s_add_i32 m0, s53, 0xc000
	ds_read_b128 v[190:193], v160
	ds_read_b128 v[194:197], v160 offset:1024
	ds_read_b128 v[198:201], v160 offset:2048
	ds_read_b128 v[202:205], v160 offset:3072
	ds_read_b128 v[206:209], v160 offset:4096
	ds_read_b128 v[210:213], v160 offset:5120
	ds_read_b128 v[214:217], v160 offset:6144
	ds_read_b128 v[218:221], v160 offset:7168
	global_load_lds_dwordx4 v[154:155], off
	v_lshl_add_u64 v[154:155], s[34:35], 0, v[142:143]
	s_add_i32 m0, s53, 0xe000
	s_nop 0
	global_load_lds_dwordx4 v[154:155], off
	s_waitcnt vmcnt(8)
	s_waitcnt lgkmcnt(0)
	s_barrier
	s_setprio 1
	s_waitcnt lgkmcnt(0)
	v_mfma_f32_16x16x32_bf16 v[124:127], v[150:153], v[190:193], v[124:127]
	v_mfma_f32_16x16x32_bf16 v[120:123], v[166:169], v[190:193], v[120:123]
	v_mfma_f32_16x16x32_bf16 v[108:111], v[150:153], v[198:201], v[108:111]
	v_mfma_f32_16x16x32_bf16 v[104:107], v[166:169], v[198:201], v[104:107]
	v_mfma_f32_16x16x32_bf16 v[92:95], v[150:153], v[206:209], v[92:95]
	v_mfma_f32_16x16x32_bf16 v[88:91], v[166:169], v[206:209], v[88:91]
	v_mfma_f32_16x16x32_bf16 v[76:79], v[150:153], v[214:217], v[76:79]
	v_mfma_f32_16x16x32_bf16 v[72:75], v[166:169], v[214:217], v[72:75]
	v_mfma_f32_16x16x32_bf16 v[124:127], v[162:165], v[194:197], v[124:127]
	v_mfma_f32_16x16x32_bf16 v[120:123], v[170:173], v[194:197], v[120:123]
	v_mfma_f32_16x16x32_bf16 v[108:111], v[162:165], v[202:205], v[108:111]
	v_mfma_f32_16x16x32_bf16 v[104:107], v[170:173], v[202:205], v[104:107]
	v_mfma_f32_16x16x32_bf16 v[92:95], v[162:165], v[210:213], v[92:95]
	v_mfma_f32_16x16x32_bf16 v[88:91], v[170:173], v[210:213], v[88:91]
	v_mfma_f32_16x16x32_bf16 v[76:79], v[162:165], v[218:221], v[76:79]
	v_mfma_f32_16x16x32_bf16 v[72:75], v[170:173], v[218:221], v[72:75]
	v_mfma_f32_16x16x32_bf16 v[116:119], v[174:177], v[190:193], v[116:119]
	v_mfma_f32_16x16x32_bf16 v[112:115], v[182:185], v[190:193], v[112:115]
	v_mfma_f32_16x16x32_bf16 v[100:103], v[174:177], v[198:201], v[100:103]
	v_mfma_f32_16x16x32_bf16 v[96:99], v[182:185], v[198:201], v[96:99]
	v_mfma_f32_16x16x32_bf16 v[84:87], v[174:177], v[206:209], v[84:87]
	v_mfma_f32_16x16x32_bf16 v[80:83], v[182:185], v[206:209], v[80:83]
	v_mfma_f32_16x16x32_bf16 v[68:71], v[174:177], v[214:217], v[68:71]
	v_mfma_f32_16x16x32_bf16 v[64:67], v[182:185], v[214:217], v[64:67]
	v_mfma_f32_16x16x32_bf16 v[116:119], v[178:181], v[194:197], v[116:119]
	v_mfma_f32_16x16x32_bf16 v[112:115], v[186:189], v[194:197], v[112:115]
	v_mfma_f32_16x16x32_bf16 v[100:103], v[178:181], v[202:205], v[100:103]
	v_mfma_f32_16x16x32_bf16 v[96:99], v[186:189], v[202:205], v[96:99]
	v_mfma_f32_16x16x32_bf16 v[84:87], v[178:181], v[210:213], v[84:87]
	v_mfma_f32_16x16x32_bf16 v[80:83], v[186:189], v[210:213], v[80:83]
	v_mfma_f32_16x16x32_bf16 v[68:71], v[178:181], v[218:221], v[68:71]
	v_mfma_f32_16x16x32_bf16 v[64:67], v[186:189], v[218:221], v[64:67]
	s_setprio 0
	s_barrier
	s_add_i32 s68, s62, s33
	v_lshl_add_u64 v[154:155], s[84:85], 0, v[132:133]
	s_mov_b32 m0, s68
	ds_read_b128 v[190:193], v160 offset:16384
	ds_read_b128 v[194:197], v160 offset:17408
	ds_read_b128 v[198:201], v160 offset:18432
	ds_read_b128 v[202:205], v160 offset:19456
	ds_read_b128 v[206:209], v160 offset:20480
	ds_read_b128 v[210:213], v160 offset:21504
	ds_read_b128 v[214:217], v160 offset:22528
	ds_read_b128 v[218:221], v160 offset:23552
	global_load_lds_dwordx4 v[154:155], off
	s_add_i32 m0, s68, 0x2000
	s_add_u32 s68, s84, 0x100000
	v_lshl_add_u64 v[222:223], s[84:85], 0, v[128:129]
	s_addc_u32 s69, s85, 0
	s_add_i32 s70, s63, s33
	global_load_lds_dwordx4 v[222:223], off
	v_lshl_add_u64 v[224:225], s[68:69], 0, v[132:133]
	s_mov_b32 m0, s70
	v_lshl_add_u64 v[226:227], s[86:87], 0, v[130:131]
	global_load_lds_dwordx4 v[224:225], off
	v_lshl_add_u64 v[224:225], s[68:69], 0, v[128:129]
	s_add_i32 m0, s70, 0x2000
	s_nop 0
	global_load_lds_dwordx4 v[224:225], off
	v_lshl_add_u64 v[224:225], s[86:87], 0, v[134:135]
	s_mov_b32 m0, s53
	s_nop 0
	global_load_lds_dwordx4 v[224:225], off
	s_mov_b32 m0, s54
	s_nop 0
	global_load_lds_dwordx4 v[226:227], off
	s_waitcnt vmcnt(8)
	s_waitcnt lgkmcnt(0)
	s_barrier
; #define PG8_STAGE(bufoff, gbase, voff) do { _Pragma("unroll") for (int _i = 0; _i < 2; ++_i) \
;         __builtin_amdgcn_global_load_lds((const unsigned*)((const char*)(gbase) + (voff)[_i]), (PG8_LAS unsigned*)(lds + (bufoff) + ldsw + _i * 8192), 16, 0, 0); } while (0)
; #define PG8_LDA(dst, b, h) do { _Pragma("unroll") for (int m = 0; m < 4; ++m) _Pragma("unroll") for (int k = 0; k < 2; ++k) dst[m][k] = *(const PG8_LAS bf16x8*)(lds + PG8_SA(b, h) + aoff + m * 2048 + k * 1024); } while (0)
; #define PG8_LDB(dst, b, h) do { _Pragma("unroll") for (int n = 0; n < 2; ++n) _Pragma("unroll") for (int k = 0; k < 2; ++k) dst[n][k] = *(const PG8_LAS bf16x8*)(lds + PG8_SB(b, h) + boff + n * 2048 + k * 1024); } while (0)
; #define PG8_MMA(ai, bj, At, Bt) do { __builtin_amdgcn_s_setprio(1); _Pragma("unroll") for (int m = 0; m < 4; ++m) _Pragma("unroll") for (int n = 0; n < 2; ++n) _Pragma("unroll") for (int k = 0; k < 2; ++k) \
;         acc[ai][bj][m][n] = __builtin_amdgcn_mfma_f32_16x16x32_bf16(Bt[n][k], At[m][k], acc[ai][bj][m][n], 0, 0, 0); __builtin_amdgcn_s_setprio(0); } while (0)
; #define PG8_WAIT_V(n) asm volatile("s_waitcnt vmcnt(" #n ")" ::: "memory")
; #define PG8_WAIT_L(n) asm volatile("s_waitcnt lgkmcnt(" #n ")" ::: "memory")
; #define PG8_BAR __builtin_amdgcn_s_barrier()
; #define PG8_SCHED __builtin_amdgcn_sched_barrier(0)
; template <class Epi, class Sched, bool ALIGN_EPI = false, bool SP2 = false>
; __device__ __forceinline__ void gemm_phase(PG8_LAS unsigned char* lds, const Gemm g, const Sched& S, const Epi& E) {
;     ...
;             PG8_WAIT_V(8); PG8_WAIT_L(0); PG8_BAR; PG8_MMA(1, 0, At, B0); PG8_MMA(1, 1, At, B1); PG8_BAR; PG8_SCHED;
;             PG8_LDB(B0, 1, 0); PG8_LDB(B1, 1, 1); PG8_SCHED; PG8_LDA(At, 1, 0); PG8_STAGE(PG8_SA(0, 1), a2 + hstepA, voffA);
;             PG8_WAIT_V(8); PG8_WAIT_L(0); PG8_BAR; PG8_MMA(0, 0, At, B0); PG8_MMA(0, 1, At, B1); PG8_BAR; PG8_SCHED;
	s_setprio 1
	s_waitcnt lgkmcnt(0)
	v_mfma_f32_16x16x32_bf16 v[60:63], v[150:153], v[190:193], v[60:63]
	v_mfma_f32_16x16x32_bf16 v[56:59], v[166:169], v[190:193], v[56:59]
	v_mfma_f32_16x16x32_bf16 v[44:47], v[150:153], v[198:201], v[44:47]
	v_mfma_f32_16x16x32_bf16 v[40:43], v[166:169], v[198:201], v[40:43]
	v_mfma_f32_16x16x32_bf16 v[28:31], v[150:153], v[206:209], v[28:31]
	v_mfma_f32_16x16x32_bf16 v[24:27], v[166:169], v[206:209], v[24:27]
	v_mfma_f32_16x16x32_bf16 v[12:15], v[150:153], v[214:217], v[12:15]
	v_mfma_f32_16x16x32_bf16 v[8:11], v[166:169], v[214:217], v[8:11]
	v_mfma_f32_16x16x32_bf16 v[60:63], v[162:165], v[194:197], v[60:63]
	v_mfma_f32_16x16x32_bf16 v[56:59], v[170:173], v[194:197], v[56:59]
	v_mfma_f32_16x16x32_bf16 v[44:47], v[162:165], v[202:205], v[44:47]
	v_mfma_f32_16x16x32_bf16 v[40:43], v[170:173], v[202:205], v[40:43]
	v_mfma_f32_16x16x32_bf16 v[28:31], v[162:165], v[210:213], v[28:31]
	v_mfma_f32_16x16x32_bf16 v[24:27], v[170:173], v[210:213], v[24:27]
	v_mfma_f32_16x16x32_bf16 v[12:15], v[162:165], v[218:221], v[12:15]
	v_mfma_f32_16x16x32_bf16 v[8:11], v[170:173], v[218:221], v[8:11]
	v_mfma_f32_16x16x32_bf16 v[52:55], v[174:177], v[190:193], v[52:55]
	v_mfma_f32_16x16x32_bf16 v[48:51], v[182:185], v[190:193], v[48:51]
	v_mfma_f32_16x16x32_bf16 v[36:39], v[174:177], v[198:201], v[36:39]
	v_mfma_f32_16x16x32_bf16 v[32:35], v[182:185], v[198:201], v[32:35]
	v_mfma_f32_16x16x32_bf16 v[20:23], v[174:177], v[206:209], v[20:23]
	v_mfma_f32_16x16x32_bf16 v[16:19], v[182:185], v[206:209], v[16:19]
	v_mfma_f32_16x16x32_bf16 v[4:7], v[174:177], v[214:217], v[4:7]
	v_mfma_f32_16x16x32_bf16 v[0:3], v[182:185], v[214:217], v[0:3]
	v_mfma_f32_16x16x32_bf16 v[52:55], v[178:181], v[194:197], v[52:55]
	v_mfma_f32_16x16x32_bf16 v[48:51], v[186:189], v[194:197], v[48:51]
	v_mfma_f32_16x16x32_bf16 v[36:39], v[178:181], v[202:205], v[36:39]
	v_mfma_f32_16x16x32_bf16 v[32:35], v[186:189], v[202:205], v[32:35]
	v_mfma_f32_16x16x32_bf16 v[20:23], v[178:181], v[210:213], v[20:23]
	v_mfma_f32_16x16x32_bf16 v[16:19], v[186:189], v[210:213], v[16:19]
	v_mfma_f32_16x16x32_bf16 v[4:7], v[178:181], v[218:221], v[4:7]
	v_mfma_f32_16x16x32_bf16 v[0:3], v[186:189], v[218:221], v[0:3]
	s_setprio 0
	s_barrier
	s_add_i32 s70, 0, 0x18000
	v_add_u32_e32 v136, s70, v157
	s_add_i32 s71, 0, 0x1c000
	ds_read_b128 v[150:153], v136
	ds_read_b128 v[162:165], v136 offset:1024
	ds_read_b128 v[166:169], v136 offset:2048
	ds_read_b128 v[170:173], v136 offset:3072
	v_add_u32_e32 v136, s71, v157
	ds_read_b128 v[174:177], v136
	ds_read_b128 v[178:181], v136 offset:1024
	ds_read_b128 v[182:185], v136 offset:2048
	ds_read_b128 v[186:189], v136 offset:3072
	s_add_u32 s68, s86, 0x100000
	s_addc_u32 s69, s87, 0
	s_mov_b32 m0, s55
	v_lshl_add_u64 v[228:229], s[68:69], 0, v[134:135]
	ds_read_b128 v[190:193], v160 offset:32768
	ds_read_b128 v[194:197], v160 offset:33792
	ds_read_b128 v[198:201], v160 offset:34816
	ds_read_b128 v[202:205], v160 offset:35840
	ds_read_b128 v[206:209], v160 offset:36864
	ds_read_b128 v[210:213], v160 offset:37888
	ds_read_b128 v[214:217], v160 offset:38912
	ds_read_b128 v[218:221], v160 offset:39936
	global_load_lds_dwordx4 v[228:229], off
	v_lshl_add_u64 v[228:229], s[68:69], 0, v[130:131]
	s_mov_b32 m0, s56
	s_nop 0
	global_load_lds_dwordx4 v[228:229], off
	s_waitcnt vmcnt(8)
	s_waitcnt lgkmcnt(0)
	s_barrier
	s_setprio 1
	s_waitcnt lgkmcnt(0)
	v_mfma_f32_16x16x32_bf16 v[124:127], v[150:153], v[190:193], v[124:127]
	v_mfma_f32_16x16x32_bf16 v[120:123], v[166:169], v[190:193], v[120:123]
	v_mfma_f32_16x16x32_bf16 v[108:111], v[150:153], v[198:201], v[108:111]
	v_mfma_f32_16x16x32_bf16 v[104:107], v[166:169], v[198:201], v[104:107]
	v_mfma_f32_16x16x32_bf16 v[92:95], v[150:153], v[206:209], v[92:95]
	v_mfma_f32_16x16x32_bf16 v[88:91], v[166:169], v[206:209], v[88:91]
	v_mfma_f32_16x16x32_bf16 v[76:79], v[150:153], v[214:217], v[76:79]
	v_mfma_f32_16x16x32_bf16 v[72:75], v[166:169], v[214:217], v[72:75]
	v_mfma_f32_16x16x32_bf16 v[124:127], v[162:165], v[194:197], v[124:127]
	v_mfma_f32_16x16x32_bf16 v[120:123], v[170:173], v[194:197], v[120:123]
	v_mfma_f32_16x16x32_bf16 v[108:111], v[162:165], v[202:205], v[108:111]
	v_mfma_f32_16x16x32_bf16 v[104:107], v[170:173], v[202:205], v[104:107]
	v_mfma_f32_16x16x32_bf16 v[92:95], v[162:165], v[210:213], v[92:95]
	v_mfma_f32_16x16x32_bf16 v[88:91], v[170:173], v[210:213], v[88:91]
	v_mfma_f32_16x16x32_bf16 v[76:79], v[162:165], v[218:221], v[76:79]
	v_mfma_f32_16x16x32_bf16 v[72:75], v[170:173], v[218:221], v[72:75]
	v_mfma_f32_16x16x32_bf16 v[116:119], v[174:177], v[190:193], v[116:119]
	v_mfma_f32_16x16x32_bf16 v[112:115], v[182:185], v[190:193], v[112:115]
	v_mfma_f32_16x16x32_bf16 v[100:103], v[174:177], v[198:201], v[100:103]
	v_mfma_f32_16x16x32_bf16 v[96:99], v[182:185], v[198:201], v[96:99]
	v_mfma_f32_16x16x32_bf16 v[84:87], v[174:177], v[206:209], v[84:87]
	v_mfma_f32_16x16x32_bf16 v[80:83], v[182:185], v[206:209], v[80:83]
	v_mfma_f32_16x16x32_bf16 v[68:71], v[174:177], v[214:217], v[68:71]
	v_mfma_f32_16x16x32_bf16 v[64:67], v[182:185], v[214:217], v[64:67]
	v_mfma_f32_16x16x32_bf16 v[116:119], v[178:181], v[194:197], v[116:119]
	v_mfma_f32_16x16x32_bf16 v[112:115], v[186:189], v[194:197], v[112:115]
	v_mfma_f32_16x16x32_bf16 v[100:103], v[178:181], v[202:205], v[100:103]
	v_mfma_f32_16x16x32_bf16 v[96:99], v[186:189], v[202:205], v[96:99]
	v_mfma_f32_16x16x32_bf16 v[84:87], v[178:181], v[210:213], v[84:87]
	v_mfma_f32_16x16x32_bf16 v[80:83], v[186:189], v[210:213], v[80:83]
	v_mfma_f32_16x16x32_bf16 v[68:71], v[178:181], v[218:221], v[68:71]
	v_mfma_f32_16x16x32_bf16 v[64:67], v[186:189], v[218:221], v[64:67]
	s_setprio 0
	s_barrier
; #define PG8_STAGE(bufoff, gbase, voff) do { _Pragma("unroll") for (int _i = 0; _i < 2; ++_i) \
;         __builtin_amdgcn_global_load_lds((const unsigned*)((const char*)(gbase) + (voff)[_i]), (PG8_LAS unsigned*)(lds + (bufoff) + ldsw + _i * 8192), 16, 0, 0); } while (0)
; #define PG8_LDA(dst, b, h) do { _Pragma("unroll") for (int m = 0; m < 4; ++m) _Pragma("unroll") for (int k = 0; k < 2; ++k) dst[m][k] = *(const PG8_LAS bf16x8*)(lds + PG8_SA(b, h) + aoff + m * 2048 + k * 1024); } while (0)
; #define PG8_MMA(ai, bj, At, Bt) do { __builtin_amdgcn_s_setprio(1); _Pragma("unroll") for (int m = 0; m < 4; ++m) _Pragma("unroll") for (int n = 0; n < 2; ++n) _Pragma("unroll") for (int k = 0; k < 2; ++k) \
;         acc[ai][bj][m][n] = __builtin_amdgcn_mfma_f32_16x16x32_bf16(Bt[n][k], At[m][k], acc[ai][bj][m][n], 0, 0, 0); __builtin_amdgcn_s_setprio(0); } while (0)
; #define PG8_WAIT_V(n) asm volatile("s_waitcnt vmcnt(" #n ")" ::: "memory")
; #define PG8_WAIT_L(n) asm volatile("s_waitcnt lgkmcnt(" #n ")" ::: "memory")
; #define PG8_BAR __builtin_amdgcn_s_barrier()
; #define PG8_SCHED __builtin_amdgcn_sched_barrier(0)
; template <class Epi, class Sched, bool ALIGN_EPI = false, bool SP2 = false>
; __device__ __forceinline__ void gemm_phase(PG8_LAS unsigned char* lds, const Gemm g, const Sched& S, const Epi& E) {
;     ...
;             PG8_LDA(At, 1, 1); PG8_STAGE(PG8_SB(1, 0), b3, voffB); PG8_STAGE(PG8_SB(1, 1), b3 + hstep, voffB); PG8_STAGE(PG8_SA(1, 0), a3, voffA);
;             PG8_WAIT_V(8); PG8_WAIT_L(0); PG8_BAR; PG8_MMA(1, 0, At, B0); PG8_MMA(1, 1, At, B1); PG8_BAR; PG8_SCHED;
	s_add_i32 s68, s70, s33
	v_lshl_add_u64 v[154:155], v[154:155], 0, s[12:13]
	s_mov_b32 m0, s68
	ds_read_b128 v[190:193], v160 offset:49152
	ds_read_b128 v[194:197], v160 offset:50176
	ds_read_b128 v[198:201], v160 offset:51200
	ds_read_b128 v[202:205], v160 offset:52224
	ds_read_b128 v[206:209], v160 offset:53248
	ds_read_b128 v[210:213], v160 offset:54272
	ds_read_b128 v[214:217], v160 offset:55296
	ds_read_b128 v[218:221], v160 offset:56320
	global_load_lds_dwordx4 v[154:155], off
	s_add_i32 m0, s68, 0x2000
	s_add_u32 s68, s84, 0x100080
	v_lshl_add_u64 v[154:155], v[222:223], 0, s[12:13]
	s_addc_u32 s69, s85, 0
	s_add_i32 s70, s71, s33
	global_load_lds_dwordx4 v[154:155], off
	v_lshl_add_u64 v[154:155], s[68:69], 0, v[132:133]
	s_mov_b32 m0, s70
	s_nop 0
	global_load_lds_dwordx4 v[154:155], off
	v_lshl_add_u64 v[154:155], s[68:69], 0, v[128:129]
	s_add_i32 m0, s70, 0x2000
	s_nop 0
	global_load_lds_dwordx4 v[154:155], off
	v_lshl_add_u64 v[154:155], v[224:225], 0, s[12:13]
	s_mov_b32 m0, s60
	s_nop 0
	global_load_lds_dwordx4 v[154:155], off
	v_lshl_add_u64 v[154:155], v[226:227], 0, s[12:13]
	s_mov_b32 m0, s61
	s_nop 0
	global_load_lds_dwordx4 v[154:155], off
	s_waitcnt vmcnt(8)
	s_waitcnt lgkmcnt(0)
	s_barrier
	s_setprio 1
	s_waitcnt lgkmcnt(0)
	v_mfma_f32_16x16x32_bf16 v[60:63], v[150:153], v[190:193], v[60:63]
	v_mfma_f32_16x16x32_bf16 v[56:59], v[166:169], v[190:193], v[56:59]
	v_mfma_f32_16x16x32_bf16 v[44:47], v[150:153], v[198:201], v[44:47]
	v_mfma_f32_16x16x32_bf16 v[40:43], v[166:169], v[198:201], v[40:43]
	v_mfma_f32_16x16x32_bf16 v[28:31], v[150:153], v[206:209], v[28:31]
	v_mfma_f32_16x16x32_bf16 v[24:27], v[166:169], v[206:209], v[24:27]
	v_mfma_f32_16x16x32_bf16 v[12:15], v[150:153], v[214:217], v[12:15]
	v_mfma_f32_16x16x32_bf16 v[8:11], v[166:169], v[214:217], v[8:11]
	v_mfma_f32_16x16x32_bf16 v[60:63], v[162:165], v[194:197], v[60:63]
	v_mfma_f32_16x16x32_bf16 v[56:59], v[170:173], v[194:197], v[56:59]
	v_mfma_f32_16x16x32_bf16 v[44:47], v[162:165], v[202:205], v[44:47]
	v_mfma_f32_16x16x32_bf16 v[40:43], v[170:173], v[202:205], v[40:43]
	v_mfma_f32_16x16x32_bf16 v[28:31], v[162:165], v[210:213], v[28:31]
	v_mfma_f32_16x16x32_bf16 v[24:27], v[170:173], v[210:213], v[24:27]
	v_mfma_f32_16x16x32_bf16 v[12:15], v[162:165], v[218:221], v[12:15]
	v_mfma_f32_16x16x32_bf16 v[8:11], v[170:173], v[218:221], v[8:11]
	v_mfma_f32_16x16x32_bf16 v[52:55], v[174:177], v[190:193], v[52:55]
	v_mfma_f32_16x16x32_bf16 v[48:51], v[182:185], v[190:193], v[48:51]
	v_mfma_f32_16x16x32_bf16 v[36:39], v[174:177], v[198:201], v[36:39]
	v_mfma_f32_16x16x32_bf16 v[32:35], v[182:185], v[198:201], v[32:35]
	v_mfma_f32_16x16x32_bf16 v[20:23], v[174:177], v[206:209], v[20:23]
	v_mfma_f32_16x16x32_bf16 v[16:19], v[182:185], v[206:209], v[16:19]
	v_mfma_f32_16x16x32_bf16 v[4:7], v[174:177], v[214:217], v[4:7]
	v_mfma_f32_16x16x32_bf16 v[0:3], v[182:185], v[214:217], v[0:3]
	v_mfma_f32_16x16x32_bf16 v[52:55], v[178:181], v[194:197], v[52:55]
	v_mfma_f32_16x16x32_bf16 v[48:51], v[186:189], v[194:197], v[48:51]
	v_mfma_f32_16x16x32_bf16 v[36:39], v[178:181], v[202:205], v[36:39]
	v_mfma_f32_16x16x32_bf16 v[32:35], v[186:189], v[202:205], v[32:35]
	v_mfma_f32_16x16x32_bf16 v[20:23], v[178:181], v[210:213], v[20:23]
	v_mfma_f32_16x16x32_bf16 v[16:19], v[186:189], v[210:213], v[16:19]
	v_mfma_f32_16x16x32_bf16 v[4:7], v[178:181], v[218:221], v[4:7]
	v_mfma_f32_16x16x32_bf16 v[0:3], v[186:189], v[218:221], v[0:3]
	s_setprio 0
	s_barrier
	s_add_i32 s67, s67, 2
	s_add_u32 s34, s34, 0x100
	s_addc_u32 s35, s35, 0
	s_add_u32 s65, s65, 0x100
	s_addc_u32 s66, s66, 0
	s_cmp_gt_u32 s67, 61
	s_cbranch_scc0 .LBB0_115
	s_and_b64 vcc, exec, s[14:15]
	s_cbranch_vccz .LBB0_118
	s_barrier

; #define PG8_STAGE(bufoff, gbase, voff) do { _Pragma("unroll") for (int _i = 0; _i < 2; ++_i) \
;         __builtin_amdgcn_global_load_lds((const unsigned*)((const char*)(gbase) + (voff)[_i]), (PG8_LAS unsigned*)(lds + (bufoff) + ldsw + _i * 8192), 16, 0, 0); } while (0)
; #define PG8_LDA(dst, b, h) do { _Pragma("unroll") for (int m = 0; m < 4; ++m) _Pragma("unroll") for (int k = 0; k < 2; ++k) dst[m][k] = *(const PG8_LAS bf16x8*)(lds + PG8_SA(b, h) + aoff + m * 2048 + k * 1024); } while (0)
; #define PG8_LDB(dst, b, h) do { _Pragma("unroll") for (int n = 0; n < 2; ++n) _Pragma("unroll") for (int k = 0; k < 2; ++k) dst[n][k] = *(const PG8_LAS bf16x8*)(lds + PG8_SB(b, h) + boff + n * 2048 + k * 1024); } while (0)
; #define PG8_MMA(ai, bj, At, Bt) do { __builtin_amdgcn_s_setprio(1); _Pragma("unroll") for (int m = 0; m < 4; ++m) _Pragma("unroll") for (int n = 0; n < 2; ++n) _Pragma("unroll") for (int k = 0; k < 2; ++k) \
;         acc[ai][bj][m][n] = __builtin_amdgcn_mfma_f32_16x16x32_bf16(Bt[n][k], At[m][k], acc[ai][bj][m][n], 0, 0, 0); __builtin_amdgcn_s_setprio(0); } while (0)
; #define PG8_WAIT_V(n) asm volatile("s_waitcnt vmcnt(" #n ")" ::: "memory")
; #define PG8_BAR __builtin_amdgcn_s_barrier()
; template <class Epi, class Sched, bool ALIGN_EPI = false, bool SP2 = false>
; __device__ __forceinline__ void gemm_phase(PG8_LAS unsigned char* lds, const Gemm g, const Sched& S, const Epi& E) {
;     ...
;         for (int t = 0; t < nt; t += 2) {
;             const bool last = (t == nt - 2);
;             const char* a1 = cA + (size_t)(t + 1) * kstepA;
;             const char* a2 = last ? nA : cA + (size_t)(t + 2) * kstepA; const char* b2 = last ? nB : cB + (size_t)(t + 2) * kstep;
;             const char* a3 = a2 + kstepA; const char* b3 = b2 + kstep;
;             if (last && has_next) S.a_ready(nxt);
;             if constexpr (SP2) {
;             PG8_LDB(B0, 0, 0); PG8_LDB(B1, 0, 1); PG8_SCHED; PG8_LDA(At, 0, 0); PG8_STAGE(PG8_SA(1, 1), a1 + hstepA, voffA);
;             PG8_WAIT_V(8); PG8_WAIT_L(0); PG8_BAR; PG8_MMA(0, 0, At, B0); PG8_MMA(0, 1, At, B1); PG8_BAR; PG8_SCHED;
;             PG8_LDA(At, 0, 1); PG8_STAGE(PG8_SB(0, 0), b2, voffB); PG8_STAGE(PG8_SB(0, 1), b2 + hstep, voffB); PG8_STAGE(PG8_SA(0, 0), a2, voffA);
;             PG8_WAIT_V(8); PG8_WAIT_L(0); PG8_BAR; PG8_MMA(1, 0, At, B0); PG8_MMA(1, 1, At, B1); PG8_BAR; PG8_SCHED;
.LBB0_1198:
	ds_read_b128 v[144:147], v153
	ds_read_b128 v[158:161], v153 offset:1024
	ds_read_b128 v[162:165], v153 offset:2048
	ds_read_b128 v[166:169], v153 offset:3072
	ds_read_b128 v[170:173], v154
	ds_read_b128 v[174:177], v154 offset:1024
	ds_read_b128 v[178:181], v154 offset:2048
	ds_read_b128 v[182:185], v154 offset:3072
	s_add_u32 s38, s34, 0xfff00080
	s_addc_u32 s39, s35, -1
	s_cmp_eq_u32 s65, 60
	s_cselect_b32 s41, s21, s39
	s_cselect_b32 s40, s27, s38
	s_cselect_b32 s39, s19, s64
	s_cselect_b32 s38, s62, s63
	v_lshl_add_u64 v[148:149], s[34:35], 0, v[136:137]
	s_add_i32 m0, s31, 0xc000
	ds_read_b128 v[186:189], v155
	ds_read_b128 v[190:193], v155 offset:1024
	ds_read_b128 v[194:197], v155 offset:2048
	ds_read_b128 v[198:201], v155 offset:3072
	ds_read_b128 v[202:205], v155 offset:4096
	ds_read_b128 v[206:209], v155 offset:5120
	ds_read_b128 v[210:213], v155 offset:6144
	ds_read_b128 v[214:217], v155 offset:7168
	global_load_lds_dwordx4 v[148:149], off
	v_lshl_add_u64 v[148:149], s[34:35], 0, v[138:139]
	s_add_i32 m0, s31, 0xe000
	s_nop 0
	global_load_lds_dwordx4 v[148:149], off
	s_waitcnt vmcnt(8)
	s_waitcnt lgkmcnt(0)
	s_barrier
	s_setprio 1
	s_waitcnt lgkmcnt(0)
	v_mfma_f32_16x16x32_bf16 v[124:127], v[144:147], v[186:189], v[124:127]
	v_mfma_f32_16x16x32_bf16 v[120:123], v[162:165], v[186:189], v[120:123]
	v_mfma_f32_16x16x32_bf16 v[108:111], v[144:147], v[194:197], v[108:111]
	v_mfma_f32_16x16x32_bf16 v[48:51], v[162:165], v[194:197], v[48:51]
	v_mfma_f32_16x16x32_bf16 v[100:103], v[144:147], v[202:205], v[100:103]
	v_mfma_f32_16x16x32_bf16 v[64:67], v[162:165], v[202:205], v[64:67]
	v_mfma_f32_16x16x32_bf16 v[92:95], v[144:147], v[210:213], v[92:95]
	v_mfma_f32_16x16x32_bf16 v[80:83], v[162:165], v[210:213], v[80:83]
	v_mfma_f32_16x16x32_bf16 v[124:127], v[158:161], v[190:193], v[124:127]
	v_mfma_f32_16x16x32_bf16 v[120:123], v[166:169], v[190:193], v[120:123]
	v_mfma_f32_16x16x32_bf16 v[108:111], v[158:161], v[198:201], v[108:111]
	v_mfma_f32_16x16x32_bf16 v[48:51], v[166:169], v[198:201], v[48:51]
	v_mfma_f32_16x16x32_bf16 v[100:103], v[158:161], v[206:209], v[100:103]
	v_mfma_f32_16x16x32_bf16 v[64:67], v[166:169], v[206:209], v[64:67]
	v_mfma_f32_16x16x32_bf16 v[92:95], v[158:161], v[214:217], v[92:95]
	v_mfma_f32_16x16x32_bf16 v[80:83], v[166:169], v[214:217], v[80:83]
	v_mfma_f32_16x16x32_bf16 v[116:119], v[170:173], v[186:189], v[116:119]
	v_mfma_f32_16x16x32_bf16 v[112:115], v[178:181], v[186:189], v[112:115]
	v_mfma_f32_16x16x32_bf16 v[104:107], v[170:173], v[194:197], v[104:107]
	v_mfma_f32_16x16x32_bf16 v[52:55], v[178:181], v[194:197], v[52:55]
	v_mfma_f32_16x16x32_bf16 v[96:99], v[170:173], v[202:205], v[96:99]
	v_mfma_f32_16x16x32_bf16 v[76:79], v[178:181], v[202:205], v[76:79]
	v_mfma_f32_16x16x32_bf16 v[88:91], v[170:173], v[210:213], v[88:91]
	v_mfma_f32_16x16x32_bf16 v[84:87], v[178:181], v[210:213], v[84:87]
	v_mfma_f32_16x16x32_bf16 v[116:119], v[174:177], v[190:193], v[116:119]
	v_mfma_f32_16x16x32_bf16 v[112:115], v[182:185], v[190:193], v[112:115]
	v_mfma_f32_16x16x32_bf16 v[104:107], v[174:177], v[198:201], v[104:107]
	v_mfma_f32_16x16x32_bf16 v[52:55], v[182:185], v[198:201], v[52:55]
	v_mfma_f32_16x16x32_bf16 v[96:99], v[174:177], v[206:209], v[96:99]
	v_mfma_f32_16x16x32_bf16 v[76:79], v[182:185], v[206:209], v[76:79]
	v_mfma_f32_16x16x32_bf16 v[88:91], v[174:177], v[214:217], v[88:91]
	v_mfma_f32_16x16x32_bf16 v[84:87], v[182:185], v[214:217], v[84:87]
	s_setprio 0
	s_barrier
	s_add_i32 s66, s60, s33
	v_lshl_add_u64 v[148:149], s[38:39], 0, v[130:131]
	s_mov_b32 m0, s66
	ds_read_b128 v[186:189], v155 offset:16384
	ds_read_b128 v[190:193], v155 offset:17408
	ds_read_b128 v[194:197], v155 offset:18432
	ds_read_b128 v[198:201], v155 offset:19456
	ds_read_b128 v[202:205], v155 offset:20480
	ds_read_b128 v[206:209], v155 offset:21504
	ds_read_b128 v[210:213], v155 offset:22528
	ds_read_b128 v[214:217], v155 offset:23552
	global_load_lds_dwordx4 v[148:149], off
	s_add_i32 m0, s66, 0x2000
	s_add_u32 s66, s38, 0x100000
	v_lshl_add_u64 v[218:219], s[38:39], 0, v[134:135]
	s_addc_u32 s67, s39, 0
	s_add_i32 s68, s61, s33
	global_load_lds_dwordx4 v[218:219], off
	v_lshl_add_u64 v[220:221], s[66:67], 0, v[130:131]
	s_mov_b32 m0, s68
	v_lshl_add_u64 v[222:223], s[40:41], 0, v[132:133]
	global_load_lds_dwordx4 v[220:221], off
	v_lshl_add_u64 v[220:221], s[66:67], 0, v[134:135]
	s_add_i32 m0, s68, 0x2000
	s_nop 0
	global_load_lds_dwordx4 v[220:221], off
	v_lshl_add_u64 v[220:221], s[40:41], 0, v[128:129]
	s_mov_b32 m0, s31
	s_nop 0
	global_load_lds_dwordx4 v[220:221], off
	s_mov_b32 m0, s52
	s_nop 0
	global_load_lds_dwordx4 v[222:223], off
	s_waitcnt vmcnt(8)
	s_waitcnt lgkmcnt(0)
	s_barrier
; #define PG8_STAGE(bufoff, gbase, voff) do { _Pragma("unroll") for (int _i = 0; _i < 2; ++_i) \
;         __builtin_amdgcn_global_load_lds((const unsigned*)((const char*)(gbase) + (voff)[_i]), (PG8_LAS unsigned*)(lds + (bufoff) + ldsw + _i * 8192), 16, 0, 0); } while (0)
; #define PG8_LDA(dst, b, h) do { _Pragma("unroll") for (int m = 0; m < 4; ++m) _Pragma("unroll") for (int k = 0; k < 2; ++k) dst[m][k] = *(const PG8_LAS bf16x8*)(lds + PG8_SA(b, h) + aoff + m * 2048 + k * 1024); } while (0)
; #define PG8_LDB(dst, b, h) do { _Pragma("unroll") for (int n = 0; n < 2; ++n) _Pragma("unroll") for (int k = 0; k < 2; ++k) dst[n][k] = *(const PG8_LAS bf16x8*)(lds + PG8_SB(b, h) + boff + n * 2048 + k * 1024); } while (0)
; #define PG8_MMA(ai, bj, At, Bt) do { __builtin_amdgcn_s_setprio(1); _Pragma("unroll") for (int m = 0; m < 4; ++m) _Pragma("unroll") for (int n = 0; n < 2; ++n) _Pragma("unroll") for (int k = 0; k < 2; ++k) \
;         acc[ai][bj][m][n] = __builtin_amdgcn_mfma_f32_16x16x32_bf16(Bt[n][k], At[m][k], acc[ai][bj][m][n], 0, 0, 0); __builtin_amdgcn_s_setprio(0); } while (0)
; #define PG8_WAIT_V(n) asm volatile("s_waitcnt vmcnt(" #n ")" ::: "memory")
; #define PG8_WAIT_L(n) asm volatile("s_waitcnt lgkmcnt(" #n ")" ::: "memory")
; #define PG8_BAR __builtin_amdgcn_s_barrier()
; #define PG8_SCHED __builtin_amdgcn_sched_barrier(0)
; template <class Epi, class Sched, bool ALIGN_EPI = false, bool SP2 = false>
; __device__ __forceinline__ void gemm_phase(PG8_LAS unsigned char* lds, const Gemm g, const Sched& S, const Epi& E) {
;     ...
;             PG8_WAIT_V(8); PG8_WAIT_L(0); PG8_BAR; PG8_MMA(1, 0, At, B0); PG8_MMA(1, 1, At, B1); PG8_BAR; PG8_SCHED;
;             PG8_LDB(B0, 1, 0); PG8_LDB(B1, 1, 1); PG8_SCHED; PG8_LDA(At, 1, 0); PG8_STAGE(PG8_SA(0, 1), a2 + hstepA, voffA);
;             PG8_WAIT_V(8); PG8_WAIT_L(0); PG8_BAR; PG8_MMA(0, 0, At, B0); PG8_MMA(0, 1, At, B1); PG8_BAR; PG8_SCHED;
	s_setprio 1
	s_waitcnt lgkmcnt(0)
	v_mfma_f32_16x16x32_bf16 v[72:75], v[144:147], v[186:189], v[72:75]
	v_mfma_f32_16x16x32_bf16 v[68:71], v[162:165], v[186:189], v[68:71]
	v_mfma_f32_16x16x32_bf16 v[44:47], v[144:147], v[194:197], v[44:47]
	v_mfma_f32_16x16x32_bf16 v[40:43], v[162:165], v[194:197], v[40:43]
	v_mfma_f32_16x16x32_bf16 v[28:31], v[144:147], v[202:205], v[28:31]
	v_mfma_f32_16x16x32_bf16 v[24:27], v[162:165], v[202:205], v[24:27]
	v_mfma_f32_16x16x32_bf16 v[12:15], v[144:147], v[210:213], v[12:15]
	v_mfma_f32_16x16x32_bf16 v[8:11], v[162:165], v[210:213], v[8:11]
	v_mfma_f32_16x16x32_bf16 v[72:75], v[158:161], v[190:193], v[72:75]
	v_mfma_f32_16x16x32_bf16 v[68:71], v[166:169], v[190:193], v[68:71]
	v_mfma_f32_16x16x32_bf16 v[44:47], v[158:161], v[198:201], v[44:47]
	v_mfma_f32_16x16x32_bf16 v[40:43], v[166:169], v[198:201], v[40:43]
	v_mfma_f32_16x16x32_bf16 v[28:31], v[158:161], v[206:209], v[28:31]
	v_mfma_f32_16x16x32_bf16 v[24:27], v[166:169], v[206:209], v[24:27]
	v_mfma_f32_16x16x32_bf16 v[12:15], v[158:161], v[214:217], v[12:15]
	v_mfma_f32_16x16x32_bf16 v[8:11], v[166:169], v[214:217], v[8:11]
	v_mfma_f32_16x16x32_bf16 v[60:63], v[170:173], v[186:189], v[60:63]
	v_mfma_f32_16x16x32_bf16 v[56:59], v[178:181], v[186:189], v[56:59]
	v_mfma_f32_16x16x32_bf16 v[36:39], v[170:173], v[194:197], v[36:39]
	v_mfma_f32_16x16x32_bf16 v[32:35], v[178:181], v[194:197], v[32:35]
	v_mfma_f32_16x16x32_bf16 v[20:23], v[170:173], v[202:205], v[20:23]
	v_mfma_f32_16x16x32_bf16 v[16:19], v[178:181], v[202:205], v[16:19]
	v_mfma_f32_16x16x32_bf16 v[4:7], v[170:173], v[210:213], v[4:7]
	v_mfma_f32_16x16x32_bf16 v[0:3], v[178:181], v[210:213], v[0:3]
	v_mfma_f32_16x16x32_bf16 v[60:63], v[174:177], v[190:193], v[60:63]
	v_mfma_f32_16x16x32_bf16 v[56:59], v[182:185], v[190:193], v[56:59]
	v_mfma_f32_16x16x32_bf16 v[36:39], v[174:177], v[198:201], v[36:39]
	v_mfma_f32_16x16x32_bf16 v[32:35], v[182:185], v[198:201], v[32:35]
	v_mfma_f32_16x16x32_bf16 v[20:23], v[174:177], v[206:209], v[20:23]
	v_mfma_f32_16x16x32_bf16 v[16:19], v[182:185], v[206:209], v[16:19]
	v_mfma_f32_16x16x32_bf16 v[4:7], v[174:177], v[214:217], v[4:7]
	v_mfma_f32_16x16x32_bf16 v[0:3], v[182:185], v[214:217], v[0:3]
	s_setprio 0
	s_barrier
	s_add_i32 s66, 0, 0x18000
	v_add_u32_e32 v157, s66, v151
	s_add_i32 s67, 0, 0x1c000
	ds_read_b128 v[144:147], v157
	ds_read_b128 v[158:161], v157 offset:1024
	ds_read_b128 v[162:165], v157 offset:2048
	ds_read_b128 v[166:169], v157 offset:3072
	v_add_u32_e32 v157, s67, v151
	ds_read_b128 v[170:173], v157
	ds_read_b128 v[174:177], v157 offset:1024
	ds_read_b128 v[178:181], v157 offset:2048
	ds_read_b128 v[182:185], v157 offset:3072
	s_add_u32 s40, s40, 0x100000
	s_addc_u32 s41, s41, 0
	s_mov_b32 m0, s53
	v_lshl_add_u64 v[224:225], s[40:41], 0, v[128:129]
	ds_read_b128 v[186:189], v155 offset:32768
	ds_read_b128 v[190:193], v155 offset:33792
	ds_read_b128 v[194:197], v155 offset:34816
	ds_read_b128 v[198:201], v155 offset:35840
	ds_read_b128 v[202:205], v155 offset:36864
	ds_read_b128 v[206:209], v155 offset:37888
	ds_read_b128 v[210:213], v155 offset:38912
	ds_read_b128 v[214:217], v155 offset:39936
	global_load_lds_dwordx4 v[224:225], off
	v_lshl_add_u64 v[224:225], s[40:41], 0, v[132:133]
	s_mov_b32 m0, s54
	s_nop 0
	global_load_lds_dwordx4 v[224:225], off
	s_waitcnt vmcnt(8)
	s_waitcnt lgkmcnt(0)
	s_barrier
	s_setprio 1
	s_waitcnt lgkmcnt(0)
	v_mfma_f32_16x16x32_bf16 v[124:127], v[144:147], v[186:189], v[124:127]
	v_mfma_f32_16x16x32_bf16 v[120:123], v[162:165], v[186:189], v[120:123]
	v_mfma_f32_16x16x32_bf16 v[108:111], v[144:147], v[194:197], v[108:111]
	v_mfma_f32_16x16x32_bf16 v[48:51], v[162:165], v[194:197], v[48:51]
	v_mfma_f32_16x16x32_bf16 v[100:103], v[144:147], v[202:205], v[100:103]
	v_mfma_f32_16x16x32_bf16 v[64:67], v[162:165], v[202:205], v[64:67]
	v_mfma_f32_16x16x32_bf16 v[92:95], v[144:147], v[210:213], v[92:95]
	v_mfma_f32_16x16x32_bf16 v[80:83], v[162:165], v[210:213], v[80:83]
	v_mfma_f32_16x16x32_bf16 v[124:127], v[158:161], v[190:193], v[124:127]
	v_mfma_f32_16x16x32_bf16 v[120:123], v[166:169], v[190:193], v[120:123]
	v_mfma_f32_16x16x32_bf16 v[108:111], v[158:161], v[198:201], v[108:111]
	v_mfma_f32_16x16x32_bf16 v[48:51], v[166:169], v[198:201], v[48:51]
	v_mfma_f32_16x16x32_bf16 v[100:103], v[158:161], v[206:209], v[100:103]
	v_mfma_f32_16x16x32_bf16 v[64:67], v[166:169], v[206:209], v[64:67]
	v_mfma_f32_16x16x32_bf16 v[92:95], v[158:161], v[214:217], v[92:95]
	v_mfma_f32_16x16x32_bf16 v[80:83], v[166:169], v[214:217], v[80:83]
	v_mfma_f32_16x16x32_bf16 v[116:119], v[170:173], v[186:189], v[116:119]
	v_mfma_f32_16x16x32_bf16 v[112:115], v[178:181], v[186:189], v[112:115]
	v_mfma_f32_16x16x32_bf16 v[104:107], v[170:173], v[194:197], v[104:107]
	v_mfma_f32_16x16x32_bf16 v[52:55], v[178:181], v[194:197], v[52:55]
	v_mfma_f32_16x16x32_bf16 v[96:99], v[170:173], v[202:205], v[96:99]
	v_mfma_f32_16x16x32_bf16 v[76:79], v[178:181], v[202:205], v[76:79]
	v_mfma_f32_16x16x32_bf16 v[88:91], v[170:173], v[210:213], v[88:91]
	v_mfma_f32_16x16x32_bf16 v[84:87], v[178:181], v[210:213], v[84:87]
	v_mfma_f32_16x16x32_bf16 v[116:119], v[174:177], v[190:193], v[116:119]
	v_mfma_f32_16x16x32_bf16 v[112:115], v[182:185], v[190:193], v[112:115]
	v_mfma_f32_16x16x32_bf16 v[104:107], v[174:177], v[198:201], v[104:107]
	v_mfma_f32_16x16x32_bf16 v[52:55], v[182:185], v[198:201], v[52:55]
	v_mfma_f32_16x16x32_bf16 v[96:99], v[174:177], v[206:209], v[96:99]
	v_mfma_f32_16x16x32_bf16 v[76:79], v[182:185], v[206:209], v[76:79]
	v_mfma_f32_16x16x32_bf16 v[88:91], v[174:177], v[214:217], v[88:91]
	v_mfma_f32_16x16x32_bf16 v[84:87], v[182:185], v[214:217], v[84:87]
	s_setprio 0
	s_barrier
; #define PG8_STAGE(bufoff, gbase, voff) do { _Pragma("unroll") for (int _i = 0; _i < 2; ++_i) \
;         __builtin_amdgcn_global_load_lds((const unsigned*)((const char*)(gbase) + (voff)[_i]), (PG8_LAS unsigned*)(lds + (bufoff) + ldsw + _i * 8192), 16, 0, 0); } while (0)
; #define PG8_LDA(dst, b, h) do { _Pragma("unroll") for (int m = 0; m < 4; ++m) _Pragma("unroll") for (int k = 0; k < 2; ++k) dst[m][k] = *(const PG8_LAS bf16x8*)(lds + PG8_SA(b, h) + aoff + m * 2048 + k * 1024); } while (0)
; #define PG8_MMA(ai, bj, At, Bt) do { __builtin_amdgcn_s_setprio(1); _Pragma("unroll") for (int m = 0; m < 4; ++m) _Pragma("unroll") for (int n = 0; n < 2; ++n) _Pragma("unroll") for (int k = 0; k < 2; ++k) \
;         acc[ai][bj][m][n] = __builtin_amdgcn_mfma_f32_16x16x32_bf16(Bt[n][k], At[m][k], acc[ai][bj][m][n], 0, 0, 0); __builtin_amdgcn_s_setprio(0); } while (0)
; #define PG8_WAIT_V(n) asm volatile("s_waitcnt vmcnt(" #n ")" ::: "memory")
; #define PG8_WAIT_L(n) asm volatile("s_waitcnt lgkmcnt(" #n ")" ::: "memory")
; #define PG8_BAR __builtin_amdgcn_s_barrier()
; #define PG8_SCHED __builtin_amdgcn_sched_barrier(0)
; template <class Epi, class Sched, bool ALIGN_EPI = false, bool SP2 = false>
; __device__ __forceinline__ void gemm_phase(PG8_LAS unsigned char* lds, const Gemm g, const Sched& S, const Epi& E) {
;     ...
;             PG8_LDA(At, 1, 1); PG8_STAGE(PG8_SB(1, 0), b3, voffB); PG8_STAGE(PG8_SB(1, 1), b3 + hstep, voffB); PG8_STAGE(PG8_SA(1, 0), a3, voffA);
;             PG8_WAIT_V(8); PG8_WAIT_L(0); PG8_BAR; PG8_MMA(1, 0, At, B0); PG8_MMA(1, 1, At, B1); PG8_BAR; PG8_SCHED;
	s_add_i32 s40, s66, s33
	v_lshl_add_u64 v[148:149], v[148:149], 0, s[14:15]
	s_mov_b32 m0, s40
	ds_read_b128 v[186:189], v155 offset:49152
	ds_read_b128 v[190:193], v155 offset:50176
	ds_read_b128 v[194:197], v155 offset:51200
	ds_read_b128 v[198:201], v155 offset:52224
	ds_read_b128 v[202:205], v155 offset:53248
	ds_read_b128 v[206:209], v155 offset:54272
	ds_read_b128 v[210:213], v155 offset:55296
	ds_read_b128 v[214:217], v155 offset:56320
	global_load_lds_dwordx4 v[148:149], off
	s_add_i32 m0, s40, 0x2000
	s_add_u32 s38, s38, 0x100080
	v_lshl_add_u64 v[148:149], v[218:219], 0, s[14:15]
	s_addc_u32 s39, s39, 0
	s_add_i32 s40, s67, s33
	global_load_lds_dwordx4 v[148:149], off
	v_lshl_add_u64 v[148:149], s[38:39], 0, v[130:131]
	s_mov_b32 m0, s40
	s_nop 0
	global_load_lds_dwordx4 v[148:149], off
	v_lshl_add_u64 v[148:149], s[38:39], 0, v[134:135]
	s_add_i32 m0, s40, 0x2000
	s_nop 0
	global_load_lds_dwordx4 v[148:149], off
	v_lshl_add_u64 v[148:149], v[220:221], 0, s[14:15]
	s_mov_b32 m0, s56
	s_nop 0
	global_load_lds_dwordx4 v[148:149], off
	v_lshl_add_u64 v[148:149], v[222:223], 0, s[14:15]
	s_mov_b32 m0, s57
	s_nop 0
	global_load_lds_dwordx4 v[148:149], off
	s_waitcnt vmcnt(8)
	s_waitcnt lgkmcnt(0)
	s_barrier
	s_setprio 1
	s_waitcnt lgkmcnt(0)
	v_mfma_f32_16x16x32_bf16 v[72:75], v[144:147], v[186:189], v[72:75]
	v_mfma_f32_16x16x32_bf16 v[68:71], v[162:165], v[186:189], v[68:71]
	v_mfma_f32_16x16x32_bf16 v[44:47], v[144:147], v[194:197], v[44:47]
	v_mfma_f32_16x16x32_bf16 v[40:43], v[162:165], v[194:197], v[40:43]
	v_mfma_f32_16x16x32_bf16 v[28:31], v[144:147], v[202:205], v[28:31]
	v_mfma_f32_16x16x32_bf16 v[24:27], v[162:165], v[202:205], v[24:27]
	v_mfma_f32_16x16x32_bf16 v[12:15], v[144:147], v[210:213], v[12:15]
	v_mfma_f32_16x16x32_bf16 v[8:11], v[162:165], v[210:213], v[8:11]
	v_mfma_f32_16x16x32_bf16 v[72:75], v[158:161], v[190:193], v[72:75]
	v_mfma_f32_16x16x32_bf16 v[68:71], v[166:169], v[190:193], v[68:71]
	v_mfma_f32_16x16x32_bf16 v[44:47], v[158:161], v[198:201], v[44:47]
	v_mfma_f32_16x16x32_bf16 v[40:43], v[166:169], v[198:201], v[40:43]
	v_mfma_f32_16x16x32_bf16 v[28:31], v[158:161], v[206:209], v[28:31]
	v_mfma_f32_16x16x32_bf16 v[24:27], v[166:169], v[206:209], v[24:27]
	v_mfma_f32_16x16x32_bf16 v[12:15], v[158:161], v[214:217], v[12:15]
	v_mfma_f32_16x16x32_bf16 v[8:11], v[166:169], v[214:217], v[8:11]
	v_mfma_f32_16x16x32_bf16 v[60:63], v[170:173], v[186:189], v[60:63]
	v_mfma_f32_16x16x32_bf16 v[56:59], v[178:181], v[186:189], v[56:59]
	v_mfma_f32_16x16x32_bf16 v[36:39], v[170:173], v[194:197], v[36:39]
	v_mfma_f32_16x16x32_bf16 v[32:35], v[178:181], v[194:197], v[32:35]
	v_mfma_f32_16x16x32_bf16 v[20:23], v[170:173], v[202:205], v[20:23]
	v_mfma_f32_16x16x32_bf16 v[16:19], v[178:181], v[202:205], v[16:19]
	v_mfma_f32_16x16x32_bf16 v[4:7], v[170:173], v[210:213], v[4:7]
	v_mfma_f32_16x16x32_bf16 v[0:3], v[178:181], v[210:213], v[0:3]
	v_mfma_f32_16x16x32_bf16 v[60:63], v[174:177], v[190:193], v[60:63]
	v_mfma_f32_16x16x32_bf16 v[56:59], v[182:185], v[190:193], v[56:59]
	v_mfma_f32_16x16x32_bf16 v[36:39], v[174:177], v[198:201], v[36:39]
	v_mfma_f32_16x16x32_bf16 v[32:35], v[182:185], v[198:201], v[32:35]
	v_mfma_f32_16x16x32_bf16 v[20:23], v[174:177], v[206:209], v[20:23]
	v_mfma_f32_16x16x32_bf16 v[16:19], v[182:185], v[206:209], v[16:19]
	v_mfma_f32_16x16x32_bf16 v[4:7], v[174:177], v[214:217], v[4:7]
	v_mfma_f32_16x16x32_bf16 v[0:3], v[182:185], v[214:217], v[0:3]
	s_setprio 0
	s_barrier
	s_add_i32 s65, s65, 2
	s_add_u32 s34, s34, 0x100
	s_addc_u32 s35, s35, 0
	s_add_u32 s63, s63, 0x100
	s_addc_u32 s64, s64, 0
	s_cmp_gt_u32 s65, 61
	s_cbranch_scc0 .LBB0_1198
	s_and_b64 vcc, exec, s[16:17]
	s_cbranch_vccz .LBB0_1201
	s_barrier

; #define PG8_STAGE(bufoff, gbase, voff) do { _Pragma("unroll") for (int _i = 0; _i < 2; ++_i) \
;         __builtin_amdgcn_global_load_lds((const unsigned*)((const char*)(gbase) + (voff)[_i]), (PG8_LAS unsigned*)(lds + (bufoff) + ldsw + _i * 8192), 16, 0, 0); } while (0)
; #define PG8_LDA(dst, b, h) do { _Pragma("unroll") for (int m = 0; m < 4; ++m) _Pragma("unroll") for (int k = 0; k < 2; ++k) dst[m][k] = *(const PG8_LAS bf16x8*)(lds + PG8_SA(b, h) + aoff + m * 2048 + k * 1024); } while (0)
; #define PG8_LDB(dst, b, h) do { _Pragma("unroll") for (int n = 0; n < 2; ++n) _Pragma("unroll") for (int k = 0; k < 2; ++k) dst[n][k] = *(const PG8_LAS bf16x8*)(lds + PG8_SB(b, h) + boff + n * 2048 + k * 1024); } while (0)
; #define PG8_MMA(ai, bj, At, Bt) do { __builtin_amdgcn_s_setprio(1); _Pragma("unroll") for (int m = 0; m < 4; ++m) _Pragma("unroll") for (int n = 0; n < 2; ++n) _Pragma("unroll") for (int k = 0; k < 2; ++k) \
;         acc[ai][bj][m][n] = __builtin_amdgcn_mfma_f32_16x16x32_bf16(Bt[n][k], At[m][k], acc[ai][bj][m][n], 0, 0, 0); __builtin_amdgcn_s_setprio(0); } while (0)
; #define PG8_WAIT_V(n) asm volatile("s_waitcnt vmcnt(" #n ")" ::: "memory")
; #define PG8_BAR __builtin_amdgcn_s_barrier()
; template <class Epi, class Sched, bool ALIGN_EPI = false, bool SP2 = false>
; __device__ __forceinline__ void gemm_phase(PG8_LAS unsigned char* lds, const Gemm g, const Sched& S, const Epi& E) {
;     ...
;         for (int t = 0; t < nt; t += 2) {
;             const bool last = (t == nt - 2);
;             const char* a1 = cA + (size_t)(t + 1) * kstepA;
;             const char* a2 = last ? nA : cA + (size_t)(t + 2) * kstepA; const char* b2 = last ? nB : cB + (size_t)(t + 2) * kstep;
;             const char* a3 = a2 + kstepA; const char* b3 = b2 + kstep;
;             if (last && has_next) S.a_ready(nxt);
;             if constexpr (SP2) {
;             PG8_LDB(B0, 0, 0); PG8_LDB(B1, 0, 1); PG8_SCHED; PG8_LDA(At, 0, 0); PG8_STAGE(PG8_SA(1, 1), a1 + hstepA, voffA);
;             PG8_WAIT_V(8); PG8_WAIT_L(0); PG8_BAR; PG8_MMA(0, 0, At, B0); PG8_MMA(0, 1, At, B1); PG8_BAR; PG8_SCHED;
;             PG8_LDA(At, 0, 1); PG8_STAGE(PG8_SB(0, 0), b2, voffB); PG8_STAGE(PG8_SB(0, 1), b2 + hstep, voffB); PG8_STAGE(PG8_SA(0, 0), a2, voffA);
;             PG8_WAIT_V(8); PG8_WAIT_L(0); PG8_BAR; PG8_MMA(1, 0, At, B0); PG8_MMA(1, 1, At, B1); PG8_BAR; PG8_SCHED;
.LBB0_1310:
	ds_read_b128 v[128:131], v236
	ds_read_b128 v[132:135], v236 offset:1024
	ds_read_b128 v[136:139], v236 offset:2048
	ds_read_b128 v[140:143], v236 offset:3072
	ds_read_b128 v[144:147], v237
	ds_read_b128 v[148:151], v237 offset:1024
	ds_read_b128 v[152:155], v237 offset:2048
	ds_read_b128 v[156:159], v237 offset:3072
	s_add_u32 s96, s94, 0x100
	s_addc_u32 s97, s95, 0
	s_cmp_eq_u32 s71, 60
	s_cselect_b32 s7, s41, s97
	s_cselect_b32 s6, s52, s96
	s_cselect_b32 vcc_hi, s39, s70
	s_cselect_b32 vcc_lo, s53, s69
	v_lshl_add_u64 v[164:165], s[94:95], 0, v[178:179]
	s_add_i32 m0, s56, 0xc000
	ds_read_b128 v[160:163], v238
	ds_read_b128 v[186:189], v238 offset:1024
	ds_read_b128 v[190:193], v238 offset:2048
	ds_read_b128 v[194:197], v238 offset:3072
	ds_read_b128 v[198:201], v238 offset:4096
	ds_read_b128 v[202:205], v238 offset:5120
	ds_read_b128 v[206:209], v238 offset:6144
	ds_read_b128 v[210:213], v238 offset:7168
	global_load_lds_dwordx4 v[164:165], off
	v_lshl_add_u64 v[164:165], s[94:95], 0, v[180:181]
	s_add_i32 m0, s56, 0xe000
	s_nop 0
	global_load_lds_dwordx4 v[164:165], off
	s_waitcnt vmcnt(8)
	s_waitcnt lgkmcnt(0)
	s_barrier
	s_setprio 1
	s_waitcnt lgkmcnt(0)
	v_mfma_f32_16x16x32_bf16 v[124:127], v[128:131], v[160:163], v[124:127]
	v_mfma_f32_16x16x32_bf16 v[120:123], v[136:139], v[160:163], v[120:123]
	v_mfma_f32_16x16x32_bf16 v[108:111], v[128:131], v[190:193], v[108:111]
	v_mfma_f32_16x16x32_bf16 v[104:107], v[136:139], v[190:193], v[104:107]
	v_mfma_f32_16x16x32_bf16 v[92:95], v[128:131], v[198:201], v[92:95]
	v_mfma_f32_16x16x32_bf16 v[88:91], v[136:139], v[198:201], v[88:91]
	v_mfma_f32_16x16x32_bf16 v[76:79], v[128:131], v[206:209], v[76:79]
	v_mfma_f32_16x16x32_bf16 v[72:75], v[136:139], v[206:209], v[72:75]
	v_mfma_f32_16x16x32_bf16 v[124:127], v[132:135], v[186:189], v[124:127]
	v_mfma_f32_16x16x32_bf16 v[120:123], v[140:143], v[186:189], v[120:123]
	v_mfma_f32_16x16x32_bf16 v[108:111], v[132:135], v[194:197], v[108:111]
	v_mfma_f32_16x16x32_bf16 v[104:107], v[140:143], v[194:197], v[104:107]
	v_mfma_f32_16x16x32_bf16 v[92:95], v[132:135], v[202:205], v[92:95]
	v_mfma_f32_16x16x32_bf16 v[88:91], v[140:143], v[202:205], v[88:91]
	v_mfma_f32_16x16x32_bf16 v[76:79], v[132:135], v[210:213], v[76:79]
	v_mfma_f32_16x16x32_bf16 v[72:75], v[140:143], v[210:213], v[72:75]
	v_mfma_f32_16x16x32_bf16 v[116:119], v[144:147], v[160:163], v[116:119]
	v_mfma_f32_16x16x32_bf16 v[112:115], v[152:155], v[160:163], v[112:115]
	v_mfma_f32_16x16x32_bf16 v[100:103], v[144:147], v[190:193], v[100:103]
	v_mfma_f32_16x16x32_bf16 v[96:99], v[152:155], v[190:193], v[96:99]
	v_mfma_f32_16x16x32_bf16 v[84:87], v[144:147], v[198:201], v[84:87]
	v_mfma_f32_16x16x32_bf16 v[80:83], v[152:155], v[198:201], v[80:83]
	v_mfma_f32_16x16x32_bf16 v[68:71], v[144:147], v[206:209], v[68:71]
	v_mfma_f32_16x16x32_bf16 v[64:67], v[152:155], v[206:209], v[64:67]
	v_mfma_f32_16x16x32_bf16 v[116:119], v[148:151], v[186:189], v[116:119]
	v_mfma_f32_16x16x32_bf16 v[112:115], v[156:159], v[186:189], v[112:115]
	v_mfma_f32_16x16x32_bf16 v[100:103], v[148:151], v[194:197], v[100:103]
	v_mfma_f32_16x16x32_bf16 v[96:99], v[156:159], v[194:197], v[96:99]
	v_mfma_f32_16x16x32_bf16 v[84:87], v[148:151], v[202:205], v[84:87]
	v_mfma_f32_16x16x32_bf16 v[80:83], v[156:159], v[202:205], v[80:83]
	v_mfma_f32_16x16x32_bf16 v[68:71], v[148:151], v[210:213], v[68:71]
	v_mfma_f32_16x16x32_bf16 v[64:67], v[156:159], v[210:213], v[64:67]
	s_setprio 0
	s_barrier
	s_add_i32 s72, s65, s55
	v_lshl_add_u64 v[164:165], vcc, 0, v[168:169]
	s_mov_b32 m0, s72
	ds_read_b128 v[160:163], v238 offset:16384
	ds_read_b128 v[186:189], v238 offset:17408
	ds_read_b128 v[190:193], v238 offset:18432
	ds_read_b128 v[194:197], v238 offset:19456
	ds_read_b128 v[198:201], v238 offset:20480
	ds_read_b128 v[202:205], v238 offset:21504
	ds_read_b128 v[206:209], v238 offset:22528
	ds_read_b128 v[210:213], v238 offset:23552
	global_load_lds_dwordx4 v[164:165], off
	s_add_i32 m0, s72, 0x2000
	s_add_u32 s72, vcc_lo, 0x100000
	v_lshl_add_u64 v[214:215], vcc, 0, v[172:173]
	s_addc_u32 s73, vcc_hi, 0
	s_add_i32 s74, s66, s55
	global_load_lds_dwordx4 v[214:215], off
	v_lshl_add_u64 v[216:217], s[72:73], 0, v[168:169]
	s_mov_b32 m0, s74
	v_lshl_add_u64 v[218:219], s[6:7], 0, v[170:171]
	global_load_lds_dwordx4 v[216:217], off
	v_lshl_add_u64 v[216:217], s[72:73], 0, v[172:173]
	s_add_i32 m0, s74, 0x2000
	s_nop 0
	global_load_lds_dwordx4 v[216:217], off
	v_lshl_add_u64 v[216:217], s[6:7], 0, v[166:167]
	s_mov_b32 m0, s56
	s_nop 0
	global_load_lds_dwordx4 v[216:217], off
	s_mov_b32 m0, s57
	s_nop 0
	global_load_lds_dwordx4 v[218:219], off
	s_waitcnt vmcnt(8)
	s_waitcnt lgkmcnt(0)
	s_barrier
; #define PG8_STAGE(bufoff, gbase, voff) do { _Pragma("unroll") for (int _i = 0; _i < 2; ++_i) \
;         __builtin_amdgcn_global_load_lds((const unsigned*)((const char*)(gbase) + (voff)[_i]), (PG8_LAS unsigned*)(lds + (bufoff) + ldsw + _i * 8192), 16, 0, 0); } while (0)
; #define PG8_LDA(dst, b, h) do { _Pragma("unroll") for (int m = 0; m < 4; ++m) _Pragma("unroll") for (int k = 0; k < 2; ++k) dst[m][k] = *(const PG8_LAS bf16x8*)(lds + PG8_SA(b, h) + aoff + m * 2048 + k * 1024); } while (0)
; #define PG8_LDB(dst, b, h) do { _Pragma("unroll") for (int n = 0; n < 2; ++n) _Pragma("unroll") for (int k = 0; k < 2; ++k) dst[n][k] = *(const PG8_LAS bf16x8*)(lds + PG8_SB(b, h) + boff + n * 2048 + k * 1024); } while (0)
; #define PG8_MMA(ai, bj, At, Bt) do { __builtin_amdgcn_s_setprio(1); _Pragma("unroll") for (int m = 0; m < 4; ++m) _Pragma("unroll") for (int n = 0; n < 2; ++n) _Pragma("unroll") for (int k = 0; k < 2; ++k) \
;         acc[ai][bj][m][n] = __builtin_amdgcn_mfma_f32_16x16x32_bf16(Bt[n][k], At[m][k], acc[ai][bj][m][n], 0, 0, 0); __builtin_amdgcn_s_setprio(0); } while (0)
; #define PG8_WAIT_V(n) asm volatile("s_waitcnt vmcnt(" #n ")" ::: "memory")
; #define PG8_WAIT_L(n) asm volatile("s_waitcnt lgkmcnt(" #n ")" ::: "memory")
; #define PG8_BAR __builtin_amdgcn_s_barrier()
; #define PG8_SCHED __builtin_amdgcn_sched_barrier(0)
; template <class Epi, class Sched, bool ALIGN_EPI = false, bool SP2 = false>
; __device__ __forceinline__ void gemm_phase(PG8_LAS unsigned char* lds, const Gemm g, const Sched& S, const Epi& E) {
;     ...
;             PG8_WAIT_V(8); PG8_WAIT_L(0); PG8_BAR; PG8_MMA(1, 0, At, B0); PG8_MMA(1, 1, At, B1); PG8_BAR; PG8_SCHED;
;             PG8_LDB(B0, 1, 0); PG8_LDB(B1, 1, 1); PG8_SCHED; PG8_LDA(At, 1, 0); PG8_STAGE(PG8_SA(0, 1), a2 + hstepA, voffA);
;             PG8_WAIT_V(8); PG8_WAIT_L(0); PG8_BAR; PG8_MMA(0, 0, At, B0); PG8_MMA(0, 1, At, B1); PG8_BAR; PG8_SCHED;
	s_setprio 1
	s_waitcnt lgkmcnt(0)
	v_mfma_f32_16x16x32_bf16 v[60:63], v[128:131], v[160:163], v[60:63]
	v_mfma_f32_16x16x32_bf16 v[56:59], v[136:139], v[160:163], v[56:59]
	v_mfma_f32_16x16x32_bf16 v[44:47], v[128:131], v[190:193], v[44:47]
	v_mfma_f32_16x16x32_bf16 v[40:43], v[136:139], v[190:193], v[40:43]
	v_mfma_f32_16x16x32_bf16 v[28:31], v[128:131], v[198:201], v[28:31]
	v_mfma_f32_16x16x32_bf16 v[24:27], v[136:139], v[198:201], v[24:27]
	v_mfma_f32_16x16x32_bf16 v[12:15], v[128:131], v[206:209], v[12:15]
	v_mfma_f32_16x16x32_bf16 v[8:11], v[136:139], v[206:209], v[8:11]
	v_mfma_f32_16x16x32_bf16 v[60:63], v[132:135], v[186:189], v[60:63]
	v_mfma_f32_16x16x32_bf16 v[56:59], v[140:143], v[186:189], v[56:59]
	v_mfma_f32_16x16x32_bf16 v[44:47], v[132:135], v[194:197], v[44:47]
	v_mfma_f32_16x16x32_bf16 v[40:43], v[140:143], v[194:197], v[40:43]
	v_mfma_f32_16x16x32_bf16 v[28:31], v[132:135], v[202:205], v[28:31]
	v_mfma_f32_16x16x32_bf16 v[24:27], v[140:143], v[202:205], v[24:27]
	v_mfma_f32_16x16x32_bf16 v[12:15], v[132:135], v[210:213], v[12:15]
	v_mfma_f32_16x16x32_bf16 v[8:11], v[140:143], v[210:213], v[8:11]
	v_mfma_f32_16x16x32_bf16 v[52:55], v[144:147], v[160:163], v[52:55]
	v_mfma_f32_16x16x32_bf16 v[48:51], v[152:155], v[160:163], v[48:51]
	v_mfma_f32_16x16x32_bf16 v[36:39], v[144:147], v[190:193], v[36:39]
	v_mfma_f32_16x16x32_bf16 v[32:35], v[152:155], v[190:193], v[32:35]
	v_mfma_f32_16x16x32_bf16 v[20:23], v[144:147], v[198:201], v[20:23]
	v_mfma_f32_16x16x32_bf16 v[16:19], v[152:155], v[198:201], v[16:19]
	v_mfma_f32_16x16x32_bf16 v[4:7], v[144:147], v[206:209], v[4:7]
	v_mfma_f32_16x16x32_bf16 v[0:3], v[152:155], v[206:209], v[0:3]
	v_mfma_f32_16x16x32_bf16 v[52:55], v[148:151], v[186:189], v[52:55]
	v_mfma_f32_16x16x32_bf16 v[48:51], v[156:159], v[186:189], v[48:51]
	v_mfma_f32_16x16x32_bf16 v[36:39], v[148:151], v[194:197], v[36:39]
	v_mfma_f32_16x16x32_bf16 v[32:35], v[156:159], v[194:197], v[32:35]
	v_mfma_f32_16x16x32_bf16 v[20:23], v[148:151], v[202:205], v[20:23]
	v_mfma_f32_16x16x32_bf16 v[16:19], v[156:159], v[202:205], v[16:19]
	v_mfma_f32_16x16x32_bf16 v[4:7], v[148:151], v[210:213], v[4:7]
	v_mfma_f32_16x16x32_bf16 v[0:3], v[156:159], v[210:213], v[0:3]
	s_setprio 0
	s_barrier
	s_add_i32 s72, 0, 0x18000
	s_add_i32 s73, 0, 0x1c000
	v_add_u32_e32 v140, s72, v234
	v_add_u32_e32 v156, s73, v234
	ds_read_b128 v[128:131], v140
	ds_read_b128 v[132:135], v140 offset:1024
	ds_read_b128 v[136:139], v140 offset:2048
	ds_read_b128 v[140:143], v140 offset:3072
	ds_read_b128 v[144:147], v156
	ds_read_b128 v[148:151], v156 offset:1024
	ds_read_b128 v[152:155], v156 offset:2048
	ds_read_b128 v[156:159], v156 offset:3072
	s_add_u32 s6, s6, 0x100000
	s_addc_u32 s7, s7, 0
	s_mov_b32 m0, s58
	v_lshl_add_u64 v[220:221], s[6:7], 0, v[166:167]
	ds_read_b128 v[160:163], v238 offset:32768
	ds_read_b128 v[186:189], v238 offset:33792
	ds_read_b128 v[190:193], v238 offset:34816
	ds_read_b128 v[194:197], v238 offset:35840
	ds_read_b128 v[198:201], v238 offset:36864
	ds_read_b128 v[202:205], v238 offset:37888
	ds_read_b128 v[206:209], v238 offset:38912
	ds_read_b128 v[210:213], v238 offset:39936
	global_load_lds_dwordx4 v[220:221], off
	v_lshl_add_u64 v[220:221], s[6:7], 0, v[170:171]
	s_mov_b32 m0, s59
	s_nop 0
	global_load_lds_dwordx4 v[220:221], off
	s_waitcnt vmcnt(8)
	s_waitcnt lgkmcnt(0)
	s_barrier
	s_setprio 1
	s_waitcnt lgkmcnt(0)
	v_mfma_f32_16x16x32_bf16 v[124:127], v[128:131], v[160:163], v[124:127]
	v_mfma_f32_16x16x32_bf16 v[120:123], v[136:139], v[160:163], v[120:123]
	v_mfma_f32_16x16x32_bf16 v[108:111], v[128:131], v[190:193], v[108:111]
	v_mfma_f32_16x16x32_bf16 v[104:107], v[136:139], v[190:193], v[104:107]
	v_mfma_f32_16x16x32_bf16 v[92:95], v[128:131], v[198:201], v[92:95]
	v_mfma_f32_16x16x32_bf16 v[88:91], v[136:139], v[198:201], v[88:91]
	v_mfma_f32_16x16x32_bf16 v[76:79], v[128:131], v[206:209], v[76:79]
	v_mfma_f32_16x16x32_bf16 v[72:75], v[136:139], v[206:209], v[72:75]
	v_mfma_f32_16x16x32_bf16 v[124:127], v[132:135], v[186:189], v[124:127]
	v_mfma_f32_16x16x32_bf16 v[120:123], v[140:143], v[186:189], v[120:123]
	v_mfma_f32_16x16x32_bf16 v[108:111], v[132:135], v[194:197], v[108:111]
	v_mfma_f32_16x16x32_bf16 v[104:107], v[140:143], v[194:197], v[104:107]
	v_mfma_f32_16x16x32_bf16 v[92:95], v[132:135], v[202:205], v[92:95]
	v_mfma_f32_16x16x32_bf16 v[88:91], v[140:143], v[202:205], v[88:91]
	v_mfma_f32_16x16x32_bf16 v[76:79], v[132:135], v[210:213], v[76:79]
	v_mfma_f32_16x16x32_bf16 v[72:75], v[140:143], v[210:213], v[72:75]
	v_mfma_f32_16x16x32_bf16 v[116:119], v[144:147], v[160:163], v[116:119]
	v_mfma_f32_16x16x32_bf16 v[112:115], v[152:155], v[160:163], v[112:115]
	v_mfma_f32_16x16x32_bf16 v[100:103], v[144:147], v[190:193], v[100:103]
	v_mfma_f32_16x16x32_bf16 v[96:99], v[152:155], v[190:193], v[96:99]
	v_mfma_f32_16x16x32_bf16 v[84:87], v[144:147], v[198:201], v[84:87]
	v_mfma_f32_16x16x32_bf16 v[80:83], v[152:155], v[198:201], v[80:83]
	v_mfma_f32_16x16x32_bf16 v[68:71], v[144:147], v[206:209], v[68:71]
	v_mfma_f32_16x16x32_bf16 v[64:67], v[152:155], v[206:209], v[64:67]
	v_mfma_f32_16x16x32_bf16 v[116:119], v[148:151], v[186:189], v[116:119]
	v_mfma_f32_16x16x32_bf16 v[112:115], v[156:159], v[186:189], v[112:115]
	v_mfma_f32_16x16x32_bf16 v[100:103], v[148:151], v[194:197], v[100:103]
	v_mfma_f32_16x16x32_bf16 v[96:99], v[156:159], v[194:197], v[96:99]
	v_mfma_f32_16x16x32_bf16 v[84:87], v[148:151], v[202:205], v[84:87]
	v_mfma_f32_16x16x32_bf16 v[80:83], v[156:159], v[202:205], v[80:83]
	v_mfma_f32_16x16x32_bf16 v[68:71], v[148:151], v[210:213], v[68:71]
	v_mfma_f32_16x16x32_bf16 v[64:67], v[156:159], v[210:213], v[64:67]
	s_setprio 0
	s_barrier
; #define PG8_STAGE(bufoff, gbase, voff) do { _Pragma("unroll") for (int _i = 0; _i < 2; ++_i) \
;         __builtin_amdgcn_global_load_lds((const unsigned*)((const char*)(gbase) + (voff)[_i]), (PG8_LAS unsigned*)(lds + (bufoff) + ldsw + _i * 8192), 16, 0, 0); } while (0)
; #define PG8_LDA(dst, b, h) do { _Pragma("unroll") for (int m = 0; m < 4; ++m) _Pragma("unroll") for (int k = 0; k < 2; ++k) dst[m][k] = *(const PG8_LAS bf16x8*)(lds + PG8_SA(b, h) + aoff + m * 2048 + k * 1024); } while (0)
; #define PG8_MMA(ai, bj, At, Bt) do { __builtin_amdgcn_s_setprio(1); _Pragma("unroll") for (int m = 0; m < 4; ++m) _Pragma("unroll") for (int n = 0; n < 2; ++n) _Pragma("unroll") for (int k = 0; k < 2; ++k) \
;         acc[ai][bj][m][n] = __builtin_amdgcn_mfma_f32_16x16x32_bf16(Bt[n][k], At[m][k], acc[ai][bj][m][n], 0, 0, 0); __builtin_amdgcn_s_setprio(0); } while (0)
; #define PG8_WAIT_V(n) asm volatile("s_waitcnt vmcnt(" #n ")" ::: "memory")
; #define PG8_WAIT_L(n) asm volatile("s_waitcnt lgkmcnt(" #n ")" ::: "memory")
; #define PG8_BAR __builtin_amdgcn_s_barrier()
; #define PG8_SCHED __builtin_amdgcn_sched_barrier(0)
; template <class Epi, class Sched, bool ALIGN_EPI = false, bool SP2 = false>
; __device__ __forceinline__ void gemm_phase(PG8_LAS unsigned char* lds, const Gemm g, const Sched& S, const Epi& E) {
;     ...
;             PG8_LDA(At, 1, 1); PG8_STAGE(PG8_SB(1, 0), b3, voffB); PG8_STAGE(PG8_SB(1, 1), b3 + hstep, voffB); PG8_STAGE(PG8_SA(1, 0), a3, voffA);
;             PG8_WAIT_V(8); PG8_WAIT_L(0); PG8_BAR; PG8_MMA(1, 0, At, B0); PG8_MMA(1, 1, At, B1); PG8_BAR; PG8_SCHED;
	s_add_i32 s6, s72, s55
	v_lshl_add_u64 v[164:165], v[164:165], 0, s[10:11]
	s_mov_b32 m0, s6
	ds_read_b128 v[160:163], v238 offset:49152
	ds_read_b128 v[186:189], v238 offset:50176
	ds_read_b128 v[190:193], v238 offset:51200
	ds_read_b128 v[194:197], v238 offset:52224
	ds_read_b128 v[198:201], v238 offset:53248
	ds_read_b128 v[202:205], v238 offset:54272
	ds_read_b128 v[206:209], v238 offset:55296
	ds_read_b128 v[210:213], v238 offset:56320
	global_load_lds_dwordx4 v[164:165], off
	s_add_i32 m0, s6, 0x2000
	s_add_u32 s6, vcc_lo, 0x100080
	v_lshl_add_u64 v[164:165], v[214:215], 0, s[10:11]
	s_addc_u32 s7, vcc_hi, 0
	s_add_i32 s72, s73, s55
	global_load_lds_dwordx4 v[164:165], off
	v_lshl_add_u64 v[164:165], s[6:7], 0, v[168:169]
	s_mov_b32 m0, s72
	s_nop 0
	global_load_lds_dwordx4 v[164:165], off
	v_lshl_add_u64 v[164:165], s[6:7], 0, v[172:173]
	s_add_i32 m0, s72, 0x2000
	s_nop 0
	global_load_lds_dwordx4 v[164:165], off
	v_lshl_add_u64 v[164:165], v[216:217], 0, s[10:11]
	s_mov_b32 m0, s63
	s_nop 0
	global_load_lds_dwordx4 v[164:165], off
	v_lshl_add_u64 v[164:165], v[218:219], 0, s[10:11]
	s_mov_b32 m0, s64
	s_nop 0
	global_load_lds_dwordx4 v[164:165], off
	s_waitcnt vmcnt(8)
	s_waitcnt lgkmcnt(0)
	s_barrier
	s_setprio 1
	s_waitcnt lgkmcnt(0)
	v_mfma_f32_16x16x32_bf16 v[60:63], v[128:131], v[160:163], v[60:63]
	v_mfma_f32_16x16x32_bf16 v[56:59], v[136:139], v[160:163], v[56:59]
	v_mfma_f32_16x16x32_bf16 v[44:47], v[128:131], v[190:193], v[44:47]
	v_mfma_f32_16x16x32_bf16 v[40:43], v[136:139], v[190:193], v[40:43]
	v_mfma_f32_16x16x32_bf16 v[28:31], v[128:131], v[198:201], v[28:31]
	v_mfma_f32_16x16x32_bf16 v[24:27], v[136:139], v[198:201], v[24:27]
	v_mfma_f32_16x16x32_bf16 v[12:15], v[128:131], v[206:209], v[12:15]
	v_mfma_f32_16x16x32_bf16 v[8:11], v[136:139], v[206:209], v[8:11]
	v_mfma_f32_16x16x32_bf16 v[60:63], v[132:135], v[186:189], v[60:63]
	v_mfma_f32_16x16x32_bf16 v[56:59], v[140:143], v[186:189], v[56:59]
	v_mfma_f32_16x16x32_bf16 v[44:47], v[132:135], v[194:197], v[44:47]
	v_mfma_f32_16x16x32_bf16 v[40:43], v[140:143], v[194:197], v[40:43]
	v_mfma_f32_16x16x32_bf16 v[28:31], v[132:135], v[202:205], v[28:31]
	v_mfma_f32_16x16x32_bf16 v[24:27], v[140:143], v[202:205], v[24:27]
	v_mfma_f32_16x16x32_bf16 v[12:15], v[132:135], v[210:213], v[12:15]
	v_mfma_f32_16x16x32_bf16 v[8:11], v[140:143], v[210:213], v[8:11]
	v_mfma_f32_16x16x32_bf16 v[52:55], v[144:147], v[160:163], v[52:55]
	v_mfma_f32_16x16x32_bf16 v[48:51], v[152:155], v[160:163], v[48:51]
	v_mfma_f32_16x16x32_bf16 v[36:39], v[144:147], v[190:193], v[36:39]
	v_mfma_f32_16x16x32_bf16 v[32:35], v[152:155], v[190:193], v[32:35]
	v_mfma_f32_16x16x32_bf16 v[20:23], v[144:147], v[198:201], v[20:23]
	v_mfma_f32_16x16x32_bf16 v[16:19], v[152:155], v[198:201], v[16:19]
	v_mfma_f32_16x16x32_bf16 v[4:7], v[144:147], v[206:209], v[4:7]
	v_mfma_f32_16x16x32_bf16 v[0:3], v[152:155], v[206:209], v[0:3]
	v_mfma_f32_16x16x32_bf16 v[52:55], v[148:151], v[186:189], v[52:55]
	v_mfma_f32_16x16x32_bf16 v[48:51], v[156:159], v[186:189], v[48:51]
	v_mfma_f32_16x16x32_bf16 v[36:39], v[148:151], v[194:197], v[36:39]
	v_mfma_f32_16x16x32_bf16 v[32:35], v[156:159], v[194:197], v[32:35]
	v_mfma_f32_16x16x32_bf16 v[20:23], v[148:151], v[202:205], v[20:23]
	v_mfma_f32_16x16x32_bf16 v[16:19], v[156:159], v[202:205], v[16:19]
	v_mfma_f32_16x16x32_bf16 v[4:7], v[148:151], v[210:213], v[4:7]
	v_mfma_f32_16x16x32_bf16 v[0:3], v[156:159], v[210:213], v[0:3]
	s_setprio 0
	s_barrier
	s_add_i32 s71, s71, 2
	s_add_u32 s69, s69, 0x100
	s_addc_u32 s70, s70, 0
	s_cmp_gt_u32 s71, 61
	s_mov_b64 s[94:95], s[96:97]
	s_cbranch_scc0 .LBB0_1310
	s_and_b64 vcc, exec, s[12:13]
	s_cbranch_vccz .LBB0_1313
	s_barrier

; #define PG8_STAGE(bufoff, gbase, voff) do { _Pragma("unroll") for (int _i = 0; _i < 2; ++_i) \
;         __builtin_amdgcn_global_load_lds((const unsigned*)((const char*)(gbase) + (voff)[_i]), (PG8_LAS unsigned*)(lds + (bufoff) + ldsw + _i * 8192), 16, 0, 0); } while (0)
; #define PG8_LDA(dst, b, h) do { _Pragma("unroll") for (int m = 0; m < 4; ++m) _Pragma("unroll") for (int k = 0; k < 2; ++k) dst[m][k] = *(const PG8_LAS bf16x8*)(lds + PG8_SA(b, h) + aoff + m * 2048 + k * 1024); } while (0)
; #define PG8_LDB(dst, b, h) do { _Pragma("unroll") for (int n = 0; n < 2; ++n) _Pragma("unroll") for (int k = 0; k < 2; ++k) dst[n][k] = *(const PG8_LAS bf16x8*)(lds + PG8_SB(b, h) + boff + n * 2048 + k * 1024); } while (0)
; #define PG8_WAIT_V(n) asm volatile("s_waitcnt vmcnt(" #n ")" ::: "memory")
; #define PG8_WAIT_L(n) asm volatile("s_waitcnt lgkmcnt(" #n ")" ::: "memory")
; #define PG8_BAR __builtin_amdgcn_s_barrier()
; #define PG8_SCHED __builtin_amdgcn_sched_barrier(0)
; template <class Epi, class Sched, bool ALIGN_EPI = false, bool SP2 = false>
; __device__ __forceinline__ void gemm_phase(PG8_LAS unsigned char* lds, const Gemm g, const Sched& S, const Epi& E) {
;     ...
;         const bool has_next = S.next(ui + 1, nxt);
;         const char* nA = has_next ? (const char*)g.A + (size_t)nxt.pm * tstep : cA; const char* nB = has_next ? (const char*)g.Bt + (size_t)nxt.pn * tstep : cB;
;         for (int t = 0; t < nt; t += 2) {
;             const bool last = (t == nt - 2);
;             const char* a1 = cA + (size_t)(t + 1) * kstepA;
;             const char* a2 = last ? nA : cA + (size_t)(t + 2) * kstepA; const char* b2 = last ? nB : cB + (size_t)(t + 2) * kstep;
;             const char* a3 = a2 + kstepA; const char* b3 = b2 + kstep;
;             if (last && has_next) S.a_ready(nxt);
;             if constexpr (SP2) {
;             PG8_LDB(B0, 0, 0); PG8_LDB(B1, 0, 1); PG8_SCHED; PG8_LDA(At, 0, 0); PG8_STAGE(PG8_SA(1, 1), a1 + hstepA, voffA);
;             PG8_WAIT_V(8); PG8_WAIT_L(0); PG8_BAR; PG8_MMA(0, 0, At, B0); PG8_MMA(0, 1, At, B1); PG8_BAR; PG8_SCHED;
;             PG8_LDA(At, 0, 1); PG8_STAGE(PG8_SB(0, 0), b2, voffB); PG8_STAGE(PG8_SB(0, 1), b2 + hstep, voffB); PG8_STAGE(PG8_SA(0, 0), a2, voffA);
;             PG8_WAIT_V(8); PG8_WAIT_L(0); PG8_BAR; PG8_MMA(1, 0, At, B0); PG8_MMA(1, 1, At, B1); PG8_BAR; PG8_SCHED;
.LBB0_1346:
	ds_read_b128 v[0:3], v145
	ds_read_b128 v[4:7], v145 offset:1024
	ds_read_b128 v[8:11], v145 offset:2048
	ds_read_b128 v[12:15], v145 offset:3072
	ds_read_b128 v[16:19], v146
	ds_read_b128 v[20:23], v146 offset:1024
	ds_read_b128 v[24:27], v146 offset:2048
	ds_read_b128 v[28:31], v146 offset:3072
	s_ashr_i32 s23, s22, 31
	s_lshl_b64 s[24:25], s[22:23], 17
	s_add_u32 s24, s7, s24
	s_addc_u32 s25, s29, s25
	s_and_b64 s[26:27], s[0:1], exec
	s_cselect_b32 s85, s25, s35
	s_cselect_b32 s84, s24, s34
	s_ashr_i32 s21, s20, 31
	s_lshl_b64 s[26:27], s[20:21], 17
	s_add_u32 s26, s33, s26
	s_addc_u32 s27, s52, s27
	s_and_b64 s[40:41], s[0:1], exec
	s_cselect_b32 s41, s27, s39
	s_cselect_b32 s40, s26, s38
	s_add_u32 s64, s34, 0x10080
	s_addc_u32 s65, s35, 0
	s_mov_b32 m0, s62
	v_lshl_add_u64 v[64:65], s[64:65], 0, v[134:135]
	s_add_i32 s21, s31, 0xe000
	ds_read_b128 v[32:35], v147
	ds_read_b128 v[36:39], v147 offset:1024
	ds_read_b128 v[40:43], v147 offset:2048
	ds_read_b128 v[44:47], v147 offset:3072
	ds_read_b128 v[48:51], v147 offset:4096
	ds_read_b128 v[52:55], v147 offset:5120
	ds_read_b128 v[56:59], v147 offset:6144
	ds_read_b128 v[60:63], v147 offset:7168
	global_load_lds_dwordx4 v[64:65], off
	v_lshl_add_u64 v[64:65], s[64:65], 0, v[130:131]
	s_mov_b32 m0, s21
	s_nop 0
	global_load_lds_dwordx4 v[64:65], off
	s_waitcnt vmcnt(8)
	s_waitcnt lgkmcnt(0)
	s_barrier
	s_setprio 1
	s_waitcnt lgkmcnt(0)
	v_mfma_f32_16x16x32_bf16 v[64:67], v[0:3], v[32:35], 0
	v_mfma_f32_16x16x32_bf16 v[68:71], v[8:11], v[32:35], 0
	v_mfma_f32_16x16x32_bf16 v[72:75], v[0:3], v[40:43], 0
	v_mfma_f32_16x16x32_bf16 v[76:79], v[8:11], v[40:43], 0
	v_mfma_f32_16x16x32_bf16 v[80:83], v[0:3], v[48:51], 0
	v_mfma_f32_16x16x32_bf16 v[84:87], v[8:11], v[48:51], 0
	v_mfma_f32_16x16x32_bf16 v[88:91], v[0:3], v[56:59], 0
	v_mfma_f32_16x16x32_bf16 v[92:95], v[8:11], v[56:59], 0
	v_mfma_f32_16x16x32_bf16 v[64:67], v[4:7], v[36:39], v[64:67]
	v_mfma_f32_16x16x32_bf16 v[68:71], v[12:15], v[36:39], v[68:71]
	v_mfma_f32_16x16x32_bf16 v[72:75], v[4:7], v[44:47], v[72:75]
	v_mfma_f32_16x16x32_bf16 v[76:79], v[12:15], v[44:47], v[76:79]
	v_mfma_f32_16x16x32_bf16 v[80:83], v[4:7], v[52:55], v[80:83]
	v_mfma_f32_16x16x32_bf16 v[84:87], v[12:15], v[52:55], v[84:87]
	v_mfma_f32_16x16x32_bf16 v[88:91], v[4:7], v[60:63], v[88:91]
	v_mfma_f32_16x16x32_bf16 v[92:95], v[12:15], v[60:63], v[92:95]
	v_mfma_f32_16x16x32_bf16 v[96:99], v[16:19], v[32:35], 0
	v_mfma_f32_16x16x32_bf16 v[32:35], v[24:27], v[32:35], 0
	v_mfma_f32_16x16x32_bf16 v[96:99], v[20:23], v[36:39], v[96:99]
	v_mfma_f32_16x16x32_bf16 v[32:35], v[28:31], v[36:39], v[32:35]
	v_mfma_f32_16x16x32_bf16 v[36:39], v[16:19], v[40:43], 0
	v_mfma_f32_16x16x32_bf16 v[40:43], v[24:27], v[40:43], 0
	v_mfma_f32_16x16x32_bf16 v[36:39], v[20:23], v[44:47], v[36:39]
	v_mfma_f32_16x16x32_bf16 v[40:43], v[28:31], v[44:47], v[40:43]
	v_mfma_f32_16x16x32_bf16 v[44:47], v[16:19], v[48:51], 0
	v_mfma_f32_16x16x32_bf16 v[48:51], v[24:27], v[48:51], 0
	v_mfma_f32_16x16x32_bf16 v[44:47], v[20:23], v[52:55], v[44:47]
	v_mfma_f32_16x16x32_bf16 v[48:51], v[28:31], v[52:55], v[48:51]
	v_mfma_f32_16x16x32_bf16 v[52:55], v[16:19], v[56:59], 0
	v_mfma_f32_16x16x32_bf16 v[56:59], v[24:27], v[56:59], 0
	v_mfma_f32_16x16x32_bf16 v[52:55], v[20:23], v[60:63], v[52:55]
	v_mfma_f32_16x16x32_bf16 v[56:59], v[28:31], v[60:63], v[56:59]
	s_setprio 0
	s_barrier
	s_add_i32 s66, s3, s53
	v_lshl_add_u64 v[140:141], s[38:39], 0, v[132:133]
	s_add_i32 s23, s66, 0x2000
	v_lshl_add_u64 v[148:149], v[140:141], 0, s[16:17]
	s_mov_b32 m0, s66
	v_lshl_add_u64 v[212:213], s[38:39], 0, v[128:129]
	s_add_u32 s68, s38, 0x10100
	ds_read_b128 v[60:63], v147 offset:16384
	ds_read_b128 v[100:103], v147 offset:17408
	ds_read_b128 v[104:107], v147 offset:18432
	ds_read_b128 v[108:111], v147 offset:19456
	ds_read_b128 v[112:115], v147 offset:20480
	ds_read_b128 v[116:119], v147 offset:21504
	ds_read_b128 v[120:123], v147 offset:22528
	ds_read_b128 v[124:127], v147 offset:23552
	global_load_lds_dwordx4 v[148:149], off
	v_lshl_add_u64 v[148:149], v[212:213], 0, s[16:17]
	s_mov_b32 m0, s23
	s_addc_u32 s69, s39, 0
	s_add_i32 s64, s61, s53
	global_load_lds_dwordx4 v[148:149], off
	v_lshl_add_u64 v[148:149], s[68:69], 0, v[132:133]
	s_mov_b32 m0, s64
	s_add_i32 s65, s64, 0x2000
	global_load_lds_dwordx4 v[148:149], off
	v_lshl_add_u64 v[148:149], s[68:69], 0, v[128:129]
	s_mov_b32 m0, s65
	v_lshl_add_u64 v[214:215], s[34:35], 0, v[134:135]
	global_load_lds_dwordx4 v[148:149], off
	v_lshl_add_u64 v[148:149], v[214:215], 0, s[16:17]
	s_mov_b32 m0, s31
	v_lshl_add_u64 v[216:217], s[34:35], 0, v[130:131]
	global_load_lds_dwordx4 v[148:149], off
	v_lshl_add_u64 v[148:149], v[216:217], 0, s[16:17]
	s_mov_b32 m0, s54
	s_nop 0
	global_load_lds_dwordx4 v[148:149], off
	s_waitcnt vmcnt(8)
	s_waitcnt lgkmcnt(0)
	s_barrier
; #define PG8_STAGE(bufoff, gbase, voff) do { _Pragma("unroll") for (int _i = 0; _i < 2; ++_i) \
;         __builtin_amdgcn_global_load_lds((const unsigned*)((const char*)(gbase) + (voff)[_i]), (PG8_LAS unsigned*)(lds + (bufoff) + ldsw + _i * 8192), 16, 0, 0); } while (0)
; #define PG8_LDA(dst, b, h) do { _Pragma("unroll") for (int m = 0; m < 4; ++m) _Pragma("unroll") for (int k = 0; k < 2; ++k) dst[m][k] = *(const PG8_LAS bf16x8*)(lds + PG8_SA(b, h) + aoff + m * 2048 + k * 1024); } while (0)
; #define PG8_LDB(dst, b, h) do { _Pragma("unroll") for (int n = 0; n < 2; ++n) _Pragma("unroll") for (int k = 0; k < 2; ++k) dst[n][k] = *(const PG8_LAS bf16x8*)(lds + PG8_SB(b, h) + boff + n * 2048 + k * 1024); } while (0)
; #define PG8_MMA(ai, bj, At, Bt) do { __builtin_amdgcn_s_setprio(1); _Pragma("unroll") for (int m = 0; m < 4; ++m) _Pragma("unroll") for (int n = 0; n < 2; ++n) _Pragma("unroll") for (int k = 0; k < 2; ++k) \
;         acc[ai][bj][m][n] = __builtin_amdgcn_mfma_f32_16x16x32_bf16(Bt[n][k], At[m][k], acc[ai][bj][m][n], 0, 0, 0); __builtin_amdgcn_s_setprio(0); } while (0)
; #define PG8_WAIT_V(n) asm volatile("s_waitcnt vmcnt(" #n ")" ::: "memory")
; #define PG8_WAIT_L(n) asm volatile("s_waitcnt lgkmcnt(" #n ")" ::: "memory")
; #define PG8_BAR __builtin_amdgcn_s_barrier()
; #define PG8_SCHED __builtin_amdgcn_sched_barrier(0)
; template <class Epi, class Sched, bool ALIGN_EPI = false, bool SP2 = false>
; __device__ __forceinline__ void gemm_phase(PG8_LAS unsigned char* lds, const Gemm g, const Sched& S, const Epi& E) {
;     ...
;             PG8_WAIT_V(8); PG8_WAIT_L(0); PG8_BAR; PG8_MMA(1, 0, At, B0); PG8_MMA(1, 1, At, B1); PG8_BAR; PG8_SCHED;
;             PG8_LDB(B0, 1, 0); PG8_LDB(B1, 1, 1); PG8_SCHED; PG8_LDA(At, 1, 0); PG8_STAGE(PG8_SA(0, 1), a2 + hstepA, voffA);
;             PG8_WAIT_V(8); PG8_WAIT_L(0); PG8_BAR; PG8_MMA(0, 0, At, B0); PG8_MMA(0, 1, At, B1); PG8_BAR; PG8_SCHED;
	s_setprio 1
	s_waitcnt lgkmcnt(0)
	v_mfma_f32_16x16x32_bf16 v[148:151], v[0:3], v[60:63], 0
	v_mfma_f32_16x16x32_bf16 v[156:159], v[0:3], v[104:107], 0
	v_mfma_f32_16x16x32_bf16 v[164:167], v[0:3], v[112:115], 0
	v_mfma_f32_16x16x32_bf16 v[0:3], v[0:3], v[120:123], 0
	v_mfma_f32_16x16x32_bf16 v[148:151], v[4:7], v[100:103], v[148:151]
	v_mfma_f32_16x16x32_bf16 v[156:159], v[4:7], v[108:111], v[156:159]
	v_mfma_f32_16x16x32_bf16 v[164:167], v[4:7], v[116:119], v[164:167]
	v_mfma_f32_16x16x32_bf16 v[0:3], v[4:7], v[124:127], v[0:3]
	v_mfma_f32_16x16x32_bf16 v[4:7], v[8:11], v[120:123], 0
	v_mfma_f32_16x16x32_bf16 v[152:155], v[8:11], v[60:63], 0
	v_mfma_f32_16x16x32_bf16 v[160:163], v[8:11], v[104:107], 0
	v_mfma_f32_16x16x32_bf16 v[168:171], v[8:11], v[112:115], 0
	v_mfma_f32_16x16x32_bf16 v[4:7], v[12:15], v[124:127], v[4:7]
	v_mfma_f32_16x16x32_bf16 v[152:155], v[12:15], v[100:103], v[152:155]
	v_mfma_f32_16x16x32_bf16 v[160:163], v[12:15], v[108:111], v[160:163]
	v_mfma_f32_16x16x32_bf16 v[168:171], v[12:15], v[116:119], v[168:171]
	v_mfma_f32_16x16x32_bf16 v[8:11], v[16:19], v[60:63], 0
	v_mfma_f32_16x16x32_bf16 v[12:15], v[24:27], v[60:63], 0
	v_mfma_f32_16x16x32_bf16 v[8:11], v[20:23], v[100:103], v[8:11]
	v_mfma_f32_16x16x32_bf16 v[12:15], v[28:31], v[100:103], v[12:15]
	v_mfma_f32_16x16x32_bf16 v[60:63], v[16:19], v[104:107], 0
	v_mfma_f32_16x16x32_bf16 v[100:103], v[24:27], v[104:107], 0
	v_mfma_f32_16x16x32_bf16 v[104:107], v[16:19], v[112:115], 0
	v_mfma_f32_16x16x32_bf16 v[16:19], v[16:19], v[120:123], 0
	v_mfma_f32_16x16x32_bf16 v[60:63], v[20:23], v[108:111], v[60:63]
	v_mfma_f32_16x16x32_bf16 v[100:103], v[28:31], v[108:111], v[100:103]
	v_mfma_f32_16x16x32_bf16 v[104:107], v[20:23], v[116:119], v[104:107]
	v_mfma_f32_16x16x32_bf16 v[108:111], v[24:27], v[112:115], 0
	v_mfma_f32_16x16x32_bf16 v[16:19], v[20:23], v[124:127], v[16:19]
	v_mfma_f32_16x16x32_bf16 v[20:23], v[24:27], v[120:123], 0
	v_mfma_f32_16x16x32_bf16 v[108:111], v[28:31], v[116:119], v[108:111]
	v_mfma_f32_16x16x32_bf16 v[20:23], v[28:31], v[124:127], v[20:23]
	s_setprio 0
	s_barrier
	s_add_i32 s67, 0, 0x18000
	s_add_i32 s72, 0, 0x1c000
	v_add_u32_e32 v224, s67, v143
	v_add_u32_e32 v232, s72, v143
	ds_read_b128 v[24:27], v224
	ds_read_b128 v[28:31], v224 offset:1024
	ds_read_b128 v[112:115], v224 offset:2048
	ds_read_b128 v[116:119], v224 offset:3072
	ds_read_b128 v[120:123], v232
	ds_read_b128 v[124:127], v232 offset:1024
	ds_read_b128 v[172:175], v232 offset:2048
	ds_read_b128 v[176:179], v232 offset:3072
	s_add_u32 s68, s34, 0x10100
	s_addc_u32 s69, s35, 0
	s_mov_b32 m0, s55
	v_lshl_add_u64 v[218:219], s[68:69], 0, v[134:135]
	ds_read_b128 v[180:183], v147 offset:32768
	ds_read_b128 v[184:187], v147 offset:33792
	ds_read_b128 v[188:191], v147 offset:34816
	ds_read_b128 v[192:195], v147 offset:35840
	ds_read_b128 v[196:199], v147 offset:36864
	ds_read_b128 v[200:203], v147 offset:37888
	ds_read_b128 v[204:207], v147 offset:38912
	ds_read_b128 v[208:211], v147 offset:39936
	global_load_lds_dwordx4 v[218:219], off
	v_lshl_add_u64 v[218:219], s[68:69], 0, v[130:131]
	s_mov_b32 m0, s56
	s_nop 0
	global_load_lds_dwordx4 v[218:219], off
	s_waitcnt vmcnt(8)
	s_waitcnt lgkmcnt(0)
	s_barrier
	s_setprio 1
	s_waitcnt lgkmcnt(0)
	v_mfma_f32_16x16x32_bf16 v[64:67], v[24:27], v[180:183], v[64:67]
	v_mfma_f32_16x16x32_bf16 v[68:71], v[112:115], v[180:183], v[68:71]
	v_mfma_f32_16x16x32_bf16 v[72:75], v[24:27], v[188:191], v[72:75]
	v_mfma_f32_16x16x32_bf16 v[76:79], v[112:115], v[188:191], v[76:79]
	v_mfma_f32_16x16x32_bf16 v[80:83], v[24:27], v[196:199], v[80:83]
	v_mfma_f32_16x16x32_bf16 v[84:87], v[112:115], v[196:199], v[84:87]
	v_mfma_f32_16x16x32_bf16 v[88:91], v[24:27], v[204:207], v[88:91]
	v_mfma_f32_16x16x32_bf16 v[92:95], v[112:115], v[204:207], v[92:95]
	v_mfma_f32_16x16x32_bf16 v[64:67], v[28:31], v[184:187], v[64:67]
	v_mfma_f32_16x16x32_bf16 v[68:71], v[116:119], v[184:187], v[68:71]
	v_mfma_f32_16x16x32_bf16 v[72:75], v[28:31], v[192:195], v[72:75]
	v_mfma_f32_16x16x32_bf16 v[76:79], v[116:119], v[192:195], v[76:79]
	v_mfma_f32_16x16x32_bf16 v[80:83], v[28:31], v[200:203], v[80:83]
	v_mfma_f32_16x16x32_bf16 v[84:87], v[116:119], v[200:203], v[84:87]
	v_mfma_f32_16x16x32_bf16 v[88:91], v[28:31], v[208:211], v[88:91]
	v_mfma_f32_16x16x32_bf16 v[92:95], v[116:119], v[208:211], v[92:95]
	v_mfma_f32_16x16x32_bf16 v[96:99], v[120:123], v[180:183], v[96:99]
	v_mfma_f32_16x16x32_bf16 v[32:35], v[172:175], v[180:183], v[32:35]
	v_mfma_f32_16x16x32_bf16 v[36:39], v[120:123], v[188:191], v[36:39]
	v_mfma_f32_16x16x32_bf16 v[40:43], v[172:175], v[188:191], v[40:43]
	v_mfma_f32_16x16x32_bf16 v[44:47], v[120:123], v[196:199], v[44:47]
	v_mfma_f32_16x16x32_bf16 v[48:51], v[172:175], v[196:199], v[48:51]
	v_mfma_f32_16x16x32_bf16 v[52:55], v[120:123], v[204:207], v[52:55]
	v_mfma_f32_16x16x32_bf16 v[56:59], v[172:175], v[204:207], v[56:59]
	v_mfma_f32_16x16x32_bf16 v[96:99], v[124:127], v[184:187], v[96:99]
	v_mfma_f32_16x16x32_bf16 v[32:35], v[176:179], v[184:187], v[32:35]
	v_mfma_f32_16x16x32_bf16 v[36:39], v[124:127], v[192:195], v[36:39]
	v_mfma_f32_16x16x32_bf16 v[40:43], v[176:179], v[192:195], v[40:43]
	v_mfma_f32_16x16x32_bf16 v[44:47], v[124:127], v[200:203], v[44:47]
	v_mfma_f32_16x16x32_bf16 v[48:51], v[176:179], v[200:203], v[48:51]
	v_mfma_f32_16x16x32_bf16 v[52:55], v[124:127], v[208:211], v[52:55]
	v_mfma_f32_16x16x32_bf16 v[56:59], v[176:179], v[208:211], v[56:59]
	s_setprio 0
	s_barrier
; #define PG8_STAGE(bufoff, gbase, voff) do { _Pragma("unroll") for (int _i = 0; _i < 2; ++_i) \
;         __builtin_amdgcn_global_load_lds((const unsigned*)((const char*)(gbase) + (voff)[_i]), (PG8_LAS unsigned*)(lds + (bufoff) + ldsw + _i * 8192), 16, 0, 0); } while (0)
; #define PG8_LDA(dst, b, h) do { _Pragma("unroll") for (int m = 0; m < 4; ++m) _Pragma("unroll") for (int k = 0; k < 2; ++k) dst[m][k] = *(const PG8_LAS bf16x8*)(lds + PG8_SA(b, h) + aoff + m * 2048 + k * 1024); } while (0)
; #define PG8_LDB(dst, b, h) do { _Pragma("unroll") for (int n = 0; n < 2; ++n) _Pragma("unroll") for (int k = 0; k < 2; ++k) dst[n][k] = *(const PG8_LAS bf16x8*)(lds + PG8_SB(b, h) + boff + n * 2048 + k * 1024); } while (0)
; #define PG8_MMA(ai, bj, At, Bt) do { __builtin_amdgcn_s_setprio(1); _Pragma("unroll") for (int m = 0; m < 4; ++m) _Pragma("unroll") for (int n = 0; n < 2; ++n) _Pragma("unroll") for (int k = 0; k < 2; ++k) \
;         acc[ai][bj][m][n] = __builtin_amdgcn_mfma_f32_16x16x32_bf16(Bt[n][k], At[m][k], acc[ai][bj][m][n], 0, 0, 0); __builtin_amdgcn_s_setprio(0); } while (0)
; #define PG8_WAIT_V(n) asm volatile("s_waitcnt vmcnt(" #n ")" ::: "memory")
; #define PG8_WAIT_L(n) asm volatile("s_waitcnt lgkmcnt(" #n ")" ::: "memory")
; #define PG8_BAR __builtin_amdgcn_s_barrier()
; #define PG8_SCHED __builtin_amdgcn_sched_barrier(0)
; template <class Epi, class Sched, bool ALIGN_EPI = false, bool SP2 = false>
; __device__ __forceinline__ void gemm_phase(PG8_LAS unsigned char* lds, const Gemm g, const Sched& S, const Epi& E) {
;     ...
;             PG8_LDB(B0, 0, 0); PG8_LDB(B1, 0, 1); PG8_SCHED; PG8_LDA(At, 0, 0); PG8_STAGE(PG8_SA(1, 1), a1 + hstepA, voffA);
;             PG8_WAIT_V(8); PG8_WAIT_L(0); PG8_BAR; PG8_MMA(0, 0, At, B0); PG8_MMA(0, 1, At, B1); PG8_BAR; PG8_SCHED;
;     ...
;             PG8_LDA(At, 1, 1); PG8_STAGE(PG8_SB(1, 0), b3, voffB); PG8_STAGE(PG8_SB(1, 1), b3 + hstep, voffB); PG8_STAGE(PG8_SA(1, 0), a3, voffA);
;             PG8_WAIT_V(8); PG8_WAIT_L(0); PG8_BAR; PG8_MMA(1, 0, At, B0); PG8_MMA(1, 1, At, B1); PG8_BAR; PG8_SCHED;
	s_add_i32 s68, s67, s53
	s_add_i32 s67, s68, 0x2000
	v_lshl_add_u64 v[140:141], v[140:141], 0, s[18:19]
	s_mov_b32 m0, s68
	s_add_u32 s70, s38, 0x10180
	ds_read_b128 v[180:183], v147 offset:49152
	ds_read_b128 v[184:187], v147 offset:50176
	ds_read_b128 v[188:191], v147 offset:51200
	ds_read_b128 v[192:195], v147 offset:52224
	ds_read_b128 v[196:199], v147 offset:53248
	ds_read_b128 v[200:203], v147 offset:54272
	ds_read_b128 v[204:207], v147 offset:55296
	ds_read_b128 v[208:211], v147 offset:56320
	global_load_lds_dwordx4 v[140:141], off
	v_lshl_add_u64 v[140:141], v[212:213], 0, s[18:19]
	s_mov_b32 m0, s67
	s_addc_u32 s71, s39, 0
	s_add_i32 s38, s72, s53
	global_load_lds_dwordx4 v[140:141], off
	v_lshl_add_u64 v[140:141], s[70:71], 0, v[132:133]
	s_mov_b32 m0, s38
	s_add_i32 s39, s38, 0x2000
	global_load_lds_dwordx4 v[140:141], off
	v_lshl_add_u64 v[140:141], s[70:71], 0, v[128:129]
	s_mov_b32 m0, s39
	s_nop 0
	global_load_lds_dwordx4 v[140:141], off
	v_lshl_add_u64 v[140:141], v[214:215], 0, s[18:19]
	s_mov_b32 m0, s59
	s_nop 0
	global_load_lds_dwordx4 v[140:141], off
	v_lshl_add_u64 v[140:141], v[216:217], 0, s[18:19]
	s_mov_b32 m0, s60
	s_nop 0
	global_load_lds_dwordx4 v[140:141], off
	s_waitcnt vmcnt(8)
	s_waitcnt lgkmcnt(0)
	s_barrier
	s_setprio 1
	s_waitcnt lgkmcnt(0)
	v_mfma_f32_16x16x32_bf16 v[0:3], v[24:27], v[204:207], v[0:3]
	v_mfma_f32_16x16x32_bf16 v[4:7], v[112:115], v[204:207], v[4:7]
	v_mfma_f32_16x16x32_bf16 v[148:151], v[24:27], v[180:183], v[148:151]
	v_mfma_f32_16x16x32_bf16 v[152:155], v[112:115], v[180:183], v[152:155]
	v_mfma_f32_16x16x32_bf16 v[156:159], v[24:27], v[188:191], v[156:159]
	v_mfma_f32_16x16x32_bf16 v[160:163], v[112:115], v[188:191], v[160:163]
	v_mfma_f32_16x16x32_bf16 v[164:167], v[24:27], v[196:199], v[164:167]
	v_mfma_f32_16x16x32_bf16 v[168:171], v[112:115], v[196:199], v[168:171]
	v_mfma_f32_16x16x32_bf16 v[0:3], v[28:31], v[208:211], v[0:3]
	v_mfma_f32_16x16x32_bf16 v[4:7], v[116:119], v[208:211], v[4:7]
	v_mfma_f32_16x16x32_bf16 v[148:151], v[28:31], v[184:187], v[148:151]
	v_mfma_f32_16x16x32_bf16 v[152:155], v[116:119], v[184:187], v[152:155]
	v_mfma_f32_16x16x32_bf16 v[156:159], v[28:31], v[192:195], v[156:159]
	v_mfma_f32_16x16x32_bf16 v[160:163], v[116:119], v[192:195], v[160:163]
	v_mfma_f32_16x16x32_bf16 v[164:167], v[28:31], v[200:203], v[164:167]
	v_mfma_f32_16x16x32_bf16 v[168:171], v[116:119], v[200:203], v[168:171]
	v_mfma_f32_16x16x32_bf16 v[8:11], v[120:123], v[180:183], v[8:11]
	v_mfma_f32_16x16x32_bf16 v[12:15], v[172:175], v[180:183], v[12:15]
	v_mfma_f32_16x16x32_bf16 v[24:27], v[120:123], v[188:191], v[60:63]
	v_mfma_f32_16x16x32_bf16 v[28:31], v[172:175], v[188:191], v[100:103]
	v_mfma_f32_16x16x32_bf16 v[60:63], v[120:123], v[196:199], v[104:107]
	v_mfma_f32_16x16x32_bf16 v[100:103], v[172:175], v[196:199], v[108:111]
	v_mfma_f32_16x16x32_bf16 v[16:19], v[120:123], v[204:207], v[16:19]
	v_mfma_f32_16x16x32_bf16 v[20:23], v[172:175], v[204:207], v[20:23]
	v_mfma_f32_16x16x32_bf16 v[8:11], v[124:127], v[184:187], v[8:11]
	v_mfma_f32_16x16x32_bf16 v[12:15], v[176:179], v[184:187], v[12:15]
	v_mfma_f32_16x16x32_bf16 v[24:27], v[124:127], v[192:195], v[24:27]
	v_mfma_f32_16x16x32_bf16 v[28:31], v[176:179], v[192:195], v[28:31]
	v_mfma_f32_16x16x32_bf16 v[60:63], v[124:127], v[200:203], v[60:63]
	v_mfma_f32_16x16x32_bf16 v[100:103], v[176:179], v[200:203], v[100:103]
	v_mfma_f32_16x16x32_bf16 v[16:19], v[124:127], v[208:211], v[16:19]
	v_mfma_f32_16x16x32_bf16 v[20:23], v[176:179], v[208:211], v[20:23]
	s_setprio 0
	s_barrier
	ds_read_b128 v[104:107], v145
	ds_read_b128 v[108:111], v145 offset:1024
	ds_read_b128 v[112:115], v145 offset:2048
	ds_read_b128 v[116:119], v145 offset:3072
	ds_read_b128 v[120:123], v146
	ds_read_b128 v[124:127], v146 offset:1024
	ds_read_b128 v[172:175], v146 offset:2048
	ds_read_b128 v[176:179], v146 offset:3072
	s_add_u32 s34, s34, 0x10180
	s_addc_u32 s35, s35, 0
	s_mov_b32 m0, s62
	v_lshl_add_u64 v[140:141], s[34:35], 0, v[134:135]
	ds_read_b128 v[180:183], v147
	ds_read_b128 v[184:187], v147 offset:1024
	ds_read_b128 v[188:191], v147 offset:2048
	ds_read_b128 v[192:195], v147 offset:3072
	ds_read_b128 v[196:199], v147 offset:4096
	ds_read_b128 v[200:203], v147 offset:5120
	ds_read_b128 v[204:207], v147 offset:6144
	ds_read_b128 v[208:211], v147 offset:7168
	global_load_lds_dwordx4 v[140:141], off
	v_lshl_add_u64 v[140:141], s[34:35], 0, v[130:131]
	s_mov_b32 m0, s21
	s_nop 0
	global_load_lds_dwordx4 v[140:141], off
	s_waitcnt vmcnt(8)
	s_waitcnt lgkmcnt(0)
	s_barrier
; #define PG8_STAGE(bufoff, gbase, voff) do { _Pragma("unroll") for (int _i = 0; _i < 2; ++_i) \
;         __builtin_amdgcn_global_load_lds((const unsigned*)((const char*)(gbase) + (voff)[_i]), (PG8_LAS unsigned*)(lds + (bufoff) + ldsw + _i * 8192), 16, 0, 0); } while (0)
; #define PG8_LDA(dst, b, h) do { _Pragma("unroll") for (int m = 0; m < 4; ++m) _Pragma("unroll") for (int k = 0; k < 2; ++k) dst[m][k] = *(const PG8_LAS bf16x8*)(lds + PG8_SA(b, h) + aoff + m * 2048 + k * 1024); } while (0)
; #define PG8_MMA(ai, bj, At, Bt) do { __builtin_amdgcn_s_setprio(1); _Pragma("unroll") for (int m = 0; m < 4; ++m) _Pragma("unroll") for (int n = 0; n < 2; ++n) _Pragma("unroll") for (int k = 0; k < 2; ++k) \
;         acc[ai][bj][m][n] = __builtin_amdgcn_mfma_f32_16x16x32_bf16(Bt[n][k], At[m][k], acc[ai][bj][m][n], 0, 0, 0); __builtin_amdgcn_s_setprio(0); } while (0)
; #define PG8_WAIT_V(n) asm volatile("s_waitcnt vmcnt(" #n ")" ::: "memory")
; #define PG8_WAIT_L(n) asm volatile("s_waitcnt lgkmcnt(" #n ")" ::: "memory")
; #define PG8_BAR __builtin_amdgcn_s_barrier()
; #define PG8_SCHED __builtin_amdgcn_sched_barrier(0)
; template <class Epi, class Sched, bool ALIGN_EPI = false, bool SP2 = false>
; __device__ __forceinline__ void gemm_phase(PG8_LAS unsigned char* lds, const Gemm g, const Sched& S, const Epi& E) {
;     ...
;             PG8_WAIT_V(8); PG8_WAIT_L(0); PG8_BAR; PG8_MMA(0, 0, At, B0); PG8_MMA(0, 1, At, B1); PG8_BAR; PG8_SCHED;
;             PG8_LDA(At, 0, 1); PG8_STAGE(PG8_SB(0, 0), b2, voffB); PG8_STAGE(PG8_SB(0, 1), b2 + hstep, voffB); PG8_STAGE(PG8_SA(0, 0), a2, voffA);
;             PG8_WAIT_V(8); PG8_WAIT_L(0); PG8_BAR; PG8_MMA(1, 0, At, B0); PG8_MMA(1, 1, At, B1); PG8_BAR; PG8_SCHED;
	s_setprio 1
	s_waitcnt lgkmcnt(0)
	v_mfma_f32_16x16x32_bf16 v[88:91], v[104:107], v[204:207], v[88:91]
	v_mfma_f32_16x16x32_bf16 v[64:67], v[104:107], v[180:183], v[64:67]
	v_mfma_f32_16x16x32_bf16 v[68:71], v[112:115], v[180:183], v[68:71]
	v_mfma_f32_16x16x32_bf16 v[72:75], v[104:107], v[188:191], v[72:75]
	v_mfma_f32_16x16x32_bf16 v[76:79], v[112:115], v[188:191], v[76:79]
	v_mfma_f32_16x16x32_bf16 v[80:83], v[104:107], v[196:199], v[80:83]
	v_mfma_f32_16x16x32_bf16 v[84:87], v[112:115], v[196:199], v[84:87]
	v_mfma_f32_16x16x32_bf16 v[212:215], v[108:111], v[208:211], v[88:91]
	v_mfma_f32_16x16x32_bf16 v[88:91], v[112:115], v[204:207], v[92:95]
	v_mfma_f32_16x16x32_bf16 v[64:67], v[108:111], v[184:187], v[64:67]
	v_mfma_f32_16x16x32_bf16 v[68:71], v[116:119], v[184:187], v[68:71]
	v_mfma_f32_16x16x32_bf16 v[72:75], v[108:111], v[192:195], v[72:75]
	v_mfma_f32_16x16x32_bf16 v[76:79], v[116:119], v[192:195], v[76:79]
	v_mfma_f32_16x16x32_bf16 v[80:83], v[108:111], v[200:203], v[80:83]
	v_mfma_f32_16x16x32_bf16 v[84:87], v[116:119], v[200:203], v[84:87]
	v_mfma_f32_16x16x32_bf16 v[92:95], v[116:119], v[208:211], v[88:91]
	v_mfma_f32_16x16x32_bf16 v[48:51], v[172:175], v[196:199], v[48:51]
	v_mfma_f32_16x16x32_bf16 v[88:91], v[120:123], v[180:183], v[96:99]
	v_mfma_f32_16x16x32_bf16 v[32:35], v[172:175], v[180:183], v[32:35]
	v_mfma_f32_16x16x32_bf16 v[36:39], v[120:123], v[188:191], v[36:39]
	v_mfma_f32_16x16x32_bf16 v[40:43], v[172:175], v[188:191], v[40:43]
	v_mfma_f32_16x16x32_bf16 v[44:47], v[120:123], v[196:199], v[44:47]
	v_mfma_f32_16x16x32_bf16 v[180:183], v[176:179], v[200:203], v[48:51]
	v_mfma_f32_16x16x32_bf16 v[48:51], v[120:123], v[204:207], v[52:55]
	v_mfma_f32_16x16x32_bf16 v[32:35], v[176:179], v[184:187], v[32:35]
	v_mfma_f32_16x16x32_bf16 v[36:39], v[124:127], v[192:195], v[36:39]
	v_mfma_f32_16x16x32_bf16 v[40:43], v[176:179], v[192:195], v[40:43]
	v_mfma_f32_16x16x32_bf16 v[44:47], v[124:127], v[200:203], v[44:47]
	v_mfma_f32_16x16x32_bf16 v[52:55], v[124:127], v[208:211], v[48:51]
	v_mfma_f32_16x16x32_bf16 v[48:51], v[172:175], v[204:207], v[56:59]
	v_mfma_f32_16x16x32_bf16 v[216:219], v[124:127], v[184:187], v[88:91]
	v_mfma_f32_16x16x32_bf16 v[184:187], v[176:179], v[208:211], v[48:51]
	s_setprio 0
	s_barrier
	s_mov_b32 m0, s66
	v_lshl_add_u64 v[140:141], s[40:41], 0, v[132:133]
	s_add_u32 s34, s40, 0x10000
	s_nop 0
	ds_read_b128 v[48:51], v147 offset:16384
	ds_read_b128 v[56:59], v147 offset:17408
	ds_read_b128 v[88:91], v147 offset:18432
	ds_read_b128 v[96:99], v147 offset:19456
	ds_read_b128 v[188:191], v147 offset:20480
	ds_read_b128 v[192:195], v147 offset:21504
	ds_read_b128 v[196:199], v147 offset:22528
	ds_read_b128 v[200:203], v147 offset:23552
	global_load_lds_dwordx4 v[140:141], off
	v_lshl_add_u64 v[252:253], s[40:41], 0, v[128:129]
	s_mov_b32 m0, s23
	s_addc_u32 s35, s41, 0
	global_load_lds_dwordx4 v[252:253], off
	v_lshl_add_u64 v[204:205], s[34:35], 0, v[132:133]
	s_mov_b32 m0, s64
	v_lshl_add_u64 v[136:137], s[84:85], 0, v[134:135]
	global_load_lds_dwordx4 v[204:205], off
	v_lshl_add_u64 v[204:205], s[34:35], 0, v[128:129]
	s_mov_b32 m0, s65
	v_lshl_add_u64 v[138:139], s[84:85], 0, v[130:131]
	global_load_lds_dwordx4 v[204:205], off
	s_mov_b32 m0, s31
	s_nop 0
	global_load_lds_dwordx4 v[136:137], off
	s_mov_b32 m0, s54
	s_nop 0
	global_load_lds_dwordx4 v[138:139], off
	s_waitcnt vmcnt(8)
	s_waitcnt lgkmcnt(0)
	s_barrier
	s_setprio 1
	s_waitcnt lgkmcnt(0)
	v_mfma_f32_16x16x32_bf16 v[0:3], v[104:107], v[196:199], v[0:3]
	v_mfma_f32_16x16x32_bf16 v[4:7], v[112:115], v[196:199], v[4:7]
	v_mfma_f32_16x16x32_bf16 v[148:151], v[104:107], v[48:51], v[148:151]
	v_mfma_f32_16x16x32_bf16 v[152:155], v[112:115], v[48:51], v[152:155]
	v_mfma_f32_16x16x32_bf16 v[156:159], v[104:107], v[88:91], v[156:159]
	v_mfma_f32_16x16x32_bf16 v[160:163], v[112:115], v[88:91], v[160:163]
	v_mfma_f32_16x16x32_bf16 v[164:167], v[104:107], v[188:191], v[164:167]
	v_mfma_f32_16x16x32_bf16 v[168:171], v[112:115], v[188:191], v[168:171]
	v_mfma_f32_16x16x32_bf16 v[0:3], v[108:111], v[200:203], v[0:3]
	v_mfma_f32_16x16x32_bf16 v[4:7], v[116:119], v[200:203], v[4:7]
	v_mfma_f32_16x16x32_bf16 v[148:151], v[108:111], v[56:59], v[148:151]
	v_mfma_f32_16x16x32_bf16 v[152:155], v[116:119], v[56:59], v[152:155]
	v_mfma_f32_16x16x32_bf16 v[156:159], v[108:111], v[96:99], v[156:159]
	v_mfma_f32_16x16x32_bf16 v[160:163], v[116:119], v[96:99], v[160:163]
	v_mfma_f32_16x16x32_bf16 v[164:167], v[108:111], v[192:195], v[164:167]
	v_mfma_f32_16x16x32_bf16 v[168:171], v[116:119], v[192:195], v[168:171]
	v_mfma_f32_16x16x32_bf16 v[12:15], v[172:175], v[48:51], v[12:15]
	v_mfma_f32_16x16x32_bf16 v[204:207], v[176:179], v[56:59], v[12:15]
	v_mfma_f32_16x16x32_bf16 v[12:15], v[120:123], v[88:91], v[24:27]
	v_mfma_f32_16x16x32_bf16 v[24:27], v[124:127], v[96:99], v[12:15]
	v_mfma_f32_16x16x32_bf16 v[12:15], v[172:175], v[88:91], v[28:31]
	v_mfma_f32_16x16x32_bf16 v[208:211], v[176:179], v[96:99], v[12:15]
	v_mfma_f32_16x16x32_bf16 v[12:15], v[120:123], v[188:191], v[60:63]
	v_mfma_f32_16x16x32_bf16 v[220:223], v[124:127], v[192:195], v[12:15]
	v_mfma_f32_16x16x32_bf16 v[12:15], v[172:175], v[188:191], v[100:103]
	v_mfma_f32_16x16x32_bf16 v[8:11], v[120:123], v[48:51], v[8:11]
	v_mfma_f32_16x16x32_bf16 v[188:191], v[176:179], v[192:195], v[12:15]
	v_mfma_f32_16x16x32_bf16 v[12:15], v[120:123], v[196:199], v[16:19]
	v_mfma_f32_16x16x32_bf16 v[8:11], v[124:127], v[56:59], v[8:11]
	v_mfma_f32_16x16x32_bf16 v[192:195], v[124:127], v[200:203], v[12:15]
	v_mfma_f32_16x16x32_bf16 v[12:15], v[172:175], v[196:199], v[20:23]
	v_mfma_f32_16x16x32_bf16 v[172:175], v[176:179], v[200:203], v[12:15]
	s_setprio 0
	s_barrier
; #define PG8_STAGE(bufoff, gbase, voff) do { _Pragma("unroll") for (int _i = 0; _i < 2; ++_i) \
;         __builtin_amdgcn_global_load_lds((const unsigned*)((const char*)(gbase) + (voff)[_i]), (PG8_LAS unsigned*)(lds + (bufoff) + ldsw + _i * 8192), 16, 0, 0); } while (0)
; #define PG8_LDA(dst, b, h) do { _Pragma("unroll") for (int m = 0; m < 4; ++m) _Pragma("unroll") for (int k = 0; k < 2; ++k) dst[m][k] = *(const PG8_LAS bf16x8*)(lds + PG8_SA(b, h) + aoff + m * 2048 + k * 1024); } while (0)
; #define PG8_LDB(dst, b, h) do { _Pragma("unroll") for (int n = 0; n < 2; ++n) _Pragma("unroll") for (int k = 0; k < 2; ++k) dst[n][k] = *(const PG8_LAS bf16x8*)(lds + PG8_SB(b, h) + boff + n * 2048 + k * 1024); } while (0)
; #define PG8_MMA(ai, bj, At, Bt) do { __builtin_amdgcn_s_setprio(1); _Pragma("unroll") for (int m = 0; m < 4; ++m) _Pragma("unroll") for (int n = 0; n < 2; ++n) _Pragma("unroll") for (int k = 0; k < 2; ++k) \
;         acc[ai][bj][m][n] = __builtin_amdgcn_mfma_f32_16x16x32_bf16(Bt[n][k], At[m][k], acc[ai][bj][m][n], 0, 0, 0); __builtin_amdgcn_s_setprio(0); } while (0)
; #define PG8_WAIT_V(n) asm volatile("s_waitcnt vmcnt(" #n ")" ::: "memory")
; #define PG8_WAIT_L(n) asm volatile("s_waitcnt lgkmcnt(" #n ")" ::: "memory")
; #define PG8_BAR __builtin_amdgcn_s_barrier()
; #define PG8_SCHED __builtin_amdgcn_sched_barrier(0)
; template <class Epi, class Sched, bool ALIGN_EPI = false, bool SP2 = false>
; __device__ __forceinline__ void gemm_phase(PG8_LAS unsigned char* lds, const Gemm g, const Sched& S, const Epi& E) {
;     ...
;             PG8_WAIT_V(8); PG8_WAIT_L(0); PG8_BAR; PG8_MMA(1, 0, At, B0); PG8_MMA(1, 1, At, B1); PG8_BAR; PG8_SCHED;
;             PG8_LDB(B0, 1, 0); PG8_LDB(B1, 1, 1); PG8_SCHED; PG8_LDA(At, 1, 0); PG8_STAGE(PG8_SA(0, 1), a2 + hstepA, voffA);
;             PG8_WAIT_V(8); PG8_WAIT_L(0); PG8_BAR; PG8_MMA(0, 0, At, B0); PG8_MMA(0, 1, At, B1); PG8_BAR; PG8_SCHED;
;             PG8_LDA(At, 1, 1); PG8_STAGE(PG8_SB(1, 0), b3, voffB); PG8_STAGE(PG8_SB(1, 1), b3 + hstep, voffB); PG8_STAGE(PG8_SA(1, 0), a3, voffA);
;             PG8_WAIT_V(8); PG8_WAIT_L(0); PG8_BAR; PG8_MMA(1, 0, At, B0); PG8_MMA(1, 1, At, B1); PG8_BAR; PG8_SCHED;
;     ...
;         if constexpr (ALIGN_EPI) { if (wr == 0) PG8_BAR; }
	s_nop 4
	ds_read_b128 v[12:15], v224
	ds_read_b128 v[16:19], v224 offset:1024
	ds_read_b128 v[176:179], v224 offset:2048
	ds_read_b128 v[196:199], v224 offset:3072
	ds_read_b128 v[200:203], v232
	ds_read_b128 v[224:227], v232 offset:1024
	ds_read_b128 v[228:231], v232 offset:2048
	ds_read_b128 v[232:235], v232 offset:3072
	s_add_u32 s34, s84, 0x10000
	s_addc_u32 s35, s85, 0
	s_mov_b32 m0, s55
	v_lshl_add_u64 v[48:49], s[34:35], 0, v[134:135]
	ds_read_b128 v[20:23], v147 offset:32768
	ds_read_b128 v[28:31], v147 offset:33792
	ds_read_b128 v[60:63], v147 offset:34816
	ds_read_b128 v[100:103], v147 offset:35840
	ds_read_b128 v[236:239], v147 offset:36864
	ds_read_b128 v[240:243], v147 offset:37888
	ds_read_b128 v[244:247], v147 offset:38912
	ds_read_b128 v[248:251], v147 offset:39936
	global_load_lds_dwordx4 v[48:49], off
	v_lshl_add_u64 v[48:49], s[34:35], 0, v[130:131]
	s_mov_b32 m0, s56
	s_nop 0
	global_load_lds_dwordx4 v[48:49], off
	s_waitcnt vmcnt(8)
	s_waitcnt lgkmcnt(0)
	s_barrier
	s_setprio 1
	s_waitcnt lgkmcnt(0)
	v_mfma_f32_16x16x32_bf16 v[48:51], v[12:15], v[20:23], v[64:67]
	v_mfma_f32_16x16x32_bf16 v[120:123], v[16:19], v[28:31], v[48:51]
	v_mfma_f32_16x16x32_bf16 v[48:51], v[176:179], v[20:23], v[68:71]
	v_mfma_f32_16x16x32_bf16 v[112:115], v[196:199], v[28:31], v[48:51]
	v_mfma_f32_16x16x32_bf16 v[48:51], v[12:15], v[60:63], v[72:75]
	v_mfma_f32_16x16x32_bf16 v[104:107], v[16:19], v[100:103], v[48:51]
	v_mfma_f32_16x16x32_bf16 v[48:51], v[176:179], v[60:63], v[76:79]
	v_mfma_f32_16x16x32_bf16 v[96:99], v[196:199], v[100:103], v[48:51]
	v_mfma_f32_16x16x32_bf16 v[48:51], v[12:15], v[236:239], v[80:83]
	v_mfma_f32_16x16x32_bf16 v[88:91], v[16:19], v[240:243], v[48:51]
	v_mfma_f32_16x16x32_bf16 v[48:51], v[176:179], v[236:239], v[84:87]
	v_mfma_f32_16x16x32_bf16 v[80:83], v[196:199], v[240:243], v[48:51]
	v_mfma_f32_16x16x32_bf16 v[48:51], v[12:15], v[244:247], v[212:215]
	v_mfma_f32_16x16x32_bf16 v[56:59], v[16:19], v[248:251], v[48:51]
	v_mfma_f32_16x16x32_bf16 v[48:51], v[176:179], v[244:247], v[92:95]
	v_mfma_f32_16x16x32_bf16 v[48:51], v[196:199], v[248:251], v[48:51]
	v_mfma_f32_16x16x32_bf16 v[64:67], v[200:203], v[20:23], v[216:219]
	v_mfma_f32_16x16x32_bf16 v[20:23], v[228:231], v[20:23], v[32:35]
	v_mfma_f32_16x16x32_bf16 v[116:119], v[232:235], v[28:31], v[20:23]
	v_mfma_f32_16x16x32_bf16 v[20:23], v[200:203], v[60:63], v[36:39]
	v_mfma_f32_16x16x32_bf16 v[108:111], v[224:227], v[100:103], v[20:23]
	v_mfma_f32_16x16x32_bf16 v[20:23], v[228:231], v[60:63], v[40:43]
	v_mfma_f32_16x16x32_bf16 v[100:103], v[232:235], v[100:103], v[20:23]
	v_mfma_f32_16x16x32_bf16 v[20:23], v[200:203], v[236:239], v[44:47]
	v_mfma_f32_16x16x32_bf16 v[92:95], v[224:227], v[240:243], v[20:23]
	v_mfma_f32_16x16x32_bf16 v[20:23], v[228:231], v[236:239], v[180:183]
	v_mfma_f32_16x16x32_bf16 v[84:87], v[232:235], v[240:243], v[20:23]
	v_mfma_f32_16x16x32_bf16 v[20:23], v[200:203], v[244:247], v[52:55]
	v_mfma_f32_16x16x32_bf16 v[60:63], v[224:227], v[248:251], v[20:23]
	v_mfma_f32_16x16x32_bf16 v[20:23], v[228:231], v[244:247], v[184:187]
	v_mfma_f32_16x16x32_bf16 v[124:127], v[224:227], v[28:31], v[64:67]
	v_mfma_f32_16x16x32_bf16 v[52:55], v[232:235], v[248:251], v[20:23]
	s_setprio 0
	s_barrier
	s_mov_b32 m0, s68
	s_nop 2
	v_lshl_add_u64 v[20:21], v[140:141], 0, s[10:11]
	s_add_u32 s34, s40, 0x10080
	ds_read_b128 v[32:35], v147 offset:49152
	ds_read_b128 v[40:43], v147 offset:50176
	ds_read_b128 v[180:183], v147 offset:51200
	ds_read_b128 v[184:187], v147 offset:52224
	ds_read_b128 v[212:215], v147 offset:53248
	ds_read_b128 v[216:219], v147 offset:54272
	ds_read_b128 v[236:239], v147 offset:55296
	ds_read_b128 v[240:243], v147 offset:56320
	global_load_lds_dwordx4 v[20:21], off
	v_lshl_add_u64 v[20:21], v[252:253], 0, s[10:11]
	s_mov_b32 m0, s67
	s_addc_u32 s35, s41, 0
	global_load_lds_dwordx4 v[20:21], off
	v_lshl_add_u64 v[20:21], s[34:35], 0, v[132:133]
	s_mov_b32 m0, s38
	s_nop 0
	global_load_lds_dwordx4 v[20:21], off
	v_lshl_add_u64 v[20:21], s[34:35], 0, v[128:129]
	s_mov_b32 m0, s39
	s_nop 0
	global_load_lds_dwordx4 v[20:21], off
	v_lshl_add_u64 v[20:21], v[136:137], 0, s[10:11]
	s_mov_b32 m0, s59
	s_nop 0
	global_load_lds_dwordx4 v[20:21], off
	v_lshl_add_u64 v[20:21], v[138:139], 0, s[10:11]
	s_mov_b32 m0, s60
	s_nop 0
	global_load_lds_dwordx4 v[20:21], off
	s_waitcnt vmcnt(8)
	s_waitcnt lgkmcnt(0)
	s_barrier
	s_setprio 1
	s_waitcnt lgkmcnt(0)
	v_mfma_f32_16x16x32_bf16 v[20:23], v[12:15], v[32:35], v[148:151]
	v_mfma_f32_16x16x32_bf16 v[76:79], v[16:19], v[40:43], v[20:23]
	v_mfma_f32_16x16x32_bf16 v[20:23], v[176:179], v[32:35], v[152:155]
	v_mfma_f32_16x16x32_bf16 v[68:71], v[196:199], v[40:43], v[20:23]
	v_mfma_f32_16x16x32_bf16 v[20:23], v[12:15], v[180:183], v[156:159]
	v_mfma_f32_16x16x32_bf16 v[44:47], v[16:19], v[184:187], v[20:23]
	v_mfma_f32_16x16x32_bf16 v[20:23], v[176:179], v[180:183], v[160:163]
	v_mfma_f32_16x16x32_bf16 v[36:39], v[196:199], v[184:187], v[20:23]
	v_mfma_f32_16x16x32_bf16 v[20:23], v[12:15], v[212:215], v[164:167]
	v_mfma_f32_16x16x32_bf16 v[0:3], v[12:15], v[236:239], v[0:3]
	v_mfma_f32_16x16x32_bf16 v[28:31], v[16:19], v[216:219], v[20:23]
	v_mfma_f32_16x16x32_bf16 v[20:23], v[176:179], v[212:215], v[168:171]
	v_mfma_f32_16x16x32_bf16 v[12:15], v[16:19], v[240:243], v[0:3]
	v_mfma_f32_16x16x32_bf16 v[0:3], v[176:179], v[236:239], v[4:7]
	v_mfma_f32_16x16x32_bf16 v[20:23], v[196:199], v[216:219], v[20:23]
	v_mfma_f32_16x16x32_bf16 v[4:7], v[196:199], v[240:243], v[0:3]
	v_mfma_f32_16x16x32_bf16 v[0:3], v[200:203], v[32:35], v[8:11]
	v_mfma_f32_16x16x32_bf16 v[72:75], v[224:227], v[40:43], v[0:3]
	v_mfma_f32_16x16x32_bf16 v[0:3], v[228:231], v[32:35], v[204:207]
	v_mfma_f32_16x16x32_bf16 v[64:67], v[232:235], v[40:43], v[0:3]
	v_mfma_f32_16x16x32_bf16 v[0:3], v[200:203], v[180:183], v[24:27]
	v_mfma_f32_16x16x32_bf16 v[40:43], v[224:227], v[184:187], v[0:3]
	v_mfma_f32_16x16x32_bf16 v[0:3], v[228:231], v[180:183], v[208:211]
	v_mfma_f32_16x16x32_bf16 v[32:35], v[232:235], v[184:187], v[0:3]
	v_mfma_f32_16x16x32_bf16 v[0:3], v[200:203], v[212:215], v[220:223]
	v_mfma_f32_16x16x32_bf16 v[24:27], v[224:227], v[216:219], v[0:3]
	v_mfma_f32_16x16x32_bf16 v[0:3], v[228:231], v[212:215], v[188:191]
	v_mfma_f32_16x16x32_bf16 v[16:19], v[232:235], v[216:219], v[0:3]
	v_mfma_f32_16x16x32_bf16 v[0:3], v[200:203], v[236:239], v[192:195]
	v_mfma_f32_16x16x32_bf16 v[8:11], v[224:227], v[240:243], v[0:3]
	v_mfma_f32_16x16x32_bf16 v[0:3], v[228:231], v[236:239], v[172:175]
	v_mfma_f32_16x16x32_bf16 v[0:3], v[232:235], v[240:243], v[0:3]
	s_setprio 0
	s_barrier
	s_andn2_b64 vcc, exec, s[12:13]
	s_cbranch_vccnz .LBB0_1348
	s_barrier

; #define PG8_STAGE(bufoff, gbase, voff) do { _Pragma("unroll") for (int _i = 0; _i < 2; ++_i) \
;         __builtin_amdgcn_global_load_lds((const unsigned*)((const char*)(gbase) + (voff)[_i]), (PG8_LAS unsigned*)(lds + (bufoff) + ldsw + _i * 8192), 16, 0, 0); } while (0)
; #define PG8_LDA(dst, b, h) do { _Pragma("unroll") for (int m = 0; m < 4; ++m) _Pragma("unroll") for (int k = 0; k < 2; ++k) dst[m][k] = *(const PG8_LAS bf16x8*)(lds + PG8_SA(b, h) + aoff + m * 2048 + k * 1024); } while (0)
; #define PG8_LDB(dst, b, h) do { _Pragma("unroll") for (int n = 0; n < 2; ++n) _Pragma("unroll") for (int k = 0; k < 2; ++k) dst[n][k] = *(const PG8_LAS bf16x8*)(lds + PG8_SB(b, h) + boff + n * 2048 + k * 1024); } while (0)
; #define PG8_MMA(ai, bj, At, Bt) do { __builtin_amdgcn_s_setprio(1); _Pragma("unroll") for (int m = 0; m < 4; ++m) _Pragma("unroll") for (int n = 0; n < 2; ++n) _Pragma("unroll") for (int k = 0; k < 2; ++k) \
;         acc[ai][bj][m][n] = __builtin_amdgcn_mfma_f32_16x16x32_bf16(Bt[n][k], At[m][k], acc[ai][bj][m][n], 0, 0, 0); __builtin_amdgcn_s_setprio(0); } while (0)
; #define PG8_WAIT_V(n) asm volatile("s_waitcnt vmcnt(" #n ")" ::: "memory")
; #define PG8_BAR __builtin_amdgcn_s_barrier()
; template <class Epi, class Sched, bool ALIGN_EPI = false, bool SP2 = false>
; __device__ __forceinline__ void gemm_phase(PG8_LAS unsigned char* lds, const Gemm g, const Sched& S, const Epi& E) {
;     ...
;         for (int t = 0; t < nt; t += 2) {
;             const bool last = (t == nt - 2);
;             const char* a1 = cA + (size_t)(t + 1) * kstepA;
;             const char* a2 = last ? nA : cA + (size_t)(t + 2) * kstepA; const char* b2 = last ? nB : cB + (size_t)(t + 2) * kstep;
;             const char* a3 = a2 + kstepA; const char* b3 = b2 + kstep;
;             if (last && has_next) S.a_ready(nxt);
;             if constexpr (SP2) {
;             PG8_LDB(B0, 0, 0); PG8_LDB(B1, 0, 1); PG8_SCHED; PG8_LDA(At, 0, 0); PG8_STAGE(PG8_SA(1, 1), a1 + hstepA, voffA);
;             PG8_WAIT_V(8); PG8_WAIT_L(0); PG8_BAR; PG8_MMA(0, 0, At, B0); PG8_MMA(0, 1, At, B1); PG8_BAR; PG8_SCHED;
;             PG8_LDA(At, 0, 1); PG8_STAGE(PG8_SB(0, 0), b2, voffB); PG8_STAGE(PG8_SB(0, 1), b2 + hstep, voffB); PG8_STAGE(PG8_SA(0, 0), a2, voffA);
;             PG8_WAIT_V(8); PG8_WAIT_L(0); PG8_BAR; PG8_MMA(1, 0, At, B0); PG8_MMA(1, 1, At, B1); PG8_BAR; PG8_SCHED;
.LBB0_1515:
	ds_read_b128 v[144:147], v153
	ds_read_b128 v[158:161], v153 offset:1024
	ds_read_b128 v[162:165], v153 offset:2048
	ds_read_b128 v[166:169], v153 offset:3072
	ds_read_b128 v[170:173], v154
	ds_read_b128 v[174:177], v154 offset:1024
	ds_read_b128 v[178:181], v154 offset:2048
	ds_read_b128 v[182:185], v154 offset:3072
	s_add_u32 s24, s22, 0x4000
	s_addc_u32 s25, s23, 0
	s_cmpk_eq_i32 s63, 0xa8
	s_cselect_b32 s30, s6, s24
	s_cselect_b32 s31, s7, s25
	s_cselect_b32 s26, s20, s61
	s_cselect_b32 s27, s21, s62
	s_add_u32 s24, s30, 0x8000
	s_addc_u32 s25, s31, 0
	v_lshl_add_u64 v[148:149], s[22:23], 0, v[136:137]
	s_add_i32 m0, s34, 0xc000
	ds_read_b128 v[186:189], v155
	ds_read_b128 v[190:193], v155 offset:1024
	ds_read_b128 v[194:197], v155 offset:2048
	ds_read_b128 v[198:201], v155 offset:3072
	ds_read_b128 v[202:205], v155 offset:4096
	ds_read_b128 v[206:209], v155 offset:5120
	ds_read_b128 v[210:213], v155 offset:6144
	ds_read_b128 v[214:217], v155 offset:7168
	global_load_lds_dwordx4 v[148:149], off
	v_lshl_add_u64 v[148:149], s[22:23], 0, v[138:139]
	s_add_i32 m0, s34, 0xe000
	s_nop 0
	global_load_lds_dwordx4 v[148:149], off
	s_waitcnt vmcnt(8)
	s_waitcnt lgkmcnt(0)
	s_barrier
	s_setprio 1
	s_waitcnt lgkmcnt(0)
	v_mfma_f32_16x16x32_bf16 v[124:127], v[144:147], v[186:189], v[124:127]
	v_mfma_f32_16x16x32_bf16 v[120:123], v[162:165], v[186:189], v[120:123]
	v_mfma_f32_16x16x32_bf16 v[108:111], v[144:147], v[194:197], v[108:111]
	v_mfma_f32_16x16x32_bf16 v[48:51], v[162:165], v[194:197], v[48:51]
	v_mfma_f32_16x16x32_bf16 v[100:103], v[144:147], v[202:205], v[100:103]
	v_mfma_f32_16x16x32_bf16 v[64:67], v[162:165], v[202:205], v[64:67]
	v_mfma_f32_16x16x32_bf16 v[92:95], v[144:147], v[210:213], v[92:95]
	v_mfma_f32_16x16x32_bf16 v[80:83], v[162:165], v[210:213], v[80:83]
	v_mfma_f32_16x16x32_bf16 v[124:127], v[158:161], v[190:193], v[124:127]
	v_mfma_f32_16x16x32_bf16 v[120:123], v[166:169], v[190:193], v[120:123]
	v_mfma_f32_16x16x32_bf16 v[108:111], v[158:161], v[198:201], v[108:111]
	v_mfma_f32_16x16x32_bf16 v[48:51], v[166:169], v[198:201], v[48:51]
	v_mfma_f32_16x16x32_bf16 v[100:103], v[158:161], v[206:209], v[100:103]
	v_mfma_f32_16x16x32_bf16 v[64:67], v[166:169], v[206:209], v[64:67]
	v_mfma_f32_16x16x32_bf16 v[92:95], v[158:161], v[214:217], v[92:95]
	v_mfma_f32_16x16x32_bf16 v[80:83], v[166:169], v[214:217], v[80:83]
	v_mfma_f32_16x16x32_bf16 v[116:119], v[170:173], v[186:189], v[116:119]
	v_mfma_f32_16x16x32_bf16 v[112:115], v[178:181], v[186:189], v[112:115]
	v_mfma_f32_16x16x32_bf16 v[104:107], v[170:173], v[194:197], v[104:107]
	v_mfma_f32_16x16x32_bf16 v[52:55], v[178:181], v[194:197], v[52:55]
	v_mfma_f32_16x16x32_bf16 v[96:99], v[170:173], v[202:205], v[96:99]
	v_mfma_f32_16x16x32_bf16 v[76:79], v[178:181], v[202:205], v[76:79]
	v_mfma_f32_16x16x32_bf16 v[88:91], v[170:173], v[210:213], v[88:91]
	v_mfma_f32_16x16x32_bf16 v[84:87], v[178:181], v[210:213], v[84:87]
	v_mfma_f32_16x16x32_bf16 v[116:119], v[174:177], v[190:193], v[116:119]
	v_mfma_f32_16x16x32_bf16 v[112:115], v[182:185], v[190:193], v[112:115]
	v_mfma_f32_16x16x32_bf16 v[104:107], v[174:177], v[198:201], v[104:107]
	v_mfma_f32_16x16x32_bf16 v[52:55], v[182:185], v[198:201], v[52:55]
	v_mfma_f32_16x16x32_bf16 v[96:99], v[174:177], v[206:209], v[96:99]
	v_mfma_f32_16x16x32_bf16 v[76:79], v[182:185], v[206:209], v[76:79]
	v_mfma_f32_16x16x32_bf16 v[88:91], v[174:177], v[214:217], v[88:91]
	v_mfma_f32_16x16x32_bf16 v[84:87], v[182:185], v[214:217], v[84:87]
	s_setprio 0
	s_barrier
	s_add_i32 s64, s55, s33
	v_lshl_add_u64 v[148:149], s[26:27], 0, v[130:131]
	s_mov_b32 m0, s64
	ds_read_b128 v[186:189], v155 offset:16384
	ds_read_b128 v[190:193], v155 offset:17408
	ds_read_b128 v[194:197], v155 offset:18432
	ds_read_b128 v[198:201], v155 offset:19456
	ds_read_b128 v[202:205], v155 offset:20480
	ds_read_b128 v[206:209], v155 offset:21504
	ds_read_b128 v[210:213], v155 offset:22528
	ds_read_b128 v[214:217], v155 offset:23552
	global_load_lds_dwordx4 v[148:149], off
	s_add_i32 m0, s64, 0x2000
	s_add_u32 s64, s26, 0x2b0000
	v_lshl_add_u64 v[218:219], s[26:27], 0, v[134:135]
	s_addc_u32 s65, s27, 0
	s_add_i32 s66, s56, s33
	global_load_lds_dwordx4 v[218:219], off
	v_lshl_add_u64 v[220:221], s[64:65], 0, v[130:131]
	s_mov_b32 m0, s66
	s_nop 0
	global_load_lds_dwordx4 v[220:221], off
	v_lshl_add_u64 v[220:221], s[64:65], 0, v[134:135]
	s_add_i32 m0, s66, 0x2000
	s_nop 0
	global_load_lds_dwordx4 v[220:221], off
	v_lshl_add_u64 v[220:221], s[30:31], 0, v[128:129]
	s_mov_b32 m0, s34
	s_nop 0
	global_load_lds_dwordx4 v[220:221], off
	v_lshl_add_u64 v[220:221], s[30:31], 0, v[132:133]
	s_mov_b32 m0, s35
	s_nop 0
	global_load_lds_dwordx4 v[220:221], off
	s_waitcnt vmcnt(8)
	s_waitcnt lgkmcnt(0)
	s_barrier
; #define PG8_STAGE(bufoff, gbase, voff) do { _Pragma("unroll") for (int _i = 0; _i < 2; ++_i) \
;         __builtin_amdgcn_global_load_lds((const unsigned*)((const char*)(gbase) + (voff)[_i]), (PG8_LAS unsigned*)(lds + (bufoff) + ldsw + _i * 8192), 16, 0, 0); } while (0)
; #define PG8_LDA(dst, b, h) do { _Pragma("unroll") for (int m = 0; m < 4; ++m) _Pragma("unroll") for (int k = 0; k < 2; ++k) dst[m][k] = *(const PG8_LAS bf16x8*)(lds + PG8_SA(b, h) + aoff + m * 2048 + k * 1024); } while (0)
; #define PG8_LDB(dst, b, h) do { _Pragma("unroll") for (int n = 0; n < 2; ++n) _Pragma("unroll") for (int k = 0; k < 2; ++k) dst[n][k] = *(const PG8_LAS bf16x8*)(lds + PG8_SB(b, h) + boff + n * 2048 + k * 1024); } while (0)
; #define PG8_MMA(ai, bj, At, Bt) do { __builtin_amdgcn_s_setprio(1); _Pragma("unroll") for (int m = 0; m < 4; ++m) _Pragma("unroll") for (int n = 0; n < 2; ++n) _Pragma("unroll") for (int k = 0; k < 2; ++k) \
;         acc[ai][bj][m][n] = __builtin_amdgcn_mfma_f32_16x16x32_bf16(Bt[n][k], At[m][k], acc[ai][bj][m][n], 0, 0, 0); __builtin_amdgcn_s_setprio(0); } while (0)
; #define PG8_WAIT_V(n) asm volatile("s_waitcnt vmcnt(" #n ")" ::: "memory")
; #define PG8_WAIT_L(n) asm volatile("s_waitcnt lgkmcnt(" #n ")" ::: "memory")
; #define PG8_BAR __builtin_amdgcn_s_barrier()
; #define PG8_SCHED __builtin_amdgcn_sched_barrier(0)
; template <class Epi, class Sched, bool ALIGN_EPI = false, bool SP2 = false>
; __device__ __forceinline__ void gemm_phase(PG8_LAS unsigned char* lds, const Gemm g, const Sched& S, const Epi& E) {
;     ...
;             PG8_WAIT_V(8); PG8_WAIT_L(0); PG8_BAR; PG8_MMA(1, 0, At, B0); PG8_MMA(1, 1, At, B1); PG8_BAR; PG8_SCHED;
;             PG8_LDB(B0, 1, 0); PG8_LDB(B1, 1, 1); PG8_SCHED; PG8_LDA(At, 1, 0); PG8_STAGE(PG8_SA(0, 1), a2 + hstepA, voffA);
;             PG8_WAIT_V(8); PG8_WAIT_L(0); PG8_BAR; PG8_MMA(0, 0, At, B0); PG8_MMA(0, 1, At, B1); PG8_BAR; PG8_SCHED;
	s_setprio 1
	s_waitcnt lgkmcnt(0)
	v_mfma_f32_16x16x32_bf16 v[72:75], v[144:147], v[186:189], v[72:75]
	v_mfma_f32_16x16x32_bf16 v[68:71], v[162:165], v[186:189], v[68:71]
	v_mfma_f32_16x16x32_bf16 v[44:47], v[144:147], v[194:197], v[44:47]
	v_mfma_f32_16x16x32_bf16 v[40:43], v[162:165], v[194:197], v[40:43]
	v_mfma_f32_16x16x32_bf16 v[28:31], v[144:147], v[202:205], v[28:31]
	v_mfma_f32_16x16x32_bf16 v[24:27], v[162:165], v[202:205], v[24:27]
	v_mfma_f32_16x16x32_bf16 v[12:15], v[144:147], v[210:213], v[12:15]
	v_mfma_f32_16x16x32_bf16 v[8:11], v[162:165], v[210:213], v[8:11]
	v_mfma_f32_16x16x32_bf16 v[72:75], v[158:161], v[190:193], v[72:75]
	v_mfma_f32_16x16x32_bf16 v[68:71], v[166:169], v[190:193], v[68:71]
	v_mfma_f32_16x16x32_bf16 v[44:47], v[158:161], v[198:201], v[44:47]
	v_mfma_f32_16x16x32_bf16 v[40:43], v[166:169], v[198:201], v[40:43]
	v_mfma_f32_16x16x32_bf16 v[28:31], v[158:161], v[206:209], v[28:31]
	v_mfma_f32_16x16x32_bf16 v[24:27], v[166:169], v[206:209], v[24:27]
	v_mfma_f32_16x16x32_bf16 v[12:15], v[158:161], v[214:217], v[12:15]
	v_mfma_f32_16x16x32_bf16 v[8:11], v[166:169], v[214:217], v[8:11]
	v_mfma_f32_16x16x32_bf16 v[60:63], v[170:173], v[186:189], v[60:63]
	v_mfma_f32_16x16x32_bf16 v[56:59], v[178:181], v[186:189], v[56:59]
	v_mfma_f32_16x16x32_bf16 v[36:39], v[170:173], v[194:197], v[36:39]
	v_mfma_f32_16x16x32_bf16 v[32:35], v[178:181], v[194:197], v[32:35]
	v_mfma_f32_16x16x32_bf16 v[20:23], v[170:173], v[202:205], v[20:23]
	v_mfma_f32_16x16x32_bf16 v[16:19], v[178:181], v[202:205], v[16:19]
	v_mfma_f32_16x16x32_bf16 v[4:7], v[170:173], v[210:213], v[4:7]
	v_mfma_f32_16x16x32_bf16 v[0:3], v[178:181], v[210:213], v[0:3]
	v_mfma_f32_16x16x32_bf16 v[60:63], v[174:177], v[190:193], v[60:63]
	v_mfma_f32_16x16x32_bf16 v[56:59], v[182:185], v[190:193], v[56:59]
	v_mfma_f32_16x16x32_bf16 v[36:39], v[174:177], v[198:201], v[36:39]
	v_mfma_f32_16x16x32_bf16 v[32:35], v[182:185], v[198:201], v[32:35]
	v_mfma_f32_16x16x32_bf16 v[20:23], v[174:177], v[206:209], v[20:23]
	v_mfma_f32_16x16x32_bf16 v[16:19], v[182:185], v[206:209], v[16:19]
	v_mfma_f32_16x16x32_bf16 v[4:7], v[174:177], v[214:217], v[4:7]
	v_mfma_f32_16x16x32_bf16 v[0:3], v[182:185], v[214:217], v[0:3]
	s_setprio 0
	s_barrier
	s_add_i32 s64, 0, 0x18000
	v_add_u32_e32 v157, s64, v151
	s_add_i32 s65, 0, 0x1c000
	ds_read_b128 v[144:147], v157
	ds_read_b128 v[158:161], v157 offset:1024
	ds_read_b128 v[162:165], v157 offset:2048
	ds_read_b128 v[166:169], v157 offset:3072
	v_add_u32_e32 v157, s65, v151
	ds_read_b128 v[170:173], v157
	ds_read_b128 v[174:177], v157 offset:1024
	ds_read_b128 v[178:181], v157 offset:2048
	ds_read_b128 v[182:185], v157 offset:3072
	s_add_u32 s30, s30, 0x4000
	s_addc_u32 s31, s31, 0
	s_mov_b32 m0, s38
	v_lshl_add_u64 v[220:221], s[30:31], 0, v[128:129]
	ds_read_b128 v[186:189], v155 offset:32768
	ds_read_b128 v[190:193], v155 offset:33792
	ds_read_b128 v[194:197], v155 offset:34816
	ds_read_b128 v[198:201], v155 offset:35840
	ds_read_b128 v[202:205], v155 offset:36864
	ds_read_b128 v[206:209], v155 offset:37888
	ds_read_b128 v[210:213], v155 offset:38912
	ds_read_b128 v[214:217], v155 offset:39936
	global_load_lds_dwordx4 v[220:221], off
	v_lshl_add_u64 v[220:221], s[30:31], 0, v[132:133]
	s_mov_b32 m0, s39
	s_nop 0
	global_load_lds_dwordx4 v[220:221], off
	s_waitcnt vmcnt(8)
	s_waitcnt lgkmcnt(0)
	s_barrier
	s_setprio 1
	s_waitcnt lgkmcnt(0)
	v_mfma_f32_16x16x32_bf16 v[124:127], v[144:147], v[186:189], v[124:127]
	v_mfma_f32_16x16x32_bf16 v[120:123], v[162:165], v[186:189], v[120:123]
	v_mfma_f32_16x16x32_bf16 v[108:111], v[144:147], v[194:197], v[108:111]
	v_mfma_f32_16x16x32_bf16 v[48:51], v[162:165], v[194:197], v[48:51]
	v_mfma_f32_16x16x32_bf16 v[100:103], v[144:147], v[202:205], v[100:103]
	v_mfma_f32_16x16x32_bf16 v[64:67], v[162:165], v[202:205], v[64:67]
	v_mfma_f32_16x16x32_bf16 v[92:95], v[144:147], v[210:213], v[92:95]
	v_mfma_f32_16x16x32_bf16 v[80:83], v[162:165], v[210:213], v[80:83]
	v_mfma_f32_16x16x32_bf16 v[124:127], v[158:161], v[190:193], v[124:127]
	v_mfma_f32_16x16x32_bf16 v[120:123], v[166:169], v[190:193], v[120:123]
	v_mfma_f32_16x16x32_bf16 v[108:111], v[158:161], v[198:201], v[108:111]
	v_mfma_f32_16x16x32_bf16 v[48:51], v[166:169], v[198:201], v[48:51]
	v_mfma_f32_16x16x32_bf16 v[100:103], v[158:161], v[206:209], v[100:103]
	v_mfma_f32_16x16x32_bf16 v[64:67], v[166:169], v[206:209], v[64:67]
	v_mfma_f32_16x16x32_bf16 v[92:95], v[158:161], v[214:217], v[92:95]
	v_mfma_f32_16x16x32_bf16 v[80:83], v[166:169], v[214:217], v[80:83]
	v_mfma_f32_16x16x32_bf16 v[116:119], v[170:173], v[186:189], v[116:119]
	v_mfma_f32_16x16x32_bf16 v[112:115], v[178:181], v[186:189], v[112:115]
	v_mfma_f32_16x16x32_bf16 v[104:107], v[170:173], v[194:197], v[104:107]
	v_mfma_f32_16x16x32_bf16 v[52:55], v[178:181], v[194:197], v[52:55]
	v_mfma_f32_16x16x32_bf16 v[96:99], v[170:173], v[202:205], v[96:99]
	v_mfma_f32_16x16x32_bf16 v[76:79], v[178:181], v[202:205], v[76:79]
	v_mfma_f32_16x16x32_bf16 v[88:91], v[170:173], v[210:213], v[88:91]
	v_mfma_f32_16x16x32_bf16 v[84:87], v[178:181], v[210:213], v[84:87]
	v_mfma_f32_16x16x32_bf16 v[116:119], v[174:177], v[190:193], v[116:119]
	v_mfma_f32_16x16x32_bf16 v[112:115], v[182:185], v[190:193], v[112:115]
	v_mfma_f32_16x16x32_bf16 v[104:107], v[174:177], v[198:201], v[104:107]
	v_mfma_f32_16x16x32_bf16 v[52:55], v[182:185], v[198:201], v[52:55]
	v_mfma_f32_16x16x32_bf16 v[96:99], v[174:177], v[206:209], v[96:99]
	v_mfma_f32_16x16x32_bf16 v[76:79], v[182:185], v[206:209], v[76:79]
	v_mfma_f32_16x16x32_bf16 v[88:91], v[174:177], v[214:217], v[88:91]
	v_mfma_f32_16x16x32_bf16 v[84:87], v[182:185], v[214:217], v[84:87]
	s_setprio 0
	s_barrier
; #define PG8_STAGE(bufoff, gbase, voff) do { _Pragma("unroll") for (int _i = 0; _i < 2; ++_i) \
;         __builtin_amdgcn_global_load_lds((const unsigned*)((const char*)(gbase) + (voff)[_i]), (PG8_LAS unsigned*)(lds + (bufoff) + ldsw + _i * 8192), 16, 0, 0); } while (0)
; #define PG8_LDA(dst, b, h) do { _Pragma("unroll") for (int m = 0; m < 4; ++m) _Pragma("unroll") for (int k = 0; k < 2; ++k) dst[m][k] = *(const PG8_LAS bf16x8*)(lds + PG8_SA(b, h) + aoff + m * 2048 + k * 1024); } while (0)
; #define PG8_MMA(ai, bj, At, Bt) do { __builtin_amdgcn_s_setprio(1); _Pragma("unroll") for (int m = 0; m < 4; ++m) _Pragma("unroll") for (int n = 0; n < 2; ++n) _Pragma("unroll") for (int k = 0; k < 2; ++k) \
;         acc[ai][bj][m][n] = __builtin_amdgcn_mfma_f32_16x16x32_bf16(Bt[n][k], At[m][k], acc[ai][bj][m][n], 0, 0, 0); __builtin_amdgcn_s_setprio(0); } while (0)
; #define PG8_WAIT_V(n) asm volatile("s_waitcnt vmcnt(" #n ")" ::: "memory")
; #define PG8_WAIT_L(n) asm volatile("s_waitcnt lgkmcnt(" #n ")" ::: "memory")
; #define PG8_BAR __builtin_amdgcn_s_barrier()
; #define PG8_SCHED __builtin_amdgcn_sched_barrier(0)
; template <class Epi, class Sched, bool ALIGN_EPI = false, bool SP2 = false>
; __device__ __forceinline__ void gemm_phase(PG8_LAS unsigned char* lds, const Gemm g, const Sched& S, const Epi& E) {
;     ...
;             PG8_LDA(At, 1, 1); PG8_STAGE(PG8_SB(1, 0), b3, voffB); PG8_STAGE(PG8_SB(1, 1), b3 + hstep, voffB); PG8_STAGE(PG8_SA(1, 0), a3, voffA);
;             PG8_WAIT_V(8); PG8_WAIT_L(0); PG8_BAR; PG8_MMA(1, 0, At, B0); PG8_MMA(1, 1, At, B1); PG8_BAR; PG8_SCHED;
	s_add_i32 s30, s64, s33
	v_lshl_add_u64 v[148:149], v[148:149], 0, s[16:17]
	s_mov_b32 m0, s30
	ds_read_b128 v[186:189], v155 offset:49152
	ds_read_b128 v[190:193], v155 offset:50176
	ds_read_b128 v[194:197], v155 offset:51200
	ds_read_b128 v[198:201], v155 offset:52224
	ds_read_b128 v[202:205], v155 offset:53248
	ds_read_b128 v[206:209], v155 offset:54272
	ds_read_b128 v[210:213], v155 offset:55296
	ds_read_b128 v[214:217], v155 offset:56320
	global_load_lds_dwordx4 v[148:149], off
	s_add_i32 m0, s30, 0x2000
	s_add_u32 s26, s26, 0x2b0080
	v_lshl_add_u64 v[148:149], v[218:219], 0, s[16:17]
	s_addc_u32 s27, s27, 0
	s_add_i32 s30, s65, s33
	global_load_lds_dwordx4 v[148:149], off
	v_lshl_add_u64 v[148:149], s[26:27], 0, v[130:131]
	s_mov_b32 m0, s30
	s_nop 0
	global_load_lds_dwordx4 v[148:149], off
	v_lshl_add_u64 v[148:149], s[26:27], 0, v[134:135]
	s_add_i32 m0, s30, 0x2000
	s_nop 0
	global_load_lds_dwordx4 v[148:149], off
	v_lshl_add_u64 v[148:149], s[24:25], 0, v[128:129]
	s_mov_b32 m0, s41
	s_nop 0
	global_load_lds_dwordx4 v[148:149], off
	v_lshl_add_u64 v[148:149], s[24:25], 0, v[132:133]
	s_mov_b32 m0, s52
	s_nop 0
	global_load_lds_dwordx4 v[148:149], off
	s_waitcnt vmcnt(8)
	s_waitcnt lgkmcnt(0)
	s_barrier
	s_setprio 1
	s_waitcnt lgkmcnt(0)
	v_mfma_f32_16x16x32_bf16 v[72:75], v[144:147], v[186:189], v[72:75]
	v_mfma_f32_16x16x32_bf16 v[68:71], v[162:165], v[186:189], v[68:71]
	v_mfma_f32_16x16x32_bf16 v[44:47], v[144:147], v[194:197], v[44:47]
	v_mfma_f32_16x16x32_bf16 v[40:43], v[162:165], v[194:197], v[40:43]
	v_mfma_f32_16x16x32_bf16 v[28:31], v[144:147], v[202:205], v[28:31]
	v_mfma_f32_16x16x32_bf16 v[24:27], v[162:165], v[202:205], v[24:27]
	v_mfma_f32_16x16x32_bf16 v[12:15], v[144:147], v[210:213], v[12:15]
	v_mfma_f32_16x16x32_bf16 v[8:11], v[162:165], v[210:213], v[8:11]
	v_mfma_f32_16x16x32_bf16 v[72:75], v[158:161], v[190:193], v[72:75]
	v_mfma_f32_16x16x32_bf16 v[68:71], v[166:169], v[190:193], v[68:71]
	v_mfma_f32_16x16x32_bf16 v[44:47], v[158:161], v[198:201], v[44:47]
	v_mfma_f32_16x16x32_bf16 v[40:43], v[166:169], v[198:201], v[40:43]
	v_mfma_f32_16x16x32_bf16 v[28:31], v[158:161], v[206:209], v[28:31]
	v_mfma_f32_16x16x32_bf16 v[24:27], v[166:169], v[206:209], v[24:27]
	v_mfma_f32_16x16x32_bf16 v[12:15], v[158:161], v[214:217], v[12:15]
	v_mfma_f32_16x16x32_bf16 v[8:11], v[166:169], v[214:217], v[8:11]
	v_mfma_f32_16x16x32_bf16 v[60:63], v[170:173], v[186:189], v[60:63]
	v_mfma_f32_16x16x32_bf16 v[56:59], v[178:181], v[186:189], v[56:59]
	v_mfma_f32_16x16x32_bf16 v[36:39], v[170:173], v[194:197], v[36:39]
	v_mfma_f32_16x16x32_bf16 v[32:35], v[178:181], v[194:197], v[32:35]
	v_mfma_f32_16x16x32_bf16 v[20:23], v[170:173], v[202:205], v[20:23]
	v_mfma_f32_16x16x32_bf16 v[16:19], v[178:181], v[202:205], v[16:19]
	v_mfma_f32_16x16x32_bf16 v[4:7], v[170:173], v[210:213], v[4:7]
	v_mfma_f32_16x16x32_bf16 v[0:3], v[178:181], v[210:213], v[0:3]
	v_mfma_f32_16x16x32_bf16 v[60:63], v[174:177], v[190:193], v[60:63]
	v_mfma_f32_16x16x32_bf16 v[56:59], v[182:185], v[190:193], v[56:59]
	v_mfma_f32_16x16x32_bf16 v[36:39], v[174:177], v[198:201], v[36:39]
	v_mfma_f32_16x16x32_bf16 v[32:35], v[182:185], v[198:201], v[32:35]
	v_mfma_f32_16x16x32_bf16 v[20:23], v[174:177], v[206:209], v[20:23]
	v_mfma_f32_16x16x32_bf16 v[16:19], v[182:185], v[206:209], v[16:19]
	v_mfma_f32_16x16x32_bf16 v[4:7], v[174:177], v[214:217], v[4:7]
	v_mfma_f32_16x16x32_bf16 v[0:3], v[182:185], v[214:217], v[0:3]
	s_setprio 0
	s_barrier
	s_add_i32 s63, s63, 2
	s_add_u32 s61, s61, 0x100
	s_addc_u32 s62, s62, 0
	s_add_u32 s22, s22, 0x10000
	s_addc_u32 s23, s23, 0
	s_cmpk_gt_u32 s63, 0xa9
	s_cbranch_scc0 .LBB0_1515
	s_and_b64 vcc, exec, s[18:19]
	s_cbranch_vccz .LBB0_1518
	s_barrier

; #define PG8_STAGE(bufoff, gbase, voff) do { _Pragma("unroll") for (int _i = 0; _i < 2; ++_i) \
;         __builtin_amdgcn_global_load_lds((const unsigned*)((const char*)(gbase) + (voff)[_i]), (PG8_LAS unsigned*)(lds + (bufoff) + ldsw + _i * 8192), 16, 0, 0); } while (0)
; #define PG8_LDA(dst, b, h) do { _Pragma("unroll") for (int m = 0; m < 4; ++m) _Pragma("unroll") for (int k = 0; k < 2; ++k) dst[m][k] = *(const PG8_LAS bf16x8*)(lds + PG8_SA(b, h) + aoff + m * 2048 + k * 1024); } while (0)
; #define PG8_LDB(dst, b, h) do { _Pragma("unroll") for (int n = 0; n < 2; ++n) _Pragma("unroll") for (int k = 0; k < 2; ++k) dst[n][k] = *(const PG8_LAS bf16x8*)(lds + PG8_SB(b, h) + boff + n * 2048 + k * 1024); } while (0)
; #define PG8_MMA(ai, bj, At, Bt) do { __builtin_amdgcn_s_setprio(1); _Pragma("unroll") for (int m = 0; m < 4; ++m) _Pragma("unroll") for (int n = 0; n < 2; ++n) _Pragma("unroll") for (int k = 0; k < 2; ++k) \
;         acc[ai][bj][m][n] = __builtin_amdgcn_mfma_f32_16x16x32_bf16(Bt[n][k], At[m][k], acc[ai][bj][m][n], 0, 0, 0); __builtin_amdgcn_s_setprio(0); } while (0)
; #define PG8_WAIT_V(n) asm volatile("s_waitcnt vmcnt(" #n ")" ::: "memory")
; #define PG8_BAR __builtin_amdgcn_s_barrier()
; template <class Epi, class Sched, bool ALIGN_EPI = false, bool SP2 = false>
; __device__ __forceinline__ void gemm_phase(PG8_LAS unsigned char* lds, const Gemm g, const Sched& S, const Epi& E) {
;     ...
;         for (int t = 0; t < nt; t += 2) {
;             const bool last = (t == nt - 2);
;             const char* a1 = cA + (size_t)(t + 1) * kstepA;
;             const char* a2 = last ? nA : cA + (size_t)(t + 2) * kstepA; const char* b2 = last ? nB : cB + (size_t)(t + 2) * kstep;
;             const char* a3 = a2 + kstepA; const char* b3 = b2 + kstep;
;             if (last && has_next) S.a_ready(nxt);
;             if constexpr (SP2) {
;             PG8_LDB(B0, 0, 0); PG8_LDB(B1, 0, 1); PG8_SCHED; PG8_LDA(At, 0, 0); PG8_STAGE(PG8_SA(1, 1), a1 + hstepA, voffA);
;             PG8_WAIT_V(8); PG8_WAIT_L(0); PG8_BAR; PG8_MMA(0, 0, At, B0); PG8_MMA(0, 1, At, B1); PG8_BAR; PG8_SCHED;
;             PG8_LDA(At, 0, 1); PG8_STAGE(PG8_SB(0, 0), b2, voffB); PG8_STAGE(PG8_SB(0, 1), b2 + hstep, voffB); PG8_STAGE(PG8_SA(0, 0), a2, voffA);
;             PG8_WAIT_V(8); PG8_WAIT_L(0); PG8_BAR; PG8_MMA(1, 0, At, B0); PG8_MMA(1, 1, At, B1); PG8_BAR; PG8_SCHED;
.LBB0_1631:
	ds_read_b128 v[144:147], v155
	ds_read_b128 v[148:151], v155 offset:1024
	ds_read_b128 v[160:163], v155 offset:2048
	ds_read_b128 v[164:167], v155 offset:3072
	ds_read_b128 v[168:171], v156
	ds_read_b128 v[172:175], v156 offset:1024
	ds_read_b128 v[176:179], v156 offset:2048
	ds_read_b128 v[180:183], v156 offset:3072
	s_add_u32 s65, s84, 0xfff00080
	s_addc_u32 s66, s85, -1
	s_cmp_eq_u32 s64, 60
	s_cselect_b32 s89, s25, s66
	s_cselect_b32 s88, s35, s65
	s_cselect_b32 s87, s23, s63
	s_cselect_b32 s86, s61, s62
	v_lshl_add_u64 v[216:217], s[84:85], 0, v[136:137]
	s_add_i32 m0, s29, 0xc000
	ds_read_b128 v[184:187], v157
	ds_read_b128 v[188:191], v157 offset:1024
	ds_read_b128 v[192:195], v157 offset:2048
	ds_read_b128 v[196:199], v157 offset:3072
	ds_read_b128 v[200:203], v157 offset:4096
	ds_read_b128 v[204:207], v157 offset:5120
	ds_read_b128 v[208:211], v157 offset:6144
	ds_read_b128 v[212:215], v157 offset:7168
	global_load_lds_dwordx4 v[216:217], off
	v_lshl_add_u64 v[216:217], s[84:85], 0, v[138:139]
	s_add_i32 m0, s29, 0xe000
	s_nop 0
	global_load_lds_dwordx4 v[216:217], off
	s_waitcnt vmcnt(8)
	s_waitcnt lgkmcnt(0)
	s_barrier
	s_setprio 1
	s_waitcnt lgkmcnt(0)
	v_mfma_f32_16x16x32_bf16 v[124:127], v[144:147], v[184:187], v[124:127]
	v_mfma_f32_16x16x32_bf16 v[120:123], v[160:163], v[184:187], v[120:123]
	v_mfma_f32_16x16x32_bf16 v[108:111], v[144:147], v[192:195], v[108:111]
	v_mfma_f32_16x16x32_bf16 v[32:35], v[160:163], v[192:195], v[32:35]
	v_mfma_f32_16x16x32_bf16 v[100:103], v[144:147], v[200:203], v[100:103]
	v_mfma_f32_16x16x32_bf16 v[52:55], v[160:163], v[200:203], v[52:55]
	v_mfma_f32_16x16x32_bf16 v[92:95], v[144:147], v[208:211], v[92:95]
	v_mfma_f32_16x16x32_bf16 v[72:75], v[160:163], v[208:211], v[72:75]
	v_mfma_f32_16x16x32_bf16 v[124:127], v[148:151], v[188:191], v[124:127]
	v_mfma_f32_16x16x32_bf16 v[120:123], v[164:167], v[188:191], v[120:123]
	v_mfma_f32_16x16x32_bf16 v[108:111], v[148:151], v[196:199], v[108:111]
	v_mfma_f32_16x16x32_bf16 v[32:35], v[164:167], v[196:199], v[32:35]
	v_mfma_f32_16x16x32_bf16 v[100:103], v[148:151], v[204:207], v[100:103]
	v_mfma_f32_16x16x32_bf16 v[52:55], v[164:167], v[204:207], v[52:55]
	v_mfma_f32_16x16x32_bf16 v[92:95], v[148:151], v[212:215], v[92:95]
	v_mfma_f32_16x16x32_bf16 v[72:75], v[164:167], v[212:215], v[72:75]
	v_mfma_f32_16x16x32_bf16 v[116:119], v[168:171], v[184:187], v[116:119]
	v_mfma_f32_16x16x32_bf16 v[112:115], v[176:179], v[184:187], v[112:115]
	v_mfma_f32_16x16x32_bf16 v[104:107], v[168:171], v[192:195], v[104:107]
	v_mfma_f32_16x16x32_bf16 v[44:47], v[176:179], v[192:195], v[44:47]
	v_mfma_f32_16x16x32_bf16 v[96:99], v[168:171], v[200:203], v[96:99]
	v_mfma_f32_16x16x32_bf16 v[68:71], v[176:179], v[200:203], v[68:71]
	v_mfma_f32_16x16x32_bf16 v[88:91], v[168:171], v[208:211], v[88:91]
	v_mfma_f32_16x16x32_bf16 v[84:87], v[176:179], v[208:211], v[84:87]
	v_mfma_f32_16x16x32_bf16 v[116:119], v[172:175], v[188:191], v[116:119]
	v_mfma_f32_16x16x32_bf16 v[112:115], v[180:183], v[188:191], v[112:115]
	v_mfma_f32_16x16x32_bf16 v[104:107], v[172:175], v[196:199], v[104:107]
	v_mfma_f32_16x16x32_bf16 v[44:47], v[180:183], v[196:199], v[44:47]
	v_mfma_f32_16x16x32_bf16 v[96:99], v[172:175], v[204:207], v[96:99]
	v_mfma_f32_16x16x32_bf16 v[68:71], v[180:183], v[204:207], v[68:71]
	v_mfma_f32_16x16x32_bf16 v[88:91], v[172:175], v[212:215], v[88:91]
	v_mfma_f32_16x16x32_bf16 v[84:87], v[180:183], v[212:215], v[84:87]
	s_setprio 0
	s_barrier
	s_add_i32 s65, s58, s3
	v_lshl_add_u64 v[216:217], s[86:87], 0, v[130:131]
	s_mov_b32 m0, s65
	ds_read_b128 v[184:187], v157 offset:16384
	ds_read_b128 v[188:191], v157 offset:17408
	ds_read_b128 v[192:195], v157 offset:18432
	ds_read_b128 v[196:199], v157 offset:19456
	ds_read_b128 v[200:203], v157 offset:20480
	ds_read_b128 v[204:207], v157 offset:21504
	ds_read_b128 v[208:211], v157 offset:22528
	ds_read_b128 v[212:215], v157 offset:23552
	global_load_lds_dwordx4 v[216:217], off
	s_add_i32 m0, s65, 0x2000
	s_add_u32 s66, s86, 0x100000
	v_lshl_add_u64 v[218:219], s[86:87], 0, v[134:135]
	s_addc_u32 s67, s87, 0
	s_add_i32 s65, s59, s3
	global_load_lds_dwordx4 v[218:219], off
	v_lshl_add_u64 v[220:221], s[66:67], 0, v[130:131]
	s_mov_b32 m0, s65
	v_lshl_add_u64 v[222:223], s[88:89], 0, v[132:133]
	global_load_lds_dwordx4 v[220:221], off
	v_lshl_add_u64 v[220:221], s[66:67], 0, v[134:135]
	s_add_i32 m0, s65, 0x2000
	s_nop 0
	global_load_lds_dwordx4 v[220:221], off
	v_lshl_add_u64 v[220:221], s[88:89], 0, v[128:129]
	s_mov_b32 m0, s29
	s_nop 0
	global_load_lds_dwordx4 v[220:221], off
	s_mov_b32 m0, s33
	s_nop 0
	global_load_lds_dwordx4 v[222:223], off
	s_waitcnt vmcnt(8)
	s_waitcnt lgkmcnt(0)
	s_barrier
; #define PG8_STAGE(bufoff, gbase, voff) do { _Pragma("unroll") for (int _i = 0; _i < 2; ++_i) \
;         __builtin_amdgcn_global_load_lds((const unsigned*)((const char*)(gbase) + (voff)[_i]), (PG8_LAS unsigned*)(lds + (bufoff) + ldsw + _i * 8192), 16, 0, 0); } while (0)
; #define PG8_LDA(dst, b, h) do { _Pragma("unroll") for (int m = 0; m < 4; ++m) _Pragma("unroll") for (int k = 0; k < 2; ++k) dst[m][k] = *(const PG8_LAS bf16x8*)(lds + PG8_SA(b, h) + aoff + m * 2048 + k * 1024); } while (0)
; #define PG8_LDB(dst, b, h) do { _Pragma("unroll") for (int n = 0; n < 2; ++n) _Pragma("unroll") for (int k = 0; k < 2; ++k) dst[n][k] = *(const PG8_LAS bf16x8*)(lds + PG8_SB(b, h) + boff + n * 2048 + k * 1024); } while (0)
; #define PG8_MMA(ai, bj, At, Bt) do { __builtin_amdgcn_s_setprio(1); _Pragma("unroll") for (int m = 0; m < 4; ++m) _Pragma("unroll") for (int n = 0; n < 2; ++n) _Pragma("unroll") for (int k = 0; k < 2; ++k) \
;         acc[ai][bj][m][n] = __builtin_amdgcn_mfma_f32_16x16x32_bf16(Bt[n][k], At[m][k], acc[ai][bj][m][n], 0, 0, 0); __builtin_amdgcn_s_setprio(0); } while (0)
; #define PG8_WAIT_V(n) asm volatile("s_waitcnt vmcnt(" #n ")" ::: "memory")
; #define PG8_WAIT_L(n) asm volatile("s_waitcnt lgkmcnt(" #n ")" ::: "memory")
; #define PG8_BAR __builtin_amdgcn_s_barrier()
; #define PG8_SCHED __builtin_amdgcn_sched_barrier(0)
; template <class Epi, class Sched, bool ALIGN_EPI = false, bool SP2 = false>
; __device__ __forceinline__ void gemm_phase(PG8_LAS unsigned char* lds, const Gemm g, const Sched& S, const Epi& E) {
;     ...
;             PG8_WAIT_V(8); PG8_WAIT_L(0); PG8_BAR; PG8_MMA(1, 0, At, B0); PG8_MMA(1, 1, At, B1); PG8_BAR; PG8_SCHED;
;             PG8_LDB(B0, 1, 0); PG8_LDB(B1, 1, 1); PG8_SCHED; PG8_LDA(At, 1, 0); PG8_STAGE(PG8_SA(0, 1), a2 + hstepA, voffA);
;             PG8_WAIT_V(8); PG8_WAIT_L(0); PG8_BAR; PG8_MMA(0, 0, At, B0); PG8_MMA(0, 1, At, B1); PG8_BAR; PG8_SCHED;
	s_setprio 1
	s_waitcnt lgkmcnt(0)
	v_mfma_f32_16x16x32_bf16 v[80:83], v[144:147], v[184:187], v[80:83]
	v_mfma_f32_16x16x32_bf16 v[76:79], v[160:163], v[184:187], v[76:79]
	v_mfma_f32_16x16x32_bf16 v[56:59], v[144:147], v[192:195], v[56:59]
	v_mfma_f32_16x16x32_bf16 v[48:51], v[160:163], v[192:195], v[48:51]
	v_mfma_f32_16x16x32_bf16 v[28:31], v[144:147], v[200:203], v[28:31]
	v_mfma_f32_16x16x32_bf16 v[24:27], v[160:163], v[200:203], v[24:27]
	v_mfma_f32_16x16x32_bf16 v[12:15], v[144:147], v[208:211], v[12:15]
	v_mfma_f32_16x16x32_bf16 v[8:11], v[160:163], v[208:211], v[8:11]
	v_mfma_f32_16x16x32_bf16 v[80:83], v[148:151], v[188:191], v[80:83]
	v_mfma_f32_16x16x32_bf16 v[76:79], v[164:167], v[188:191], v[76:79]
	v_mfma_f32_16x16x32_bf16 v[56:59], v[148:151], v[196:199], v[56:59]
	v_mfma_f32_16x16x32_bf16 v[48:51], v[164:167], v[196:199], v[48:51]
	v_mfma_f32_16x16x32_bf16 v[28:31], v[148:151], v[204:207], v[28:31]
	v_mfma_f32_16x16x32_bf16 v[24:27], v[164:167], v[204:207], v[24:27]
	v_mfma_f32_16x16x32_bf16 v[12:15], v[148:151], v[212:215], v[12:15]
	v_mfma_f32_16x16x32_bf16 v[8:11], v[164:167], v[212:215], v[8:11]
	v_mfma_f32_16x16x32_bf16 v[64:67], v[168:171], v[184:187], v[64:67]
	v_mfma_f32_16x16x32_bf16 v[60:63], v[176:179], v[184:187], v[60:63]
	v_mfma_f32_16x16x32_bf16 v[40:43], v[168:171], v[192:195], v[40:43]
	v_mfma_f32_16x16x32_bf16 v[36:39], v[176:179], v[192:195], v[36:39]
	v_mfma_f32_16x16x32_bf16 v[20:23], v[168:171], v[200:203], v[20:23]
	v_mfma_f32_16x16x32_bf16 v[16:19], v[176:179], v[200:203], v[16:19]
	v_mfma_f32_16x16x32_bf16 v[4:7], v[168:171], v[208:211], v[4:7]
	v_mfma_f32_16x16x32_bf16 v[0:3], v[176:179], v[208:211], v[0:3]
	v_mfma_f32_16x16x32_bf16 v[64:67], v[172:175], v[188:191], v[64:67]
	v_mfma_f32_16x16x32_bf16 v[60:63], v[180:183], v[188:191], v[60:63]
	v_mfma_f32_16x16x32_bf16 v[40:43], v[172:175], v[196:199], v[40:43]
	v_mfma_f32_16x16x32_bf16 v[36:39], v[180:183], v[196:199], v[36:39]
	v_mfma_f32_16x16x32_bf16 v[20:23], v[172:175], v[204:207], v[20:23]
	v_mfma_f32_16x16x32_bf16 v[16:19], v[180:183], v[204:207], v[16:19]
	v_mfma_f32_16x16x32_bf16 v[4:7], v[172:175], v[212:215], v[4:7]
	v_mfma_f32_16x16x32_bf16 v[0:3], v[180:183], v[212:215], v[0:3]
	s_setprio 0
	s_barrier
	s_add_i32 s65, 0, 0x18000
	s_add_i32 s68, 0, 0x1c000
	v_add_u32_e32 v164, s65, v153
	v_add_u32_e32 v180, s68, v153
	ds_read_b128 v[144:147], v164
	ds_read_b128 v[148:151], v164 offset:1024
	ds_read_b128 v[160:163], v164 offset:2048
	ds_read_b128 v[164:167], v164 offset:3072
	ds_read_b128 v[168:171], v180
	ds_read_b128 v[172:175], v180 offset:1024
	ds_read_b128 v[176:179], v180 offset:2048
	ds_read_b128 v[180:183], v180 offset:3072
	s_add_u32 s66, s88, 0x100000
	s_addc_u32 s67, s89, 0
	s_mov_b32 m0, s41
	v_lshl_add_u64 v[224:225], s[66:67], 0, v[128:129]
	ds_read_b128 v[184:187], v157 offset:32768
	ds_read_b128 v[188:191], v157 offset:33792
	ds_read_b128 v[192:195], v157 offset:34816
	ds_read_b128 v[196:199], v157 offset:35840
	ds_read_b128 v[200:203], v157 offset:36864
	ds_read_b128 v[204:207], v157 offset:37888
	ds_read_b128 v[208:211], v157 offset:38912
	ds_read_b128 v[212:215], v157 offset:39936
	global_load_lds_dwordx4 v[224:225], off
	v_lshl_add_u64 v[224:225], s[66:67], 0, v[132:133]
	s_mov_b32 m0, s52
	s_nop 0
	global_load_lds_dwordx4 v[224:225], off
	s_waitcnt vmcnt(8)
	s_waitcnt lgkmcnt(0)
	s_barrier
	s_setprio 1
	s_waitcnt lgkmcnt(0)
	v_mfma_f32_16x16x32_bf16 v[124:127], v[144:147], v[184:187], v[124:127]
	v_mfma_f32_16x16x32_bf16 v[120:123], v[160:163], v[184:187], v[120:123]
	v_mfma_f32_16x16x32_bf16 v[108:111], v[144:147], v[192:195], v[108:111]
	v_mfma_f32_16x16x32_bf16 v[32:35], v[160:163], v[192:195], v[32:35]
	v_mfma_f32_16x16x32_bf16 v[100:103], v[144:147], v[200:203], v[100:103]
	v_mfma_f32_16x16x32_bf16 v[52:55], v[160:163], v[200:203], v[52:55]
	v_mfma_f32_16x16x32_bf16 v[92:95], v[144:147], v[208:211], v[92:95]
	v_mfma_f32_16x16x32_bf16 v[72:75], v[160:163], v[208:211], v[72:75]
	v_mfma_f32_16x16x32_bf16 v[124:127], v[148:151], v[188:191], v[124:127]
	v_mfma_f32_16x16x32_bf16 v[120:123], v[164:167], v[188:191], v[120:123]
	v_mfma_f32_16x16x32_bf16 v[108:111], v[148:151], v[196:199], v[108:111]
	v_mfma_f32_16x16x32_bf16 v[32:35], v[164:167], v[196:199], v[32:35]
	v_mfma_f32_16x16x32_bf16 v[100:103], v[148:151], v[204:207], v[100:103]
	v_mfma_f32_16x16x32_bf16 v[52:55], v[164:167], v[204:207], v[52:55]
	v_mfma_f32_16x16x32_bf16 v[92:95], v[148:151], v[212:215], v[92:95]
	v_mfma_f32_16x16x32_bf16 v[72:75], v[164:167], v[212:215], v[72:75]
	v_mfma_f32_16x16x32_bf16 v[116:119], v[168:171], v[184:187], v[116:119]
	v_mfma_f32_16x16x32_bf16 v[112:115], v[176:179], v[184:187], v[112:115]
	v_mfma_f32_16x16x32_bf16 v[104:107], v[168:171], v[192:195], v[104:107]
	v_mfma_f32_16x16x32_bf16 v[44:47], v[176:179], v[192:195], v[44:47]
	v_mfma_f32_16x16x32_bf16 v[96:99], v[168:171], v[200:203], v[96:99]
	v_mfma_f32_16x16x32_bf16 v[68:71], v[176:179], v[200:203], v[68:71]
	v_mfma_f32_16x16x32_bf16 v[88:91], v[168:171], v[208:211], v[88:91]
	v_mfma_f32_16x16x32_bf16 v[84:87], v[176:179], v[208:211], v[84:87]
	v_mfma_f32_16x16x32_bf16 v[116:119], v[172:175], v[188:191], v[116:119]
	v_mfma_f32_16x16x32_bf16 v[112:115], v[180:183], v[188:191], v[112:115]
	v_mfma_f32_16x16x32_bf16 v[104:107], v[172:175], v[196:199], v[104:107]
	v_mfma_f32_16x16x32_bf16 v[44:47], v[180:183], v[196:199], v[44:47]
	v_mfma_f32_16x16x32_bf16 v[96:99], v[172:175], v[204:207], v[96:99]
	v_mfma_f32_16x16x32_bf16 v[68:71], v[180:183], v[204:207], v[68:71]
	v_mfma_f32_16x16x32_bf16 v[88:91], v[172:175], v[212:215], v[88:91]
	v_mfma_f32_16x16x32_bf16 v[84:87], v[180:183], v[212:215], v[84:87]
	s_setprio 0
	s_barrier
; #define PG8_STAGE(bufoff, gbase, voff) do { _Pragma("unroll") for (int _i = 0; _i < 2; ++_i) \
;         __builtin_amdgcn_global_load_lds((const unsigned*)((const char*)(gbase) + (voff)[_i]), (PG8_LAS unsigned*)(lds + (bufoff) + ldsw + _i * 8192), 16, 0, 0); } while (0)
; #define PG8_LDA(dst, b, h) do { _Pragma("unroll") for (int m = 0; m < 4; ++m) _Pragma("unroll") for (int k = 0; k < 2; ++k) dst[m][k] = *(const PG8_LAS bf16x8*)(lds + PG8_SA(b, h) + aoff + m * 2048 + k * 1024); } while (0)
; #define PG8_MMA(ai, bj, At, Bt) do { __builtin_amdgcn_s_setprio(1); _Pragma("unroll") for (int m = 0; m < 4; ++m) _Pragma("unroll") for (int n = 0; n < 2; ++n) _Pragma("unroll") for (int k = 0; k < 2; ++k) \
;         acc[ai][bj][m][n] = __builtin_amdgcn_mfma_f32_16x16x32_bf16(Bt[n][k], At[m][k], acc[ai][bj][m][n], 0, 0, 0); __builtin_amdgcn_s_setprio(0); } while (0)
; #define PG8_WAIT_V(n) asm volatile("s_waitcnt vmcnt(" #n ")" ::: "memory")
; #define PG8_WAIT_L(n) asm volatile("s_waitcnt lgkmcnt(" #n ")" ::: "memory")
; #define PG8_BAR __builtin_amdgcn_s_barrier()
; #define PG8_SCHED __builtin_amdgcn_sched_barrier(0)
; template <class Epi, class Sched, bool ALIGN_EPI = false, bool SP2 = false>
; __device__ __forceinline__ void gemm_phase(PG8_LAS unsigned char* lds, const Gemm g, const Sched& S, const Epi& E) {
;     ...
;             PG8_LDA(At, 1, 1); PG8_STAGE(PG8_SB(1, 0), b3, voffB); PG8_STAGE(PG8_SB(1, 1), b3 + hstep, voffB); PG8_STAGE(PG8_SA(1, 0), a3, voffA);
;             PG8_WAIT_V(8); PG8_WAIT_L(0); PG8_BAR; PG8_MMA(1, 0, At, B0); PG8_MMA(1, 1, At, B1); PG8_BAR; PG8_SCHED;
	s_add_i32 s65, s65, s3
	v_lshl_add_u64 v[216:217], v[216:217], 0, s[18:19]
	s_mov_b32 m0, s65
	ds_read_b128 v[184:187], v157 offset:49152
	ds_read_b128 v[188:191], v157 offset:50176
	ds_read_b128 v[192:195], v157 offset:51200
	ds_read_b128 v[196:199], v157 offset:52224
	ds_read_b128 v[200:203], v157 offset:53248
	ds_read_b128 v[204:207], v157 offset:54272
	ds_read_b128 v[208:211], v157 offset:55296
	ds_read_b128 v[212:215], v157 offset:56320
	global_load_lds_dwordx4 v[216:217], off
	s_add_i32 m0, s65, 0x2000
	s_add_u32 s66, s86, 0x100080
	v_lshl_add_u64 v[216:217], v[218:219], 0, s[18:19]
	s_addc_u32 s67, s87, 0
	s_add_i32 s65, s68, s3
	global_load_lds_dwordx4 v[216:217], off
	v_lshl_add_u64 v[216:217], s[66:67], 0, v[130:131]
	s_mov_b32 m0, s65
	s_nop 0
	global_load_lds_dwordx4 v[216:217], off
	v_lshl_add_u64 v[216:217], s[66:67], 0, v[134:135]
	s_add_i32 m0, s65, 0x2000
	s_nop 0
	global_load_lds_dwordx4 v[216:217], off
	v_lshl_add_u64 v[216:217], v[220:221], 0, s[18:19]
	s_mov_b32 m0, s54
	s_nop 0
	global_load_lds_dwordx4 v[216:217], off
	v_lshl_add_u64 v[216:217], v[222:223], 0, s[18:19]
	s_mov_b32 m0, s55
	s_nop 0
	global_load_lds_dwordx4 v[216:217], off
	s_waitcnt vmcnt(8)
	s_waitcnt lgkmcnt(0)
	s_barrier
	s_setprio 1
	s_waitcnt lgkmcnt(0)
	v_mfma_f32_16x16x32_bf16 v[80:83], v[144:147], v[184:187], v[80:83]
	v_mfma_f32_16x16x32_bf16 v[76:79], v[160:163], v[184:187], v[76:79]
	v_mfma_f32_16x16x32_bf16 v[56:59], v[144:147], v[192:195], v[56:59]
	v_mfma_f32_16x16x32_bf16 v[48:51], v[160:163], v[192:195], v[48:51]
	v_mfma_f32_16x16x32_bf16 v[28:31], v[144:147], v[200:203], v[28:31]
	v_mfma_f32_16x16x32_bf16 v[24:27], v[160:163], v[200:203], v[24:27]
	v_mfma_f32_16x16x32_bf16 v[12:15], v[144:147], v[208:211], v[12:15]
	v_mfma_f32_16x16x32_bf16 v[8:11], v[160:163], v[208:211], v[8:11]
	v_mfma_f32_16x16x32_bf16 v[80:83], v[148:151], v[188:191], v[80:83]
	v_mfma_f32_16x16x32_bf16 v[76:79], v[164:167], v[188:191], v[76:79]
	v_mfma_f32_16x16x32_bf16 v[56:59], v[148:151], v[196:199], v[56:59]
	v_mfma_f32_16x16x32_bf16 v[48:51], v[164:167], v[196:199], v[48:51]
	v_mfma_f32_16x16x32_bf16 v[28:31], v[148:151], v[204:207], v[28:31]
	v_mfma_f32_16x16x32_bf16 v[24:27], v[164:167], v[204:207], v[24:27]
	v_mfma_f32_16x16x32_bf16 v[12:15], v[148:151], v[212:215], v[12:15]
	v_mfma_f32_16x16x32_bf16 v[8:11], v[164:167], v[212:215], v[8:11]
	v_mfma_f32_16x16x32_bf16 v[64:67], v[168:171], v[184:187], v[64:67]
	v_mfma_f32_16x16x32_bf16 v[60:63], v[176:179], v[184:187], v[60:63]
	v_mfma_f32_16x16x32_bf16 v[40:43], v[168:171], v[192:195], v[40:43]
	v_mfma_f32_16x16x32_bf16 v[36:39], v[176:179], v[192:195], v[36:39]
	v_mfma_f32_16x16x32_bf16 v[20:23], v[168:171], v[200:203], v[20:23]
	v_mfma_f32_16x16x32_bf16 v[16:19], v[176:179], v[200:203], v[16:19]
	v_mfma_f32_16x16x32_bf16 v[4:7], v[168:171], v[208:211], v[4:7]
	v_mfma_f32_16x16x32_bf16 v[0:3], v[176:179], v[208:211], v[0:3]
	v_mfma_f32_16x16x32_bf16 v[64:67], v[172:175], v[188:191], v[64:67]
	v_mfma_f32_16x16x32_bf16 v[60:63], v[180:183], v[188:191], v[60:63]
	v_mfma_f32_16x16x32_bf16 v[40:43], v[172:175], v[196:199], v[40:43]
	v_mfma_f32_16x16x32_bf16 v[36:39], v[180:183], v[196:199], v[36:39]
	v_mfma_f32_16x16x32_bf16 v[20:23], v[172:175], v[204:207], v[20:23]
	v_mfma_f32_16x16x32_bf16 v[16:19], v[180:183], v[204:207], v[16:19]
	v_mfma_f32_16x16x32_bf16 v[4:7], v[172:175], v[212:215], v[4:7]
	v_mfma_f32_16x16x32_bf16 v[0:3], v[180:183], v[212:215], v[0:3]
	s_setprio 0
	s_barrier
	s_add_i32 s64, s64, 2
	s_add_u32 s84, s84, 0x100
	s_addc_u32 s85, s85, 0
	s_add_u32 s62, s62, 0x100
	s_addc_u32 s63, s63, 0
	s_cmp_gt_u32 s64, 61
	s_cbranch_scc0 .LBB0_1631
	s_and_b64 vcc, exec, s[20:21]
	s_cbranch_vccz .LBB0_1634
	s_barrier

; #define PG8_STAGE(bufoff, gbase, voff) do { _Pragma("unroll") for (int _i = 0; _i < 2; ++_i) \
;         __builtin_amdgcn_global_load_lds((const unsigned*)((const char*)(gbase) + (voff)[_i]), (PG8_LAS unsigned*)(lds + (bufoff) + ldsw + _i * 8192), 16, 0, 0); } while (0)
; #define PG8_LDA(dst, b, h) do { _Pragma("unroll") for (int m = 0; m < 4; ++m) _Pragma("unroll") for (int k = 0; k < 2; ++k) dst[m][k] = *(const PG8_LAS bf16x8*)(lds + PG8_SA(b, h) + aoff + m * 2048 + k * 1024); } while (0)
; #define PG8_LDB(dst, b, h) do { _Pragma("unroll") for (int n = 0; n < 2; ++n) _Pragma("unroll") for (int k = 0; k < 2; ++k) dst[n][k] = *(const PG8_LAS bf16x8*)(lds + PG8_SB(b, h) + boff + n * 2048 + k * 1024); } while (0)
; #define PG8_MMA(ai, bj, At, Bt) do { __builtin_amdgcn_s_setprio(1); _Pragma("unroll") for (int m = 0; m < 4; ++m) _Pragma("unroll") for (int n = 0; n < 2; ++n) _Pragma("unroll") for (int k = 0; k < 2; ++k) \
;         acc[ai][bj][m][n] = __builtin_amdgcn_mfma_f32_16x16x32_bf16(Bt[n][k], At[m][k], acc[ai][bj][m][n], 0, 0, 0); __builtin_amdgcn_s_setprio(0); } while (0)
; #define PG8_WAIT_V(n) asm volatile("s_waitcnt vmcnt(" #n ")" ::: "memory")
; #define PG8_BAR __builtin_amdgcn_s_barrier()
; template <class Epi, class Sched, bool ALIGN_EPI = false, bool SP2 = false>
; __device__ __forceinline__ void gemm_phase(PG8_LAS unsigned char* lds, const Gemm g, const Sched& S, const Epi& E) {
;     ...
;         for (int t = 0; t < nt; t += 2) {
;             const bool last = (t == nt - 2);
;             const char* a1 = cA + (size_t)(t + 1) * kstepA;
;             const char* a2 = last ? nA : cA + (size_t)(t + 2) * kstepA; const char* b2 = last ? nB : cB + (size_t)(t + 2) * kstep;
;             const char* a3 = a2 + kstepA; const char* b3 = b2 + kstep;
;             if (last && has_next) S.a_ready(nxt);
;             if constexpr (SP2) {
;             PG8_LDB(B0, 0, 0); PG8_LDB(B1, 0, 1); PG8_SCHED; PG8_LDA(At, 0, 0); PG8_STAGE(PG8_SA(1, 1), a1 + hstepA, voffA);
;             PG8_WAIT_V(8); PG8_WAIT_L(0); PG8_BAR; PG8_MMA(0, 0, At, B0); PG8_MMA(0, 1, At, B1); PG8_BAR; PG8_SCHED;
;             PG8_LDA(At, 0, 1); PG8_STAGE(PG8_SB(0, 0), b2, voffB); PG8_STAGE(PG8_SB(0, 1), b2 + hstep, voffB); PG8_STAGE(PG8_SA(0, 0), a2, voffA);
;             PG8_WAIT_V(8); PG8_WAIT_L(0); PG8_BAR; PG8_MMA(1, 0, At, B0); PG8_MMA(1, 1, At, B1); PG8_BAR; PG8_SCHED;
.LBB0_1741:
	ds_read_b128 v[150:153], v158
	ds_read_b128 v[162:165], v158 offset:1024
	ds_read_b128 v[166:169], v158 offset:2048
	ds_read_b128 v[170:173], v158 offset:3072
	ds_read_b128 v[174:177], v159
	ds_read_b128 v[178:181], v159 offset:1024
	ds_read_b128 v[182:185], v159 offset:2048
	ds_read_b128 v[186:189], v159 offset:3072
	s_add_u32 s40, s34, 0xfff00080
	s_addc_u32 s41, s35, -1
	s_cmp_eq_u32 s67, 60
	s_cselect_b32 s85, s21, s41
	s_cselect_b32 s84, s27, s40
	s_cselect_b32 s41, s19, s66
	s_cselect_b32 s40, s31, s65
	v_lshl_add_u64 v[154:155], s[34:35], 0, v[140:141]
	s_add_i32 m0, s53, 0xc000
	ds_read_b128 v[190:193], v160
	ds_read_b128 v[194:197], v160 offset:1024
	ds_read_b128 v[198:201], v160 offset:2048
	ds_read_b128 v[202:205], v160 offset:3072
	ds_read_b128 v[206:209], v160 offset:4096
	ds_read_b128 v[210:213], v160 offset:5120
	ds_read_b128 v[214:217], v160 offset:6144
	ds_read_b128 v[218:221], v160 offset:7168
	global_load_lds_dwordx4 v[154:155], off
	v_lshl_add_u64 v[154:155], s[34:35], 0, v[142:143]
	s_add_i32 m0, s53, 0xe000
	s_nop 0
	global_load_lds_dwordx4 v[154:155], off
	s_waitcnt vmcnt(8)
	s_waitcnt lgkmcnt(0)
	s_barrier
	s_setprio 1
	s_waitcnt lgkmcnt(0)
	v_mfma_f32_16x16x32_bf16 v[124:127], v[150:153], v[190:193], v[124:127]
	v_mfma_f32_16x16x32_bf16 v[120:123], v[166:169], v[190:193], v[120:123]
	v_mfma_f32_16x16x32_bf16 v[108:111], v[150:153], v[198:201], v[108:111]
	v_mfma_f32_16x16x32_bf16 v[104:107], v[166:169], v[198:201], v[104:107]
	v_mfma_f32_16x16x32_bf16 v[92:95], v[150:153], v[206:209], v[92:95]
	v_mfma_f32_16x16x32_bf16 v[88:91], v[166:169], v[206:209], v[88:91]
	v_mfma_f32_16x16x32_bf16 v[76:79], v[150:153], v[214:217], v[76:79]
	v_mfma_f32_16x16x32_bf16 v[72:75], v[166:169], v[214:217], v[72:75]
	v_mfma_f32_16x16x32_bf16 v[124:127], v[162:165], v[194:197], v[124:127]
	v_mfma_f32_16x16x32_bf16 v[120:123], v[170:173], v[194:197], v[120:123]
	v_mfma_f32_16x16x32_bf16 v[108:111], v[162:165], v[202:205], v[108:111]
	v_mfma_f32_16x16x32_bf16 v[104:107], v[170:173], v[202:205], v[104:107]
	v_mfma_f32_16x16x32_bf16 v[92:95], v[162:165], v[210:213], v[92:95]
	v_mfma_f32_16x16x32_bf16 v[88:91], v[170:173], v[210:213], v[88:91]
	v_mfma_f32_16x16x32_bf16 v[76:79], v[162:165], v[218:221], v[76:79]
	v_mfma_f32_16x16x32_bf16 v[72:75], v[170:173], v[218:221], v[72:75]
	v_mfma_f32_16x16x32_bf16 v[116:119], v[174:177], v[190:193], v[116:119]
	v_mfma_f32_16x16x32_bf16 v[112:115], v[182:185], v[190:193], v[112:115]
	v_mfma_f32_16x16x32_bf16 v[100:103], v[174:177], v[198:201], v[100:103]
	v_mfma_f32_16x16x32_bf16 v[96:99], v[182:185], v[198:201], v[96:99]
	v_mfma_f32_16x16x32_bf16 v[84:87], v[174:177], v[206:209], v[84:87]
	v_mfma_f32_16x16x32_bf16 v[80:83], v[182:185], v[206:209], v[80:83]
	v_mfma_f32_16x16x32_bf16 v[68:71], v[174:177], v[214:217], v[68:71]
	v_mfma_f32_16x16x32_bf16 v[64:67], v[182:185], v[214:217], v[64:67]
	v_mfma_f32_16x16x32_bf16 v[116:119], v[178:181], v[194:197], v[116:119]
	v_mfma_f32_16x16x32_bf16 v[112:115], v[186:189], v[194:197], v[112:115]
	v_mfma_f32_16x16x32_bf16 v[100:103], v[178:181], v[202:205], v[100:103]
	v_mfma_f32_16x16x32_bf16 v[96:99], v[186:189], v[202:205], v[96:99]
	v_mfma_f32_16x16x32_bf16 v[84:87], v[178:181], v[210:213], v[84:87]
	v_mfma_f32_16x16x32_bf16 v[80:83], v[186:189], v[210:213], v[80:83]
	v_mfma_f32_16x16x32_bf16 v[68:71], v[178:181], v[218:221], v[68:71]
	v_mfma_f32_16x16x32_bf16 v[64:67], v[186:189], v[218:221], v[64:67]
	s_setprio 0
	s_barrier
	s_add_i32 s68, s62, s33
	v_lshl_add_u64 v[154:155], s[40:41], 0, v[132:133]
	s_mov_b32 m0, s68
	ds_read_b128 v[190:193], v160 offset:16384
	ds_read_b128 v[194:197], v160 offset:17408
	ds_read_b128 v[198:201], v160 offset:18432
	ds_read_b128 v[202:205], v160 offset:19456
	ds_read_b128 v[206:209], v160 offset:20480
	ds_read_b128 v[210:213], v160 offset:21504
	ds_read_b128 v[214:217], v160 offset:22528
	ds_read_b128 v[218:221], v160 offset:23552
	global_load_lds_dwordx4 v[154:155], off
	s_add_i32 m0, s68, 0x2000
	s_add_u32 s68, s40, 0x100000
	v_lshl_add_u64 v[222:223], s[40:41], 0, v[128:129]
	s_addc_u32 s69, s41, 0
	s_add_i32 s70, s63, s33
	global_load_lds_dwordx4 v[222:223], off
	v_lshl_add_u64 v[224:225], s[68:69], 0, v[132:133]
	s_mov_b32 m0, s70
	v_lshl_add_u64 v[226:227], s[84:85], 0, v[130:131]
	global_load_lds_dwordx4 v[224:225], off
	v_lshl_add_u64 v[224:225], s[68:69], 0, v[128:129]
	s_add_i32 m0, s70, 0x2000
	s_nop 0
	global_load_lds_dwordx4 v[224:225], off
	v_lshl_add_u64 v[224:225], s[84:85], 0, v[134:135]
	s_mov_b32 m0, s53
	s_nop 0
	global_load_lds_dwordx4 v[224:225], off
	s_mov_b32 m0, s54
	s_nop 0
	global_load_lds_dwordx4 v[226:227], off
	s_waitcnt vmcnt(8)
	s_waitcnt lgkmcnt(0)
	s_barrier
; #define PG8_STAGE(bufoff, gbase, voff) do { _Pragma("unroll") for (int _i = 0; _i < 2; ++_i) \
;         __builtin_amdgcn_global_load_lds((const unsigned*)((const char*)(gbase) + (voff)[_i]), (PG8_LAS unsigned*)(lds + (bufoff) + ldsw + _i * 8192), 16, 0, 0); } while (0)
; #define PG8_LDA(dst, b, h) do { _Pragma("unroll") for (int m = 0; m < 4; ++m) _Pragma("unroll") for (int k = 0; k < 2; ++k) dst[m][k] = *(const PG8_LAS bf16x8*)(lds + PG8_SA(b, h) + aoff + m * 2048 + k * 1024); } while (0)
; #define PG8_LDB(dst, b, h) do { _Pragma("unroll") for (int n = 0; n < 2; ++n) _Pragma("unroll") for (int k = 0; k < 2; ++k) dst[n][k] = *(const PG8_LAS bf16x8*)(lds + PG8_SB(b, h) + boff + n * 2048 + k * 1024); } while (0)
; #define PG8_MMA(ai, bj, At, Bt) do { __builtin_amdgcn_s_setprio(1); _Pragma("unroll") for (int m = 0; m < 4; ++m) _Pragma("unroll") for (int n = 0; n < 2; ++n) _Pragma("unroll") for (int k = 0; k < 2; ++k) \
;         acc[ai][bj][m][n] = __builtin_amdgcn_mfma_f32_16x16x32_bf16(Bt[n][k], At[m][k], acc[ai][bj][m][n], 0, 0, 0); __builtin_amdgcn_s_setprio(0); } while (0)
; #define PG8_WAIT_V(n) asm volatile("s_waitcnt vmcnt(" #n ")" ::: "memory")
; #define PG8_WAIT_L(n) asm volatile("s_waitcnt lgkmcnt(" #n ")" ::: "memory")
; #define PG8_BAR __builtin_amdgcn_s_barrier()
; #define PG8_SCHED __builtin_amdgcn_sched_barrier(0)
; template <class Epi, class Sched, bool ALIGN_EPI = false, bool SP2 = false>
; __device__ __forceinline__ void gemm_phase(PG8_LAS unsigned char* lds, const Gemm g, const Sched& S, const Epi& E) {
;     ...
;             PG8_WAIT_V(8); PG8_WAIT_L(0); PG8_BAR; PG8_MMA(1, 0, At, B0); PG8_MMA(1, 1, At, B1); PG8_BAR; PG8_SCHED;
;             PG8_LDB(B0, 1, 0); PG8_LDB(B1, 1, 1); PG8_SCHED; PG8_LDA(At, 1, 0); PG8_STAGE(PG8_SA(0, 1), a2 + hstepA, voffA);
;             PG8_WAIT_V(8); PG8_WAIT_L(0); PG8_BAR; PG8_MMA(0, 0, At, B0); PG8_MMA(0, 1, At, B1); PG8_BAR; PG8_SCHED;
	s_setprio 1
	s_waitcnt lgkmcnt(0)
	v_mfma_f32_16x16x32_bf16 v[60:63], v[150:153], v[190:193], v[60:63]
	v_mfma_f32_16x16x32_bf16 v[56:59], v[166:169], v[190:193], v[56:59]
	v_mfma_f32_16x16x32_bf16 v[44:47], v[150:153], v[198:201], v[44:47]
	v_mfma_f32_16x16x32_bf16 v[40:43], v[166:169], v[198:201], v[40:43]
	v_mfma_f32_16x16x32_bf16 v[28:31], v[150:153], v[206:209], v[28:31]
	v_mfma_f32_16x16x32_bf16 v[24:27], v[166:169], v[206:209], v[24:27]
	v_mfma_f32_16x16x32_bf16 v[12:15], v[150:153], v[214:217], v[12:15]
	v_mfma_f32_16x16x32_bf16 v[8:11], v[166:169], v[214:217], v[8:11]
	v_mfma_f32_16x16x32_bf16 v[60:63], v[162:165], v[194:197], v[60:63]
	v_mfma_f32_16x16x32_bf16 v[56:59], v[170:173], v[194:197], v[56:59]
	v_mfma_f32_16x16x32_bf16 v[44:47], v[162:165], v[202:205], v[44:47]
	v_mfma_f32_16x16x32_bf16 v[40:43], v[170:173], v[202:205], v[40:43]
	v_mfma_f32_16x16x32_bf16 v[28:31], v[162:165], v[210:213], v[28:31]
	v_mfma_f32_16x16x32_bf16 v[24:27], v[170:173], v[210:213], v[24:27]
	v_mfma_f32_16x16x32_bf16 v[12:15], v[162:165], v[218:221], v[12:15]
	v_mfma_f32_16x16x32_bf16 v[8:11], v[170:173], v[218:221], v[8:11]
	v_mfma_f32_16x16x32_bf16 v[52:55], v[174:177], v[190:193], v[52:55]
	v_mfma_f32_16x16x32_bf16 v[48:51], v[182:185], v[190:193], v[48:51]
	v_mfma_f32_16x16x32_bf16 v[36:39], v[174:177], v[198:201], v[36:39]
	v_mfma_f32_16x16x32_bf16 v[32:35], v[182:185], v[198:201], v[32:35]
	v_mfma_f32_16x16x32_bf16 v[20:23], v[174:177], v[206:209], v[20:23]
	v_mfma_f32_16x16x32_bf16 v[16:19], v[182:185], v[206:209], v[16:19]
	v_mfma_f32_16x16x32_bf16 v[4:7], v[174:177], v[214:217], v[4:7]
	v_mfma_f32_16x16x32_bf16 v[0:3], v[182:185], v[214:217], v[0:3]
	v_mfma_f32_16x16x32_bf16 v[52:55], v[178:181], v[194:197], v[52:55]
	v_mfma_f32_16x16x32_bf16 v[48:51], v[186:189], v[194:197], v[48:51]
	v_mfma_f32_16x16x32_bf16 v[36:39], v[178:181], v[202:205], v[36:39]
	v_mfma_f32_16x16x32_bf16 v[32:35], v[186:189], v[202:205], v[32:35]
	v_mfma_f32_16x16x32_bf16 v[20:23], v[178:181], v[210:213], v[20:23]
	v_mfma_f32_16x16x32_bf16 v[16:19], v[186:189], v[210:213], v[16:19]
	v_mfma_f32_16x16x32_bf16 v[4:7], v[178:181], v[218:221], v[4:7]
	v_mfma_f32_16x16x32_bf16 v[0:3], v[186:189], v[218:221], v[0:3]
	s_setprio 0
	s_barrier
	s_add_i32 s70, 0, 0x18000
	v_add_u32_e32 v136, s70, v157
	s_add_i32 s71, 0, 0x1c000
	ds_read_b128 v[150:153], v136
	ds_read_b128 v[162:165], v136 offset:1024
	ds_read_b128 v[166:169], v136 offset:2048
	ds_read_b128 v[170:173], v136 offset:3072
	v_add_u32_e32 v136, s71, v157
	ds_read_b128 v[174:177], v136
	ds_read_b128 v[178:181], v136 offset:1024
	ds_read_b128 v[182:185], v136 offset:2048
	ds_read_b128 v[186:189], v136 offset:3072
	s_add_u32 s68, s84, 0x100000
	s_addc_u32 s69, s85, 0
	s_mov_b32 m0, s55
	v_lshl_add_u64 v[228:229], s[68:69], 0, v[134:135]
	ds_read_b128 v[190:193], v160 offset:32768
	ds_read_b128 v[194:197], v160 offset:33792
	ds_read_b128 v[198:201], v160 offset:34816
	ds_read_b128 v[202:205], v160 offset:35840
	ds_read_b128 v[206:209], v160 offset:36864
	ds_read_b128 v[210:213], v160 offset:37888
	ds_read_b128 v[214:217], v160 offset:38912
	ds_read_b128 v[218:221], v160 offset:39936
	global_load_lds_dwordx4 v[228:229], off
	v_lshl_add_u64 v[228:229], s[68:69], 0, v[130:131]
	s_mov_b32 m0, s56
	s_nop 0
	global_load_lds_dwordx4 v[228:229], off
	s_waitcnt vmcnt(8)
	s_waitcnt lgkmcnt(0)
	s_barrier
	s_setprio 1
	s_waitcnt lgkmcnt(0)
	v_mfma_f32_16x16x32_bf16 v[124:127], v[150:153], v[190:193], v[124:127]
	v_mfma_f32_16x16x32_bf16 v[120:123], v[166:169], v[190:193], v[120:123]
	v_mfma_f32_16x16x32_bf16 v[108:111], v[150:153], v[198:201], v[108:111]
	v_mfma_f32_16x16x32_bf16 v[104:107], v[166:169], v[198:201], v[104:107]
	v_mfma_f32_16x16x32_bf16 v[92:95], v[150:153], v[206:209], v[92:95]
	v_mfma_f32_16x16x32_bf16 v[88:91], v[166:169], v[206:209], v[88:91]
	v_mfma_f32_16x16x32_bf16 v[76:79], v[150:153], v[214:217], v[76:79]
	v_mfma_f32_16x16x32_bf16 v[72:75], v[166:169], v[214:217], v[72:75]
	v_mfma_f32_16x16x32_bf16 v[124:127], v[162:165], v[194:197], v[124:127]
	v_mfma_f32_16x16x32_bf16 v[120:123], v[170:173], v[194:197], v[120:123]
	v_mfma_f32_16x16x32_bf16 v[108:111], v[162:165], v[202:205], v[108:111]
	v_mfma_f32_16x16x32_bf16 v[104:107], v[170:173], v[202:205], v[104:107]
	v_mfma_f32_16x16x32_bf16 v[92:95], v[162:165], v[210:213], v[92:95]
	v_mfma_f32_16x16x32_bf16 v[88:91], v[170:173], v[210:213], v[88:91]
	v_mfma_f32_16x16x32_bf16 v[76:79], v[162:165], v[218:221], v[76:79]
	v_mfma_f32_16x16x32_bf16 v[72:75], v[170:173], v[218:221], v[72:75]
	v_mfma_f32_16x16x32_bf16 v[116:119], v[174:177], v[190:193], v[116:119]
	v_mfma_f32_16x16x32_bf16 v[112:115], v[182:185], v[190:193], v[112:115]
	v_mfma_f32_16x16x32_bf16 v[100:103], v[174:177], v[198:201], v[100:103]
	v_mfma_f32_16x16x32_bf16 v[96:99], v[182:185], v[198:201], v[96:99]
	v_mfma_f32_16x16x32_bf16 v[84:87], v[174:177], v[206:209], v[84:87]
	v_mfma_f32_16x16x32_bf16 v[80:83], v[182:185], v[206:209], v[80:83]
	v_mfma_f32_16x16x32_bf16 v[68:71], v[174:177], v[214:217], v[68:71]
	v_mfma_f32_16x16x32_bf16 v[64:67], v[182:185], v[214:217], v[64:67]
	v_mfma_f32_16x16x32_bf16 v[116:119], v[178:181], v[194:197], v[116:119]
	v_mfma_f32_16x16x32_bf16 v[112:115], v[186:189], v[194:197], v[112:115]
	v_mfma_f32_16x16x32_bf16 v[100:103], v[178:181], v[202:205], v[100:103]
	v_mfma_f32_16x16x32_bf16 v[96:99], v[186:189], v[202:205], v[96:99]
	v_mfma_f32_16x16x32_bf16 v[84:87], v[178:181], v[210:213], v[84:87]
	v_mfma_f32_16x16x32_bf16 v[80:83], v[186:189], v[210:213], v[80:83]
	v_mfma_f32_16x16x32_bf16 v[68:71], v[178:181], v[218:221], v[68:71]
	v_mfma_f32_16x16x32_bf16 v[64:67], v[186:189], v[218:221], v[64:67]
	s_setprio 0
	s_barrier
; #define PG8_STAGE(bufoff, gbase, voff) do { _Pragma("unroll") for (int _i = 0; _i < 2; ++_i) \
;         __builtin_amdgcn_global_load_lds((const unsigned*)((const char*)(gbase) + (voff)[_i]), (PG8_LAS unsigned*)(lds + (bufoff) + ldsw + _i * 8192), 16, 0, 0); } while (0)
; #define PG8_LDA(dst, b, h) do { _Pragma("unroll") for (int m = 0; m < 4; ++m) _Pragma("unroll") for (int k = 0; k < 2; ++k) dst[m][k] = *(const PG8_LAS bf16x8*)(lds + PG8_SA(b, h) + aoff + m * 2048 + k * 1024); } while (0)
; #define PG8_MMA(ai, bj, At, Bt) do { __builtin_amdgcn_s_setprio(1); _Pragma("unroll") for (int m = 0; m < 4; ++m) _Pragma("unroll") for (int n = 0; n < 2; ++n) _Pragma("unroll") for (int k = 0; k < 2; ++k) \
;         acc[ai][bj][m][n] = __builtin_amdgcn_mfma_f32_16x16x32_bf16(Bt[n][k], At[m][k], acc[ai][bj][m][n], 0, 0, 0); __builtin_amdgcn_s_setprio(0); } while (0)
; #define PG8_WAIT_V(n) asm volatile("s_waitcnt vmcnt(" #n ")" ::: "memory")
; #define PG8_WAIT_L(n) asm volatile("s_waitcnt lgkmcnt(" #n ")" ::: "memory")
; #define PG8_BAR __builtin_amdgcn_s_barrier()
; #define PG8_SCHED __builtin_amdgcn_sched_barrier(0)
; template <class Epi, class Sched, bool ALIGN_EPI = false, bool SP2 = false>
; __device__ __forceinline__ void gemm_phase(PG8_LAS unsigned char* lds, const Gemm g, const Sched& S, const Epi& E) {
;     ...
;             PG8_LDA(At, 1, 1); PG8_STAGE(PG8_SB(1, 0), b3, voffB); PG8_STAGE(PG8_SB(1, 1), b3 + hstep, voffB); PG8_STAGE(PG8_SA(1, 0), a3, voffA);
;             PG8_WAIT_V(8); PG8_WAIT_L(0); PG8_BAR; PG8_MMA(1, 0, At, B0); PG8_MMA(1, 1, At, B1); PG8_BAR; PG8_SCHED;
	s_add_i32 s68, s70, s33
	v_lshl_add_u64 v[154:155], v[154:155], 0, s[12:13]
	s_mov_b32 m0, s68
	ds_read_b128 v[190:193], v160 offset:49152
	ds_read_b128 v[194:197], v160 offset:50176
	ds_read_b128 v[198:201], v160 offset:51200
	ds_read_b128 v[202:205], v160 offset:52224
	ds_read_b128 v[206:209], v160 offset:53248
	ds_read_b128 v[210:213], v160 offset:54272
	ds_read_b128 v[214:217], v160 offset:55296
	ds_read_b128 v[218:221], v160 offset:56320
	global_load_lds_dwordx4 v[154:155], off
	s_add_i32 m0, s68, 0x2000
	s_add_u32 s40, s40, 0x100080
	v_lshl_add_u64 v[154:155], v[222:223], 0, s[12:13]
	s_addc_u32 s41, s41, 0
	s_add_i32 s68, s71, s33
	global_load_lds_dwordx4 v[154:155], off
	v_lshl_add_u64 v[154:155], s[40:41], 0, v[132:133]
	s_mov_b32 m0, s68
	s_nop 0
	global_load_lds_dwordx4 v[154:155], off
	v_lshl_add_u64 v[154:155], s[40:41], 0, v[128:129]
	s_add_i32 m0, s68, 0x2000
	s_nop 0
	global_load_lds_dwordx4 v[154:155], off
	v_lshl_add_u64 v[154:155], v[224:225], 0, s[12:13]
	s_mov_b32 m0, s60
	s_nop 0
	global_load_lds_dwordx4 v[154:155], off
	v_lshl_add_u64 v[154:155], v[226:227], 0, s[12:13]
	s_mov_b32 m0, s61
	s_nop 0
	global_load_lds_dwordx4 v[154:155], off
	s_waitcnt vmcnt(8)
	s_waitcnt lgkmcnt(0)
	s_barrier
	s_setprio 1
	s_waitcnt lgkmcnt(0)
	v_mfma_f32_16x16x32_bf16 v[60:63], v[150:153], v[190:193], v[60:63]
	v_mfma_f32_16x16x32_bf16 v[56:59], v[166:169], v[190:193], v[56:59]
	v_mfma_f32_16x16x32_bf16 v[44:47], v[150:153], v[198:201], v[44:47]
	v_mfma_f32_16x16x32_bf16 v[40:43], v[166:169], v[198:201], v[40:43]
	v_mfma_f32_16x16x32_bf16 v[28:31], v[150:153], v[206:209], v[28:31]
	v_mfma_f32_16x16x32_bf16 v[24:27], v[166:169], v[206:209], v[24:27]
	v_mfma_f32_16x16x32_bf16 v[12:15], v[150:153], v[214:217], v[12:15]
	v_mfma_f32_16x16x32_bf16 v[8:11], v[166:169], v[214:217], v[8:11]
	v_mfma_f32_16x16x32_bf16 v[60:63], v[162:165], v[194:197], v[60:63]
	v_mfma_f32_16x16x32_bf16 v[56:59], v[170:173], v[194:197], v[56:59]
	v_mfma_f32_16x16x32_bf16 v[44:47], v[162:165], v[202:205], v[44:47]
	v_mfma_f32_16x16x32_bf16 v[40:43], v[170:173], v[202:205], v[40:43]
	v_mfma_f32_16x16x32_bf16 v[28:31], v[162:165], v[210:213], v[28:31]
	v_mfma_f32_16x16x32_bf16 v[24:27], v[170:173], v[210:213], v[24:27]
	v_mfma_f32_16x16x32_bf16 v[12:15], v[162:165], v[218:221], v[12:15]
	v_mfma_f32_16x16x32_bf16 v[8:11], v[170:173], v[218:221], v[8:11]
	v_mfma_f32_16x16x32_bf16 v[52:55], v[174:177], v[190:193], v[52:55]
	v_mfma_f32_16x16x32_bf16 v[48:51], v[182:185], v[190:193], v[48:51]
	v_mfma_f32_16x16x32_bf16 v[36:39], v[174:177], v[198:201], v[36:39]
	v_mfma_f32_16x16x32_bf16 v[32:35], v[182:185], v[198:201], v[32:35]
	v_mfma_f32_16x16x32_bf16 v[20:23], v[174:177], v[206:209], v[20:23]
	v_mfma_f32_16x16x32_bf16 v[16:19], v[182:185], v[206:209], v[16:19]
	v_mfma_f32_16x16x32_bf16 v[4:7], v[174:177], v[214:217], v[4:7]
	v_mfma_f32_16x16x32_bf16 v[0:3], v[182:185], v[214:217], v[0:3]
	v_mfma_f32_16x16x32_bf16 v[52:55], v[178:181], v[194:197], v[52:55]
	v_mfma_f32_16x16x32_bf16 v[48:51], v[186:189], v[194:197], v[48:51]
	v_mfma_f32_16x16x32_bf16 v[36:39], v[178:181], v[202:205], v[36:39]
	v_mfma_f32_16x16x32_bf16 v[32:35], v[186:189], v[202:205], v[32:35]
	v_mfma_f32_16x16x32_bf16 v[20:23], v[178:181], v[210:213], v[20:23]
	v_mfma_f32_16x16x32_bf16 v[16:19], v[186:189], v[210:213], v[16:19]
	v_mfma_f32_16x16x32_bf16 v[4:7], v[178:181], v[218:221], v[4:7]
	v_mfma_f32_16x16x32_bf16 v[0:3], v[186:189], v[218:221], v[0:3]
	s_setprio 0
	s_barrier
	s_add_i32 s67, s67, 2
	s_add_u32 s34, s34, 0x100
	s_addc_u32 s35, s35, 0
	s_add_u32 s65, s65, 0x100
	s_addc_u32 s66, s66, 0
	s_cmp_gt_u32 s67, 61
	s_cbranch_scc0 .LBB0_1741
	s_and_b64 vcc, exec, s[14:15]
	s_cbranch_vccz .LBB0_1744
	s_barrier

; #define PG8_STAGE(bufoff, gbase, voff) do { _Pragma("unroll") for (int _i = 0; _i < 2; ++_i) \
;         __builtin_amdgcn_global_load_lds((const unsigned*)((const char*)(gbase) + (voff)[_i]), (PG8_LAS unsigned*)(lds + (bufoff) + ldsw + _i * 8192), 16, 0, 0); } while (0)
; #define PG8_LDA(dst, b, h) do { _Pragma("unroll") for (int m = 0; m < 4; ++m) _Pragma("unroll") for (int k = 0; k < 2; ++k) dst[m][k] = *(const PG8_LAS bf16x8*)(lds + PG8_SA(b, h) + aoff + m * 2048 + k * 1024); } while (0)
; #define PG8_LDB(dst, b, h) do { _Pragma("unroll") for (int n = 0; n < 2; ++n) _Pragma("unroll") for (int k = 0; k < 2; ++k) dst[n][k] = *(const PG8_LAS bf16x8*)(lds + PG8_SB(b, h) + boff + n * 2048 + k * 1024); } while (0)
; #define PG8_MMA(ai, bj, At, Bt) do { __builtin_amdgcn_s_setprio(1); _Pragma("unroll") for (int m = 0; m < 4; ++m) _Pragma("unroll") for (int n = 0; n < 2; ++n) _Pragma("unroll") for (int k = 0; k < 2; ++k) \
;         acc[ai][bj][m][n] = __builtin_amdgcn_mfma_f32_16x16x32_bf16(Bt[n][k], At[m][k], acc[ai][bj][m][n], 0, 0, 0); __builtin_amdgcn_s_setprio(0); } while (0)
; #define PG8_WAIT_V(n) asm volatile("s_waitcnt vmcnt(" #n ")" ::: "memory")
; #define PG8_BAR __builtin_amdgcn_s_barrier()
; template <class Epi, class Sched, bool ALIGN_EPI = false, bool SP2 = false>
; __device__ __forceinline__ void gemm_phase(PG8_LAS unsigned char* lds, const Gemm g, const Sched& S, const Epi& E) {
;     ...
;         for (int t = 0; t < nt; t += 2) {
;             const bool last = (t == nt - 2);
;             const char* a1 = cA + (size_t)(t + 1) * kstepA;
;             const char* a2 = last ? nA : cA + (size_t)(t + 2) * kstepA; const char* b2 = last ? nB : cB + (size_t)(t + 2) * kstep;
;             const char* a3 = a2 + kstepA; const char* b3 = b2 + kstep;
;             if (last && has_next) S.a_ready(nxt);
;             if constexpr (SP2) {
;             PG8_LDB(B0, 0, 0); PG8_LDB(B1, 0, 1); PG8_SCHED; PG8_LDA(At, 0, 0); PG8_STAGE(PG8_SA(1, 1), a1 + hstepA, voffA);
;             PG8_WAIT_V(8); PG8_WAIT_L(0); PG8_BAR; PG8_MMA(0, 0, At, B0); PG8_MMA(0, 1, At, B1); PG8_BAR; PG8_SCHED;
;             PG8_LDA(At, 0, 1); PG8_STAGE(PG8_SB(0, 0), b2, voffB); PG8_STAGE(PG8_SB(0, 1), b2 + hstep, voffB); PG8_STAGE(PG8_SA(0, 0), a2, voffA);
;             PG8_WAIT_V(8); PG8_WAIT_L(0); PG8_BAR; PG8_MMA(1, 0, At, B0); PG8_MMA(1, 1, At, B1); PG8_BAR; PG8_SCHED;
.LBB0_2770:
	ds_read_b128 v[144:147], v153
	ds_read_b128 v[158:161], v153 offset:1024
	ds_read_b128 v[162:165], v153 offset:2048
	ds_read_b128 v[166:169], v153 offset:3072
	ds_read_b128 v[170:173], v154
	ds_read_b128 v[174:177], v154 offset:1024
	ds_read_b128 v[178:181], v154 offset:2048
	ds_read_b128 v[182:185], v154 offset:3072
	s_add_u32 s48, s46, 0xfff00080
	s_addc_u32 s49, s47, -1
	s_cmp_eq_u32 s69, 60
	s_cselect_b32 s51, s31, s49
	s_cselect_b32 s50, s43, s48
	s_cselect_b32 s49, s27, s68
	s_cselect_b32 s48, s66, s67
	v_lshl_add_u64 v[148:149], s[46:47], 0, v[136:137]
	s_add_i32 m0, s45, 0xc000
	ds_read_b128 v[186:189], v155
	ds_read_b128 v[190:193], v155 offset:1024
	ds_read_b128 v[194:197], v155 offset:2048
	ds_read_b128 v[198:201], v155 offset:3072
	ds_read_b128 v[202:205], v155 offset:4096
	ds_read_b128 v[206:209], v155 offset:5120
	ds_read_b128 v[210:213], v155 offset:6144
	ds_read_b128 v[214:217], v155 offset:7168
	global_load_lds_dwordx4 v[148:149], off
	v_lshl_add_u64 v[148:149], s[46:47], 0, v[138:139]
	s_add_i32 m0, s45, 0xe000
	s_nop 0
	global_load_lds_dwordx4 v[148:149], off
	s_waitcnt vmcnt(8)
	s_waitcnt lgkmcnt(0)
	s_barrier
	s_setprio 1
	s_waitcnt lgkmcnt(0)
	v_mfma_f32_16x16x32_bf16 v[124:127], v[144:147], v[186:189], v[124:127]
	v_mfma_f32_16x16x32_bf16 v[120:123], v[162:165], v[186:189], v[120:123]
	v_mfma_f32_16x16x32_bf16 v[108:111], v[144:147], v[194:197], v[108:111]
	v_mfma_f32_16x16x32_bf16 v[104:107], v[162:165], v[194:197], v[104:107]
	v_mfma_f32_16x16x32_bf16 v[92:95], v[144:147], v[202:205], v[92:95]
	v_mfma_f32_16x16x32_bf16 v[88:91], v[162:165], v[202:205], v[88:91]
	v_mfma_f32_16x16x32_bf16 v[76:79], v[144:147], v[210:213], v[76:79]
	v_mfma_f32_16x16x32_bf16 v[72:75], v[162:165], v[210:213], v[72:75]
	v_mfma_f32_16x16x32_bf16 v[124:127], v[158:161], v[190:193], v[124:127]
	v_mfma_f32_16x16x32_bf16 v[120:123], v[166:169], v[190:193], v[120:123]
	v_mfma_f32_16x16x32_bf16 v[108:111], v[158:161], v[198:201], v[108:111]
	v_mfma_f32_16x16x32_bf16 v[104:107], v[166:169], v[198:201], v[104:107]
	v_mfma_f32_16x16x32_bf16 v[92:95], v[158:161], v[206:209], v[92:95]
	v_mfma_f32_16x16x32_bf16 v[88:91], v[166:169], v[206:209], v[88:91]
	v_mfma_f32_16x16x32_bf16 v[76:79], v[158:161], v[214:217], v[76:79]
	v_mfma_f32_16x16x32_bf16 v[72:75], v[166:169], v[214:217], v[72:75]
	v_mfma_f32_16x16x32_bf16 v[116:119], v[170:173], v[186:189], v[116:119]
	v_mfma_f32_16x16x32_bf16 v[112:115], v[178:181], v[186:189], v[112:115]
	v_mfma_f32_16x16x32_bf16 v[100:103], v[170:173], v[194:197], v[100:103]
	v_mfma_f32_16x16x32_bf16 v[96:99], v[178:181], v[194:197], v[96:99]
	v_mfma_f32_16x16x32_bf16 v[84:87], v[170:173], v[202:205], v[84:87]
	v_mfma_f32_16x16x32_bf16 v[80:83], v[178:181], v[202:205], v[80:83]
	v_mfma_f32_16x16x32_bf16 v[68:71], v[170:173], v[210:213], v[68:71]
	v_mfma_f32_16x16x32_bf16 v[64:67], v[178:181], v[210:213], v[64:67]
	v_mfma_f32_16x16x32_bf16 v[116:119], v[174:177], v[190:193], v[116:119]
	v_mfma_f32_16x16x32_bf16 v[112:115], v[182:185], v[190:193], v[112:115]
	v_mfma_f32_16x16x32_bf16 v[100:103], v[174:177], v[198:201], v[100:103]
	v_mfma_f32_16x16x32_bf16 v[96:99], v[182:185], v[198:201], v[96:99]
	v_mfma_f32_16x16x32_bf16 v[84:87], v[174:177], v[206:209], v[84:87]
	v_mfma_f32_16x16x32_bf16 v[80:83], v[182:185], v[206:209], v[80:83]
	v_mfma_f32_16x16x32_bf16 v[68:71], v[174:177], v[214:217], v[68:71]
	v_mfma_f32_16x16x32_bf16 v[64:67], v[182:185], v[214:217], v[64:67]
	s_setprio 0
	s_barrier
	s_add_i32 s70, s60, s33
	v_lshl_add_u64 v[148:149], s[48:49], 0, v[130:131]
	s_mov_b32 m0, s70
	ds_read_b128 v[186:189], v155 offset:16384
	ds_read_b128 v[190:193], v155 offset:17408
	ds_read_b128 v[194:197], v155 offset:18432
	ds_read_b128 v[198:201], v155 offset:19456
	ds_read_b128 v[202:205], v155 offset:20480
	ds_read_b128 v[206:209], v155 offset:21504
	ds_read_b128 v[210:213], v155 offset:22528
	ds_read_b128 v[214:217], v155 offset:23552
	global_load_lds_dwordx4 v[148:149], off
	s_add_i32 m0, s70, 0x2000
	s_add_u32 s70, s48, 0x100000
	v_lshl_add_u64 v[218:219], s[48:49], 0, v[134:135]
	s_addc_u32 s71, s49, 0
	s_add_i32 s72, s61, s33
	global_load_lds_dwordx4 v[218:219], off
	v_lshl_add_u64 v[220:221], s[70:71], 0, v[130:131]
	s_mov_b32 m0, s72
	v_lshl_add_u64 v[222:223], s[50:51], 0, v[132:133]
	global_load_lds_dwordx4 v[220:221], off
	v_lshl_add_u64 v[220:221], s[70:71], 0, v[134:135]
	s_add_i32 m0, s72, 0x2000
	s_nop 0
	global_load_lds_dwordx4 v[220:221], off
	v_lshl_add_u64 v[220:221], s[50:51], 0, v[128:129]
	s_mov_b32 m0, s45
	s_nop 0
	global_load_lds_dwordx4 v[220:221], off
	s_mov_b32 m0, s52
	s_nop 0
	global_load_lds_dwordx4 v[222:223], off
	s_waitcnt vmcnt(8)
	s_waitcnt lgkmcnt(0)
	s_barrier
; #define PG8_STAGE(bufoff, gbase, voff) do { _Pragma("unroll") for (int _i = 0; _i < 2; ++_i) \
;         __builtin_amdgcn_global_load_lds((const unsigned*)((const char*)(gbase) + (voff)[_i]), (PG8_LAS unsigned*)(lds + (bufoff) + ldsw + _i * 8192), 16, 0, 0); } while (0)
; #define PG8_LDA(dst, b, h) do { _Pragma("unroll") for (int m = 0; m < 4; ++m) _Pragma("unroll") for (int k = 0; k < 2; ++k) dst[m][k] = *(const PG8_LAS bf16x8*)(lds + PG8_SA(b, h) + aoff + m * 2048 + k * 1024); } while (0)
; #define PG8_LDB(dst, b, h) do { _Pragma("unroll") for (int n = 0; n < 2; ++n) _Pragma("unroll") for (int k = 0; k < 2; ++k) dst[n][k] = *(const PG8_LAS bf16x8*)(lds + PG8_SB(b, h) + boff + n * 2048 + k * 1024); } while (0)
; #define PG8_MMA(ai, bj, At, Bt) do { __builtin_amdgcn_s_setprio(1); _Pragma("unroll") for (int m = 0; m < 4; ++m) _Pragma("unroll") for (int n = 0; n < 2; ++n) _Pragma("unroll") for (int k = 0; k < 2; ++k) \
;         acc[ai][bj][m][n] = __builtin_amdgcn_mfma_f32_16x16x32_bf16(Bt[n][k], At[m][k], acc[ai][bj][m][n], 0, 0, 0); __builtin_amdgcn_s_setprio(0); } while (0)
; #define PG8_WAIT_V(n) asm volatile("s_waitcnt vmcnt(" #n ")" ::: "memory")
; #define PG8_WAIT_L(n) asm volatile("s_waitcnt lgkmcnt(" #n ")" ::: "memory")
; #define PG8_BAR __builtin_amdgcn_s_barrier()
; #define PG8_SCHED __builtin_amdgcn_sched_barrier(0)
; template <class Epi, class Sched, bool ALIGN_EPI = false, bool SP2 = false>
; __device__ __forceinline__ void gemm_phase(PG8_LAS unsigned char* lds, const Gemm g, const Sched& S, const Epi& E) {
;     ...
;             PG8_WAIT_V(8); PG8_WAIT_L(0); PG8_BAR; PG8_MMA(1, 0, At, B0); PG8_MMA(1, 1, At, B1); PG8_BAR; PG8_SCHED;
;             PG8_LDB(B0, 1, 0); PG8_LDB(B1, 1, 1); PG8_SCHED; PG8_LDA(At, 1, 0); PG8_STAGE(PG8_SA(0, 1), a2 + hstepA, voffA);
;             PG8_WAIT_V(8); PG8_WAIT_L(0); PG8_BAR; PG8_MMA(0, 0, At, B0); PG8_MMA(0, 1, At, B1); PG8_BAR; PG8_SCHED;
	s_setprio 1
	s_waitcnt lgkmcnt(0)
	v_mfma_f32_16x16x32_bf16 v[60:63], v[144:147], v[186:189], v[60:63]
	v_mfma_f32_16x16x32_bf16 v[56:59], v[162:165], v[186:189], v[56:59]
	v_mfma_f32_16x16x32_bf16 v[44:47], v[144:147], v[194:197], v[44:47]
	v_mfma_f32_16x16x32_bf16 v[40:43], v[162:165], v[194:197], v[40:43]
	v_mfma_f32_16x16x32_bf16 v[28:31], v[144:147], v[202:205], v[28:31]
	v_mfma_f32_16x16x32_bf16 v[24:27], v[162:165], v[202:205], v[24:27]
	v_mfma_f32_16x16x32_bf16 v[12:15], v[144:147], v[210:213], v[12:15]
	v_mfma_f32_16x16x32_bf16 v[8:11], v[162:165], v[210:213], v[8:11]
	v_mfma_f32_16x16x32_bf16 v[60:63], v[158:161], v[190:193], v[60:63]
	v_mfma_f32_16x16x32_bf16 v[56:59], v[166:169], v[190:193], v[56:59]
	v_mfma_f32_16x16x32_bf16 v[44:47], v[158:161], v[198:201], v[44:47]
	v_mfma_f32_16x16x32_bf16 v[40:43], v[166:169], v[198:201], v[40:43]
	v_mfma_f32_16x16x32_bf16 v[28:31], v[158:161], v[206:209], v[28:31]
	v_mfma_f32_16x16x32_bf16 v[24:27], v[166:169], v[206:209], v[24:27]
	v_mfma_f32_16x16x32_bf16 v[12:15], v[158:161], v[214:217], v[12:15]
	v_mfma_f32_16x16x32_bf16 v[8:11], v[166:169], v[214:217], v[8:11]
	v_mfma_f32_16x16x32_bf16 v[52:55], v[170:173], v[186:189], v[52:55]
	v_mfma_f32_16x16x32_bf16 v[48:51], v[178:181], v[186:189], v[48:51]
	v_mfma_f32_16x16x32_bf16 v[36:39], v[170:173], v[194:197], v[36:39]
	v_mfma_f32_16x16x32_bf16 v[32:35], v[178:181], v[194:197], v[32:35]
	v_mfma_f32_16x16x32_bf16 v[20:23], v[170:173], v[202:205], v[20:23]
	v_mfma_f32_16x16x32_bf16 v[16:19], v[178:181], v[202:205], v[16:19]
	v_mfma_f32_16x16x32_bf16 v[4:7], v[170:173], v[210:213], v[4:7]
	v_mfma_f32_16x16x32_bf16 v[0:3], v[178:181], v[210:213], v[0:3]
	v_mfma_f32_16x16x32_bf16 v[52:55], v[174:177], v[190:193], v[52:55]
	v_mfma_f32_16x16x32_bf16 v[48:51], v[182:185], v[190:193], v[48:51]
	v_mfma_f32_16x16x32_bf16 v[36:39], v[174:177], v[198:201], v[36:39]
	v_mfma_f32_16x16x32_bf16 v[32:35], v[182:185], v[198:201], v[32:35]
	v_mfma_f32_16x16x32_bf16 v[20:23], v[174:177], v[206:209], v[20:23]
	v_mfma_f32_16x16x32_bf16 v[16:19], v[182:185], v[206:209], v[16:19]
	v_mfma_f32_16x16x32_bf16 v[4:7], v[174:177], v[214:217], v[4:7]
	v_mfma_f32_16x16x32_bf16 v[0:3], v[182:185], v[214:217], v[0:3]
	s_setprio 0
	s_barrier
	s_add_i32 s70, 0, 0x18000
	v_add_u32_e32 v157, s70, v151
	s_add_i32 s71, 0, 0x1c000
	ds_read_b128 v[144:147], v157
	ds_read_b128 v[158:161], v157 offset:1024
	ds_read_b128 v[162:165], v157 offset:2048
	ds_read_b128 v[166:169], v157 offset:3072
	v_add_u32_e32 v157, s71, v151
	ds_read_b128 v[170:173], v157
	ds_read_b128 v[174:177], v157 offset:1024
	ds_read_b128 v[178:181], v157 offset:2048
	ds_read_b128 v[182:185], v157 offset:3072
	s_add_u32 s50, s50, 0x100000
	s_addc_u32 s51, s51, 0
	s_mov_b32 m0, s53
	v_lshl_add_u64 v[224:225], s[50:51], 0, v[128:129]
	ds_read_b128 v[186:189], v155 offset:32768
	ds_read_b128 v[190:193], v155 offset:33792
	ds_read_b128 v[194:197], v155 offset:34816
	ds_read_b128 v[198:201], v155 offset:35840
	ds_read_b128 v[202:205], v155 offset:36864
	ds_read_b128 v[206:209], v155 offset:37888
	ds_read_b128 v[210:213], v155 offset:38912
	ds_read_b128 v[214:217], v155 offset:39936
	global_load_lds_dwordx4 v[224:225], off
	v_lshl_add_u64 v[224:225], s[50:51], 0, v[132:133]
	s_mov_b32 m0, s54
	s_nop 0
	global_load_lds_dwordx4 v[224:225], off
	s_waitcnt vmcnt(8)
	s_waitcnt lgkmcnt(0)
	s_barrier
	s_setprio 1
	s_waitcnt lgkmcnt(0)
	v_mfma_f32_16x16x32_bf16 v[124:127], v[144:147], v[186:189], v[124:127]
	v_mfma_f32_16x16x32_bf16 v[120:123], v[162:165], v[186:189], v[120:123]
	v_mfma_f32_16x16x32_bf16 v[108:111], v[144:147], v[194:197], v[108:111]
	v_mfma_f32_16x16x32_bf16 v[104:107], v[162:165], v[194:197], v[104:107]
	v_mfma_f32_16x16x32_bf16 v[92:95], v[144:147], v[202:205], v[92:95]
	v_mfma_f32_16x16x32_bf16 v[88:91], v[162:165], v[202:205], v[88:91]
	v_mfma_f32_16x16x32_bf16 v[76:79], v[144:147], v[210:213], v[76:79]
	v_mfma_f32_16x16x32_bf16 v[72:75], v[162:165], v[210:213], v[72:75]
	v_mfma_f32_16x16x32_bf16 v[124:127], v[158:161], v[190:193], v[124:127]
	v_mfma_f32_16x16x32_bf16 v[120:123], v[166:169], v[190:193], v[120:123]
	v_mfma_f32_16x16x32_bf16 v[108:111], v[158:161], v[198:201], v[108:111]
	v_mfma_f32_16x16x32_bf16 v[104:107], v[166:169], v[198:201], v[104:107]
	v_mfma_f32_16x16x32_bf16 v[92:95], v[158:161], v[206:209], v[92:95]
	v_mfma_f32_16x16x32_bf16 v[88:91], v[166:169], v[206:209], v[88:91]
	v_mfma_f32_16x16x32_bf16 v[76:79], v[158:161], v[214:217], v[76:79]
	v_mfma_f32_16x16x32_bf16 v[72:75], v[166:169], v[214:217], v[72:75]
	v_mfma_f32_16x16x32_bf16 v[116:119], v[170:173], v[186:189], v[116:119]
	v_mfma_f32_16x16x32_bf16 v[112:115], v[178:181], v[186:189], v[112:115]
	v_mfma_f32_16x16x32_bf16 v[100:103], v[170:173], v[194:197], v[100:103]
	v_mfma_f32_16x16x32_bf16 v[96:99], v[178:181], v[194:197], v[96:99]
	v_mfma_f32_16x16x32_bf16 v[84:87], v[170:173], v[202:205], v[84:87]
	v_mfma_f32_16x16x32_bf16 v[80:83], v[178:181], v[202:205], v[80:83]
	v_mfma_f32_16x16x32_bf16 v[68:71], v[170:173], v[210:213], v[68:71]
	v_mfma_f32_16x16x32_bf16 v[64:67], v[178:181], v[210:213], v[64:67]
	v_mfma_f32_16x16x32_bf16 v[116:119], v[174:177], v[190:193], v[116:119]
	v_mfma_f32_16x16x32_bf16 v[112:115], v[182:185], v[190:193], v[112:115]
	v_mfma_f32_16x16x32_bf16 v[100:103], v[174:177], v[198:201], v[100:103]
	v_mfma_f32_16x16x32_bf16 v[96:99], v[182:185], v[198:201], v[96:99]
	v_mfma_f32_16x16x32_bf16 v[84:87], v[174:177], v[206:209], v[84:87]
	v_mfma_f32_16x16x32_bf16 v[80:83], v[182:185], v[206:209], v[80:83]
	v_mfma_f32_16x16x32_bf16 v[68:71], v[174:177], v[214:217], v[68:71]
	v_mfma_f32_16x16x32_bf16 v[64:67], v[182:185], v[214:217], v[64:67]
	s_setprio 0
	s_barrier
; #define PG8_STAGE(bufoff, gbase, voff) do { _Pragma("unroll") for (int _i = 0; _i < 2; ++_i) \
;         __builtin_amdgcn_global_load_lds((const unsigned*)((const char*)(gbase) + (voff)[_i]), (PG8_LAS unsigned*)(lds + (bufoff) + ldsw + _i * 8192), 16, 0, 0); } while (0)
; #define PG8_LDA(dst, b, h) do { _Pragma("unroll") for (int m = 0; m < 4; ++m) _Pragma("unroll") for (int k = 0; k < 2; ++k) dst[m][k] = *(const PG8_LAS bf16x8*)(lds + PG8_SA(b, h) + aoff + m * 2048 + k * 1024); } while (0)
; #define PG8_LDB(dst, b, h) do { _Pragma("unroll") for (int n = 0; n < 2; ++n) _Pragma("unroll") for (int k = 0; k < 2; ++k) dst[n][k] = *(const PG8_LAS bf16x8*)(lds + PG8_SB(b, h) + boff + n * 2048 + k * 1024); } while (0)
; template <class Epi, class Sched, bool ALIGN_EPI = false, bool SP2 = false>
; __device__ __forceinline__ void gemm_phase(PG8_LAS unsigned char* lds, const Gemm g, const Sched& S, const Epi& E) {
;     ...
;         for (int t = 0; t < nt; t += 2) {
;             const bool last = (t == nt - 2);
;             const char* a1 = cA + (size_t)(t + 1) * kstepA;
;             const char* a2 = last ? nA : cA + (size_t)(t + 2) * kstepA; const char* b2 = last ? nB : cB + (size_t)(t + 2) * kstep;
;             const char* a3 = a2 + kstepA; const char* b3 = b2 + kstep;
;             if (last && has_next) S.a_ready(nxt);
;             if constexpr (SP2) {
;             PG8_LDB(B0, 0, 0); PG8_LDB(B1, 0, 1); PG8_SCHED; PG8_LDA(At, 0, 0); PG8_STAGE(PG8_SA(1, 1), a1 + hstepA, voffA);
;             PG8_WAIT_V(8); PG8_WAIT_L(0); PG8_BAR; PG8_MMA(0, 0, At, B0); PG8_MMA(0, 1, At, B1); PG8_BAR; PG8_SCHED;
;             PG8_LDA(At, 0, 1); PG8_STAGE(PG8_SB(0, 0), b2, voffB); PG8_STAGE(PG8_SB(0, 1), b2 + hstep, voffB); PG8_STAGE(PG8_SA(0, 0), a2, voffA);
;             PG8_WAIT_V(8); PG8_WAIT_L(0); PG8_BAR; PG8_MMA(1, 0, At, B0); PG8_MMA(1, 1, At, B1); PG8_BAR; PG8_SCHED;
;             PG8_LDB(B0, 1, 0); PG8_LDB(B1, 1, 1); PG8_SCHED; PG8_LDA(At, 1, 0); PG8_STAGE(PG8_SA(0, 1), a2 + hstepA, voffA);
;             PG8_WAIT_V(8); PG8_WAIT_L(0); PG8_BAR; PG8_MMA(0, 0, At, B0); PG8_MMA(0, 1, At, B1); PG8_BAR; PG8_SCHED;
;             PG8_LDA(At, 1, 1); PG8_STAGE(PG8_SB(1, 0), b3, voffB); PG8_STAGE(PG8_SB(1, 1), b3 + hstep, voffB); PG8_STAGE(PG8_SA(1, 0), a3, voffA);
;             PG8_WAIT_V(8); PG8_WAIT_L(0); PG8_BAR; PG8_MMA(1, 0, At, B0); PG8_MMA(1, 1, At, B1); PG8_BAR; PG8_SCHED;
	s_add_i32 s50, s70, s33
	v_lshl_add_u64 v[148:149], v[148:149], 0, s[16:17]
	s_mov_b32 m0, s50
	ds_read_b128 v[186:189], v155 offset:49152
	ds_read_b128 v[190:193], v155 offset:50176
	ds_read_b128 v[194:197], v155 offset:51200
	ds_read_b128 v[198:201], v155 offset:52224
	ds_read_b128 v[202:205], v155 offset:53248
	ds_read_b128 v[206:209], v155 offset:54272
	ds_read_b128 v[210:213], v155 offset:55296
	ds_read_b128 v[214:217], v155 offset:56320
	global_load_lds_dwordx4 v[148:149], off
	s_add_i32 m0, s50, 0x2000
	s_add_u32 s48, s48, 0x100080
	v_lshl_add_u64 v[148:149], v[218:219], 0, s[16:17]
	s_addc_u32 s49, s49, 0
	s_add_i32 s50, s71, s33
	global_load_lds_dwordx4 v[148:149], off
	v_lshl_add_u64 v[148:149], s[48:49], 0, v[130:131]
	s_mov_b32 m0, s50
	s_nop 0
	global_load_lds_dwordx4 v[148:149], off
	v_lshl_add_u64 v[148:149], s[48:49], 0, v[134:135]
	s_add_i32 m0, s50, 0x2000
	s_nop 0
	global_load_lds_dwordx4 v[148:149], off
	v_lshl_add_u64 v[148:149], v[220:221], 0, s[16:17]
	s_mov_b32 m0, s56
	s_nop 0
	global_load_lds_dwordx4 v[148:149], off
	v_lshl_add_u64 v[148:149], v[222:223], 0, s[16:17]
	s_mov_b32 m0, s57
	s_nop 0
	global_load_lds_dwordx4 v[148:149], off
	s_waitcnt vmcnt(8)
	s_waitcnt lgkmcnt(0)
	s_barrier
	s_setprio 1
	s_waitcnt lgkmcnt(0)
	v_mfma_f32_16x16x32_bf16 v[60:63], v[144:147], v[186:189], v[60:63]
	v_mfma_f32_16x16x32_bf16 v[56:59], v[162:165], v[186:189], v[56:59]
	v_mfma_f32_16x16x32_bf16 v[44:47], v[144:147], v[194:197], v[44:47]
	v_mfma_f32_16x16x32_bf16 v[40:43], v[162:165], v[194:197], v[40:43]
	v_mfma_f32_16x16x32_bf16 v[28:31], v[144:147], v[202:205], v[28:31]
	v_mfma_f32_16x16x32_bf16 v[24:27], v[162:165], v[202:205], v[24:27]
	v_mfma_f32_16x16x32_bf16 v[12:15], v[144:147], v[210:213], v[12:15]
	v_mfma_f32_16x16x32_bf16 v[8:11], v[162:165], v[210:213], v[8:11]
	v_mfma_f32_16x16x32_bf16 v[60:63], v[158:161], v[190:193], v[60:63]
	v_mfma_f32_16x16x32_bf16 v[56:59], v[166:169], v[190:193], v[56:59]
	v_mfma_f32_16x16x32_bf16 v[44:47], v[158:161], v[198:201], v[44:47]
	v_mfma_f32_16x16x32_bf16 v[40:43], v[166:169], v[198:201], v[40:43]
	v_mfma_f32_16x16x32_bf16 v[28:31], v[158:161], v[206:209], v[28:31]
	v_mfma_f32_16x16x32_bf16 v[24:27], v[166:169], v[206:209], v[24:27]
	v_mfma_f32_16x16x32_bf16 v[12:15], v[158:161], v[214:217], v[12:15]
	v_mfma_f32_16x16x32_bf16 v[8:11], v[166:169], v[214:217], v[8:11]
	v_mfma_f32_16x16x32_bf16 v[52:55], v[170:173], v[186:189], v[52:55]
	v_mfma_f32_16x16x32_bf16 v[48:51], v[178:181], v[186:189], v[48:51]
	v_mfma_f32_16x16x32_bf16 v[36:39], v[170:173], v[194:197], v[36:39]
	v_mfma_f32_16x16x32_bf16 v[32:35], v[178:181], v[194:197], v[32:35]
	v_mfma_f32_16x16x32_bf16 v[20:23], v[170:173], v[202:205], v[20:23]
	v_mfma_f32_16x16x32_bf16 v[16:19], v[178:181], v[202:205], v[16:19]
	v_mfma_f32_16x16x32_bf16 v[4:7], v[170:173], v[210:213], v[4:7]
	v_mfma_f32_16x16x32_bf16 v[0:3], v[178:181], v[210:213], v[0:3]
	v_mfma_f32_16x16x32_bf16 v[52:55], v[174:177], v[190:193], v[52:55]
	v_mfma_f32_16x16x32_bf16 v[48:51], v[182:185], v[190:193], v[48:51]
	v_mfma_f32_16x16x32_bf16 v[36:39], v[174:177], v[198:201], v[36:39]
	v_mfma_f32_16x16x32_bf16 v[32:35], v[182:185], v[198:201], v[32:35]
	v_mfma_f32_16x16x32_bf16 v[20:23], v[174:177], v[206:209], v[20:23]
	v_mfma_f32_16x16x32_bf16 v[16:19], v[182:185], v[206:209], v[16:19]
	v_mfma_f32_16x16x32_bf16 v[4:7], v[174:177], v[214:217], v[4:7]
	v_mfma_f32_16x16x32_bf16 v[0:3], v[182:185], v[214:217], v[0:3]
	s_setprio 0
	s_barrier
	s_add_i32 s69, s69, 2
	s_add_u32 s46, s46, 0x100
	s_addc_u32 s47, s47, 0
	s_add_u32 s67, s67, 0x100
	s_addc_u32 s68, s68, 0
	s_cmp_gt_u32 s69, 61
	s_cbranch_scc0 .LBB0_2770
	s_and_b64 vcc, exec, s[18:19]
	s_cbranch_vccz .LBB0_2773
	s_barrier

; #define PG8_STAGE(bufoff, gbase, voff) do { _Pragma("unroll") for (int _i = 0; _i < 2; ++_i) \
;         __builtin_amdgcn_global_load_lds((const unsigned*)((const char*)(gbase) + (voff)[_i]), (PG8_LAS unsigned*)(lds + (bufoff) + ldsw + _i * 8192), 16, 0, 0); } while (0)
; #define PG8_LDA(dst, b, h) do { _Pragma("unroll") for (int m = 0; m < 4; ++m) _Pragma("unroll") for (int k = 0; k < 2; ++k) dst[m][k] = *(const PG8_LAS bf16x8*)(lds + PG8_SA(b, h) + aoff + m * 2048 + k * 1024); } while (0)
; #define PG8_LDB(dst, b, h) do { _Pragma("unroll") for (int n = 0; n < 2; ++n) _Pragma("unroll") for (int k = 0; k < 2; ++k) dst[n][k] = *(const PG8_LAS bf16x8*)(lds + PG8_SB(b, h) + boff + n * 2048 + k * 1024); } while (0)
; #define PG8_WAIT_V(n) asm volatile("s_waitcnt vmcnt(" #n ")" ::: "memory")
; #define PG8_WAIT_L(n) asm volatile("s_waitcnt lgkmcnt(" #n ")" ::: "memory")
; #define PG8_BAR __builtin_amdgcn_s_barrier()
; #define PG8_SCHED __builtin_amdgcn_sched_barrier(0)
; template <class Epi, class Sched, bool ALIGN_EPI = false, bool SP2 = false>
; __device__ __forceinline__ void gemm_phase(PG8_LAS unsigned char* lds, const Gemm g, const Sched& S, const Epi& E) {
;     ...
;         const bool has_next = S.next(ui + 1, nxt);
;         const char* nA = has_next ? (const char*)g.A + (size_t)nxt.pm * tstep : cA; const char* nB = has_next ? (const char*)g.Bt + (size_t)nxt.pn * tstep : cB;
;         for (int t = 0; t < nt; t += 2) {
;             const bool last = (t == nt - 2);
;             const char* a1 = cA + (size_t)(t + 1) * kstepA;
;             const char* a2 = last ? nA : cA + (size_t)(t + 2) * kstepA; const char* b2 = last ? nB : cB + (size_t)(t + 2) * kstep;
;             const char* a3 = a2 + kstepA; const char* b3 = b2 + kstep;
;             if (last && has_next) S.a_ready(nxt);
;             if constexpr (SP2) {
;             PG8_LDB(B0, 0, 0); PG8_LDB(B1, 0, 1); PG8_SCHED; PG8_LDA(At, 0, 0); PG8_STAGE(PG8_SA(1, 1), a1 + hstepA, voffA);
;             PG8_WAIT_V(8); PG8_WAIT_L(0); PG8_BAR; PG8_MMA(0, 0, At, B0); PG8_MMA(0, 1, At, B1); PG8_BAR; PG8_SCHED;
;             PG8_LDA(At, 0, 1); PG8_STAGE(PG8_SB(0, 0), b2, voffB); PG8_STAGE(PG8_SB(0, 1), b2 + hstep, voffB); PG8_STAGE(PG8_SA(0, 0), a2, voffA);
;             PG8_WAIT_V(8); PG8_WAIT_L(0); PG8_BAR; PG8_MMA(1, 0, At, B0); PG8_MMA(1, 1, At, B1); PG8_BAR; PG8_SCHED;
.LBB0_2882:
	ds_read_b128 v[128:131], v236
	ds_read_b128 v[132:135], v236 offset:1024
	ds_read_b128 v[136:139], v236 offset:2048
	ds_read_b128 v[140:143], v236 offset:3072
	ds_read_b128 v[144:147], v237
	ds_read_b128 v[148:151], v237 offset:1024
	ds_read_b128 v[152:155], v237 offset:2048
	ds_read_b128 v[156:159], v237 offset:3072
	s_add_u32 s10, s8, 0x100
	s_addc_u32 s11, s9, 0
	s_cmp_eq_u32 s88, 60
	s_cselect_b32 s61, s7, s11
	s_cselect_b32 s60, s51, s10
	s_cselect_b32 s59, s49, s87
	s_cselect_b32 s58, s85, s86
	v_lshl_add_u64 v[164:165], s[8:9], 0, v[178:179]
	s_add_i32 m0, s57, 0xc000
	ds_read_b128 v[160:163], v238
	ds_read_b128 v[186:189], v238 offset:1024
	ds_read_b128 v[190:193], v238 offset:2048
	ds_read_b128 v[194:197], v238 offset:3072
	ds_read_b128 v[198:201], v238 offset:4096
	ds_read_b128 v[202:205], v238 offset:5120
	ds_read_b128 v[206:209], v238 offset:6144
	ds_read_b128 v[210:213], v238 offset:7168
	global_load_lds_dwordx4 v[164:165], off
	v_lshl_add_u64 v[164:165], s[8:9], 0, v[180:181]
	s_add_i32 m0, s57, 0xe000
	s_nop 0
	global_load_lds_dwordx4 v[164:165], off
	s_waitcnt vmcnt(8)
	s_waitcnt lgkmcnt(0)
	s_barrier
	s_setprio 1
	s_waitcnt lgkmcnt(0)
	v_mfma_f32_16x16x32_bf16 v[124:127], v[128:131], v[160:163], v[124:127]
	v_mfma_f32_16x16x32_bf16 v[120:123], v[136:139], v[160:163], v[120:123]
	v_mfma_f32_16x16x32_bf16 v[108:111], v[128:131], v[190:193], v[108:111]
	v_mfma_f32_16x16x32_bf16 v[104:107], v[136:139], v[190:193], v[104:107]
	v_mfma_f32_16x16x32_bf16 v[92:95], v[128:131], v[198:201], v[92:95]
	v_mfma_f32_16x16x32_bf16 v[88:91], v[136:139], v[198:201], v[88:91]
	v_mfma_f32_16x16x32_bf16 v[76:79], v[128:131], v[206:209], v[76:79]
	v_mfma_f32_16x16x32_bf16 v[72:75], v[136:139], v[206:209], v[72:75]
	v_mfma_f32_16x16x32_bf16 v[124:127], v[132:135], v[186:189], v[124:127]
	v_mfma_f32_16x16x32_bf16 v[120:123], v[140:143], v[186:189], v[120:123]
	v_mfma_f32_16x16x32_bf16 v[108:111], v[132:135], v[194:197], v[108:111]
	v_mfma_f32_16x16x32_bf16 v[104:107], v[140:143], v[194:197], v[104:107]
	v_mfma_f32_16x16x32_bf16 v[92:95], v[132:135], v[202:205], v[92:95]
	v_mfma_f32_16x16x32_bf16 v[88:91], v[140:143], v[202:205], v[88:91]
	v_mfma_f32_16x16x32_bf16 v[76:79], v[132:135], v[210:213], v[76:79]
	v_mfma_f32_16x16x32_bf16 v[72:75], v[140:143], v[210:213], v[72:75]
	v_mfma_f32_16x16x32_bf16 v[116:119], v[144:147], v[160:163], v[116:119]
	v_mfma_f32_16x16x32_bf16 v[112:115], v[152:155], v[160:163], v[112:115]
	v_mfma_f32_16x16x32_bf16 v[100:103], v[144:147], v[190:193], v[100:103]
	v_mfma_f32_16x16x32_bf16 v[96:99], v[152:155], v[190:193], v[96:99]
	v_mfma_f32_16x16x32_bf16 v[84:87], v[144:147], v[198:201], v[84:87]
	v_mfma_f32_16x16x32_bf16 v[80:83], v[152:155], v[198:201], v[80:83]
	v_mfma_f32_16x16x32_bf16 v[68:71], v[144:147], v[206:209], v[68:71]
	v_mfma_f32_16x16x32_bf16 v[64:67], v[152:155], v[206:209], v[64:67]
	v_mfma_f32_16x16x32_bf16 v[116:119], v[148:151], v[186:189], v[116:119]
	v_mfma_f32_16x16x32_bf16 v[112:115], v[156:159], v[186:189], v[112:115]
	v_mfma_f32_16x16x32_bf16 v[100:103], v[148:151], v[194:197], v[100:103]
	v_mfma_f32_16x16x32_bf16 v[96:99], v[156:159], v[194:197], v[96:99]
	v_mfma_f32_16x16x32_bf16 v[84:87], v[148:151], v[202:205], v[84:87]
	v_mfma_f32_16x16x32_bf16 v[80:83], v[156:159], v[202:205], v[80:83]
	v_mfma_f32_16x16x32_bf16 v[68:71], v[148:151], v[210:213], v[68:71]
	v_mfma_f32_16x16x32_bf16 v[64:67], v[156:159], v[210:213], v[64:67]
	s_setprio 0
	s_barrier
	s_add_i32 s8, s72, s63
	v_lshl_add_u64 v[164:165], s[58:59], 0, v[168:169]
	s_mov_b32 m0, s8
	ds_read_b128 v[160:163], v238 offset:16384
	ds_read_b128 v[186:189], v238 offset:17408
	ds_read_b128 v[190:193], v238 offset:18432
	ds_read_b128 v[194:197], v238 offset:19456
	ds_read_b128 v[198:201], v238 offset:20480
	ds_read_b128 v[202:205], v238 offset:21504
	ds_read_b128 v[206:209], v238 offset:22528
	ds_read_b128 v[210:213], v238 offset:23552
	global_load_lds_dwordx4 v[164:165], off
	s_add_i32 m0, s8, 0x2000
	s_add_u32 s8, s58, 0x100000
	v_lshl_add_u64 v[214:215], s[58:59], 0, v[172:173]
	s_addc_u32 s9, s59, 0
	s_add_i32 s89, s73, s63
	global_load_lds_dwordx4 v[214:215], off
	v_lshl_add_u64 v[216:217], s[8:9], 0, v[168:169]
	s_mov_b32 m0, s89
	v_lshl_add_u64 v[218:219], s[60:61], 0, v[170:171]
	global_load_lds_dwordx4 v[216:217], off
	v_lshl_add_u64 v[216:217], s[8:9], 0, v[172:173]
	s_add_i32 m0, s89, 0x2000
	s_nop 0
	global_load_lds_dwordx4 v[216:217], off
	v_lshl_add_u64 v[216:217], s[60:61], 0, v[166:167]
	s_mov_b32 m0, s57
	s_nop 0
	global_load_lds_dwordx4 v[216:217], off
	s_mov_b32 m0, s64
	s_nop 0
	global_load_lds_dwordx4 v[218:219], off
	s_waitcnt vmcnt(8)
	s_waitcnt lgkmcnt(0)
	s_barrier
; #define PG8_STAGE(bufoff, gbase, voff) do { _Pragma("unroll") for (int _i = 0; _i < 2; ++_i) \
;         __builtin_amdgcn_global_load_lds((const unsigned*)((const char*)(gbase) + (voff)[_i]), (PG8_LAS unsigned*)(lds + (bufoff) + ldsw + _i * 8192), 16, 0, 0); } while (0)
; #define PG8_LDA(dst, b, h) do { _Pragma("unroll") for (int m = 0; m < 4; ++m) _Pragma("unroll") for (int k = 0; k < 2; ++k) dst[m][k] = *(const PG8_LAS bf16x8*)(lds + PG8_SA(b, h) + aoff + m * 2048 + k * 1024); } while (0)
; #define PG8_LDB(dst, b, h) do { _Pragma("unroll") for (int n = 0; n < 2; ++n) _Pragma("unroll") for (int k = 0; k < 2; ++k) dst[n][k] = *(const PG8_LAS bf16x8*)(lds + PG8_SB(b, h) + boff + n * 2048 + k * 1024); } while (0)
; #define PG8_MMA(ai, bj, At, Bt) do { __builtin_amdgcn_s_setprio(1); _Pragma("unroll") for (int m = 0; m < 4; ++m) _Pragma("unroll") for (int n = 0; n < 2; ++n) _Pragma("unroll") for (int k = 0; k < 2; ++k) \
;         acc[ai][bj][m][n] = __builtin_amdgcn_mfma_f32_16x16x32_bf16(Bt[n][k], At[m][k], acc[ai][bj][m][n], 0, 0, 0); __builtin_amdgcn_s_setprio(0); } while (0)
; #define PG8_WAIT_V(n) asm volatile("s_waitcnt vmcnt(" #n ")" ::: "memory")
; #define PG8_WAIT_L(n) asm volatile("s_waitcnt lgkmcnt(" #n ")" ::: "memory")
; #define PG8_BAR __builtin_amdgcn_s_barrier()
; #define PG8_SCHED __builtin_amdgcn_sched_barrier(0)
; template <class Epi, class Sched, bool ALIGN_EPI = false, bool SP2 = false>
; __device__ __forceinline__ void gemm_phase(PG8_LAS unsigned char* lds, const Gemm g, const Sched& S, const Epi& E) {
;     ...
;             PG8_WAIT_V(8); PG8_WAIT_L(0); PG8_BAR; PG8_MMA(0, 0, At, B0); PG8_MMA(0, 1, At, B1); PG8_BAR; PG8_SCHED;
;             PG8_LDA(At, 0, 1); PG8_STAGE(PG8_SB(0, 0), b2, voffB); PG8_STAGE(PG8_SB(0, 1), b2 + hstep, voffB); PG8_STAGE(PG8_SA(0, 0), a2, voffA);
;             PG8_WAIT_V(8); PG8_WAIT_L(0); PG8_BAR; PG8_MMA(1, 0, At, B0); PG8_MMA(1, 1, At, B1); PG8_BAR; PG8_SCHED;
;             PG8_LDB(B0, 1, 0); PG8_LDB(B1, 1, 1); PG8_SCHED; PG8_LDA(At, 1, 0); PG8_STAGE(PG8_SA(0, 1), a2 + hstepA, voffA);
;             PG8_WAIT_V(8); PG8_WAIT_L(0); PG8_BAR; PG8_MMA(0, 0, At, B0); PG8_MMA(0, 1, At, B1); PG8_BAR; PG8_SCHED;
	s_setprio 1
	s_waitcnt lgkmcnt(0)
	v_mfma_f32_16x16x32_bf16 v[60:63], v[128:131], v[160:163], v[60:63]
	v_mfma_f32_16x16x32_bf16 v[56:59], v[136:139], v[160:163], v[56:59]
	v_mfma_f32_16x16x32_bf16 v[44:47], v[128:131], v[190:193], v[44:47]
	v_mfma_f32_16x16x32_bf16 v[40:43], v[136:139], v[190:193], v[40:43]
	v_mfma_f32_16x16x32_bf16 v[28:31], v[128:131], v[198:201], v[28:31]
	v_mfma_f32_16x16x32_bf16 v[24:27], v[136:139], v[198:201], v[24:27]
	v_mfma_f32_16x16x32_bf16 v[12:15], v[128:131], v[206:209], v[12:15]
	v_mfma_f32_16x16x32_bf16 v[8:11], v[136:139], v[206:209], v[8:11]
	v_mfma_f32_16x16x32_bf16 v[60:63], v[132:135], v[186:189], v[60:63]
	v_mfma_f32_16x16x32_bf16 v[56:59], v[140:143], v[186:189], v[56:59]
	v_mfma_f32_16x16x32_bf16 v[44:47], v[132:135], v[194:197], v[44:47]
	v_mfma_f32_16x16x32_bf16 v[40:43], v[140:143], v[194:197], v[40:43]
	v_mfma_f32_16x16x32_bf16 v[28:31], v[132:135], v[202:205], v[28:31]
	v_mfma_f32_16x16x32_bf16 v[24:27], v[140:143], v[202:205], v[24:27]
	v_mfma_f32_16x16x32_bf16 v[12:15], v[132:135], v[210:213], v[12:15]
	v_mfma_f32_16x16x32_bf16 v[8:11], v[140:143], v[210:213], v[8:11]
	v_mfma_f32_16x16x32_bf16 v[52:55], v[144:147], v[160:163], v[52:55]
	v_mfma_f32_16x16x32_bf16 v[48:51], v[152:155], v[160:163], v[48:51]
	v_mfma_f32_16x16x32_bf16 v[36:39], v[144:147], v[190:193], v[36:39]
	v_mfma_f32_16x16x32_bf16 v[32:35], v[152:155], v[190:193], v[32:35]
	v_mfma_f32_16x16x32_bf16 v[20:23], v[144:147], v[198:201], v[20:23]
	v_mfma_f32_16x16x32_bf16 v[16:19], v[152:155], v[198:201], v[16:19]
	v_mfma_f32_16x16x32_bf16 v[4:7], v[144:147], v[206:209], v[4:7]
	v_mfma_f32_16x16x32_bf16 v[0:3], v[152:155], v[206:209], v[0:3]
	v_mfma_f32_16x16x32_bf16 v[52:55], v[148:151], v[186:189], v[52:55]
	v_mfma_f32_16x16x32_bf16 v[48:51], v[156:159], v[186:189], v[48:51]
	v_mfma_f32_16x16x32_bf16 v[36:39], v[148:151], v[194:197], v[36:39]
	v_mfma_f32_16x16x32_bf16 v[32:35], v[156:159], v[194:197], v[32:35]
	v_mfma_f32_16x16x32_bf16 v[20:23], v[148:151], v[202:205], v[20:23]
	v_mfma_f32_16x16x32_bf16 v[16:19], v[156:159], v[202:205], v[16:19]
	v_mfma_f32_16x16x32_bf16 v[4:7], v[148:151], v[210:213], v[4:7]
	v_mfma_f32_16x16x32_bf16 v[0:3], v[156:159], v[210:213], v[0:3]
	s_setprio 0
	s_barrier
	s_add_i32 s89, 0, 0x18000
	s_add_i32 s90, 0, 0x1c000
	v_add_u32_e32 v140, s89, v234
	v_add_u32_e32 v156, s90, v234
	ds_read_b128 v[128:131], v140
	ds_read_b128 v[132:135], v140 offset:1024
	ds_read_b128 v[136:139], v140 offset:2048
	ds_read_b128 v[140:143], v140 offset:3072
	ds_read_b128 v[144:147], v156
	ds_read_b128 v[148:151], v156 offset:1024
	ds_read_b128 v[152:155], v156 offset:2048
	ds_read_b128 v[156:159], v156 offset:3072
	s_add_u32 s8, s60, 0x100000
	s_addc_u32 s9, s61, 0
	s_mov_b32 m0, s65
	v_lshl_add_u64 v[220:221], s[8:9], 0, v[166:167]
	ds_read_b128 v[160:163], v238 offset:32768
	ds_read_b128 v[186:189], v238 offset:33792
	ds_read_b128 v[190:193], v238 offset:34816
	ds_read_b128 v[194:197], v238 offset:35840
	ds_read_b128 v[198:201], v238 offset:36864
	ds_read_b128 v[202:205], v238 offset:37888
	ds_read_b128 v[206:209], v238 offset:38912
	ds_read_b128 v[210:213], v238 offset:39936
	global_load_lds_dwordx4 v[220:221], off
	v_lshl_add_u64 v[220:221], s[8:9], 0, v[170:171]
	s_mov_b32 m0, s66
	s_nop 0
	global_load_lds_dwordx4 v[220:221], off
	s_waitcnt vmcnt(8)
	s_waitcnt lgkmcnt(0)
	s_barrier
	s_setprio 1
	s_waitcnt lgkmcnt(0)
	v_mfma_f32_16x16x32_bf16 v[124:127], v[128:131], v[160:163], v[124:127]
	v_mfma_f32_16x16x32_bf16 v[120:123], v[136:139], v[160:163], v[120:123]
	v_mfma_f32_16x16x32_bf16 v[108:111], v[128:131], v[190:193], v[108:111]
	v_mfma_f32_16x16x32_bf16 v[104:107], v[136:139], v[190:193], v[104:107]
	v_mfma_f32_16x16x32_bf16 v[92:95], v[128:131], v[198:201], v[92:95]
	v_mfma_f32_16x16x32_bf16 v[88:91], v[136:139], v[198:201], v[88:91]
	v_mfma_f32_16x16x32_bf16 v[76:79], v[128:131], v[206:209], v[76:79]
	v_mfma_f32_16x16x32_bf16 v[72:75], v[136:139], v[206:209], v[72:75]
	v_mfma_f32_16x16x32_bf16 v[124:127], v[132:135], v[186:189], v[124:127]
	v_mfma_f32_16x16x32_bf16 v[120:123], v[140:143], v[186:189], v[120:123]
	v_mfma_f32_16x16x32_bf16 v[108:111], v[132:135], v[194:197], v[108:111]
	v_mfma_f32_16x16x32_bf16 v[104:107], v[140:143], v[194:197], v[104:107]
	v_mfma_f32_16x16x32_bf16 v[92:95], v[132:135], v[202:205], v[92:95]
	v_mfma_f32_16x16x32_bf16 v[88:91], v[140:143], v[202:205], v[88:91]
	v_mfma_f32_16x16x32_bf16 v[76:79], v[132:135], v[210:213], v[76:79]
	v_mfma_f32_16x16x32_bf16 v[72:75], v[140:143], v[210:213], v[72:75]
	v_mfma_f32_16x16x32_bf16 v[116:119], v[144:147], v[160:163], v[116:119]
	v_mfma_f32_16x16x32_bf16 v[112:115], v[152:155], v[160:163], v[112:115]
	v_mfma_f32_16x16x32_bf16 v[100:103], v[144:147], v[190:193], v[100:103]
	v_mfma_f32_16x16x32_bf16 v[96:99], v[152:155], v[190:193], v[96:99]
	v_mfma_f32_16x16x32_bf16 v[84:87], v[144:147], v[198:201], v[84:87]
	v_mfma_f32_16x16x32_bf16 v[80:83], v[152:155], v[198:201], v[80:83]
	v_mfma_f32_16x16x32_bf16 v[68:71], v[144:147], v[206:209], v[68:71]
	v_mfma_f32_16x16x32_bf16 v[64:67], v[152:155], v[206:209], v[64:67]
	v_mfma_f32_16x16x32_bf16 v[116:119], v[148:151], v[186:189], v[116:119]
	v_mfma_f32_16x16x32_bf16 v[112:115], v[156:159], v[186:189], v[112:115]
	v_mfma_f32_16x16x32_bf16 v[100:103], v[148:151], v[194:197], v[100:103]
	v_mfma_f32_16x16x32_bf16 v[96:99], v[156:159], v[194:197], v[96:99]
	v_mfma_f32_16x16x32_bf16 v[84:87], v[148:151], v[202:205], v[84:87]
	v_mfma_f32_16x16x32_bf16 v[80:83], v[156:159], v[202:205], v[80:83]
	v_mfma_f32_16x16x32_bf16 v[68:71], v[148:151], v[210:213], v[68:71]
	v_mfma_f32_16x16x32_bf16 v[64:67], v[156:159], v[210:213], v[64:67]
	s_setprio 0
	s_barrier
; #define PG8_STAGE(bufoff, gbase, voff) do { _Pragma("unroll") for (int _i = 0; _i < 2; ++_i) \
;         __builtin_amdgcn_global_load_lds((const unsigned*)((const char*)(gbase) + (voff)[_i]), (PG8_LAS unsigned*)(lds + (bufoff) + ldsw + _i * 8192), 16, 0, 0); } while (0)
; #define PG8_LDA(dst, b, h) do { _Pragma("unroll") for (int m = 0; m < 4; ++m) _Pragma("unroll") for (int k = 0; k < 2; ++k) dst[m][k] = *(const PG8_LAS bf16x8*)(lds + PG8_SA(b, h) + aoff + m * 2048 + k * 1024); } while (0)
; #define PG8_LDB(dst, b, h) do { _Pragma("unroll") for (int n = 0; n < 2; ++n) _Pragma("unroll") for (int k = 0; k < 2; ++k) dst[n][k] = *(const PG8_LAS bf16x8*)(lds + PG8_SB(b, h) + boff + n * 2048 + k * 1024); } while (0)
; template <class Epi, class Sched, bool ALIGN_EPI = false, bool SP2 = false>
; __device__ __forceinline__ void gemm_phase(PG8_LAS unsigned char* lds, const Gemm g, const Sched& S, const Epi& E) {
;     ...
;         for (int t = 0; t < nt; t += 2) {
;             const bool last = (t == nt - 2);
;             const char* a1 = cA + (size_t)(t + 1) * kstepA;
;             const char* a2 = last ? nA : cA + (size_t)(t + 2) * kstepA; const char* b2 = last ? nB : cB + (size_t)(t + 2) * kstep;
;             const char* a3 = a2 + kstepA; const char* b3 = b2 + kstep;
;             if (last && has_next) S.a_ready(nxt);
;             if constexpr (SP2) {
;             PG8_LDB(B0, 0, 0); PG8_LDB(B1, 0, 1); PG8_SCHED; PG8_LDA(At, 0, 0); PG8_STAGE(PG8_SA(1, 1), a1 + hstepA, voffA);
;             PG8_WAIT_V(8); PG8_WAIT_L(0); PG8_BAR; PG8_MMA(0, 0, At, B0); PG8_MMA(0, 1, At, B1); PG8_BAR; PG8_SCHED;
;             PG8_LDA(At, 0, 1); PG8_STAGE(PG8_SB(0, 0), b2, voffB); PG8_STAGE(PG8_SB(0, 1), b2 + hstep, voffB); PG8_STAGE(PG8_SA(0, 0), a2, voffA);
;             PG8_WAIT_V(8); PG8_WAIT_L(0); PG8_BAR; PG8_MMA(1, 0, At, B0); PG8_MMA(1, 1, At, B1); PG8_BAR; PG8_SCHED;
;             PG8_LDB(B0, 1, 0); PG8_LDB(B1, 1, 1); PG8_SCHED; PG8_LDA(At, 1, 0); PG8_STAGE(PG8_SA(0, 1), a2 + hstepA, voffA);
;             PG8_WAIT_V(8); PG8_WAIT_L(0); PG8_BAR; PG8_MMA(0, 0, At, B0); PG8_MMA(0, 1, At, B1); PG8_BAR; PG8_SCHED;
;             PG8_LDA(At, 1, 1); PG8_STAGE(PG8_SB(1, 0), b3, voffB); PG8_STAGE(PG8_SB(1, 1), b3 + hstep, voffB); PG8_STAGE(PG8_SA(1, 0), a3, voffA);
;             PG8_WAIT_V(8); PG8_WAIT_L(0); PG8_BAR; PG8_MMA(1, 0, At, B0); PG8_MMA(1, 1, At, B1); PG8_BAR; PG8_SCHED;
	s_add_i32 s8, s89, s63
	v_lshl_add_u64 v[164:165], v[164:165], 0, s[16:17]
	s_mov_b32 m0, s8
	ds_read_b128 v[160:163], v238 offset:49152
	ds_read_b128 v[186:189], v238 offset:50176
	ds_read_b128 v[190:193], v238 offset:51200
	ds_read_b128 v[194:197], v238 offset:52224
	ds_read_b128 v[198:201], v238 offset:53248
	ds_read_b128 v[202:205], v238 offset:54272
	ds_read_b128 v[206:209], v238 offset:55296
	ds_read_b128 v[210:213], v238 offset:56320
	global_load_lds_dwordx4 v[164:165], off
	s_add_i32 m0, s8, 0x2000
	s_add_u32 s8, s58, 0x100080
	v_lshl_add_u64 v[164:165], v[214:215], 0, s[16:17]
	s_addc_u32 s9, s59, 0
	s_add_i32 s58, s90, s63
	global_load_lds_dwordx4 v[164:165], off
	v_lshl_add_u64 v[164:165], s[8:9], 0, v[168:169]
	s_mov_b32 m0, s58
	s_nop 0
	global_load_lds_dwordx4 v[164:165], off
	v_lshl_add_u64 v[164:165], s[8:9], 0, v[172:173]
	s_add_i32 m0, s58, 0x2000
	s_nop 0
	global_load_lds_dwordx4 v[164:165], off
	v_lshl_add_u64 v[164:165], v[216:217], 0, s[16:17]
	s_mov_b32 m0, s70
	s_nop 0
	global_load_lds_dwordx4 v[164:165], off
	v_lshl_add_u64 v[164:165], v[218:219], 0, s[16:17]
	s_mov_b32 m0, s71
	s_nop 0
	global_load_lds_dwordx4 v[164:165], off
	s_waitcnt vmcnt(8)
	s_waitcnt lgkmcnt(0)
	s_barrier
	s_setprio 1
	s_waitcnt lgkmcnt(0)
	v_mfma_f32_16x16x32_bf16 v[60:63], v[128:131], v[160:163], v[60:63]
	v_mfma_f32_16x16x32_bf16 v[56:59], v[136:139], v[160:163], v[56:59]
	v_mfma_f32_16x16x32_bf16 v[44:47], v[128:131], v[190:193], v[44:47]
	v_mfma_f32_16x16x32_bf16 v[40:43], v[136:139], v[190:193], v[40:43]
	v_mfma_f32_16x16x32_bf16 v[28:31], v[128:131], v[198:201], v[28:31]
	v_mfma_f32_16x16x32_bf16 v[24:27], v[136:139], v[198:201], v[24:27]
	v_mfma_f32_16x16x32_bf16 v[12:15], v[128:131], v[206:209], v[12:15]
	v_mfma_f32_16x16x32_bf16 v[8:11], v[136:139], v[206:209], v[8:11]
	v_mfma_f32_16x16x32_bf16 v[60:63], v[132:135], v[186:189], v[60:63]
	v_mfma_f32_16x16x32_bf16 v[56:59], v[140:143], v[186:189], v[56:59]
	v_mfma_f32_16x16x32_bf16 v[44:47], v[132:135], v[194:197], v[44:47]
	v_mfma_f32_16x16x32_bf16 v[40:43], v[140:143], v[194:197], v[40:43]
	v_mfma_f32_16x16x32_bf16 v[28:31], v[132:135], v[202:205], v[28:31]
	v_mfma_f32_16x16x32_bf16 v[24:27], v[140:143], v[202:205], v[24:27]
	v_mfma_f32_16x16x32_bf16 v[12:15], v[132:135], v[210:213], v[12:15]
	v_mfma_f32_16x16x32_bf16 v[8:11], v[140:143], v[210:213], v[8:11]
	v_mfma_f32_16x16x32_bf16 v[52:55], v[144:147], v[160:163], v[52:55]
	v_mfma_f32_16x16x32_bf16 v[48:51], v[152:155], v[160:163], v[48:51]
	v_mfma_f32_16x16x32_bf16 v[36:39], v[144:147], v[190:193], v[36:39]
	v_mfma_f32_16x16x32_bf16 v[32:35], v[152:155], v[190:193], v[32:35]
	v_mfma_f32_16x16x32_bf16 v[20:23], v[144:147], v[198:201], v[20:23]
	v_mfma_f32_16x16x32_bf16 v[16:19], v[152:155], v[198:201], v[16:19]
	v_mfma_f32_16x16x32_bf16 v[4:7], v[144:147], v[206:209], v[4:7]
	v_mfma_f32_16x16x32_bf16 v[0:3], v[152:155], v[206:209], v[0:3]
	v_mfma_f32_16x16x32_bf16 v[52:55], v[148:151], v[186:189], v[52:55]
	v_mfma_f32_16x16x32_bf16 v[48:51], v[156:159], v[186:189], v[48:51]
	v_mfma_f32_16x16x32_bf16 v[36:39], v[148:151], v[194:197], v[36:39]
	v_mfma_f32_16x16x32_bf16 v[32:35], v[156:159], v[194:197], v[32:35]
	v_mfma_f32_16x16x32_bf16 v[20:23], v[148:151], v[202:205], v[20:23]
	v_mfma_f32_16x16x32_bf16 v[16:19], v[156:159], v[202:205], v[16:19]
	v_mfma_f32_16x16x32_bf16 v[4:7], v[148:151], v[210:213], v[4:7]
	v_mfma_f32_16x16x32_bf16 v[0:3], v[156:159], v[210:213], v[0:3]
	s_setprio 0
	s_barrier
	s_add_i32 s88, s88, 2
	s_add_u32 s86, s86, 0x100
	s_addc_u32 s87, s87, 0
	s_cmp_gt_u32 s88, 61
	s_mov_b64 s[8:9], s[10:11]
	s_cbranch_scc0 .LBB0_2882
	s_and_b64 vcc, exec, s[18:19]
	s_cbranch_vccz .LBB0_2885
	s_barrier

; #define PG8_STAGE(bufoff, gbase, voff) do { _Pragma("unroll") for (int _i = 0; _i < 2; ++_i) \
;         __builtin_amdgcn_global_load_lds((const unsigned*)((const char*)(gbase) + (voff)[_i]), (PG8_LAS unsigned*)(lds + (bufoff) + ldsw + _i * 8192), 16, 0, 0); } while (0)
; #define PG8_LDA(dst, b, h) do { _Pragma("unroll") for (int m = 0; m < 4; ++m) _Pragma("unroll") for (int k = 0; k < 2; ++k) dst[m][k] = *(const PG8_LAS bf16x8*)(lds + PG8_SA(b, h) + aoff + m * 2048 + k * 1024); } while (0)
; #define PG8_LDB(dst, b, h) do { _Pragma("unroll") for (int n = 0; n < 2; ++n) _Pragma("unroll") for (int k = 0; k < 2; ++k) dst[n][k] = *(const PG8_LAS bf16x8*)(lds + PG8_SB(b, h) + boff + n * 2048 + k * 1024); } while (0)
; #define PG8_MMA(ai, bj, At, Bt) do { __builtin_amdgcn_s_setprio(1); _Pragma("unroll") for (int m = 0; m < 4; ++m) _Pragma("unroll") for (int n = 0; n < 2; ++n) _Pragma("unroll") for (int k = 0; k < 2; ++k) \
;         acc[ai][bj][m][n] = __builtin_amdgcn_mfma_f32_16x16x32_bf16(Bt[n][k], At[m][k], acc[ai][bj][m][n], 0, 0, 0); __builtin_amdgcn_s_setprio(0); } while (0)
; #define PG8_WAIT_V(n) asm volatile("s_waitcnt vmcnt(" #n ")" ::: "memory")
; #define PG8_WAIT_L(n) asm volatile("s_waitcnt lgkmcnt(" #n ")" ::: "memory")
; template <class Epi, class Sched, bool ALIGN_EPI = false, bool SP2 = false>
; __device__ __forceinline__ void gemm_phase(PG8_LAS unsigned char* lds, const Gemm g, const Sched& S, const Epi& E) {
;     ...
;         const bool has_next = S.next(ui + 1, nxt);
;         const char* nA = has_next ? (const char*)g.A + (size_t)nxt.pm * tstep : cA; const char* nB = has_next ? (const char*)g.Bt + (size_t)nxt.pn * tstep : cB;
;         for (int t = 0; t < nt; t += 2) {
;             const bool last = (t == nt - 2);
;             const char* a1 = cA + (size_t)(t + 1) * kstepA;
;             const char* a2 = last ? nA : cA + (size_t)(t + 2) * kstepA; const char* b2 = last ? nB : cB + (size_t)(t + 2) * kstep;
;             const char* a3 = a2 + kstepA; const char* b3 = b2 + kstep;
;             if (last && has_next) S.a_ready(nxt);
;             if constexpr (SP2) {
;             PG8_LDB(B0, 0, 0); PG8_LDB(B1, 0, 1); PG8_SCHED; PG8_LDA(At, 0, 0); PG8_STAGE(PG8_SA(1, 1), a1 + hstepA, voffA);
;             PG8_WAIT_V(8); PG8_WAIT_L(0); PG8_BAR; PG8_MMA(0, 0, At, B0); PG8_MMA(0, 1, At, B1); PG8_BAR; PG8_SCHED;
.LBB0_2918:
	ds_read_b128 v[0:3], v145
	ds_read_b128 v[4:7], v145 offset:1024
	ds_read_b128 v[8:11], v145 offset:2048
	ds_read_b128 v[12:15], v145 offset:3072
	ds_read_b128 v[16:19], v146
	ds_read_b128 v[20:23], v146 offset:1024
	ds_read_b128 v[24:27], v146 offset:2048
	ds_read_b128 v[28:31], v146 offset:3072
	s_ashr_i32 s35, s34, 31
	s_lshl_b64 s[40:41], s[34:35], 17
	s_add_u32 s40, s33, s40
	s_addc_u32 s41, s54, s41
	s_and_b64 s[42:43], s[0:1], exec
	s_cselect_b32 s53, s41, s47
	s_cselect_b32 s52, s40, s46
	s_ashr_i32 s31, s30, 31
	s_lshl_b64 s[42:43], s[30:31], 17
	s_add_u32 s42, s55, s42
	s_addc_u32 s43, s56, s43
	s_and_b64 s[50:51], s[0:1], exec
	s_cselect_b32 s51, s43, s49
	s_cselect_b32 s50, s42, s48
	s_add_u32 s74, s46, 0x10080
	s_addc_u32 s75, s47, 0
	s_mov_b32 m0, s71
	v_lshl_add_u64 v[64:65], s[74:75], 0, v[134:135]
	s_add_i32 s31, s45, 0xe000
	ds_read_b128 v[32:35], v147
	ds_read_b128 v[36:39], v147 offset:1024
	ds_read_b128 v[40:43], v147 offset:2048
	ds_read_b128 v[44:47], v147 offset:3072
	ds_read_b128 v[48:51], v147 offset:4096
	ds_read_b128 v[52:55], v147 offset:5120
	ds_read_b128 v[56:59], v147 offset:6144
	ds_read_b128 v[60:63], v147 offset:7168
	global_load_lds_dwordx4 v[64:65], off
	v_lshl_add_u64 v[64:65], s[74:75], 0, v[130:131]
	s_mov_b32 m0, s31
	s_nop 0
	global_load_lds_dwordx4 v[64:65], off
	s_waitcnt vmcnt(8)
	s_waitcnt lgkmcnt(0)
	s_barrier
	s_setprio 1
	s_waitcnt lgkmcnt(0)
	v_mfma_f32_16x16x32_bf16 v[64:67], v[0:3], v[32:35], 0
	v_mfma_f32_16x16x32_bf16 v[68:71], v[8:11], v[32:35], 0
	v_mfma_f32_16x16x32_bf16 v[72:75], v[0:3], v[40:43], 0
	v_mfma_f32_16x16x32_bf16 v[76:79], v[8:11], v[40:43], 0
	v_mfma_f32_16x16x32_bf16 v[80:83], v[0:3], v[48:51], 0
	v_mfma_f32_16x16x32_bf16 v[84:87], v[8:11], v[48:51], 0
	v_mfma_f32_16x16x32_bf16 v[88:91], v[0:3], v[56:59], 0
	v_mfma_f32_16x16x32_bf16 v[92:95], v[8:11], v[56:59], 0
	v_mfma_f32_16x16x32_bf16 v[64:67], v[4:7], v[36:39], v[64:67]
	v_mfma_f32_16x16x32_bf16 v[68:71], v[12:15], v[36:39], v[68:71]
	v_mfma_f32_16x16x32_bf16 v[72:75], v[4:7], v[44:47], v[72:75]
	v_mfma_f32_16x16x32_bf16 v[76:79], v[12:15], v[44:47], v[76:79]
	v_mfma_f32_16x16x32_bf16 v[80:83], v[4:7], v[52:55], v[80:83]
	v_mfma_f32_16x16x32_bf16 v[84:87], v[12:15], v[52:55], v[84:87]
	v_mfma_f32_16x16x32_bf16 v[88:91], v[4:7], v[60:63], v[88:91]
	v_mfma_f32_16x16x32_bf16 v[92:95], v[12:15], v[60:63], v[92:95]
	v_mfma_f32_16x16x32_bf16 v[96:99], v[16:19], v[32:35], 0
	v_mfma_f32_16x16x32_bf16 v[32:35], v[24:27], v[32:35], 0
	v_mfma_f32_16x16x32_bf16 v[96:99], v[20:23], v[36:39], v[96:99]
	v_mfma_f32_16x16x32_bf16 v[32:35], v[28:31], v[36:39], v[32:35]
	v_mfma_f32_16x16x32_bf16 v[36:39], v[16:19], v[40:43], 0
	v_mfma_f32_16x16x32_bf16 v[40:43], v[24:27], v[40:43], 0
	v_mfma_f32_16x16x32_bf16 v[36:39], v[20:23], v[44:47], v[36:39]
	v_mfma_f32_16x16x32_bf16 v[40:43], v[28:31], v[44:47], v[40:43]
	v_mfma_f32_16x16x32_bf16 v[44:47], v[16:19], v[48:51], 0
	v_mfma_f32_16x16x32_bf16 v[48:51], v[24:27], v[48:51], 0
	v_mfma_f32_16x16x32_bf16 v[44:47], v[20:23], v[52:55], v[44:47]
	v_mfma_f32_16x16x32_bf16 v[48:51], v[28:31], v[52:55], v[48:51]
	v_mfma_f32_16x16x32_bf16 v[52:55], v[16:19], v[56:59], 0
	v_mfma_f32_16x16x32_bf16 v[56:59], v[24:27], v[56:59], 0
	v_mfma_f32_16x16x32_bf16 v[52:55], v[20:23], v[60:63], v[52:55]
	v_mfma_f32_16x16x32_bf16 v[56:59], v[28:31], v[60:63], v[56:59]
	s_setprio 0
	s_barrier
	s_add_i32 s75, s65, s57
	v_lshl_add_u64 v[140:141], s[48:49], 0, v[132:133]
	s_add_i32 s35, s75, 0x2000
	v_lshl_add_u64 v[148:149], v[140:141], 0, s[16:17]
	s_mov_b32 m0, s75
	v_lshl_add_u64 v[212:213], s[48:49], 0, v[128:129]
	s_add_u32 s84, s48, 0x10100
	ds_read_b128 v[60:63], v147 offset:16384
	ds_read_b128 v[100:103], v147 offset:17408
	ds_read_b128 v[104:107], v147 offset:18432
	ds_read_b128 v[108:111], v147 offset:19456
	ds_read_b128 v[112:115], v147 offset:20480
	ds_read_b128 v[116:119], v147 offset:21504
	ds_read_b128 v[120:123], v147 offset:22528
	ds_read_b128 v[124:127], v147 offset:23552
	global_load_lds_dwordx4 v[148:149], off
	v_lshl_add_u64 v[148:149], v[212:213], 0, s[16:17]
	s_mov_b32 m0, s35
	s_addc_u32 s85, s49, 0
	s_add_i32 s73, s66, s57
	global_load_lds_dwordx4 v[148:149], off
	v_lshl_add_u64 v[148:149], s[84:85], 0, v[132:133]
	s_mov_b32 m0, s73
	s_add_i32 s74, s73, 0x2000
	global_load_lds_dwordx4 v[148:149], off
	v_lshl_add_u64 v[148:149], s[84:85], 0, v[128:129]
	s_mov_b32 m0, s74
	v_lshl_add_u64 v[214:215], s[46:47], 0, v[134:135]
	global_load_lds_dwordx4 v[148:149], off
	v_lshl_add_u64 v[148:149], v[214:215], 0, s[16:17]
	s_mov_b32 m0, s45
	v_lshl_add_u64 v[216:217], s[46:47], 0, v[130:131]
	global_load_lds_dwordx4 v[148:149], off
	v_lshl_add_u64 v[148:149], v[216:217], 0, s[16:17]
	s_mov_b32 m0, s58
	s_nop 0
	global_load_lds_dwordx4 v[148:149], off
	s_waitcnt vmcnt(8)
	s_waitcnt lgkmcnt(0)
	s_barrier
; #define PG8_STAGE(bufoff, gbase, voff) do { _Pragma("unroll") for (int _i = 0; _i < 2; ++_i) \
;         __builtin_amdgcn_global_load_lds((const unsigned*)((const char*)(gbase) + (voff)[_i]), (PG8_LAS unsigned*)(lds + (bufoff) + ldsw + _i * 8192), 16, 0, 0); } while (0)
; #define PG8_LDA(dst, b, h) do { _Pragma("unroll") for (int m = 0; m < 4; ++m) _Pragma("unroll") for (int k = 0; k < 2; ++k) dst[m][k] = *(const PG8_LAS bf16x8*)(lds + PG8_SA(b, h) + aoff + m * 2048 + k * 1024); } while (0)
; #define PG8_MMA(ai, bj, At, Bt) do { __builtin_amdgcn_s_setprio(1); _Pragma("unroll") for (int m = 0; m < 4; ++m) _Pragma("unroll") for (int n = 0; n < 2; ++n) _Pragma("unroll") for (int k = 0; k < 2; ++k) \
;         acc[ai][bj][m][n] = __builtin_amdgcn_mfma_f32_16x16x32_bf16(Bt[n][k], At[m][k], acc[ai][bj][m][n], 0, 0, 0); __builtin_amdgcn_s_setprio(0); } while (0)
; #define PG8_WAIT_V(n) asm volatile("s_waitcnt vmcnt(" #n ")" ::: "memory")
; #define PG8_WAIT_L(n) asm volatile("s_waitcnt lgkmcnt(" #n ")" ::: "memory")
; #define PG8_BAR __builtin_amdgcn_s_barrier()
; #define PG8_SCHED __builtin_amdgcn_sched_barrier(0)
; template <class Epi, class Sched, bool ALIGN_EPI = false, bool SP2 = false>
; __device__ __forceinline__ void gemm_phase(PG8_LAS unsigned char* lds, const Gemm g, const Sched& S, const Epi& E) {
;     ...
;             PG8_WAIT_V(8); PG8_WAIT_L(0); PG8_BAR; PG8_MMA(0, 0, At, B0); PG8_MMA(0, 1, At, B1); PG8_BAR; PG8_SCHED;
;             PG8_LDA(At, 0, 1); PG8_STAGE(PG8_SB(0, 0), b2, voffB); PG8_STAGE(PG8_SB(0, 1), b2 + hstep, voffB); PG8_STAGE(PG8_SA(0, 0), a2, voffA);
;             PG8_WAIT_V(8); PG8_WAIT_L(0); PG8_BAR; PG8_MMA(1, 0, At, B0); PG8_MMA(1, 1, At, B1); PG8_BAR; PG8_SCHED;
	s_setprio 1
	s_waitcnt lgkmcnt(0)
	v_mfma_f32_16x16x32_bf16 v[148:151], v[0:3], v[60:63], 0
	v_mfma_f32_16x16x32_bf16 v[156:159], v[0:3], v[104:107], 0
	v_mfma_f32_16x16x32_bf16 v[164:167], v[0:3], v[112:115], 0
	v_mfma_f32_16x16x32_bf16 v[0:3], v[0:3], v[120:123], 0
	v_mfma_f32_16x16x32_bf16 v[148:151], v[4:7], v[100:103], v[148:151]
	v_mfma_f32_16x16x32_bf16 v[156:159], v[4:7], v[108:111], v[156:159]
	v_mfma_f32_16x16x32_bf16 v[164:167], v[4:7], v[116:119], v[164:167]
	v_mfma_f32_16x16x32_bf16 v[0:3], v[4:7], v[124:127], v[0:3]
	v_mfma_f32_16x16x32_bf16 v[4:7], v[8:11], v[120:123], 0
	v_mfma_f32_16x16x32_bf16 v[152:155], v[8:11], v[60:63], 0
	v_mfma_f32_16x16x32_bf16 v[160:163], v[8:11], v[104:107], 0
	v_mfma_f32_16x16x32_bf16 v[168:171], v[8:11], v[112:115], 0
	v_mfma_f32_16x16x32_bf16 v[4:7], v[12:15], v[124:127], v[4:7]
	v_mfma_f32_16x16x32_bf16 v[152:155], v[12:15], v[100:103], v[152:155]
	v_mfma_f32_16x16x32_bf16 v[160:163], v[12:15], v[108:111], v[160:163]
	v_mfma_f32_16x16x32_bf16 v[168:171], v[12:15], v[116:119], v[168:171]
	v_mfma_f32_16x16x32_bf16 v[8:11], v[16:19], v[60:63], 0
	v_mfma_f32_16x16x32_bf16 v[12:15], v[24:27], v[60:63], 0
	v_mfma_f32_16x16x32_bf16 v[8:11], v[20:23], v[100:103], v[8:11]
	v_mfma_f32_16x16x32_bf16 v[12:15], v[28:31], v[100:103], v[12:15]
	v_mfma_f32_16x16x32_bf16 v[60:63], v[16:19], v[104:107], 0
	v_mfma_f32_16x16x32_bf16 v[100:103], v[24:27], v[104:107], 0
	v_mfma_f32_16x16x32_bf16 v[104:107], v[16:19], v[112:115], 0
	v_mfma_f32_16x16x32_bf16 v[16:19], v[16:19], v[120:123], 0
	v_mfma_f32_16x16x32_bf16 v[60:63], v[20:23], v[108:111], v[60:63]
	v_mfma_f32_16x16x32_bf16 v[100:103], v[28:31], v[108:111], v[100:103]
	v_mfma_f32_16x16x32_bf16 v[104:107], v[20:23], v[116:119], v[104:107]
	v_mfma_f32_16x16x32_bf16 v[108:111], v[24:27], v[112:115], 0
	v_mfma_f32_16x16x32_bf16 v[16:19], v[20:23], v[124:127], v[16:19]
	v_mfma_f32_16x16x32_bf16 v[20:23], v[24:27], v[120:123], 0
	v_mfma_f32_16x16x32_bf16 v[108:111], v[28:31], v[116:119], v[108:111]
	v_mfma_f32_16x16x32_bf16 v[20:23], v[28:31], v[124:127], v[20:23]
	s_setprio 0
	s_barrier
	s_add_i32 s86, 0, 0x18000
	s_add_i32 s88, 0, 0x1c000
	v_add_u32_e32 v224, s86, v143
	v_add_u32_e32 v232, s88, v143
	ds_read_b128 v[24:27], v224
	ds_read_b128 v[28:31], v224 offset:1024
	ds_read_b128 v[112:115], v224 offset:2048
	ds_read_b128 v[116:119], v224 offset:3072
	ds_read_b128 v[120:123], v232
	ds_read_b128 v[124:127], v232 offset:1024
	ds_read_b128 v[172:175], v232 offset:2048
	ds_read_b128 v[176:179], v232 offset:3072
	s_add_u32 s84, s46, 0x10100
	s_addc_u32 s85, s47, 0
	s_mov_b32 m0, s59
	v_lshl_add_u64 v[218:219], s[84:85], 0, v[134:135]
	ds_read_b128 v[180:183], v147 offset:32768
	ds_read_b128 v[184:187], v147 offset:33792
	ds_read_b128 v[188:191], v147 offset:34816
	ds_read_b128 v[192:195], v147 offset:35840
	ds_read_b128 v[196:199], v147 offset:36864
	ds_read_b128 v[200:203], v147 offset:37888
	ds_read_b128 v[204:207], v147 offset:38912
	ds_read_b128 v[208:211], v147 offset:39936
	global_load_lds_dwordx4 v[218:219], off
	v_lshl_add_u64 v[218:219], s[84:85], 0, v[130:131]
	s_mov_b32 m0, s60
	s_nop 0
	global_load_lds_dwordx4 v[218:219], off
	s_waitcnt vmcnt(8)
	s_waitcnt lgkmcnt(0)
	s_barrier
	s_setprio 1
	s_waitcnt lgkmcnt(0)
	v_mfma_f32_16x16x32_bf16 v[64:67], v[24:27], v[180:183], v[64:67]
	v_mfma_f32_16x16x32_bf16 v[68:71], v[112:115], v[180:183], v[68:71]
	v_mfma_f32_16x16x32_bf16 v[72:75], v[24:27], v[188:191], v[72:75]
	v_mfma_f32_16x16x32_bf16 v[76:79], v[112:115], v[188:191], v[76:79]
	v_mfma_f32_16x16x32_bf16 v[80:83], v[24:27], v[196:199], v[80:83]
	v_mfma_f32_16x16x32_bf16 v[84:87], v[112:115], v[196:199], v[84:87]
	v_mfma_f32_16x16x32_bf16 v[88:91], v[24:27], v[204:207], v[88:91]
	v_mfma_f32_16x16x32_bf16 v[92:95], v[112:115], v[204:207], v[92:95]
	v_mfma_f32_16x16x32_bf16 v[64:67], v[28:31], v[184:187], v[64:67]
	v_mfma_f32_16x16x32_bf16 v[68:71], v[116:119], v[184:187], v[68:71]
	v_mfma_f32_16x16x32_bf16 v[72:75], v[28:31], v[192:195], v[72:75]
	v_mfma_f32_16x16x32_bf16 v[76:79], v[116:119], v[192:195], v[76:79]
	v_mfma_f32_16x16x32_bf16 v[80:83], v[28:31], v[200:203], v[80:83]
	v_mfma_f32_16x16x32_bf16 v[84:87], v[116:119], v[200:203], v[84:87]
	v_mfma_f32_16x16x32_bf16 v[88:91], v[28:31], v[208:211], v[88:91]
	v_mfma_f32_16x16x32_bf16 v[92:95], v[116:119], v[208:211], v[92:95]
	v_mfma_f32_16x16x32_bf16 v[96:99], v[120:123], v[180:183], v[96:99]
	v_mfma_f32_16x16x32_bf16 v[32:35], v[172:175], v[180:183], v[32:35]
	v_mfma_f32_16x16x32_bf16 v[36:39], v[120:123], v[188:191], v[36:39]
	v_mfma_f32_16x16x32_bf16 v[40:43], v[172:175], v[188:191], v[40:43]
	v_mfma_f32_16x16x32_bf16 v[44:47], v[120:123], v[196:199], v[44:47]
	v_mfma_f32_16x16x32_bf16 v[48:51], v[172:175], v[196:199], v[48:51]
	v_mfma_f32_16x16x32_bf16 v[52:55], v[120:123], v[204:207], v[52:55]
	v_mfma_f32_16x16x32_bf16 v[56:59], v[172:175], v[204:207], v[56:59]
	v_mfma_f32_16x16x32_bf16 v[96:99], v[124:127], v[184:187], v[96:99]
	v_mfma_f32_16x16x32_bf16 v[32:35], v[176:179], v[184:187], v[32:35]
	v_mfma_f32_16x16x32_bf16 v[36:39], v[124:127], v[192:195], v[36:39]
	v_mfma_f32_16x16x32_bf16 v[40:43], v[176:179], v[192:195], v[40:43]
	v_mfma_f32_16x16x32_bf16 v[44:47], v[124:127], v[200:203], v[44:47]
	v_mfma_f32_16x16x32_bf16 v[48:51], v[176:179], v[200:203], v[48:51]
	v_mfma_f32_16x16x32_bf16 v[52:55], v[124:127], v[208:211], v[52:55]
	v_mfma_f32_16x16x32_bf16 v[56:59], v[176:179], v[208:211], v[56:59]
	s_setprio 0
	s_barrier
; #define PG8_STAGE(bufoff, gbase, voff) do { _Pragma("unroll") for (int _i = 0; _i < 2; ++_i) \
;         __builtin_amdgcn_global_load_lds((const unsigned*)((const char*)(gbase) + (voff)[_i]), (PG8_LAS unsigned*)(lds + (bufoff) + ldsw + _i * 8192), 16, 0, 0); } while (0)
; #define PG8_LDA(dst, b, h) do { _Pragma("unroll") for (int m = 0; m < 4; ++m) _Pragma("unroll") for (int k = 0; k < 2; ++k) dst[m][k] = *(const PG8_LAS bf16x8*)(lds + PG8_SA(b, h) + aoff + m * 2048 + k * 1024); } while (0)
; #define PG8_LDB(dst, b, h) do { _Pragma("unroll") for (int n = 0; n < 2; ++n) _Pragma("unroll") for (int k = 0; k < 2; ++k) dst[n][k] = *(const PG8_LAS bf16x8*)(lds + PG8_SB(b, h) + boff + n * 2048 + k * 1024); } while (0)
; #define PG8_MMA(ai, bj, At, Bt) do { __builtin_amdgcn_s_setprio(1); _Pragma("unroll") for (int m = 0; m < 4; ++m) _Pragma("unroll") for (int n = 0; n < 2; ++n) _Pragma("unroll") for (int k = 0; k < 2; ++k) \
;         acc[ai][bj][m][n] = __builtin_amdgcn_mfma_f32_16x16x32_bf16(Bt[n][k], At[m][k], acc[ai][bj][m][n], 0, 0, 0); __builtin_amdgcn_s_setprio(0); } while (0)
; #define PG8_WAIT_V(n) asm volatile("s_waitcnt vmcnt(" #n ")" ::: "memory")
; #define PG8_WAIT_L(n) asm volatile("s_waitcnt lgkmcnt(" #n ")" ::: "memory")
; #define PG8_BAR __builtin_amdgcn_s_barrier()
; #define PG8_SCHED __builtin_amdgcn_sched_barrier(0)
; template <class Epi, class Sched, bool ALIGN_EPI = false, bool SP2 = false>
; __device__ __forceinline__ void gemm_phase(PG8_LAS unsigned char* lds, const Gemm g, const Sched& S, const Epi& E) {
;     ...
;             PG8_WAIT_V(8); PG8_WAIT_L(0); PG8_BAR; PG8_MMA(0, 0, At, B0); PG8_MMA(0, 1, At, B1); PG8_BAR; PG8_SCHED;
;             PG8_LDA(At, 1, 1); PG8_STAGE(PG8_SB(1, 0), b3, voffB); PG8_STAGE(PG8_SB(1, 1), b3 + hstep, voffB); PG8_STAGE(PG8_SA(1, 0), a3, voffA);
;             PG8_WAIT_V(8); PG8_WAIT_L(0); PG8_BAR; PG8_MMA(1, 0, At, B0); PG8_MMA(1, 1, At, B1); PG8_BAR; PG8_SCHED;
;             } else {
;             PG8_LDB(B0, 0, 0); PG8_SCHED; PG8_LDA(At, 0, 0); PG8_STAGE(PG8_SA(1, 1), a1 + hstepA, voffA);
	s_add_i32 s85, s86, s57
	s_add_i32 s84, s85, 0x2000
	v_lshl_add_u64 v[140:141], v[140:141], 0, s[18:19]
	s_mov_b32 m0, s85
	s_add_u32 s86, s48, 0x10180
	ds_read_b128 v[180:183], v147 offset:49152
	ds_read_b128 v[184:187], v147 offset:50176
	ds_read_b128 v[188:191], v147 offset:51200
	ds_read_b128 v[192:195], v147 offset:52224
	ds_read_b128 v[196:199], v147 offset:53248
	ds_read_b128 v[200:203], v147 offset:54272
	ds_read_b128 v[204:207], v147 offset:55296
	ds_read_b128 v[208:211], v147 offset:56320
	global_load_lds_dwordx4 v[140:141], off
	v_lshl_add_u64 v[140:141], v[212:213], 0, s[18:19]
	s_mov_b32 m0, s84
	s_addc_u32 s87, s49, 0
	s_add_i32 s48, s88, s57
	global_load_lds_dwordx4 v[140:141], off
	v_lshl_add_u64 v[140:141], s[86:87], 0, v[132:133]
	s_mov_b32 m0, s48
	s_add_i32 s49, s48, 0x2000
	global_load_lds_dwordx4 v[140:141], off
	v_lshl_add_u64 v[140:141], s[86:87], 0, v[128:129]
	s_mov_b32 m0, s49
	s_nop 0
	global_load_lds_dwordx4 v[140:141], off
	v_lshl_add_u64 v[140:141], v[214:215], 0, s[18:19]
	s_mov_b32 m0, s63
	s_nop 0
	global_load_lds_dwordx4 v[140:141], off
	v_lshl_add_u64 v[140:141], v[216:217], 0, s[18:19]
	s_mov_b32 m0, s64
	s_nop 0
	global_load_lds_dwordx4 v[140:141], off
	s_waitcnt vmcnt(8)
	s_waitcnt lgkmcnt(0)
	s_barrier
	s_setprio 1
	s_waitcnt lgkmcnt(0)
	v_mfma_f32_16x16x32_bf16 v[0:3], v[24:27], v[204:207], v[0:3]
	v_mfma_f32_16x16x32_bf16 v[4:7], v[112:115], v[204:207], v[4:7]
	v_mfma_f32_16x16x32_bf16 v[148:151], v[24:27], v[180:183], v[148:151]
	v_mfma_f32_16x16x32_bf16 v[152:155], v[112:115], v[180:183], v[152:155]
	v_mfma_f32_16x16x32_bf16 v[156:159], v[24:27], v[188:191], v[156:159]
	v_mfma_f32_16x16x32_bf16 v[160:163], v[112:115], v[188:191], v[160:163]
	v_mfma_f32_16x16x32_bf16 v[164:167], v[24:27], v[196:199], v[164:167]
	v_mfma_f32_16x16x32_bf16 v[168:171], v[112:115], v[196:199], v[168:171]
	v_mfma_f32_16x16x32_bf16 v[0:3], v[28:31], v[208:211], v[0:3]
	v_mfma_f32_16x16x32_bf16 v[4:7], v[116:119], v[208:211], v[4:7]
	v_mfma_f32_16x16x32_bf16 v[148:151], v[28:31], v[184:187], v[148:151]
	v_mfma_f32_16x16x32_bf16 v[152:155], v[116:119], v[184:187], v[152:155]
	v_mfma_f32_16x16x32_bf16 v[156:159], v[28:31], v[192:195], v[156:159]
	v_mfma_f32_16x16x32_bf16 v[160:163], v[116:119], v[192:195], v[160:163]
	v_mfma_f32_16x16x32_bf16 v[164:167], v[28:31], v[200:203], v[164:167]
	v_mfma_f32_16x16x32_bf16 v[168:171], v[116:119], v[200:203], v[168:171]
	v_mfma_f32_16x16x32_bf16 v[8:11], v[120:123], v[180:183], v[8:11]
	v_mfma_f32_16x16x32_bf16 v[12:15], v[172:175], v[180:183], v[12:15]
	v_mfma_f32_16x16x32_bf16 v[24:27], v[120:123], v[188:191], v[60:63]
	v_mfma_f32_16x16x32_bf16 v[28:31], v[172:175], v[188:191], v[100:103]
	v_mfma_f32_16x16x32_bf16 v[60:63], v[120:123], v[196:199], v[104:107]
	v_mfma_f32_16x16x32_bf16 v[100:103], v[172:175], v[196:199], v[108:111]
	v_mfma_f32_16x16x32_bf16 v[16:19], v[120:123], v[204:207], v[16:19]
	v_mfma_f32_16x16x32_bf16 v[20:23], v[172:175], v[204:207], v[20:23]
	v_mfma_f32_16x16x32_bf16 v[8:11], v[124:127], v[184:187], v[8:11]
	v_mfma_f32_16x16x32_bf16 v[12:15], v[176:179], v[184:187], v[12:15]
	v_mfma_f32_16x16x32_bf16 v[24:27], v[124:127], v[192:195], v[24:27]
	v_mfma_f32_16x16x32_bf16 v[28:31], v[176:179], v[192:195], v[28:31]
	v_mfma_f32_16x16x32_bf16 v[60:63], v[124:127], v[200:203], v[60:63]
	v_mfma_f32_16x16x32_bf16 v[100:103], v[176:179], v[200:203], v[100:103]
	v_mfma_f32_16x16x32_bf16 v[16:19], v[124:127], v[208:211], v[16:19]
	v_mfma_f32_16x16x32_bf16 v[20:23], v[176:179], v[208:211], v[20:23]
	s_setprio 0
	s_barrier
	ds_read_b128 v[104:107], v145
	ds_read_b128 v[108:111], v145 offset:1024
	ds_read_b128 v[112:115], v145 offset:2048
	ds_read_b128 v[116:119], v145 offset:3072
	ds_read_b128 v[120:123], v146
	ds_read_b128 v[124:127], v146 offset:1024
	ds_read_b128 v[172:175], v146 offset:2048
	ds_read_b128 v[176:179], v146 offset:3072
	s_add_u32 s46, s46, 0x10180
	s_addc_u32 s47, s47, 0
	s_mov_b32 m0, s71
	v_lshl_add_u64 v[140:141], s[46:47], 0, v[134:135]
	ds_read_b128 v[180:183], v147
	ds_read_b128 v[184:187], v147 offset:1024
	ds_read_b128 v[188:191], v147 offset:2048
	ds_read_b128 v[192:195], v147 offset:3072
	ds_read_b128 v[196:199], v147 offset:4096
	ds_read_b128 v[200:203], v147 offset:5120
	ds_read_b128 v[204:207], v147 offset:6144
	ds_read_b128 v[208:211], v147 offset:7168
	global_load_lds_dwordx4 v[140:141], off
	v_lshl_add_u64 v[140:141], s[46:47], 0, v[130:131]
	s_mov_b32 m0, s31
	s_nop 0
	global_load_lds_dwordx4 v[140:141], off
	s_waitcnt vmcnt(8)
	s_waitcnt lgkmcnt(0)
	s_barrier
; #define PG8_STAGE(bufoff, gbase, voff) do { _Pragma("unroll") for (int _i = 0; _i < 2; ++_i) \
;         __builtin_amdgcn_global_load_lds((const unsigned*)((const char*)(gbase) + (voff)[_i]), (PG8_LAS unsigned*)(lds + (bufoff) + ldsw + _i * 8192), 16, 0, 0); } while (0)
; #define PG8_LDA(dst, b, h) do { _Pragma("unroll") for (int m = 0; m < 4; ++m) _Pragma("unroll") for (int k = 0; k < 2; ++k) dst[m][k] = *(const PG8_LAS bf16x8*)(lds + PG8_SA(b, h) + aoff + m * 2048 + k * 1024); } while (0)
; #define PG8_MMA(ai, bj, At, Bt) do { __builtin_amdgcn_s_setprio(1); _Pragma("unroll") for (int m = 0; m < 4; ++m) _Pragma("unroll") for (int n = 0; n < 2; ++n) _Pragma("unroll") for (int k = 0; k < 2; ++k) \
;         acc[ai][bj][m][n] = __builtin_amdgcn_mfma_f32_16x16x32_bf16(Bt[n][k], At[m][k], acc[ai][bj][m][n], 0, 0, 0); __builtin_amdgcn_s_setprio(0); } while (0)
; #define PG8_WAIT_V(n) asm volatile("s_waitcnt vmcnt(" #n ")" ::: "memory")
; #define PG8_WAIT_L(n) asm volatile("s_waitcnt lgkmcnt(" #n ")" ::: "memory")
; #define PG8_BAR __builtin_amdgcn_s_barrier()
; #define PG8_SCHED __builtin_amdgcn_sched_barrier(0)
; template <class Epi, class Sched, bool ALIGN_EPI = false, bool SP2 = false>
; __device__ __forceinline__ void gemm_phase(PG8_LAS unsigned char* lds, const Gemm g, const Sched& S, const Epi& E) {
;     ...
;             PG8_WAIT_V(8); PG8_WAIT_L(0); PG8_BAR; PG8_MMA(0, 0, At, B0); PG8_MMA(0, 1, At, B1); PG8_BAR; PG8_SCHED;
;             PG8_LDA(At, 0, 1); PG8_STAGE(PG8_SB(0, 0), b2, voffB); PG8_STAGE(PG8_SB(0, 1), b2 + hstep, voffB); PG8_STAGE(PG8_SA(0, 0), a2, voffA);
;             PG8_WAIT_V(8); PG8_WAIT_L(0); PG8_BAR; PG8_MMA(1, 0, At, B0); PG8_MMA(1, 1, At, B1); PG8_BAR; PG8_SCHED;
	s_setprio 1
	s_waitcnt lgkmcnt(0)
	v_mfma_f32_16x16x32_bf16 v[88:91], v[104:107], v[204:207], v[88:91]
	v_mfma_f32_16x16x32_bf16 v[64:67], v[104:107], v[180:183], v[64:67]
	v_mfma_f32_16x16x32_bf16 v[68:71], v[112:115], v[180:183], v[68:71]
	v_mfma_f32_16x16x32_bf16 v[72:75], v[104:107], v[188:191], v[72:75]
	v_mfma_f32_16x16x32_bf16 v[76:79], v[112:115], v[188:191], v[76:79]
	v_mfma_f32_16x16x32_bf16 v[80:83], v[104:107], v[196:199], v[80:83]
	v_mfma_f32_16x16x32_bf16 v[84:87], v[112:115], v[196:199], v[84:87]
	v_mfma_f32_16x16x32_bf16 v[212:215], v[108:111], v[208:211], v[88:91]
	v_mfma_f32_16x16x32_bf16 v[88:91], v[112:115], v[204:207], v[92:95]
	v_mfma_f32_16x16x32_bf16 v[64:67], v[108:111], v[184:187], v[64:67]
	v_mfma_f32_16x16x32_bf16 v[68:71], v[116:119], v[184:187], v[68:71]
	v_mfma_f32_16x16x32_bf16 v[72:75], v[108:111], v[192:195], v[72:75]
	v_mfma_f32_16x16x32_bf16 v[76:79], v[116:119], v[192:195], v[76:79]
	v_mfma_f32_16x16x32_bf16 v[80:83], v[108:111], v[200:203], v[80:83]
	v_mfma_f32_16x16x32_bf16 v[84:87], v[116:119], v[200:203], v[84:87]
	v_mfma_f32_16x16x32_bf16 v[92:95], v[116:119], v[208:211], v[88:91]
	v_mfma_f32_16x16x32_bf16 v[48:51], v[172:175], v[196:199], v[48:51]
	v_mfma_f32_16x16x32_bf16 v[88:91], v[120:123], v[180:183], v[96:99]
	v_mfma_f32_16x16x32_bf16 v[32:35], v[172:175], v[180:183], v[32:35]
	v_mfma_f32_16x16x32_bf16 v[36:39], v[120:123], v[188:191], v[36:39]
	v_mfma_f32_16x16x32_bf16 v[40:43], v[172:175], v[188:191], v[40:43]
	v_mfma_f32_16x16x32_bf16 v[44:47], v[120:123], v[196:199], v[44:47]
	v_mfma_f32_16x16x32_bf16 v[180:183], v[176:179], v[200:203], v[48:51]
	v_mfma_f32_16x16x32_bf16 v[48:51], v[120:123], v[204:207], v[52:55]
	v_mfma_f32_16x16x32_bf16 v[32:35], v[176:179], v[184:187], v[32:35]
	v_mfma_f32_16x16x32_bf16 v[36:39], v[124:127], v[192:195], v[36:39]
	v_mfma_f32_16x16x32_bf16 v[40:43], v[176:179], v[192:195], v[40:43]
	v_mfma_f32_16x16x32_bf16 v[44:47], v[124:127], v[200:203], v[44:47]
	v_mfma_f32_16x16x32_bf16 v[52:55], v[124:127], v[208:211], v[48:51]
	v_mfma_f32_16x16x32_bf16 v[48:51], v[172:175], v[204:207], v[56:59]
	v_mfma_f32_16x16x32_bf16 v[216:219], v[124:127], v[184:187], v[88:91]
	v_mfma_f32_16x16x32_bf16 v[184:187], v[176:179], v[208:211], v[48:51]
	s_setprio 0
	s_barrier
	s_mov_b32 m0, s75
	v_lshl_add_u64 v[140:141], s[50:51], 0, v[132:133]
	s_add_u32 s46, s50, 0x10000
	s_nop 0
	ds_read_b128 v[48:51], v147 offset:16384
	ds_read_b128 v[56:59], v147 offset:17408
	ds_read_b128 v[88:91], v147 offset:18432
	ds_read_b128 v[96:99], v147 offset:19456
	ds_read_b128 v[188:191], v147 offset:20480
	ds_read_b128 v[192:195], v147 offset:21504
	ds_read_b128 v[196:199], v147 offset:22528
	ds_read_b128 v[200:203], v147 offset:23552
	global_load_lds_dwordx4 v[140:141], off
	v_lshl_add_u64 v[252:253], s[50:51], 0, v[128:129]
	s_mov_b32 m0, s35
	s_addc_u32 s47, s51, 0
	global_load_lds_dwordx4 v[252:253], off
	v_lshl_add_u64 v[204:205], s[46:47], 0, v[132:133]
	s_mov_b32 m0, s73
	v_lshl_add_u64 v[136:137], s[52:53], 0, v[134:135]
	global_load_lds_dwordx4 v[204:205], off
	v_lshl_add_u64 v[204:205], s[46:47], 0, v[128:129]
	s_mov_b32 m0, s74
	v_lshl_add_u64 v[138:139], s[52:53], 0, v[130:131]
	global_load_lds_dwordx4 v[204:205], off
	s_mov_b32 m0, s45
	s_nop 0
	global_load_lds_dwordx4 v[136:137], off
	s_mov_b32 m0, s58
	s_nop 0
	global_load_lds_dwordx4 v[138:139], off
	s_waitcnt vmcnt(8)
	s_waitcnt lgkmcnt(0)
	s_barrier
	s_setprio 1
	s_waitcnt lgkmcnt(0)
	v_mfma_f32_16x16x32_bf16 v[0:3], v[104:107], v[196:199], v[0:3]
	v_mfma_f32_16x16x32_bf16 v[4:7], v[112:115], v[196:199], v[4:7]
	v_mfma_f32_16x16x32_bf16 v[148:151], v[104:107], v[48:51], v[148:151]
	v_mfma_f32_16x16x32_bf16 v[152:155], v[112:115], v[48:51], v[152:155]
	v_mfma_f32_16x16x32_bf16 v[156:159], v[104:107], v[88:91], v[156:159]
	v_mfma_f32_16x16x32_bf16 v[160:163], v[112:115], v[88:91], v[160:163]
	v_mfma_f32_16x16x32_bf16 v[164:167], v[104:107], v[188:191], v[164:167]
	v_mfma_f32_16x16x32_bf16 v[168:171], v[112:115], v[188:191], v[168:171]
	v_mfma_f32_16x16x32_bf16 v[0:3], v[108:111], v[200:203], v[0:3]
	v_mfma_f32_16x16x32_bf16 v[4:7], v[116:119], v[200:203], v[4:7]
	v_mfma_f32_16x16x32_bf16 v[148:151], v[108:111], v[56:59], v[148:151]
	v_mfma_f32_16x16x32_bf16 v[152:155], v[116:119], v[56:59], v[152:155]
	v_mfma_f32_16x16x32_bf16 v[156:159], v[108:111], v[96:99], v[156:159]
	v_mfma_f32_16x16x32_bf16 v[160:163], v[116:119], v[96:99], v[160:163]
	v_mfma_f32_16x16x32_bf16 v[164:167], v[108:111], v[192:195], v[164:167]
	v_mfma_f32_16x16x32_bf16 v[168:171], v[116:119], v[192:195], v[168:171]
	v_mfma_f32_16x16x32_bf16 v[12:15], v[172:175], v[48:51], v[12:15]
	v_mfma_f32_16x16x32_bf16 v[204:207], v[176:179], v[56:59], v[12:15]
	v_mfma_f32_16x16x32_bf16 v[12:15], v[120:123], v[88:91], v[24:27]
	v_mfma_f32_16x16x32_bf16 v[24:27], v[124:127], v[96:99], v[12:15]
	v_mfma_f32_16x16x32_bf16 v[12:15], v[172:175], v[88:91], v[28:31]
	v_mfma_f32_16x16x32_bf16 v[208:211], v[176:179], v[96:99], v[12:15]
	v_mfma_f32_16x16x32_bf16 v[12:15], v[120:123], v[188:191], v[60:63]
	v_mfma_f32_16x16x32_bf16 v[220:223], v[124:127], v[192:195], v[12:15]
	v_mfma_f32_16x16x32_bf16 v[12:15], v[172:175], v[188:191], v[100:103]
	v_mfma_f32_16x16x32_bf16 v[8:11], v[120:123], v[48:51], v[8:11]
	v_mfma_f32_16x16x32_bf16 v[188:191], v[176:179], v[192:195], v[12:15]
	v_mfma_f32_16x16x32_bf16 v[12:15], v[120:123], v[196:199], v[16:19]
	v_mfma_f32_16x16x32_bf16 v[8:11], v[124:127], v[56:59], v[8:11]
	v_mfma_f32_16x16x32_bf16 v[192:195], v[124:127], v[200:203], v[12:15]
	v_mfma_f32_16x16x32_bf16 v[12:15], v[172:175], v[196:199], v[20:23]
	v_mfma_f32_16x16x32_bf16 v[172:175], v[176:179], v[200:203], v[12:15]
	s_setprio 0
	s_barrier
; #define PG8_STAGE(bufoff, gbase, voff) do { _Pragma("unroll") for (int _i = 0; _i < 2; ++_i) \
;         __builtin_amdgcn_global_load_lds((const unsigned*)((const char*)(gbase) + (voff)[_i]), (PG8_LAS unsigned*)(lds + (bufoff) + ldsw + _i * 8192), 16, 0, 0); } while (0)
; #define PG8_LDA(dst, b, h) do { _Pragma("unroll") for (int m = 0; m < 4; ++m) _Pragma("unroll") for (int k = 0; k < 2; ++k) dst[m][k] = *(const PG8_LAS bf16x8*)(lds + PG8_SA(b, h) + aoff + m * 2048 + k * 1024); } while (0)
; #define PG8_MMA(ai, bj, At, Bt) do { __builtin_amdgcn_s_setprio(1); _Pragma("unroll") for (int m = 0; m < 4; ++m) _Pragma("unroll") for (int n = 0; n < 2; ++n) _Pragma("unroll") for (int k = 0; k < 2; ++k) \
;         acc[ai][bj][m][n] = __builtin_amdgcn_mfma_f32_16x16x32_bf16(Bt[n][k], At[m][k], acc[ai][bj][m][n], 0, 0, 0); __builtin_amdgcn_s_setprio(0); } while (0)
; #define PG8_WAIT_V(n) asm volatile("s_waitcnt vmcnt(" #n ")" ::: "memory")
; #define PG8_WAIT_L(n) asm volatile("s_waitcnt lgkmcnt(" #n ")" ::: "memory")
; #define PG8_BAR __builtin_amdgcn_s_barrier()
; #define PG8_SCHED __builtin_amdgcn_sched_barrier(0)
; template <class Epi, class Sched, bool ALIGN_EPI = false, bool SP2 = false>
; __device__ __forceinline__ void gemm_phase(PG8_LAS unsigned char* lds, const Gemm g, const Sched& S, const Epi& E) {
;     ...
;             PG8_WAIT_V(8); PG8_WAIT_L(0); PG8_BAR; PG8_MMA(0, 0, At, B0); PG8_MMA(0, 1, At, B1); PG8_BAR; PG8_SCHED;
;             PG8_LDA(At, 1, 1); PG8_STAGE(PG8_SB(1, 0), b3, voffB); PG8_STAGE(PG8_SB(1, 1), b3 + hstep, voffB); PG8_STAGE(PG8_SA(1, 0), a3, voffA);
;             PG8_WAIT_V(8); PG8_WAIT_L(0); PG8_BAR; PG8_MMA(1, 0, At, B0); PG8_MMA(1, 1, At, B1); PG8_BAR; PG8_SCHED;
;     ...
;         if constexpr (ALIGN_EPI) { if (wr == 0) PG8_BAR; }
	s_nop 4
	ds_read_b128 v[12:15], v224
	ds_read_b128 v[16:19], v224 offset:1024
	ds_read_b128 v[176:179], v224 offset:2048
	ds_read_b128 v[196:199], v224 offset:3072
	ds_read_b128 v[200:203], v232
	ds_read_b128 v[224:227], v232 offset:1024
	ds_read_b128 v[228:231], v232 offset:2048
	ds_read_b128 v[232:235], v232 offset:3072
	s_add_u32 s46, s52, 0x10000
	s_addc_u32 s47, s53, 0
	s_mov_b32 m0, s59
	v_lshl_add_u64 v[48:49], s[46:47], 0, v[134:135]
	ds_read_b128 v[20:23], v147 offset:32768
	ds_read_b128 v[28:31], v147 offset:33792
	ds_read_b128 v[60:63], v147 offset:34816
	ds_read_b128 v[100:103], v147 offset:35840
	ds_read_b128 v[236:239], v147 offset:36864
	ds_read_b128 v[240:243], v147 offset:37888
	ds_read_b128 v[244:247], v147 offset:38912
	ds_read_b128 v[248:251], v147 offset:39936
	global_load_lds_dwordx4 v[48:49], off
	v_lshl_add_u64 v[48:49], s[46:47], 0, v[130:131]
	s_mov_b32 m0, s60
	s_nop 0
	global_load_lds_dwordx4 v[48:49], off
	s_waitcnt vmcnt(8)
	s_waitcnt lgkmcnt(0)
	s_barrier
	s_setprio 1
	s_waitcnt lgkmcnt(0)
	v_mfma_f32_16x16x32_bf16 v[48:51], v[12:15], v[20:23], v[64:67]
	v_mfma_f32_16x16x32_bf16 v[120:123], v[16:19], v[28:31], v[48:51]
	v_mfma_f32_16x16x32_bf16 v[48:51], v[176:179], v[20:23], v[68:71]
	v_mfma_f32_16x16x32_bf16 v[112:115], v[196:199], v[28:31], v[48:51]
	v_mfma_f32_16x16x32_bf16 v[48:51], v[12:15], v[60:63], v[72:75]
	v_mfma_f32_16x16x32_bf16 v[104:107], v[16:19], v[100:103], v[48:51]
	v_mfma_f32_16x16x32_bf16 v[48:51], v[176:179], v[60:63], v[76:79]
	v_mfma_f32_16x16x32_bf16 v[96:99], v[196:199], v[100:103], v[48:51]
	v_mfma_f32_16x16x32_bf16 v[48:51], v[12:15], v[236:239], v[80:83]
	v_mfma_f32_16x16x32_bf16 v[88:91], v[16:19], v[240:243], v[48:51]
	v_mfma_f32_16x16x32_bf16 v[48:51], v[176:179], v[236:239], v[84:87]
	v_mfma_f32_16x16x32_bf16 v[80:83], v[196:199], v[240:243], v[48:51]
	v_mfma_f32_16x16x32_bf16 v[48:51], v[12:15], v[244:247], v[212:215]
	v_mfma_f32_16x16x32_bf16 v[56:59], v[16:19], v[248:251], v[48:51]
	v_mfma_f32_16x16x32_bf16 v[48:51], v[176:179], v[244:247], v[92:95]
	v_mfma_f32_16x16x32_bf16 v[48:51], v[196:199], v[248:251], v[48:51]
	v_mfma_f32_16x16x32_bf16 v[64:67], v[200:203], v[20:23], v[216:219]
	v_mfma_f32_16x16x32_bf16 v[20:23], v[228:231], v[20:23], v[32:35]
	v_mfma_f32_16x16x32_bf16 v[116:119], v[232:235], v[28:31], v[20:23]
	v_mfma_f32_16x16x32_bf16 v[20:23], v[200:203], v[60:63], v[36:39]
	v_mfma_f32_16x16x32_bf16 v[108:111], v[224:227], v[100:103], v[20:23]
	v_mfma_f32_16x16x32_bf16 v[20:23], v[228:231], v[60:63], v[40:43]
	v_mfma_f32_16x16x32_bf16 v[100:103], v[232:235], v[100:103], v[20:23]
	v_mfma_f32_16x16x32_bf16 v[20:23], v[200:203], v[236:239], v[44:47]
	v_mfma_f32_16x16x32_bf16 v[92:95], v[224:227], v[240:243], v[20:23]
	v_mfma_f32_16x16x32_bf16 v[20:23], v[228:231], v[236:239], v[180:183]
	v_mfma_f32_16x16x32_bf16 v[84:87], v[232:235], v[240:243], v[20:23]
	v_mfma_f32_16x16x32_bf16 v[20:23], v[200:203], v[244:247], v[52:55]
	v_mfma_f32_16x16x32_bf16 v[60:63], v[224:227], v[248:251], v[20:23]
	v_mfma_f32_16x16x32_bf16 v[20:23], v[228:231], v[244:247], v[184:187]
	v_mfma_f32_16x16x32_bf16 v[124:127], v[224:227], v[28:31], v[64:67]
	v_mfma_f32_16x16x32_bf16 v[52:55], v[232:235], v[248:251], v[20:23]
	s_setprio 0
	s_barrier
	s_mov_b32 m0, s85
	s_nop 2
	v_lshl_add_u64 v[20:21], v[140:141], 0, s[8:9]
	s_add_u32 s46, s50, 0x10080
	ds_read_b128 v[32:35], v147 offset:49152
	ds_read_b128 v[40:43], v147 offset:50176
	ds_read_b128 v[180:183], v147 offset:51200
	ds_read_b128 v[184:187], v147 offset:52224
	ds_read_b128 v[212:215], v147 offset:53248
	ds_read_b128 v[216:219], v147 offset:54272
	ds_read_b128 v[236:239], v147 offset:55296
	ds_read_b128 v[240:243], v147 offset:56320
	global_load_lds_dwordx4 v[20:21], off
	v_lshl_add_u64 v[20:21], v[252:253], 0, s[8:9]
	s_mov_b32 m0, s84
	s_addc_u32 s47, s51, 0
	global_load_lds_dwordx4 v[20:21], off
	v_lshl_add_u64 v[20:21], s[46:47], 0, v[132:133]
	s_mov_b32 m0, s48
	s_nop 0
	global_load_lds_dwordx4 v[20:21], off
	v_lshl_add_u64 v[20:21], s[46:47], 0, v[128:129]
	s_mov_b32 m0, s49
	s_nop 0
	global_load_lds_dwordx4 v[20:21], off
	v_lshl_add_u64 v[20:21], v[136:137], 0, s[8:9]
	s_mov_b32 m0, s63
	s_nop 0
	global_load_lds_dwordx4 v[20:21], off
	v_lshl_add_u64 v[20:21], v[138:139], 0, s[8:9]
	s_mov_b32 m0, s64
	s_nop 0
	global_load_lds_dwordx4 v[20:21], off
	s_waitcnt vmcnt(8)
	s_waitcnt lgkmcnt(0)
	s_barrier
	s_setprio 1
	s_waitcnt lgkmcnt(0)
	v_mfma_f32_16x16x32_bf16 v[20:23], v[12:15], v[32:35], v[148:151]
	v_mfma_f32_16x16x32_bf16 v[76:79], v[16:19], v[40:43], v[20:23]
	v_mfma_f32_16x16x32_bf16 v[20:23], v[176:179], v[32:35], v[152:155]
	v_mfma_f32_16x16x32_bf16 v[68:71], v[196:199], v[40:43], v[20:23]
	v_mfma_f32_16x16x32_bf16 v[20:23], v[12:15], v[180:183], v[156:159]
	v_mfma_f32_16x16x32_bf16 v[44:47], v[16:19], v[184:187], v[20:23]
	v_mfma_f32_16x16x32_bf16 v[20:23], v[176:179], v[180:183], v[160:163]
	v_mfma_f32_16x16x32_bf16 v[36:39], v[196:199], v[184:187], v[20:23]
	v_mfma_f32_16x16x32_bf16 v[20:23], v[12:15], v[212:215], v[164:167]
	v_mfma_f32_16x16x32_bf16 v[0:3], v[12:15], v[236:239], v[0:3]
	v_mfma_f32_16x16x32_bf16 v[28:31], v[16:19], v[216:219], v[20:23]
	v_mfma_f32_16x16x32_bf16 v[20:23], v[176:179], v[212:215], v[168:171]
	v_mfma_f32_16x16x32_bf16 v[12:15], v[16:19], v[240:243], v[0:3]
	v_mfma_f32_16x16x32_bf16 v[0:3], v[176:179], v[236:239], v[4:7]
	v_mfma_f32_16x16x32_bf16 v[20:23], v[196:199], v[216:219], v[20:23]
	v_mfma_f32_16x16x32_bf16 v[4:7], v[196:199], v[240:243], v[0:3]
	v_mfma_f32_16x16x32_bf16 v[0:3], v[200:203], v[32:35], v[8:11]
	v_mfma_f32_16x16x32_bf16 v[72:75], v[224:227], v[40:43], v[0:3]
	v_mfma_f32_16x16x32_bf16 v[0:3], v[228:231], v[32:35], v[204:207]
	v_mfma_f32_16x16x32_bf16 v[64:67], v[232:235], v[40:43], v[0:3]
	v_mfma_f32_16x16x32_bf16 v[0:3], v[200:203], v[180:183], v[24:27]
	v_mfma_f32_16x16x32_bf16 v[40:43], v[224:227], v[184:187], v[0:3]
	v_mfma_f32_16x16x32_bf16 v[0:3], v[228:231], v[180:183], v[208:211]
	v_mfma_f32_16x16x32_bf16 v[32:35], v[232:235], v[184:187], v[0:3]
	v_mfma_f32_16x16x32_bf16 v[0:3], v[200:203], v[212:215], v[220:223]
	v_mfma_f32_16x16x32_bf16 v[24:27], v[224:227], v[216:219], v[0:3]
	v_mfma_f32_16x16x32_bf16 v[0:3], v[228:231], v[212:215], v[188:191]
	v_mfma_f32_16x16x32_bf16 v[16:19], v[232:235], v[216:219], v[0:3]
	v_mfma_f32_16x16x32_bf16 v[0:3], v[200:203], v[236:239], v[192:195]
	v_mfma_f32_16x16x32_bf16 v[8:11], v[224:227], v[240:243], v[0:3]
	v_mfma_f32_16x16x32_bf16 v[0:3], v[228:231], v[236:239], v[172:175]
	v_mfma_f32_16x16x32_bf16 v[0:3], v[232:235], v[240:243], v[0:3]
	s_setprio 0
	s_barrier
	s_andn2_b64 vcc, exec, s[10:11]
	s_cbranch_vccnz .LBB0_2920
	s_barrier

; #define PG8_STAGE(bufoff, gbase, voff) do { _Pragma("unroll") for (int _i = 0; _i < 2; ++_i) \
;         __builtin_amdgcn_global_load_lds((const unsigned*)((const char*)(gbase) + (voff)[_i]), (PG8_LAS unsigned*)(lds + (bufoff) + ldsw + _i * 8192), 16, 0, 0); } while (0)
; #define PG8_LDA(dst, b, h) do { _Pragma("unroll") for (int m = 0; m < 4; ++m) _Pragma("unroll") for (int k = 0; k < 2; ++k) dst[m][k] = *(const PG8_LAS bf16x8*)(lds + PG8_SA(b, h) + aoff + m * 2048 + k * 1024); } while (0)
; #define PG8_LDB(dst, b, h) do { _Pragma("unroll") for (int n = 0; n < 2; ++n) _Pragma("unroll") for (int k = 0; k < 2; ++k) dst[n][k] = *(const PG8_LAS bf16x8*)(lds + PG8_SB(b, h) + boff + n * 2048 + k * 1024); } while (0)
; #define PG8_WAIT_V(n) asm volatile("s_waitcnt vmcnt(" #n ")" ::: "memory")
; #define PG8_WAIT_L(n) asm volatile("s_waitcnt lgkmcnt(" #n ")" ::: "memory")
; #define PG8_BAR __builtin_amdgcn_s_barrier()
; #define PG8_SCHED __builtin_amdgcn_sched_barrier(0)
; template <class Epi, class Sched, bool ALIGN_EPI = false, bool SP2 = false>
; __device__ __forceinline__ void gemm_phase(PG8_LAS unsigned char* lds, const Gemm g, const Sched& S, const Epi& E) {
;     ...
;         const bool has_next = S.next(ui + 1, nxt);
;         const char* nA = has_next ? (const char*)g.A + (size_t)nxt.pm * tstep : cA; const char* nB = has_next ? (const char*)g.Bt + (size_t)nxt.pn * tstep : cB;
;         for (int t = 0; t < nt; t += 2) {
;             const bool last = (t == nt - 2);
;             const char* a1 = cA + (size_t)(t + 1) * kstepA;
;             const char* a2 = last ? nA : cA + (size_t)(t + 2) * kstepA; const char* b2 = last ? nB : cB + (size_t)(t + 2) * kstep;
;             const char* a3 = a2 + kstepA; const char* b3 = b2 + kstep;
;             if (last && has_next) S.a_ready(nxt);
;             if constexpr (SP2) {
;             PG8_LDB(B0, 0, 0); PG8_LDB(B1, 0, 1); PG8_SCHED; PG8_LDA(At, 0, 0); PG8_STAGE(PG8_SA(1, 1), a1 + hstepA, voffA);
;             PG8_WAIT_V(8); PG8_WAIT_L(0); PG8_BAR; PG8_MMA(0, 0, At, B0); PG8_MMA(0, 1, At, B1); PG8_BAR; PG8_SCHED;
;             PG8_LDA(At, 0, 1); PG8_STAGE(PG8_SB(0, 0), b2, voffB); PG8_STAGE(PG8_SB(0, 1), b2 + hstep, voffB); PG8_STAGE(PG8_SA(0, 0), a2, voffA);
;             PG8_WAIT_V(8); PG8_WAIT_L(0); PG8_BAR; PG8_MMA(1, 0, At, B0); PG8_MMA(1, 1, At, B1); PG8_BAR; PG8_SCHED;
.LBB0_3087:
	ds_read_b128 v[144:147], v153
	ds_read_b128 v[158:161], v153 offset:1024
	ds_read_b128 v[162:165], v153 offset:2048
	ds_read_b128 v[166:169], v153 offset:3072
	ds_read_b128 v[170:173], v154
	ds_read_b128 v[174:177], v154 offset:1024
	ds_read_b128 v[178:181], v154 offset:2048
	ds_read_b128 v[182:185], v154 offset:3072
	s_add_u32 s36, s34, 0x4000
	s_addc_u32 s37, s35, 0
	s_cmpk_eq_i32 s65, 0xa8
	s_cselect_b32 s42, s6, s36
	s_cselect_b32 s43, s7, s37
	s_cselect_b32 s40, s30, s63
	s_cselect_b32 s41, s31, s64
	s_add_u32 s36, s42, 0x8000
	s_addc_u32 s37, s43, 0
	v_lshl_add_u64 v[148:149], s[34:35], 0, v[136:137]
	s_add_i32 m0, s44, 0xc000
	ds_read_b128 v[186:189], v155
	ds_read_b128 v[190:193], v155 offset:1024
	ds_read_b128 v[194:197], v155 offset:2048
	ds_read_b128 v[198:201], v155 offset:3072
	ds_read_b128 v[202:205], v155 offset:4096
	ds_read_b128 v[206:209], v155 offset:5120
	ds_read_b128 v[210:213], v155 offset:6144
	ds_read_b128 v[214:217], v155 offset:7168
	global_load_lds_dwordx4 v[148:149], off
	v_lshl_add_u64 v[148:149], s[34:35], 0, v[138:139]
	s_add_i32 m0, s44, 0xe000
	s_nop 0
	global_load_lds_dwordx4 v[148:149], off
	s_waitcnt vmcnt(8)
	s_waitcnt lgkmcnt(0)
	s_barrier
	s_setprio 1
	s_waitcnt lgkmcnt(0)
	v_mfma_f32_16x16x32_bf16 v[124:127], v[144:147], v[186:189], v[124:127]
	v_mfma_f32_16x16x32_bf16 v[120:123], v[162:165], v[186:189], v[120:123]
	v_mfma_f32_16x16x32_bf16 v[108:111], v[144:147], v[194:197], v[108:111]
	v_mfma_f32_16x16x32_bf16 v[104:107], v[162:165], v[194:197], v[104:107]
	v_mfma_f32_16x16x32_bf16 v[92:95], v[144:147], v[202:205], v[92:95]
	v_mfma_f32_16x16x32_bf16 v[88:91], v[162:165], v[202:205], v[88:91]
	v_mfma_f32_16x16x32_bf16 v[76:79], v[144:147], v[210:213], v[76:79]
	v_mfma_f32_16x16x32_bf16 v[72:75], v[162:165], v[210:213], v[72:75]
	v_mfma_f32_16x16x32_bf16 v[124:127], v[158:161], v[190:193], v[124:127]
	v_mfma_f32_16x16x32_bf16 v[120:123], v[166:169], v[190:193], v[120:123]
	v_mfma_f32_16x16x32_bf16 v[108:111], v[158:161], v[198:201], v[108:111]
	v_mfma_f32_16x16x32_bf16 v[104:107], v[166:169], v[198:201], v[104:107]
	v_mfma_f32_16x16x32_bf16 v[92:95], v[158:161], v[206:209], v[92:95]
	v_mfma_f32_16x16x32_bf16 v[88:91], v[166:169], v[206:209], v[88:91]
	v_mfma_f32_16x16x32_bf16 v[76:79], v[158:161], v[214:217], v[76:79]
	v_mfma_f32_16x16x32_bf16 v[72:75], v[166:169], v[214:217], v[72:75]
	v_mfma_f32_16x16x32_bf16 v[116:119], v[170:173], v[186:189], v[116:119]
	v_mfma_f32_16x16x32_bf16 v[112:115], v[178:181], v[186:189], v[112:115]
	v_mfma_f32_16x16x32_bf16 v[100:103], v[170:173], v[194:197], v[100:103]
	v_mfma_f32_16x16x32_bf16 v[96:99], v[178:181], v[194:197], v[96:99]
	v_mfma_f32_16x16x32_bf16 v[84:87], v[170:173], v[202:205], v[84:87]
	v_mfma_f32_16x16x32_bf16 v[80:83], v[178:181], v[202:205], v[80:83]
	v_mfma_f32_16x16x32_bf16 v[68:71], v[170:173], v[210:213], v[68:71]
	v_mfma_f32_16x16x32_bf16 v[64:67], v[178:181], v[210:213], v[64:67]
	v_mfma_f32_16x16x32_bf16 v[116:119], v[174:177], v[190:193], v[116:119]
	v_mfma_f32_16x16x32_bf16 v[112:115], v[182:185], v[190:193], v[112:115]
	v_mfma_f32_16x16x32_bf16 v[100:103], v[174:177], v[198:201], v[100:103]
	v_mfma_f32_16x16x32_bf16 v[96:99], v[182:185], v[198:201], v[96:99]
	v_mfma_f32_16x16x32_bf16 v[84:87], v[174:177], v[206:209], v[84:87]
	v_mfma_f32_16x16x32_bf16 v[80:83], v[182:185], v[206:209], v[80:83]
	v_mfma_f32_16x16x32_bf16 v[68:71], v[174:177], v[214:217], v[68:71]
	v_mfma_f32_16x16x32_bf16 v[64:67], v[182:185], v[214:217], v[64:67]
	s_setprio 0
	s_barrier
	s_add_i32 s66, s53, s33
	v_lshl_add_u64 v[148:149], s[40:41], 0, v[130:131]
	s_mov_b32 m0, s66
	ds_read_b128 v[186:189], v155 offset:16384
	ds_read_b128 v[190:193], v155 offset:17408
	ds_read_b128 v[194:197], v155 offset:18432
	ds_read_b128 v[198:201], v155 offset:19456
	ds_read_b128 v[202:205], v155 offset:20480
	ds_read_b128 v[206:209], v155 offset:21504
	ds_read_b128 v[210:213], v155 offset:22528
	ds_read_b128 v[214:217], v155 offset:23552
	global_load_lds_dwordx4 v[148:149], off
	s_add_i32 m0, s66, 0x2000
	s_add_u32 s66, s40, 0x2b0000
	v_lshl_add_u64 v[218:219], s[40:41], 0, v[134:135]
	s_addc_u32 s67, s41, 0
	s_add_i32 s68, s54, s33
	global_load_lds_dwordx4 v[218:219], off
	v_lshl_add_u64 v[220:221], s[66:67], 0, v[130:131]
	s_mov_b32 m0, s68
	s_nop 0
	global_load_lds_dwordx4 v[220:221], off
	v_lshl_add_u64 v[220:221], s[66:67], 0, v[134:135]
	s_add_i32 m0, s68, 0x2000
	s_nop 0
	global_load_lds_dwordx4 v[220:221], off
	v_lshl_add_u64 v[220:221], s[42:43], 0, v[128:129]
	s_mov_b32 m0, s44
	s_nop 0
	global_load_lds_dwordx4 v[220:221], off
	v_lshl_add_u64 v[220:221], s[42:43], 0, v[132:133]
	s_mov_b32 m0, s45
	s_nop 0
	global_load_lds_dwordx4 v[220:221], off
	s_waitcnt vmcnt(8)
	s_waitcnt lgkmcnt(0)
	s_barrier
; #define PG8_STAGE(bufoff, gbase, voff) do { _Pragma("unroll") for (int _i = 0; _i < 2; ++_i) \
;         __builtin_amdgcn_global_load_lds((const unsigned*)((const char*)(gbase) + (voff)[_i]), (PG8_LAS unsigned*)(lds + (bufoff) + ldsw + _i * 8192), 16, 0, 0); } while (0)
; #define PG8_LDA(dst, b, h) do { _Pragma("unroll") for (int m = 0; m < 4; ++m) _Pragma("unroll") for (int k = 0; k < 2; ++k) dst[m][k] = *(const PG8_LAS bf16x8*)(lds + PG8_SA(b, h) + aoff + m * 2048 + k * 1024); } while (0)
; #define PG8_LDB(dst, b, h) do { _Pragma("unroll") for (int n = 0; n < 2; ++n) _Pragma("unroll") for (int k = 0; k < 2; ++k) dst[n][k] = *(const PG8_LAS bf16x8*)(lds + PG8_SB(b, h) + boff + n * 2048 + k * 1024); } while (0)
; #define PG8_MMA(ai, bj, At, Bt) do { __builtin_amdgcn_s_setprio(1); _Pragma("unroll") for (int m = 0; m < 4; ++m) _Pragma("unroll") for (int n = 0; n < 2; ++n) _Pragma("unroll") for (int k = 0; k < 2; ++k) \
;         acc[ai][bj][m][n] = __builtin_amdgcn_mfma_f32_16x16x32_bf16(Bt[n][k], At[m][k], acc[ai][bj][m][n], 0, 0, 0); __builtin_amdgcn_s_setprio(0); } while (0)
; #define PG8_WAIT_V(n) asm volatile("s_waitcnt vmcnt(" #n ")" ::: "memory")
; #define PG8_WAIT_L(n) asm volatile("s_waitcnt lgkmcnt(" #n ")" ::: "memory")
; #define PG8_BAR __builtin_amdgcn_s_barrier()
; #define PG8_SCHED __builtin_amdgcn_sched_barrier(0)
; template <class Epi, class Sched, bool ALIGN_EPI = false, bool SP2 = false>
; __device__ __forceinline__ void gemm_phase(PG8_LAS unsigned char* lds, const Gemm g, const Sched& S, const Epi& E) {
;     ...
;             PG8_WAIT_V(8); PG8_WAIT_L(0); PG8_BAR; PG8_MMA(0, 0, At, B0); PG8_MMA(0, 1, At, B1); PG8_BAR; PG8_SCHED;
;             PG8_LDA(At, 0, 1); PG8_STAGE(PG8_SB(0, 0), b2, voffB); PG8_STAGE(PG8_SB(0, 1), b2 + hstep, voffB); PG8_STAGE(PG8_SA(0, 0), a2, voffA);
;             PG8_WAIT_V(8); PG8_WAIT_L(0); PG8_BAR; PG8_MMA(1, 0, At, B0); PG8_MMA(1, 1, At, B1); PG8_BAR; PG8_SCHED;
;             PG8_LDB(B0, 1, 0); PG8_LDB(B1, 1, 1); PG8_SCHED; PG8_LDA(At, 1, 0); PG8_STAGE(PG8_SA(0, 1), a2 + hstepA, voffA);
;             PG8_WAIT_V(8); PG8_WAIT_L(0); PG8_BAR; PG8_MMA(0, 0, At, B0); PG8_MMA(0, 1, At, B1); PG8_BAR; PG8_SCHED;
	s_setprio 1
	s_waitcnt lgkmcnt(0)
	v_mfma_f32_16x16x32_bf16 v[60:63], v[144:147], v[186:189], v[60:63]
	v_mfma_f32_16x16x32_bf16 v[56:59], v[162:165], v[186:189], v[56:59]
	v_mfma_f32_16x16x32_bf16 v[44:47], v[144:147], v[194:197], v[44:47]
	v_mfma_f32_16x16x32_bf16 v[40:43], v[162:165], v[194:197], v[40:43]
	v_mfma_f32_16x16x32_bf16 v[28:31], v[144:147], v[202:205], v[28:31]
	v_mfma_f32_16x16x32_bf16 v[24:27], v[162:165], v[202:205], v[24:27]
	v_mfma_f32_16x16x32_bf16 v[12:15], v[144:147], v[210:213], v[12:15]
	v_mfma_f32_16x16x32_bf16 v[8:11], v[162:165], v[210:213], v[8:11]
	v_mfma_f32_16x16x32_bf16 v[60:63], v[158:161], v[190:193], v[60:63]
	v_mfma_f32_16x16x32_bf16 v[56:59], v[166:169], v[190:193], v[56:59]
	v_mfma_f32_16x16x32_bf16 v[44:47], v[158:161], v[198:201], v[44:47]
	v_mfma_f32_16x16x32_bf16 v[40:43], v[166:169], v[198:201], v[40:43]
	v_mfma_f32_16x16x32_bf16 v[28:31], v[158:161], v[206:209], v[28:31]
	v_mfma_f32_16x16x32_bf16 v[24:27], v[166:169], v[206:209], v[24:27]
	v_mfma_f32_16x16x32_bf16 v[12:15], v[158:161], v[214:217], v[12:15]
	v_mfma_f32_16x16x32_bf16 v[8:11], v[166:169], v[214:217], v[8:11]
	v_mfma_f32_16x16x32_bf16 v[52:55], v[170:173], v[186:189], v[52:55]
	v_mfma_f32_16x16x32_bf16 v[48:51], v[178:181], v[186:189], v[48:51]
	v_mfma_f32_16x16x32_bf16 v[36:39], v[170:173], v[194:197], v[36:39]
	v_mfma_f32_16x16x32_bf16 v[32:35], v[178:181], v[194:197], v[32:35]
	v_mfma_f32_16x16x32_bf16 v[20:23], v[170:173], v[202:205], v[20:23]
	v_mfma_f32_16x16x32_bf16 v[16:19], v[178:181], v[202:205], v[16:19]
	v_mfma_f32_16x16x32_bf16 v[4:7], v[170:173], v[210:213], v[4:7]
	v_mfma_f32_16x16x32_bf16 v[0:3], v[178:181], v[210:213], v[0:3]
	v_mfma_f32_16x16x32_bf16 v[52:55], v[174:177], v[190:193], v[52:55]
	v_mfma_f32_16x16x32_bf16 v[48:51], v[182:185], v[190:193], v[48:51]
	v_mfma_f32_16x16x32_bf16 v[36:39], v[174:177], v[198:201], v[36:39]
	v_mfma_f32_16x16x32_bf16 v[32:35], v[182:185], v[198:201], v[32:35]
	v_mfma_f32_16x16x32_bf16 v[20:23], v[174:177], v[206:209], v[20:23]
	v_mfma_f32_16x16x32_bf16 v[16:19], v[182:185], v[206:209], v[16:19]
	v_mfma_f32_16x16x32_bf16 v[4:7], v[174:177], v[214:217], v[4:7]
	v_mfma_f32_16x16x32_bf16 v[0:3], v[182:185], v[214:217], v[0:3]
	s_setprio 0
	s_barrier
	s_add_i32 s66, 0, 0x18000
	v_add_u32_e32 v157, s66, v151
	s_add_i32 s67, 0, 0x1c000
	ds_read_b128 v[144:147], v157
	ds_read_b128 v[158:161], v157 offset:1024
	ds_read_b128 v[162:165], v157 offset:2048
	ds_read_b128 v[166:169], v157 offset:3072
	v_add_u32_e32 v157, s67, v151
	ds_read_b128 v[170:173], v157
	ds_read_b128 v[174:177], v157 offset:1024
	ds_read_b128 v[178:181], v157 offset:2048
	ds_read_b128 v[182:185], v157 offset:3072
	s_add_u32 s42, s42, 0x4000
	s_addc_u32 s43, s43, 0
	s_mov_b32 m0, s46
	v_lshl_add_u64 v[220:221], s[42:43], 0, v[128:129]
	ds_read_b128 v[186:189], v155 offset:32768
	ds_read_b128 v[190:193], v155 offset:33792
	ds_read_b128 v[194:197], v155 offset:34816
	ds_read_b128 v[198:201], v155 offset:35840
	ds_read_b128 v[202:205], v155 offset:36864
	ds_read_b128 v[206:209], v155 offset:37888
	ds_read_b128 v[210:213], v155 offset:38912
	ds_read_b128 v[214:217], v155 offset:39936
	global_load_lds_dwordx4 v[220:221], off
	v_lshl_add_u64 v[220:221], s[42:43], 0, v[132:133]
	s_mov_b32 m0, s47
	s_nop 0
	global_load_lds_dwordx4 v[220:221], off
	s_waitcnt vmcnt(8)
	s_waitcnt lgkmcnt(0)
	s_barrier
	s_setprio 1
	s_waitcnt lgkmcnt(0)
	v_mfma_f32_16x16x32_bf16 v[124:127], v[144:147], v[186:189], v[124:127]
	v_mfma_f32_16x16x32_bf16 v[120:123], v[162:165], v[186:189], v[120:123]
	v_mfma_f32_16x16x32_bf16 v[108:111], v[144:147], v[194:197], v[108:111]
	v_mfma_f32_16x16x32_bf16 v[104:107], v[162:165], v[194:197], v[104:107]
	v_mfma_f32_16x16x32_bf16 v[92:95], v[144:147], v[202:205], v[92:95]
	v_mfma_f32_16x16x32_bf16 v[88:91], v[162:165], v[202:205], v[88:91]
	v_mfma_f32_16x16x32_bf16 v[76:79], v[144:147], v[210:213], v[76:79]
	v_mfma_f32_16x16x32_bf16 v[72:75], v[162:165], v[210:213], v[72:75]
	v_mfma_f32_16x16x32_bf16 v[124:127], v[158:161], v[190:193], v[124:127]
	v_mfma_f32_16x16x32_bf16 v[120:123], v[166:169], v[190:193], v[120:123]
	v_mfma_f32_16x16x32_bf16 v[108:111], v[158:161], v[198:201], v[108:111]
	v_mfma_f32_16x16x32_bf16 v[104:107], v[166:169], v[198:201], v[104:107]
	v_mfma_f32_16x16x32_bf16 v[92:95], v[158:161], v[206:209], v[92:95]
	v_mfma_f32_16x16x32_bf16 v[88:91], v[166:169], v[206:209], v[88:91]
	v_mfma_f32_16x16x32_bf16 v[76:79], v[158:161], v[214:217], v[76:79]
	v_mfma_f32_16x16x32_bf16 v[72:75], v[166:169], v[214:217], v[72:75]
	v_mfma_f32_16x16x32_bf16 v[116:119], v[170:173], v[186:189], v[116:119]
	v_mfma_f32_16x16x32_bf16 v[112:115], v[178:181], v[186:189], v[112:115]
	v_mfma_f32_16x16x32_bf16 v[100:103], v[170:173], v[194:197], v[100:103]
	v_mfma_f32_16x16x32_bf16 v[96:99], v[178:181], v[194:197], v[96:99]
	v_mfma_f32_16x16x32_bf16 v[84:87], v[170:173], v[202:205], v[84:87]
	v_mfma_f32_16x16x32_bf16 v[80:83], v[178:181], v[202:205], v[80:83]
	v_mfma_f32_16x16x32_bf16 v[68:71], v[170:173], v[210:213], v[68:71]
	v_mfma_f32_16x16x32_bf16 v[64:67], v[178:181], v[210:213], v[64:67]
	v_mfma_f32_16x16x32_bf16 v[116:119], v[174:177], v[190:193], v[116:119]
	v_mfma_f32_16x16x32_bf16 v[112:115], v[182:185], v[190:193], v[112:115]
	v_mfma_f32_16x16x32_bf16 v[100:103], v[174:177], v[198:201], v[100:103]
	v_mfma_f32_16x16x32_bf16 v[96:99], v[182:185], v[198:201], v[96:99]
	v_mfma_f32_16x16x32_bf16 v[84:87], v[174:177], v[206:209], v[84:87]
	v_mfma_f32_16x16x32_bf16 v[80:83], v[182:185], v[206:209], v[80:83]
	v_mfma_f32_16x16x32_bf16 v[68:71], v[174:177], v[214:217], v[68:71]
	v_mfma_f32_16x16x32_bf16 v[64:67], v[182:185], v[214:217], v[64:67]
	s_setprio 0
	s_barrier
; #define PG8_STAGE(bufoff, gbase, voff) do { _Pragma("unroll") for (int _i = 0; _i < 2; ++_i) \
;         __builtin_amdgcn_global_load_lds((const unsigned*)((const char*)(gbase) + (voff)[_i]), (PG8_LAS unsigned*)(lds + (bufoff) + ldsw + _i * 8192), 16, 0, 0); } while (0)
; #define PG8_LDA(dst, b, h) do { _Pragma("unroll") for (int m = 0; m < 4; ++m) _Pragma("unroll") for (int k = 0; k < 2; ++k) dst[m][k] = *(const PG8_LAS bf16x8*)(lds + PG8_SA(b, h) + aoff + m * 2048 + k * 1024); } while (0)
; #define PG8_LDB(dst, b, h) do { _Pragma("unroll") for (int n = 0; n < 2; ++n) _Pragma("unroll") for (int k = 0; k < 2; ++k) dst[n][k] = *(const PG8_LAS bf16x8*)(lds + PG8_SB(b, h) + boff + n * 2048 + k * 1024); } while (0)
; template <class Epi, class Sched, bool ALIGN_EPI = false, bool SP2 = false>
; __device__ __forceinline__ void gemm_phase(PG8_LAS unsigned char* lds, const Gemm g, const Sched& S, const Epi& E) {
;     ...
;         for (int t = 0; t < nt; t += 2) {
;             const bool last = (t == nt - 2);
;             const char* a1 = cA + (size_t)(t + 1) * kstepA;
;             const char* a2 = last ? nA : cA + (size_t)(t + 2) * kstepA; const char* b2 = last ? nB : cB + (size_t)(t + 2) * kstep;
;             const char* a3 = a2 + kstepA; const char* b3 = b2 + kstep;
;             if (last && has_next) S.a_ready(nxt);
;             if constexpr (SP2) {
;             PG8_LDB(B0, 0, 0); PG8_LDB(B1, 0, 1); PG8_SCHED; PG8_LDA(At, 0, 0); PG8_STAGE(PG8_SA(1, 1), a1 + hstepA, voffA);
;             PG8_WAIT_V(8); PG8_WAIT_L(0); PG8_BAR; PG8_MMA(0, 0, At, B0); PG8_MMA(0, 1, At, B1); PG8_BAR; PG8_SCHED;
;             PG8_LDA(At, 0, 1); PG8_STAGE(PG8_SB(0, 0), b2, voffB); PG8_STAGE(PG8_SB(0, 1), b2 + hstep, voffB); PG8_STAGE(PG8_SA(0, 0), a2, voffA);
;             PG8_WAIT_V(8); PG8_WAIT_L(0); PG8_BAR; PG8_MMA(1, 0, At, B0); PG8_MMA(1, 1, At, B1); PG8_BAR; PG8_SCHED;
;             PG8_LDB(B0, 1, 0); PG8_LDB(B1, 1, 1); PG8_SCHED; PG8_LDA(At, 1, 0); PG8_STAGE(PG8_SA(0, 1), a2 + hstepA, voffA);
;             PG8_WAIT_V(8); PG8_WAIT_L(0); PG8_BAR; PG8_MMA(0, 0, At, B0); PG8_MMA(0, 1, At, B1); PG8_BAR; PG8_SCHED;
;             PG8_LDA(At, 1, 1); PG8_STAGE(PG8_SB(1, 0), b3, voffB); PG8_STAGE(PG8_SB(1, 1), b3 + hstep, voffB); PG8_STAGE(PG8_SA(1, 0), a3, voffA);
;             PG8_WAIT_V(8); PG8_WAIT_L(0); PG8_BAR; PG8_MMA(1, 0, At, B0); PG8_MMA(1, 1, At, B1); PG8_BAR; PG8_SCHED;
	s_add_i32 s42, s66, s33
	v_lshl_add_u64 v[148:149], v[148:149], 0, s[16:17]
	s_mov_b32 m0, s42
	ds_read_b128 v[186:189], v155 offset:49152
	ds_read_b128 v[190:193], v155 offset:50176
	ds_read_b128 v[194:197], v155 offset:51200
	ds_read_b128 v[198:201], v155 offset:52224
	ds_read_b128 v[202:205], v155 offset:53248
	ds_read_b128 v[206:209], v155 offset:54272
	ds_read_b128 v[210:213], v155 offset:55296
	ds_read_b128 v[214:217], v155 offset:56320
	global_load_lds_dwordx4 v[148:149], off
	s_add_i32 m0, s42, 0x2000
	s_add_u32 s40, s40, 0x2b0080
	v_lshl_add_u64 v[148:149], v[218:219], 0, s[16:17]
	s_addc_u32 s41, s41, 0
	s_add_i32 s42, s67, s33
	global_load_lds_dwordx4 v[148:149], off
	v_lshl_add_u64 v[148:149], s[40:41], 0, v[130:131]
	s_mov_b32 m0, s42
	s_nop 0
	global_load_lds_dwordx4 v[148:149], off
	v_lshl_add_u64 v[148:149], s[40:41], 0, v[134:135]
	s_add_i32 m0, s42, 0x2000
	s_nop 0
	global_load_lds_dwordx4 v[148:149], off
	v_lshl_add_u64 v[148:149], s[36:37], 0, v[128:129]
	s_mov_b32 m0, s49
	s_nop 0
	global_load_lds_dwordx4 v[148:149], off
	v_lshl_add_u64 v[148:149], s[36:37], 0, v[132:133]
	s_mov_b32 m0, s50
	s_nop 0
	global_load_lds_dwordx4 v[148:149], off
	s_waitcnt vmcnt(8)
	s_waitcnt lgkmcnt(0)
	s_barrier
	s_setprio 1
	s_waitcnt lgkmcnt(0)
	v_mfma_f32_16x16x32_bf16 v[60:63], v[144:147], v[186:189], v[60:63]
	v_mfma_f32_16x16x32_bf16 v[56:59], v[162:165], v[186:189], v[56:59]
	v_mfma_f32_16x16x32_bf16 v[44:47], v[144:147], v[194:197], v[44:47]
	v_mfma_f32_16x16x32_bf16 v[40:43], v[162:165], v[194:197], v[40:43]
	v_mfma_f32_16x16x32_bf16 v[28:31], v[144:147], v[202:205], v[28:31]
	v_mfma_f32_16x16x32_bf16 v[24:27], v[162:165], v[202:205], v[24:27]
	v_mfma_f32_16x16x32_bf16 v[12:15], v[144:147], v[210:213], v[12:15]
	v_mfma_f32_16x16x32_bf16 v[8:11], v[162:165], v[210:213], v[8:11]
	v_mfma_f32_16x16x32_bf16 v[60:63], v[158:161], v[190:193], v[60:63]
	v_mfma_f32_16x16x32_bf16 v[56:59], v[166:169], v[190:193], v[56:59]
	v_mfma_f32_16x16x32_bf16 v[44:47], v[158:161], v[198:201], v[44:47]
	v_mfma_f32_16x16x32_bf16 v[40:43], v[166:169], v[198:201], v[40:43]
	v_mfma_f32_16x16x32_bf16 v[28:31], v[158:161], v[206:209], v[28:31]
	v_mfma_f32_16x16x32_bf16 v[24:27], v[166:169], v[206:209], v[24:27]
	v_mfma_f32_16x16x32_bf16 v[12:15], v[158:161], v[214:217], v[12:15]
	v_mfma_f32_16x16x32_bf16 v[8:11], v[166:169], v[214:217], v[8:11]
	v_mfma_f32_16x16x32_bf16 v[52:55], v[170:173], v[186:189], v[52:55]
	v_mfma_f32_16x16x32_bf16 v[48:51], v[178:181], v[186:189], v[48:51]
	v_mfma_f32_16x16x32_bf16 v[36:39], v[170:173], v[194:197], v[36:39]
	v_mfma_f32_16x16x32_bf16 v[32:35], v[178:181], v[194:197], v[32:35]
	v_mfma_f32_16x16x32_bf16 v[20:23], v[170:173], v[202:205], v[20:23]
	v_mfma_f32_16x16x32_bf16 v[16:19], v[178:181], v[202:205], v[16:19]
	v_mfma_f32_16x16x32_bf16 v[4:7], v[170:173], v[210:213], v[4:7]
	v_mfma_f32_16x16x32_bf16 v[0:3], v[178:181], v[210:213], v[0:3]
	v_mfma_f32_16x16x32_bf16 v[52:55], v[174:177], v[190:193], v[52:55]
	v_mfma_f32_16x16x32_bf16 v[48:51], v[182:185], v[190:193], v[48:51]
	v_mfma_f32_16x16x32_bf16 v[36:39], v[174:177], v[198:201], v[36:39]
	v_mfma_f32_16x16x32_bf16 v[32:35], v[182:185], v[198:201], v[32:35]
	v_mfma_f32_16x16x32_bf16 v[20:23], v[174:177], v[206:209], v[20:23]
	v_mfma_f32_16x16x32_bf16 v[16:19], v[182:185], v[206:209], v[16:19]
	v_mfma_f32_16x16x32_bf16 v[4:7], v[174:177], v[214:217], v[4:7]
	v_mfma_f32_16x16x32_bf16 v[0:3], v[182:185], v[214:217], v[0:3]
	s_setprio 0
	s_barrier
	s_add_i32 s65, s65, 2
	s_add_u32 s63, s63, 0x100
	s_addc_u32 s64, s64, 0
	s_add_u32 s34, s34, 0x10000
	s_addc_u32 s35, s35, 0
	s_cmpk_gt_u32 s65, 0xa9
	s_cbranch_scc0 .LBB0_3087
	s_and_b64 vcc, exec, s[18:19]
	s_cbranch_vccz .LBB0_3090
	s_barrier

; #define PG8_STAGE(bufoff, gbase, voff) do { _Pragma("unroll") for (int _i = 0; _i < 2; ++_i) \
;         __builtin_amdgcn_global_load_lds((const unsigned*)((const char*)(gbase) + (voff)[_i]), (PG8_LAS unsigned*)(lds + (bufoff) + ldsw + _i * 8192), 16, 0, 0); } while (0)
; #define PG8_LDA(dst, b, h) do { _Pragma("unroll") for (int m = 0; m < 4; ++m) _Pragma("unroll") for (int k = 0; k < 2; ++k) dst[m][k] = *(const PG8_LAS bf16x8*)(lds + PG8_SA(b, h) + aoff + m * 2048 + k * 1024); } while (0)
; #define PG8_LDB(dst, b, h) do { _Pragma("unroll") for (int n = 0; n < 2; ++n) _Pragma("unroll") for (int k = 0; k < 2; ++k) dst[n][k] = *(const PG8_LAS bf16x8*)(lds + PG8_SB(b, h) + boff + n * 2048 + k * 1024); } while (0)
; #define PG8_WAIT_V(n) asm volatile("s_waitcnt vmcnt(" #n ")" ::: "memory")
; #define PG8_WAIT_L(n) asm volatile("s_waitcnt lgkmcnt(" #n ")" ::: "memory")
; #define PG8_BAR __builtin_amdgcn_s_barrier()
; #define PG8_SCHED __builtin_amdgcn_sched_barrier(0)
; template <class Epi, class Sched, bool ALIGN_EPI = false, bool SP2 = false>
; __device__ __forceinline__ void gemm_phase(PG8_LAS unsigned char* lds, const Gemm g, const Sched& S, const Epi& E) {
;     ...
;         const bool has_next = S.next(ui + 1, nxt);
;         const char* nA = has_next ? (const char*)g.A + (size_t)nxt.pm * tstep : cA; const char* nB = has_next ? (const char*)g.Bt + (size_t)nxt.pn * tstep : cB;
;         for (int t = 0; t < nt; t += 2) {
;             const bool last = (t == nt - 2);
;             const char* a1 = cA + (size_t)(t + 1) * kstepA;
;             const char* a2 = last ? nA : cA + (size_t)(t + 2) * kstepA; const char* b2 = last ? nB : cB + (size_t)(t + 2) * kstep;
;             const char* a3 = a2 + kstepA; const char* b3 = b2 + kstep;
;             if (last && has_next) S.a_ready(nxt);
;             if constexpr (SP2) {
;             PG8_LDB(B0, 0, 0); PG8_LDB(B1, 0, 1); PG8_SCHED; PG8_LDA(At, 0, 0); PG8_STAGE(PG8_SA(1, 1), a1 + hstepA, voffA);
;             PG8_WAIT_V(8); PG8_WAIT_L(0); PG8_BAR; PG8_MMA(0, 0, At, B0); PG8_MMA(0, 1, At, B1); PG8_BAR; PG8_SCHED;
;             PG8_LDA(At, 0, 1); PG8_STAGE(PG8_SB(0, 0), b2, voffB); PG8_STAGE(PG8_SB(0, 1), b2 + hstep, voffB); PG8_STAGE(PG8_SA(0, 0), a2, voffA);
;             PG8_WAIT_V(8); PG8_WAIT_L(0); PG8_BAR; PG8_MMA(1, 0, At, B0); PG8_MMA(1, 1, At, B1); PG8_BAR; PG8_SCHED;
.LBB0_3203:
	ds_read_b128 v[144:147], v155
	ds_read_b128 v[148:151], v155 offset:1024
	ds_read_b128 v[160:163], v155 offset:2048
	ds_read_b128 v[164:167], v155 offset:3072
	ds_read_b128 v[168:171], v156
	ds_read_b128 v[172:175], v156 offset:1024
	ds_read_b128 v[176:179], v156 offset:2048
	ds_read_b128 v[180:183], v156 offset:3072
	s_add_u32 s58, s56, 0xfff00080
	s_addc_u32 s59, s57, -1
	s_cmp_eq_u32 s74, 60
	s_cselect_b32 s61, s47, s59
	s_cselect_b32 s60, s53, s58
	s_cselect_b32 s59, s45, s73
	s_cselect_b32 s58, s71, s72
	v_lshl_add_u64 v[216:217], s[56:57], 0, v[136:137]
	s_add_i32 m0, s29, 0xc000
	ds_read_b128 v[184:187], v157
	ds_read_b128 v[188:191], v157 offset:1024
	ds_read_b128 v[192:195], v157 offset:2048
	ds_read_b128 v[196:199], v157 offset:3072
	ds_read_b128 v[200:203], v157 offset:4096
	ds_read_b128 v[204:207], v157 offset:5120
	ds_read_b128 v[208:211], v157 offset:6144
	ds_read_b128 v[212:215], v157 offset:7168
	global_load_lds_dwordx4 v[216:217], off
	v_lshl_add_u64 v[216:217], s[56:57], 0, v[138:139]
	s_add_i32 m0, s29, 0xe000
	s_nop 0
	global_load_lds_dwordx4 v[216:217], off
	s_waitcnt vmcnt(8)
	s_waitcnt lgkmcnt(0)
	s_barrier
	s_setprio 1
	s_waitcnt lgkmcnt(0)
	v_mfma_f32_16x16x32_bf16 v[124:127], v[144:147], v[184:187], v[124:127]
	v_mfma_f32_16x16x32_bf16 v[72:75], v[160:163], v[184:187], v[72:75]
	v_mfma_f32_16x16x32_bf16 v[116:119], v[144:147], v[192:195], v[116:119]
	v_mfma_f32_16x16x32_bf16 v[68:71], v[160:163], v[192:195], v[68:71]
	v_mfma_f32_16x16x32_bf16 v[108:111], v[144:147], v[200:203], v[108:111]
	v_mfma_f32_16x16x32_bf16 v[96:99], v[160:163], v[200:203], v[96:99]
	v_mfma_f32_16x16x32_bf16 v[92:95], v[144:147], v[208:211], v[92:95]
	v_mfma_f32_16x16x32_bf16 v[88:91], v[160:163], v[208:211], v[88:91]
	v_mfma_f32_16x16x32_bf16 v[124:127], v[148:151], v[188:191], v[124:127]
	v_mfma_f32_16x16x32_bf16 v[72:75], v[164:167], v[188:191], v[72:75]
	v_mfma_f32_16x16x32_bf16 v[116:119], v[148:151], v[196:199], v[116:119]
	v_mfma_f32_16x16x32_bf16 v[68:71], v[164:167], v[196:199], v[68:71]
	v_mfma_f32_16x16x32_bf16 v[108:111], v[148:151], v[204:207], v[108:111]
	v_mfma_f32_16x16x32_bf16 v[96:99], v[164:167], v[204:207], v[96:99]
	v_mfma_f32_16x16x32_bf16 v[92:95], v[148:151], v[212:215], v[92:95]
	v_mfma_f32_16x16x32_bf16 v[88:91], v[164:167], v[212:215], v[88:91]
	v_mfma_f32_16x16x32_bf16 v[120:123], v[168:171], v[184:187], v[120:123]
	v_mfma_f32_16x16x32_bf16 v[84:87], v[176:179], v[184:187], v[84:87]
	v_mfma_f32_16x16x32_bf16 v[112:115], v[168:171], v[192:195], v[112:115]
	v_mfma_f32_16x16x32_bf16 v[80:83], v[176:179], v[192:195], v[80:83]
	v_mfma_f32_16x16x32_bf16 v[104:107], v[168:171], v[200:203], v[104:107]
	v_mfma_f32_16x16x32_bf16 v[100:103], v[176:179], v[200:203], v[100:103]
	v_mfma_f32_16x16x32_bf16 v[76:79], v[168:171], v[208:211], v[76:79]
	v_mfma_f32_16x16x32_bf16 v[64:67], v[176:179], v[208:211], v[64:67]
	v_mfma_f32_16x16x32_bf16 v[120:123], v[172:175], v[188:191], v[120:123]
	v_mfma_f32_16x16x32_bf16 v[84:87], v[180:183], v[188:191], v[84:87]
	v_mfma_f32_16x16x32_bf16 v[112:115], v[172:175], v[196:199], v[112:115]
	v_mfma_f32_16x16x32_bf16 v[80:83], v[180:183], v[196:199], v[80:83]
	v_mfma_f32_16x16x32_bf16 v[104:107], v[172:175], v[204:207], v[104:107]
	v_mfma_f32_16x16x32_bf16 v[100:103], v[180:183], v[204:207], v[100:103]
	v_mfma_f32_16x16x32_bf16 v[76:79], v[172:175], v[212:215], v[76:79]
	v_mfma_f32_16x16x32_bf16 v[64:67], v[180:183], v[212:215], v[64:67]
	s_setprio 0
	s_barrier
	s_add_i32 s75, s68, s3
	v_lshl_add_u64 v[216:217], s[58:59], 0, v[130:131]
	s_mov_b32 m0, s75
	ds_read_b128 v[184:187], v157 offset:16384
	ds_read_b128 v[188:191], v157 offset:17408
	ds_read_b128 v[192:195], v157 offset:18432
	ds_read_b128 v[196:199], v157 offset:19456
	ds_read_b128 v[200:203], v157 offset:20480
	ds_read_b128 v[204:207], v157 offset:21504
	ds_read_b128 v[208:211], v157 offset:22528
	ds_read_b128 v[212:215], v157 offset:23552
	global_load_lds_dwordx4 v[216:217], off
	s_add_i32 m0, s75, 0x2000
	s_add_u32 s84, s58, 0x100000
	v_lshl_add_u64 v[218:219], s[58:59], 0, v[134:135]
	s_addc_u32 s85, s59, 0
	s_add_i32 s75, s69, s3
	global_load_lds_dwordx4 v[218:219], off
	v_lshl_add_u64 v[220:221], s[84:85], 0, v[130:131]
	s_mov_b32 m0, s75
	v_lshl_add_u64 v[222:223], s[60:61], 0, v[132:133]
	global_load_lds_dwordx4 v[220:221], off
	v_lshl_add_u64 v[220:221], s[84:85], 0, v[134:135]
	s_add_i32 m0, s75, 0x2000
	s_nop 0
	global_load_lds_dwordx4 v[220:221], off
	v_lshl_add_u64 v[220:221], s[60:61], 0, v[128:129]
	s_mov_b32 m0, s29
	s_nop 0
	global_load_lds_dwordx4 v[220:221], off
	s_mov_b32 m0, s33
	s_nop 0
	global_load_lds_dwordx4 v[222:223], off
	s_waitcnt vmcnt(8)
	s_waitcnt lgkmcnt(0)
	s_barrier
; #define PG8_STAGE(bufoff, gbase, voff) do { _Pragma("unroll") for (int _i = 0; _i < 2; ++_i) \
;         __builtin_amdgcn_global_load_lds((const unsigned*)((const char*)(gbase) + (voff)[_i]), (PG8_LAS unsigned*)(lds + (bufoff) + ldsw + _i * 8192), 16, 0, 0); } while (0)
; #define PG8_LDA(dst, b, h) do { _Pragma("unroll") for (int m = 0; m < 4; ++m) _Pragma("unroll") for (int k = 0; k < 2; ++k) dst[m][k] = *(const PG8_LAS bf16x8*)(lds + PG8_SA(b, h) + aoff + m * 2048 + k * 1024); } while (0)
; #define PG8_LDB(dst, b, h) do { _Pragma("unroll") for (int n = 0; n < 2; ++n) _Pragma("unroll") for (int k = 0; k < 2; ++k) dst[n][k] = *(const PG8_LAS bf16x8*)(lds + PG8_SB(b, h) + boff + n * 2048 + k * 1024); } while (0)
; #define PG8_MMA(ai, bj, At, Bt) do { __builtin_amdgcn_s_setprio(1); _Pragma("unroll") for (int m = 0; m < 4; ++m) _Pragma("unroll") for (int n = 0; n < 2; ++n) _Pragma("unroll") for (int k = 0; k < 2; ++k) \
;         acc[ai][bj][m][n] = __builtin_amdgcn_mfma_f32_16x16x32_bf16(Bt[n][k], At[m][k], acc[ai][bj][m][n], 0, 0, 0); __builtin_amdgcn_s_setprio(0); } while (0)
; #define PG8_WAIT_V(n) asm volatile("s_waitcnt vmcnt(" #n ")" ::: "memory")
; #define PG8_WAIT_L(n) asm volatile("s_waitcnt lgkmcnt(" #n ")" ::: "memory")
; #define PG8_BAR __builtin_amdgcn_s_barrier()
; #define PG8_SCHED __builtin_amdgcn_sched_barrier(0)
; template <class Epi, class Sched, bool ALIGN_EPI = false, bool SP2 = false>
; __device__ __forceinline__ void gemm_phase(PG8_LAS unsigned char* lds, const Gemm g, const Sched& S, const Epi& E) {
;     ...
;             PG8_WAIT_V(8); PG8_WAIT_L(0); PG8_BAR; PG8_MMA(0, 0, At, B0); PG8_MMA(0, 1, At, B1); PG8_BAR; PG8_SCHED;
;             PG8_LDA(At, 0, 1); PG8_STAGE(PG8_SB(0, 0), b2, voffB); PG8_STAGE(PG8_SB(0, 1), b2 + hstep, voffB); PG8_STAGE(PG8_SA(0, 0), a2, voffA);
;             PG8_WAIT_V(8); PG8_WAIT_L(0); PG8_BAR; PG8_MMA(1, 0, At, B0); PG8_MMA(1, 1, At, B1); PG8_BAR; PG8_SCHED;
;             PG8_LDB(B0, 1, 0); PG8_LDB(B1, 1, 1); PG8_SCHED; PG8_LDA(At, 1, 0); PG8_STAGE(PG8_SA(0, 1), a2 + hstepA, voffA);
;             PG8_WAIT_V(8); PG8_WAIT_L(0); PG8_BAR; PG8_MMA(0, 0, At, B0); PG8_MMA(0, 1, At, B1); PG8_BAR; PG8_SCHED;
	s_setprio 1
	s_waitcnt lgkmcnt(0)
	v_mfma_f32_16x16x32_bf16 v[60:63], v[144:147], v[184:187], v[60:63]
	v_mfma_f32_16x16x32_bf16 v[56:59], v[160:163], v[184:187], v[56:59]
	v_mfma_f32_16x16x32_bf16 v[44:47], v[144:147], v[192:195], v[44:47]
	v_mfma_f32_16x16x32_bf16 v[40:43], v[160:163], v[192:195], v[40:43]
	v_mfma_f32_16x16x32_bf16 v[28:31], v[144:147], v[200:203], v[28:31]
	v_mfma_f32_16x16x32_bf16 v[24:27], v[160:163], v[200:203], v[24:27]
	v_mfma_f32_16x16x32_bf16 v[12:15], v[144:147], v[208:211], v[12:15]
	v_mfma_f32_16x16x32_bf16 v[8:11], v[160:163], v[208:211], v[8:11]
	v_mfma_f32_16x16x32_bf16 v[60:63], v[148:151], v[188:191], v[60:63]
	v_mfma_f32_16x16x32_bf16 v[56:59], v[164:167], v[188:191], v[56:59]
	v_mfma_f32_16x16x32_bf16 v[44:47], v[148:151], v[196:199], v[44:47]
	v_mfma_f32_16x16x32_bf16 v[40:43], v[164:167], v[196:199], v[40:43]
	v_mfma_f32_16x16x32_bf16 v[28:31], v[148:151], v[204:207], v[28:31]
	v_mfma_f32_16x16x32_bf16 v[24:27], v[164:167], v[204:207], v[24:27]
	v_mfma_f32_16x16x32_bf16 v[12:15], v[148:151], v[212:215], v[12:15]
	v_mfma_f32_16x16x32_bf16 v[8:11], v[164:167], v[212:215], v[8:11]
	v_mfma_f32_16x16x32_bf16 v[52:55], v[168:171], v[184:187], v[52:55]
	v_mfma_f32_16x16x32_bf16 v[48:51], v[176:179], v[184:187], v[48:51]
	v_mfma_f32_16x16x32_bf16 v[36:39], v[168:171], v[192:195], v[36:39]
	v_mfma_f32_16x16x32_bf16 v[32:35], v[176:179], v[192:195], v[32:35]
	v_mfma_f32_16x16x32_bf16 v[20:23], v[168:171], v[200:203], v[20:23]
	v_mfma_f32_16x16x32_bf16 v[16:19], v[176:179], v[200:203], v[16:19]
	v_mfma_f32_16x16x32_bf16 v[4:7], v[168:171], v[208:211], v[4:7]
	v_mfma_f32_16x16x32_bf16 v[0:3], v[176:179], v[208:211], v[0:3]
	v_mfma_f32_16x16x32_bf16 v[52:55], v[172:175], v[188:191], v[52:55]
	v_mfma_f32_16x16x32_bf16 v[48:51], v[180:183], v[188:191], v[48:51]
	v_mfma_f32_16x16x32_bf16 v[36:39], v[172:175], v[196:199], v[36:39]
	v_mfma_f32_16x16x32_bf16 v[32:35], v[180:183], v[196:199], v[32:35]
	v_mfma_f32_16x16x32_bf16 v[20:23], v[172:175], v[204:207], v[20:23]
	v_mfma_f32_16x16x32_bf16 v[16:19], v[180:183], v[204:207], v[16:19]
	v_mfma_f32_16x16x32_bf16 v[4:7], v[172:175], v[212:215], v[4:7]
	v_mfma_f32_16x16x32_bf16 v[0:3], v[180:183], v[212:215], v[0:3]
	s_setprio 0
	s_barrier
	s_add_i32 s75, 0, 0x18000
	s_add_i32 s84, 0, 0x1c000
	v_add_u32_e32 v164, s75, v153
	v_add_u32_e32 v180, s84, v153
	ds_read_b128 v[144:147], v164
	ds_read_b128 v[148:151], v164 offset:1024
	ds_read_b128 v[160:163], v164 offset:2048
	ds_read_b128 v[164:167], v164 offset:3072
	ds_read_b128 v[168:171], v180
	ds_read_b128 v[172:175], v180 offset:1024
	ds_read_b128 v[176:179], v180 offset:2048
	ds_read_b128 v[180:183], v180 offset:3072
	s_add_u32 s60, s60, 0x100000
	s_addc_u32 s61, s61, 0
	s_mov_b32 m0, s55
	v_lshl_add_u64 v[224:225], s[60:61], 0, v[128:129]
	ds_read_b128 v[184:187], v157 offset:32768
	ds_read_b128 v[188:191], v157 offset:33792
	ds_read_b128 v[192:195], v157 offset:34816
	ds_read_b128 v[196:199], v157 offset:35840
	ds_read_b128 v[200:203], v157 offset:36864
	ds_read_b128 v[204:207], v157 offset:37888
	ds_read_b128 v[208:211], v157 offset:38912
	ds_read_b128 v[212:215], v157 offset:39936
	global_load_lds_dwordx4 v[224:225], off
	v_lshl_add_u64 v[224:225], s[60:61], 0, v[132:133]
	s_mov_b32 m0, s62
	s_nop 0
	global_load_lds_dwordx4 v[224:225], off
	s_waitcnt vmcnt(8)
	s_waitcnt lgkmcnt(0)
	s_barrier
	s_setprio 1
	s_waitcnt lgkmcnt(0)
	v_mfma_f32_16x16x32_bf16 v[124:127], v[144:147], v[184:187], v[124:127]
	v_mfma_f32_16x16x32_bf16 v[72:75], v[160:163], v[184:187], v[72:75]
	v_mfma_f32_16x16x32_bf16 v[116:119], v[144:147], v[192:195], v[116:119]
	v_mfma_f32_16x16x32_bf16 v[68:71], v[160:163], v[192:195], v[68:71]
	v_mfma_f32_16x16x32_bf16 v[108:111], v[144:147], v[200:203], v[108:111]
	v_mfma_f32_16x16x32_bf16 v[96:99], v[160:163], v[200:203], v[96:99]
	v_mfma_f32_16x16x32_bf16 v[92:95], v[144:147], v[208:211], v[92:95]
	v_mfma_f32_16x16x32_bf16 v[88:91], v[160:163], v[208:211], v[88:91]
	v_mfma_f32_16x16x32_bf16 v[124:127], v[148:151], v[188:191], v[124:127]
	v_mfma_f32_16x16x32_bf16 v[72:75], v[164:167], v[188:191], v[72:75]
	v_mfma_f32_16x16x32_bf16 v[116:119], v[148:151], v[196:199], v[116:119]
	v_mfma_f32_16x16x32_bf16 v[68:71], v[164:167], v[196:199], v[68:71]
	v_mfma_f32_16x16x32_bf16 v[108:111], v[148:151], v[204:207], v[108:111]
	v_mfma_f32_16x16x32_bf16 v[96:99], v[164:167], v[204:207], v[96:99]
	v_mfma_f32_16x16x32_bf16 v[92:95], v[148:151], v[212:215], v[92:95]
	v_mfma_f32_16x16x32_bf16 v[88:91], v[164:167], v[212:215], v[88:91]
	v_mfma_f32_16x16x32_bf16 v[120:123], v[168:171], v[184:187], v[120:123]
	v_mfma_f32_16x16x32_bf16 v[84:87], v[176:179], v[184:187], v[84:87]
	v_mfma_f32_16x16x32_bf16 v[112:115], v[168:171], v[192:195], v[112:115]
	v_mfma_f32_16x16x32_bf16 v[80:83], v[176:179], v[192:195], v[80:83]
	v_mfma_f32_16x16x32_bf16 v[104:107], v[168:171], v[200:203], v[104:107]
	v_mfma_f32_16x16x32_bf16 v[100:103], v[176:179], v[200:203], v[100:103]
	v_mfma_f32_16x16x32_bf16 v[76:79], v[168:171], v[208:211], v[76:79]
	v_mfma_f32_16x16x32_bf16 v[64:67], v[176:179], v[208:211], v[64:67]
	v_mfma_f32_16x16x32_bf16 v[120:123], v[172:175], v[188:191], v[120:123]
	v_mfma_f32_16x16x32_bf16 v[84:87], v[180:183], v[188:191], v[84:87]
	v_mfma_f32_16x16x32_bf16 v[112:115], v[172:175], v[196:199], v[112:115]
	v_mfma_f32_16x16x32_bf16 v[80:83], v[180:183], v[196:199], v[80:83]
	v_mfma_f32_16x16x32_bf16 v[104:107], v[172:175], v[204:207], v[104:107]
	v_mfma_f32_16x16x32_bf16 v[100:103], v[180:183], v[204:207], v[100:103]
	v_mfma_f32_16x16x32_bf16 v[76:79], v[172:175], v[212:215], v[76:79]
	v_mfma_f32_16x16x32_bf16 v[64:67], v[180:183], v[212:215], v[64:67]
	s_setprio 0
	s_barrier
; #define PG8_STAGE(bufoff, gbase, voff) do { _Pragma("unroll") for (int _i = 0; _i < 2; ++_i) \
;         __builtin_amdgcn_global_load_lds((const unsigned*)((const char*)(gbase) + (voff)[_i]), (PG8_LAS unsigned*)(lds + (bufoff) + ldsw + _i * 8192), 16, 0, 0); } while (0)
; #define PG8_LDA(dst, b, h) do { _Pragma("unroll") for (int m = 0; m < 4; ++m) _Pragma("unroll") for (int k = 0; k < 2; ++k) dst[m][k] = *(const PG8_LAS bf16x8*)(lds + PG8_SA(b, h) + aoff + m * 2048 + k * 1024); } while (0)
; #define PG8_LDB(dst, b, h) do { _Pragma("unroll") for (int n = 0; n < 2; ++n) _Pragma("unroll") for (int k = 0; k < 2; ++k) dst[n][k] = *(const PG8_LAS bf16x8*)(lds + PG8_SB(b, h) + boff + n * 2048 + k * 1024); } while (0)
; template <class Epi, class Sched, bool ALIGN_EPI = false, bool SP2 = false>
; __device__ __forceinline__ void gemm_phase(PG8_LAS unsigned char* lds, const Gemm g, const Sched& S, const Epi& E) {
;     ...
;         for (int t = 0; t < nt; t += 2) {
;             const bool last = (t == nt - 2);
;             const char* a1 = cA + (size_t)(t + 1) * kstepA;
;             const char* a2 = last ? nA : cA + (size_t)(t + 2) * kstepA; const char* b2 = last ? nB : cB + (size_t)(t + 2) * kstep;
;             const char* a3 = a2 + kstepA; const char* b3 = b2 + kstep;
;             if (last && has_next) S.a_ready(nxt);
;             if constexpr (SP2) {
;             PG8_LDB(B0, 0, 0); PG8_LDB(B1, 0, 1); PG8_SCHED; PG8_LDA(At, 0, 0); PG8_STAGE(PG8_SA(1, 1), a1 + hstepA, voffA);
;             PG8_WAIT_V(8); PG8_WAIT_L(0); PG8_BAR; PG8_MMA(0, 0, At, B0); PG8_MMA(0, 1, At, B1); PG8_BAR; PG8_SCHED;
;             PG8_LDA(At, 0, 1); PG8_STAGE(PG8_SB(0, 0), b2, voffB); PG8_STAGE(PG8_SB(0, 1), b2 + hstep, voffB); PG8_STAGE(PG8_SA(0, 0), a2, voffA);
;             PG8_WAIT_V(8); PG8_WAIT_L(0); PG8_BAR; PG8_MMA(1, 0, At, B0); PG8_MMA(1, 1, At, B1); PG8_BAR; PG8_SCHED;
;             PG8_LDB(B0, 1, 0); PG8_LDB(B1, 1, 1); PG8_SCHED; PG8_LDA(At, 1, 0); PG8_STAGE(PG8_SA(0, 1), a2 + hstepA, voffA);
;             PG8_WAIT_V(8); PG8_WAIT_L(0); PG8_BAR; PG8_MMA(0, 0, At, B0); PG8_MMA(0, 1, At, B1); PG8_BAR; PG8_SCHED;
;             PG8_LDA(At, 1, 1); PG8_STAGE(PG8_SB(1, 0), b3, voffB); PG8_STAGE(PG8_SB(1, 1), b3 + hstep, voffB); PG8_STAGE(PG8_SA(1, 0), a3, voffA);
;             PG8_WAIT_V(8); PG8_WAIT_L(0); PG8_BAR; PG8_MMA(1, 0, At, B0); PG8_MMA(1, 1, At, B1); PG8_BAR; PG8_SCHED;
	s_add_i32 s60, s75, s3
	v_lshl_add_u64 v[216:217], v[216:217], 0, s[20:21]
	s_mov_b32 m0, s60
	ds_read_b128 v[184:187], v157 offset:49152
	ds_read_b128 v[188:191], v157 offset:50176
	ds_read_b128 v[192:195], v157 offset:51200
	ds_read_b128 v[196:199], v157 offset:52224
	ds_read_b128 v[200:203], v157 offset:53248
	ds_read_b128 v[204:207], v157 offset:54272
	ds_read_b128 v[208:211], v157 offset:55296
	ds_read_b128 v[212:215], v157 offset:56320
	global_load_lds_dwordx4 v[216:217], off
	s_add_i32 m0, s60, 0x2000
	s_add_u32 s58, s58, 0x100080
	v_lshl_add_u64 v[216:217], v[218:219], 0, s[20:21]
	s_addc_u32 s59, s59, 0
	s_add_i32 s60, s84, s3
	global_load_lds_dwordx4 v[216:217], off
	v_lshl_add_u64 v[216:217], s[58:59], 0, v[130:131]
	s_mov_b32 m0, s60
	s_nop 0
	global_load_lds_dwordx4 v[216:217], off
	v_lshl_add_u64 v[216:217], s[58:59], 0, v[134:135]
	s_add_i32 m0, s60, 0x2000
	s_nop 0
	global_load_lds_dwordx4 v[216:217], off
	v_lshl_add_u64 v[216:217], v[220:221], 0, s[20:21]
	s_mov_b32 m0, s64
	s_nop 0
	global_load_lds_dwordx4 v[216:217], off
	v_lshl_add_u64 v[216:217], v[222:223], 0, s[20:21]
	s_mov_b32 m0, s65
	s_nop 0
	global_load_lds_dwordx4 v[216:217], off
	s_waitcnt vmcnt(8)
	s_waitcnt lgkmcnt(0)
	s_barrier
	s_setprio 1
	s_waitcnt lgkmcnt(0)
	v_mfma_f32_16x16x32_bf16 v[60:63], v[144:147], v[184:187], v[60:63]
	v_mfma_f32_16x16x32_bf16 v[56:59], v[160:163], v[184:187], v[56:59]
	v_mfma_f32_16x16x32_bf16 v[44:47], v[144:147], v[192:195], v[44:47]
	v_mfma_f32_16x16x32_bf16 v[40:43], v[160:163], v[192:195], v[40:43]
	v_mfma_f32_16x16x32_bf16 v[28:31], v[144:147], v[200:203], v[28:31]
	v_mfma_f32_16x16x32_bf16 v[24:27], v[160:163], v[200:203], v[24:27]
	v_mfma_f32_16x16x32_bf16 v[12:15], v[144:147], v[208:211], v[12:15]
	v_mfma_f32_16x16x32_bf16 v[8:11], v[160:163], v[208:211], v[8:11]
	v_mfma_f32_16x16x32_bf16 v[60:63], v[148:151], v[188:191], v[60:63]
	v_mfma_f32_16x16x32_bf16 v[56:59], v[164:167], v[188:191], v[56:59]
	v_mfma_f32_16x16x32_bf16 v[44:47], v[148:151], v[196:199], v[44:47]
	v_mfma_f32_16x16x32_bf16 v[40:43], v[164:167], v[196:199], v[40:43]
	v_mfma_f32_16x16x32_bf16 v[28:31], v[148:151], v[204:207], v[28:31]
	v_mfma_f32_16x16x32_bf16 v[24:27], v[164:167], v[204:207], v[24:27]
	v_mfma_f32_16x16x32_bf16 v[12:15], v[148:151], v[212:215], v[12:15]
	v_mfma_f32_16x16x32_bf16 v[8:11], v[164:167], v[212:215], v[8:11]
	v_mfma_f32_16x16x32_bf16 v[52:55], v[168:171], v[184:187], v[52:55]
	v_mfma_f32_16x16x32_bf16 v[48:51], v[176:179], v[184:187], v[48:51]
	v_mfma_f32_16x16x32_bf16 v[36:39], v[168:171], v[192:195], v[36:39]
	v_mfma_f32_16x16x32_bf16 v[32:35], v[176:179], v[192:195], v[32:35]
	v_mfma_f32_16x16x32_bf16 v[20:23], v[168:171], v[200:203], v[20:23]
	v_mfma_f32_16x16x32_bf16 v[16:19], v[176:179], v[200:203], v[16:19]
	v_mfma_f32_16x16x32_bf16 v[4:7], v[168:171], v[208:211], v[4:7]
	v_mfma_f32_16x16x32_bf16 v[0:3], v[176:179], v[208:211], v[0:3]
	v_mfma_f32_16x16x32_bf16 v[52:55], v[172:175], v[188:191], v[52:55]
	v_mfma_f32_16x16x32_bf16 v[48:51], v[180:183], v[188:191], v[48:51]
	v_mfma_f32_16x16x32_bf16 v[36:39], v[172:175], v[196:199], v[36:39]
	v_mfma_f32_16x16x32_bf16 v[32:35], v[180:183], v[196:199], v[32:35]
	v_mfma_f32_16x16x32_bf16 v[20:23], v[172:175], v[204:207], v[20:23]
	v_mfma_f32_16x16x32_bf16 v[16:19], v[180:183], v[204:207], v[16:19]
	v_mfma_f32_16x16x32_bf16 v[4:7], v[172:175], v[212:215], v[4:7]
	v_mfma_f32_16x16x32_bf16 v[0:3], v[180:183], v[212:215], v[0:3]
	s_setprio 0
	s_barrier
	s_add_i32 s74, s74, 2
	s_add_u32 s56, s56, 0x100
	s_addc_u32 s57, s57, 0
	s_add_u32 s72, s72, 0x100
	s_addc_u32 s73, s73, 0
	s_cmp_gt_u32 s74, 61
	s_cbranch_scc0 .LBB0_3203
	s_and_b64 vcc, exec, s[22:23]
	s_cbranch_vccz .LBB0_3206
	s_barrier
